# GEMM epilogues: IEEE division/sqrt sequences replaced by v_rcp_f32/v_sqrt_f32 (1 ulp f32, results rounded to bf16 as before), dead code removed, wait states re-derived
# speedup vs baseline: 1.0673x; 1.0241x over previous
; template <int ACT> __device__ __forceinline__ void store_tile_bf16(AccRef acc, bf16_t* dst, int ld, int row0, int col0) {
; #pragma unroll
;     for (int ai = 0; ai < 2; ++ai)
; #pragma unroll
;         for (int m = 0; m < 4; ++m) { bf16_t* rowp = dst + (size_t)(row0 + ai * 128 + m * 16) * ld + col0;
; #pragma unroll
;             for (int bj = 0; bj < 2; ++bj) { const f32x4 v0 = acc[ai][bj][m][0], v1 = acc[ai][bj][m][1];
;                 u32x4 w; w.x = cvt_pk_bf16(actf<ACT>(v0[0]), actf<ACT>(v0[1])); w.y = cvt_pk_bf16(actf<ACT>(v0[2]), actf<ACT>(v0[3]));
;                 w.z = cvt_pk_bf16(actf<ACT>(v1[0]), actf<ACT>(v1[1])); w.w = cvt_pk_bf16(actf<ACT>(v1[2]), actf<ACT>(v1[3]));
;                 *(u32x4*)(rowp + bj * 128) = w; } }
.LBB0_420:
	s_andn2_b64 vcc, exec, s[60:61]
	s_cbranch_vccnz .LBB0_413
	v_lshl_add_u64 v[130:131], s[40:41], 0, v[142:143]
	v_mul_f32_e32 v142, 0x3d372713, v126
	v_mul_f32_e32 v142, v126, v142
	v_fma_f32 v142, v126, v142, v126
	v_mul_f32_e32 v142, 0xbfcc422a, v142
	v_mul_f32_e32 v142, 0x3fb8aa3b, v142
	v_exp_f32_e32 v142, v142
	v_lshl_add_u64 v[132:133], v[130:131], 0, v[162:163]
	s_mov_b32 s3, 0xb0000
	v_add_f32_e32 v142, 1.0, v142
	v_rcp_f32_e32 v160, v142
	s_nop 0
	v_mul_f32_e32 v126, v126, v160
	v_mul_f32_e32 v142, 0x3d372713, v127
	v_mul_f32_e32 v142, v127, v142
	v_fma_f32 v142, v127, v142, v127
	v_mul_f32_e32 v142, 0xbfcc422a, v142
	v_mul_f32_e32 v142, 0x3fb8aa3b, v142
	v_exp_f32_e32 v142, v142
	s_nop 0
	v_add_f32_e32 v142, 1.0, v142
	v_rcp_f32_e32 v160, v142
	s_nop 0
	v_mul_f32_e32 v127, v127, v160
	v_cvt_pk_bf16_f32 v126, v126, v127
	v_mul_f32_e32 v127, 0x3d372713, v128
	v_mul_f32_e32 v127, v128, v127
	v_fma_f32 v127, v128, v127, v128
	v_mul_f32_e32 v127, 0xbfcc422a, v127
	v_mul_f32_e32 v127, 0x3fb8aa3b, v127
	v_exp_f32_e32 v127, v127
	s_nop 0
	v_add_f32_e32 v127, 1.0, v127
	v_rcp_f32_e32 v127, v127
	s_nop 0
	v_mul_f32_e32 v127, v128, v127
	v_mul_f32_e32 v128, 0x3d372713, v129
	v_mul_f32_e32 v128, v129, v128
	v_fma_f32 v128, v129, v128, v129
	v_mul_f32_e32 v128, 0xbfcc422a, v128
	v_mul_f32_e32 v128, 0x3fb8aa3b, v128
	v_exp_f32_e32 v128, v128
	s_nop 0
	v_add_f32_e32 v128, 1.0, v128
	v_rcp_f32_e32 v128, v128
	s_nop 0
	v_mul_f32_e32 v128, v129, v128
	v_cvt_pk_bf16_f32 v127, v127, v128
	v_mul_f32_e32 v128, 0x3d372713, v122
	v_mul_f32_e32 v128, v122, v128
	v_fma_f32 v128, v122, v128, v122
	v_mul_f32_e32 v128, 0xbfcc422a, v128
	v_mul_f32_e32 v128, 0x3fb8aa3b, v128
	v_exp_f32_e32 v128, v128
	s_nop 0
	v_add_f32_e32 v128, 1.0, v128
	v_rcp_f32_e32 v129, v128
	s_nop 0
	v_mul_f32_e32 v122, v122, v129
	v_mul_f32_e32 v128, 0x3d372713, v123
	v_mul_f32_e32 v128, v123, v128
	v_fma_f32 v128, v123, v128, v123
	v_mul_f32_e32 v128, 0xbfcc422a, v128
	v_mul_f32_e32 v128, 0x3fb8aa3b, v128
	v_exp_f32_e32 v128, v128
	s_nop 0
	v_add_f32_e32 v128, 1.0, v128
	v_rcp_f32_e32 v129, v128
	s_nop 0
	v_mul_f32_e32 v123, v123, v129
	v_cvt_pk_bf16_f32 v128, v122, v123
	v_mul_f32_e32 v122, 0x3d372713, v124
	v_mul_f32_e32 v122, v124, v122
	v_fma_f32 v122, v124, v122, v124
	v_mul_f32_e32 v122, 0xbfcc422a, v122
	v_mul_f32_e32 v122, 0x3fb8aa3b, v122
	v_exp_f32_e32 v122, v122
	s_nop 0
	v_add_f32_e32 v122, 1.0, v122
	v_rcp_f32_e32 v122, v122
	s_nop 0
	v_mul_f32_e32 v122, v124, v122
	v_mul_f32_e32 v123, 0x3d372713, v125
	v_mul_f32_e32 v123, v125, v123
	v_fma_f32 v123, v125, v123, v125
	v_mul_f32_e32 v123, 0xbfcc422a, v123
	v_mul_f32_e32 v123, 0x3fb8aa3b, v123
	v_exp_f32_e32 v123, v123
	s_nop 0
	v_add_f32_e32 v123, 1.0, v123
	v_rcp_f32_e32 v123, v123
	s_nop 0
	v_mul_f32_e32 v123, v125, v123
	v_cvt_pk_bf16_f32 v129, v122, v123
	v_mul_f32_e32 v122, 0x3d372713, v118
	v_mul_f32_e32 v122, v118, v122
	v_fma_f32 v122, v118, v122, v118
	v_mul_f32_e32 v122, 0xbfcc422a, v122
	v_mul_f32_e32 v122, 0x3fb8aa3b, v122
	v_exp_f32_e32 v122, v122
	global_store_dwordx4 v[132:133], v[126:129], off
	v_add_f32_e32 v122, 1.0, v122
	v_rcp_f32_e32 v123, v122
	s_nop 0
	v_mul_f32_e32 v118, v118, v123
	v_mul_f32_e32 v122, 0x3d372713, v119
	v_mul_f32_e32 v122, v119, v122
	v_fma_f32 v122, v119, v122, v119
	v_mul_f32_e32 v122, 0xbfcc422a, v122
	v_mul_f32_e32 v122, 0x3fb8aa3b, v122
	v_exp_f32_e32 v122, v122
	s_nop 0
	v_add_f32_e32 v122, 1.0, v122
	v_rcp_f32_e32 v123, v122
	s_nop 0
	v_mul_f32_e32 v119, v119, v123
	v_cvt_pk_bf16_f32 v118, v118, v119
	v_mul_f32_e32 v119, 0x3d372713, v120
	v_mul_f32_e32 v119, v120, v119
	v_fma_f32 v119, v120, v119, v120
	v_mul_f32_e32 v119, 0xbfcc422a, v119
	v_mul_f32_e32 v119, 0x3fb8aa3b, v119
	v_exp_f32_e32 v119, v119
	s_nop 0
	v_add_f32_e32 v119, 1.0, v119
	v_rcp_f32_e32 v119, v119
	s_nop 0
	v_mul_f32_e32 v119, v120, v119
	v_mul_f32_e32 v120, 0x3d372713, v121
	v_mul_f32_e32 v120, v121, v120
	v_fma_f32 v120, v121, v120, v121
	v_mul_f32_e32 v120, 0xbfcc422a, v120
	v_mul_f32_e32 v120, 0x3fb8aa3b, v120
	v_exp_f32_e32 v120, v120
	s_nop 0
	v_add_f32_e32 v120, 1.0, v120
	v_rcp_f32_e32 v120, v120
	s_nop 0
	v_mul_f32_e32 v120, v121, v120
	v_cvt_pk_bf16_f32 v119, v119, v120
	v_mul_f32_e32 v120, 0x3d372713, v114
	v_mul_f32_e32 v120, v114, v120
	v_fma_f32 v120, v114, v120, v114
	v_mul_f32_e32 v120, 0xbfcc422a, v120
	v_mul_f32_e32 v120, 0x3fb8aa3b, v120
	v_exp_f32_e32 v120, v120
	s_nop 0
	v_add_f32_e32 v120, 1.0, v120
	v_rcp_f32_e32 v121, v120
	s_nop 0
	v_mul_f32_e32 v114, v114, v121
	v_mul_f32_e32 v120, 0x3d372713, v115
	v_mul_f32_e32 v120, v115, v120
	v_fma_f32 v120, v115, v120, v115
	v_mul_f32_e32 v120, 0xbfcc422a, v120
	v_mul_f32_e32 v120, 0x3fb8aa3b, v120
	v_exp_f32_e32 v120, v120
	s_nop 0
	v_add_f32_e32 v120, 1.0, v120
	v_rcp_f32_e32 v121, v120
	s_nop 0
	v_mul_f32_e32 v115, v115, v121
	v_cvt_pk_bf16_f32 v120, v114, v115
	v_mul_f32_e32 v114, 0x3d372713, v116
	v_mul_f32_e32 v114, v116, v114
	v_fma_f32 v114, v116, v114, v116
	v_mul_f32_e32 v114, 0xbfcc422a, v114
	v_mul_f32_e32 v114, 0x3fb8aa3b, v114
	v_exp_f32_e32 v114, v114
	s_nop 0
	v_add_f32_e32 v114, 1.0, v114
	v_rcp_f32_e32 v114, v114
	s_nop 0
	v_mul_f32_e32 v114, v116, v114
	v_mul_f32_e32 v115, 0x3d372713, v117
	v_mul_f32_e32 v115, v117, v115
	v_fma_f32 v115, v117, v115, v117
	v_mul_f32_e32 v115, 0xbfcc422a, v115
	v_mul_f32_e32 v115, 0x3fb8aa3b, v115
	v_exp_f32_e32 v115, v115
	s_nop 0
	v_add_f32_e32 v115, 1.0, v115
	v_rcp_f32_e32 v115, v115
	s_nop 0
	v_mul_f32_e32 v115, v117, v115
	v_mul_f32_e32 v116, 0x3d372713, v110
	v_mul_f32_e32 v116, v110, v116
	v_fma_f32 v116, v110, v116, v110
	v_mul_f32_e32 v116, 0xbfcc422a, v116
; template <int ACT> __device__ __forceinline__ void store_tile_bf16(AccRef acc, bf16_t* dst, int ld, int row0, int col0) {
; #pragma unroll
;     for (int ai = 0; ai < 2; ++ai)
; #pragma unroll
;         for (int m = 0; m < 4; ++m) { bf16_t* rowp = dst + (size_t)(row0 + ai * 128 + m * 16) * ld + col0;
; #pragma unroll
;             for (int bj = 0; bj < 2; ++bj) { const f32x4 v0 = acc[ai][bj][m][0], v1 = acc[ai][bj][m][1];
;                 u32x4 w; w.x = cvt_pk_bf16(actf<ACT>(v0[0]), actf<ACT>(v0[1])); w.y = cvt_pk_bf16(actf<ACT>(v0[2]), actf<ACT>(v0[3]));
;                 w.z = cvt_pk_bf16(actf<ACT>(v1[0]), actf<ACT>(v1[1])); w.w = cvt_pk_bf16(actf<ACT>(v1[2]), actf<ACT>(v1[3]));
;                 *(u32x4*)(rowp + bj * 128) = w; } }
	v_mul_f32_e32 v116, 0x3fb8aa3b, v116
	v_exp_f32_e32 v116, v116
	v_cvt_pk_bf16_f32 v121, v114, v115
	global_store_dwordx4 v[132:133], v[118:121], off offset:256
	v_lshlrev_b64 v[114:115], 12, v[158:159]
	v_add_f32_e32 v116, 1.0, v116
	v_lshl_add_u64 v[114:115], v[130:131], 0, v[114:115]
	v_rcp_f32_e32 v117, v116
	s_nop 0
	v_mul_f32_e32 v110, v110, v117
	v_mul_f32_e32 v116, 0x3d372713, v111
	v_mul_f32_e32 v116, v111, v116
	v_fma_f32 v116, v111, v116, v111
	v_mul_f32_e32 v116, 0xbfcc422a, v116
	v_mul_f32_e32 v116, 0x3fb8aa3b, v116
	v_exp_f32_e32 v116, v116
	s_nop 0
	v_add_f32_e32 v116, 1.0, v116
	v_rcp_f32_e32 v117, v116
	s_nop 0
	v_mul_f32_e32 v111, v111, v117
	v_cvt_pk_bf16_f32 v110, v110, v111
	v_mul_f32_e32 v111, 0x3d372713, v112
	v_mul_f32_e32 v111, v112, v111
	v_fma_f32 v111, v112, v111, v112
	v_mul_f32_e32 v111, 0xbfcc422a, v111
	v_mul_f32_e32 v111, 0x3fb8aa3b, v111
	v_exp_f32_e32 v111, v111
	s_nop 0
	v_add_f32_e32 v111, 1.0, v111
	v_rcp_f32_e32 v111, v111
	s_nop 0
	v_mul_f32_e32 v111, v112, v111
	v_mul_f32_e32 v112, 0x3d372713, v113
	v_mul_f32_e32 v112, v113, v112
	v_fma_f32 v112, v113, v112, v113
	v_mul_f32_e32 v112, 0xbfcc422a, v112
	v_mul_f32_e32 v112, 0x3fb8aa3b, v112
	v_exp_f32_e32 v112, v112
	s_nop 0
	v_add_f32_e32 v112, 1.0, v112
	v_rcp_f32_e32 v112, v112
	s_nop 0
	v_mul_f32_e32 v112, v113, v112
	v_cvt_pk_bf16_f32 v111, v111, v112
	v_mul_f32_e32 v112, 0x3d372713, v106
	v_mul_f32_e32 v112, v106, v112
	v_fma_f32 v112, v106, v112, v106
	v_mul_f32_e32 v112, 0xbfcc422a, v112
	v_mul_f32_e32 v112, 0x3fb8aa3b, v112
	v_exp_f32_e32 v112, v112
	s_nop 0
	v_add_f32_e32 v112, 1.0, v112
	v_rcp_f32_e32 v113, v112
	s_nop 0
	v_mul_f32_e32 v106, v106, v113
	v_mul_f32_e32 v112, 0x3d372713, v107
	v_mul_f32_e32 v112, v107, v112
	v_fma_f32 v112, v107, v112, v107
	v_mul_f32_e32 v112, 0xbfcc422a, v112
	v_mul_f32_e32 v112, 0x3fb8aa3b, v112
	v_exp_f32_e32 v112, v112
	s_nop 0
	v_add_f32_e32 v112, 1.0, v112
	v_rcp_f32_e32 v113, v112
	s_nop 0
	v_mul_f32_e32 v107, v107, v113
	v_cvt_pk_bf16_f32 v112, v106, v107
	v_mul_f32_e32 v106, 0x3d372713, v108
	v_mul_f32_e32 v106, v108, v106
	v_fma_f32 v106, v108, v106, v108
	v_mul_f32_e32 v106, 0xbfcc422a, v106
	v_mul_f32_e32 v106, 0x3fb8aa3b, v106
	v_exp_f32_e32 v106, v106
	s_nop 0
	v_add_f32_e32 v106, 1.0, v106
	v_rcp_f32_e32 v106, v106
	s_nop 0
	v_mul_f32_e32 v106, v108, v106
	v_mul_f32_e32 v107, 0x3d372713, v109
	v_mul_f32_e32 v107, v109, v107
	v_fma_f32 v107, v109, v107, v109
	v_mul_f32_e32 v107, 0xbfcc422a, v107
	v_mul_f32_e32 v107, 0x3fb8aa3b, v107
	v_exp_f32_e32 v107, v107
	s_nop 0
	v_add_f32_e32 v107, 1.0, v107
	v_rcp_f32_e32 v107, v107
	s_nop 0
	v_mul_f32_e32 v107, v109, v107
	v_cvt_pk_bf16_f32 v113, v106, v107
	v_mul_f32_e32 v106, 0x3d372713, v102
	v_mul_f32_e32 v106, v102, v106
	v_fma_f32 v106, v102, v106, v102
	v_mul_f32_e32 v106, 0xbfcc422a, v106
	v_mul_f32_e32 v106, 0x3fb8aa3b, v106
	v_exp_f32_e32 v106, v106
	global_store_dwordx4 v[114:115], v[110:113], off
	v_add_f32_e32 v106, 1.0, v106
	v_rcp_f32_e32 v107, v106
	s_nop 0
	v_mul_f32_e32 v102, v102, v107
	v_mul_f32_e32 v106, 0x3d372713, v103
	v_mul_f32_e32 v106, v103, v106
	v_fma_f32 v106, v103, v106, v103
	v_mul_f32_e32 v106, 0xbfcc422a, v106
	v_mul_f32_e32 v106, 0x3fb8aa3b, v106
	v_exp_f32_e32 v106, v106
	s_nop 0
	v_add_f32_e32 v106, 1.0, v106
	v_rcp_f32_e32 v107, v106
	s_nop 0
	v_mul_f32_e32 v103, v103, v107
	v_cvt_pk_bf16_f32 v102, v102, v103
	v_mul_f32_e32 v103, 0x3d372713, v104
	v_mul_f32_e32 v103, v104, v103
	v_fma_f32 v103, v104, v103, v104
	v_mul_f32_e32 v103, 0xbfcc422a, v103
	v_mul_f32_e32 v103, 0x3fb8aa3b, v103
	v_exp_f32_e32 v103, v103
	s_nop 0
	v_add_f32_e32 v103, 1.0, v103
	v_rcp_f32_e32 v103, v103
	s_nop 0
	v_mul_f32_e32 v103, v104, v103
	v_mul_f32_e32 v104, 0x3d372713, v105
	v_mul_f32_e32 v104, v105, v104
	v_fma_f32 v104, v105, v104, v105
	v_mul_f32_e32 v104, 0xbfcc422a, v104
	v_mul_f32_e32 v104, 0x3fb8aa3b, v104
	v_exp_f32_e32 v104, v104
	s_nop 0
	v_add_f32_e32 v104, 1.0, v104
	v_rcp_f32_e32 v104, v104
	s_nop 0
	v_mul_f32_e32 v104, v105, v104
	v_cvt_pk_bf16_f32 v103, v103, v104
	v_mul_f32_e32 v104, 0x3d372713, v98
	v_mul_f32_e32 v104, v98, v104
	v_fma_f32 v104, v98, v104, v98
	v_mul_f32_e32 v104, 0xbfcc422a, v104
	v_mul_f32_e32 v104, 0x3fb8aa3b, v104
	v_exp_f32_e32 v104, v104
	s_nop 0
	v_add_f32_e32 v104, 1.0, v104
	v_rcp_f32_e32 v105, v104
	s_nop 0
	v_mul_f32_e32 v98, v98, v105
	v_mul_f32_e32 v104, 0x3d372713, v99
	v_mul_f32_e32 v104, v99, v104
	v_fma_f32 v104, v99, v104, v99
	v_mul_f32_e32 v104, 0xbfcc422a, v104
	v_mul_f32_e32 v104, 0x3fb8aa3b, v104
	v_exp_f32_e32 v104, v104
	s_nop 0
	v_add_f32_e32 v104, 1.0, v104
	v_rcp_f32_e32 v105, v104
	s_nop 0
	v_mul_f32_e32 v99, v99, v105
	v_cvt_pk_bf16_f32 v104, v98, v99
	v_mul_f32_e32 v98, 0x3d372713, v100
	v_mul_f32_e32 v98, v100, v98
	v_fma_f32 v98, v100, v98, v100
	v_mul_f32_e32 v98, 0xbfcc422a, v98
	v_mul_f32_e32 v98, 0x3fb8aa3b, v98
	v_exp_f32_e32 v98, v98
	s_nop 0
	v_add_f32_e32 v98, 1.0, v98
	v_rcp_f32_e32 v98, v98
	s_nop 0
	v_mul_f32_e32 v98, v100, v98
	v_mul_f32_e32 v99, 0x3d372713, v101
	v_mul_f32_e32 v99, v101, v99
	v_fma_f32 v99, v101, v99, v101
	v_mul_f32_e32 v99, 0xbfcc422a, v99
	v_mul_f32_e32 v99, 0x3fb8aa3b, v99
	v_exp_f32_e32 v99, v99
	s_nop 0
	v_add_f32_e32 v99, 1.0, v99
	v_rcp_f32_e32 v99, v99
	s_nop 0
	v_mul_f32_e32 v99, v101, v99
	v_mul_f32_e32 v100, 0x3d372713, v94
	v_mul_f32_e32 v100, v94, v100
	v_fma_f32 v100, v94, v100, v94
	v_mul_f32_e32 v100, 0xbfcc422a, v100
	v_mul_f32_e32 v100, 0x3fb8aa3b, v100
	v_exp_f32_e32 v100, v100
	v_cvt_pk_bf16_f32 v105, v98, v99
	global_store_dwordx4 v[114:115], v[102:105], off offset:256
	v_lshlrev_b64 v[98:99], 12, v[156:157]
; template <int ACT> __device__ __forceinline__ void store_tile_bf16(AccRef acc, bf16_t* dst, int ld, int row0, int col0) {
; #pragma unroll
;     for (int ai = 0; ai < 2; ++ai)
; #pragma unroll
;         for (int m = 0; m < 4; ++m) { bf16_t* rowp = dst + (size_t)(row0 + ai * 128 + m * 16) * ld + col0;
; #pragma unroll
;             for (int bj = 0; bj < 2; ++bj) { const f32x4 v0 = acc[ai][bj][m][0], v1 = acc[ai][bj][m][1];
;                 u32x4 w; w.x = cvt_pk_bf16(actf<ACT>(v0[0]), actf<ACT>(v0[1])); w.y = cvt_pk_bf16(actf<ACT>(v0[2]), actf<ACT>(v0[3]));
;                 w.z = cvt_pk_bf16(actf<ACT>(v1[0]), actf<ACT>(v1[1])); w.w = cvt_pk_bf16(actf<ACT>(v1[2]), actf<ACT>(v1[3]));
;                 *(u32x4*)(rowp + bj * 128) = w; } }
	v_add_f32_e32 v100, 1.0, v100
	v_lshl_add_u64 v[98:99], v[130:131], 0, v[98:99]
	v_rcp_f32_e32 v101, v100
	s_nop 0
	v_mul_f32_e32 v94, v94, v101
	v_mul_f32_e32 v100, 0x3d372713, v95
	v_mul_f32_e32 v100, v95, v100
	v_fma_f32 v100, v95, v100, v95
	v_mul_f32_e32 v100, 0xbfcc422a, v100
	v_mul_f32_e32 v100, 0x3fb8aa3b, v100
	v_exp_f32_e32 v100, v100
	s_nop 0
	v_add_f32_e32 v100, 1.0, v100
	v_rcp_f32_e32 v101, v100
	s_nop 0
	v_mul_f32_e32 v95, v95, v101
	v_cvt_pk_bf16_f32 v94, v94, v95
	v_mul_f32_e32 v95, 0x3d372713, v96
	v_mul_f32_e32 v95, v96, v95
	v_fma_f32 v95, v96, v95, v96
	v_mul_f32_e32 v95, 0xbfcc422a, v95
	v_mul_f32_e32 v95, 0x3fb8aa3b, v95
	v_exp_f32_e32 v95, v95
	s_nop 0
	v_add_f32_e32 v95, 1.0, v95
	v_rcp_f32_e32 v95, v95
	s_nop 0
	v_mul_f32_e32 v95, v96, v95
	v_mul_f32_e32 v96, 0x3d372713, v97
	v_mul_f32_e32 v96, v97, v96
	v_fma_f32 v96, v97, v96, v97
	v_mul_f32_e32 v96, 0xbfcc422a, v96
	v_mul_f32_e32 v96, 0x3fb8aa3b, v96
	v_exp_f32_e32 v96, v96
	s_nop 0
	v_add_f32_e32 v96, 1.0, v96
	v_rcp_f32_e32 v96, v96
	s_nop 0
	v_mul_f32_e32 v96, v97, v96
	v_cvt_pk_bf16_f32 v95, v95, v96
	v_mul_f32_e32 v96, 0x3d372713, v90
	v_mul_f32_e32 v96, v90, v96
	v_fma_f32 v96, v90, v96, v90
	v_mul_f32_e32 v96, 0xbfcc422a, v96
	v_mul_f32_e32 v96, 0x3fb8aa3b, v96
	v_exp_f32_e32 v96, v96
	s_nop 0
	v_add_f32_e32 v96, 1.0, v96
	v_rcp_f32_e32 v97, v96
	s_nop 0
	v_mul_f32_e32 v90, v90, v97
	v_mul_f32_e32 v96, 0x3d372713, v91
	v_mul_f32_e32 v96, v91, v96
	v_fma_f32 v96, v91, v96, v91
	v_mul_f32_e32 v96, 0xbfcc422a, v96
	v_mul_f32_e32 v96, 0x3fb8aa3b, v96
	v_exp_f32_e32 v96, v96
	s_nop 0
	v_add_f32_e32 v96, 1.0, v96
	v_rcp_f32_e32 v97, v96
	s_nop 0
	v_mul_f32_e32 v91, v91, v97
	v_cvt_pk_bf16_f32 v96, v90, v91
	v_mul_f32_e32 v90, 0x3d372713, v92
	v_mul_f32_e32 v90, v92, v90
	v_fma_f32 v90, v92, v90, v92
	v_mul_f32_e32 v90, 0xbfcc422a, v90
	v_mul_f32_e32 v90, 0x3fb8aa3b, v90
	v_exp_f32_e32 v90, v90
	s_nop 0
	v_add_f32_e32 v90, 1.0, v90
	v_rcp_f32_e32 v90, v90
	s_nop 0
	v_mul_f32_e32 v90, v92, v90
	v_mul_f32_e32 v91, 0x3d372713, v93
	v_mul_f32_e32 v91, v93, v91
	v_fma_f32 v91, v93, v91, v93
	v_mul_f32_e32 v91, 0xbfcc422a, v91
	v_mul_f32_e32 v91, 0x3fb8aa3b, v91
	v_exp_f32_e32 v91, v91
	s_nop 0
	v_add_f32_e32 v91, 1.0, v91
	v_rcp_f32_e32 v91, v91
	s_nop 0
	v_mul_f32_e32 v91, v93, v91
	v_cvt_pk_bf16_f32 v97, v90, v91
	v_mul_f32_e32 v90, 0x3d372713, v86
	v_mul_f32_e32 v90, v86, v90
	v_fma_f32 v90, v86, v90, v86
	v_mul_f32_e32 v90, 0xbfcc422a, v90
	v_mul_f32_e32 v90, 0x3fb8aa3b, v90
	v_exp_f32_e32 v90, v90
	global_store_dwordx4 v[98:99], v[94:97], off
	v_add_f32_e32 v90, 1.0, v90
	v_rcp_f32_e32 v91, v90
	s_nop 0
	v_mul_f32_e32 v86, v86, v91
	v_mul_f32_e32 v90, 0x3d372713, v87
	v_mul_f32_e32 v90, v87, v90
	v_fma_f32 v90, v87, v90, v87
	v_mul_f32_e32 v90, 0xbfcc422a, v90
	v_mul_f32_e32 v90, 0x3fb8aa3b, v90
	v_exp_f32_e32 v90, v90
	s_nop 0
	v_add_f32_e32 v90, 1.0, v90
	v_rcp_f32_e32 v91, v90
	s_nop 0
	v_mul_f32_e32 v87, v87, v91
	v_cvt_pk_bf16_f32 v86, v86, v87
	v_mul_f32_e32 v87, 0x3d372713, v88
	v_mul_f32_e32 v87, v88, v87
	v_fma_f32 v87, v88, v87, v88
	v_mul_f32_e32 v87, 0xbfcc422a, v87
	v_mul_f32_e32 v87, 0x3fb8aa3b, v87
	v_exp_f32_e32 v87, v87
	s_nop 0
	v_add_f32_e32 v87, 1.0, v87
	v_rcp_f32_e32 v87, v87
	s_nop 0
	v_mul_f32_e32 v87, v88, v87
	v_mul_f32_e32 v88, 0x3d372713, v89
	v_mul_f32_e32 v88, v89, v88
	v_fma_f32 v88, v89, v88, v89
	v_mul_f32_e32 v88, 0xbfcc422a, v88
	v_mul_f32_e32 v88, 0x3fb8aa3b, v88
	v_exp_f32_e32 v88, v88
	s_nop 0
	v_add_f32_e32 v88, 1.0, v88
	v_rcp_f32_e32 v88, v88
	s_nop 0
	v_mul_f32_e32 v88, v89, v88
	v_cvt_pk_bf16_f32 v87, v87, v88
	v_mul_f32_e32 v88, 0x3d372713, v82
	v_mul_f32_e32 v88, v82, v88
	v_fma_f32 v88, v82, v88, v82
	v_mul_f32_e32 v88, 0xbfcc422a, v88
	v_mul_f32_e32 v88, 0x3fb8aa3b, v88
	v_exp_f32_e32 v88, v88
	s_nop 0
	v_add_f32_e32 v88, 1.0, v88
	v_rcp_f32_e32 v89, v88
	s_nop 0
	v_mul_f32_e32 v82, v82, v89
	v_mul_f32_e32 v88, 0x3d372713, v83
	v_mul_f32_e32 v88, v83, v88
	v_fma_f32 v88, v83, v88, v83
	v_mul_f32_e32 v88, 0xbfcc422a, v88
	v_mul_f32_e32 v88, 0x3fb8aa3b, v88
	v_exp_f32_e32 v88, v88
	s_nop 0
	v_add_f32_e32 v88, 1.0, v88
	v_rcp_f32_e32 v89, v88
	s_nop 0
	v_mul_f32_e32 v83, v83, v89
	v_cvt_pk_bf16_f32 v88, v82, v83
	v_mul_f32_e32 v82, 0x3d372713, v84
	v_mul_f32_e32 v82, v84, v82
	v_fma_f32 v82, v84, v82, v84
	v_mul_f32_e32 v82, 0xbfcc422a, v82
	v_mul_f32_e32 v82, 0x3fb8aa3b, v82
	v_exp_f32_e32 v82, v82
	s_nop 0
	v_add_f32_e32 v82, 1.0, v82
	v_rcp_f32_e32 v82, v82
	s_nop 0
	v_mul_f32_e32 v82, v84, v82
	v_mul_f32_e32 v83, 0x3d372713, v85
	v_mul_f32_e32 v83, v85, v83
	v_fma_f32 v83, v85, v83, v85
	v_mul_f32_e32 v83, 0xbfcc422a, v83
	v_mul_f32_e32 v83, 0x3fb8aa3b, v83
	v_exp_f32_e32 v83, v83
	s_nop 0
	v_add_f32_e32 v83, 1.0, v83
	v_rcp_f32_e32 v83, v83
	s_nop 0
	v_mul_f32_e32 v83, v85, v83
	v_mul_f32_e32 v84, 0x3d372713, v78
	v_mul_f32_e32 v84, v78, v84
	v_fma_f32 v84, v78, v84, v78
	v_mul_f32_e32 v84, 0xbfcc422a, v84
	v_mul_f32_e32 v84, 0x3fb8aa3b, v84
	v_exp_f32_e32 v84, v84
	v_cvt_pk_bf16_f32 v89, v82, v83
	global_store_dwordx4 v[98:99], v[86:89], off offset:256
	v_lshlrev_b64 v[82:83], 12, v[154:155]
	v_add_f32_e32 v84, 1.0, v84
	v_lshl_add_u64 v[82:83], v[130:131], 0, v[82:83]
	v_rcp_f32_e32 v85, v84
	s_nop 0
	v_mul_f32_e32 v78, v78, v85
	v_mul_f32_e32 v84, 0x3d372713, v79
	v_mul_f32_e32 v84, v79, v84
	v_fma_f32 v84, v79, v84, v79
	v_mul_f32_e32 v84, 0xbfcc422a, v84
	v_mul_f32_e32 v84, 0x3fb8aa3b, v84
	v_exp_f32_e32 v84, v84
	s_nop 0
	v_add_f32_e32 v84, 1.0, v84
	v_rcp_f32_e32 v85, v84
	s_nop 0
	v_mul_f32_e32 v79, v79, v85
	v_cvt_pk_bf16_f32 v78, v78, v79
	v_mul_f32_e32 v79, 0x3d372713, v80
	v_mul_f32_e32 v79, v80, v79
; template <int ACT> __device__ __forceinline__ void store_tile_bf16(AccRef acc, bf16_t* dst, int ld, int row0, int col0) {
; #pragma unroll
;     for (int ai = 0; ai < 2; ++ai)
; #pragma unroll
;         for (int m = 0; m < 4; ++m) { bf16_t* rowp = dst + (size_t)(row0 + ai * 128 + m * 16) * ld + col0;
; #pragma unroll
;             for (int bj = 0; bj < 2; ++bj) { const f32x4 v0 = acc[ai][bj][m][0], v1 = acc[ai][bj][m][1];
;                 u32x4 w; w.x = cvt_pk_bf16(actf<ACT>(v0[0]), actf<ACT>(v0[1])); w.y = cvt_pk_bf16(actf<ACT>(v0[2]), actf<ACT>(v0[3]));
;                 w.z = cvt_pk_bf16(actf<ACT>(v1[0]), actf<ACT>(v1[1])); w.w = cvt_pk_bf16(actf<ACT>(v1[2]), actf<ACT>(v1[3]));
;                 *(u32x4*)(rowp + bj * 128) = w; } }
	v_fma_f32 v79, v80, v79, v80
	v_mul_f32_e32 v79, 0xbfcc422a, v79
	v_mul_f32_e32 v79, 0x3fb8aa3b, v79
	v_exp_f32_e32 v79, v79
	s_nop 0
	v_add_f32_e32 v79, 1.0, v79
	v_rcp_f32_e32 v79, v79
	s_nop 0
	v_mul_f32_e32 v79, v80, v79
	v_mul_f32_e32 v80, 0x3d372713, v81
	v_mul_f32_e32 v80, v81, v80
	v_fma_f32 v80, v81, v80, v81
	v_mul_f32_e32 v80, 0xbfcc422a, v80
	v_mul_f32_e32 v80, 0x3fb8aa3b, v80
	v_exp_f32_e32 v80, v80
	s_nop 0
	v_add_f32_e32 v80, 1.0, v80
	v_rcp_f32_e32 v80, v80
	s_nop 0
	v_mul_f32_e32 v80, v81, v80
	v_cvt_pk_bf16_f32 v79, v79, v80
	v_mul_f32_e32 v80, 0x3d372713, v74
	v_mul_f32_e32 v80, v74, v80
	v_fma_f32 v80, v74, v80, v74
	v_mul_f32_e32 v80, 0xbfcc422a, v80
	v_mul_f32_e32 v80, 0x3fb8aa3b, v80
	v_exp_f32_e32 v80, v80
	s_nop 0
	v_add_f32_e32 v80, 1.0, v80
	v_rcp_f32_e32 v81, v80
	s_nop 0
	v_mul_f32_e32 v74, v74, v81
	v_mul_f32_e32 v80, 0x3d372713, v75
	v_mul_f32_e32 v80, v75, v80
	v_fma_f32 v80, v75, v80, v75
	v_mul_f32_e32 v80, 0xbfcc422a, v80
	v_mul_f32_e32 v80, 0x3fb8aa3b, v80
	v_exp_f32_e32 v80, v80
	s_nop 0
	v_add_f32_e32 v80, 1.0, v80
	v_rcp_f32_e32 v81, v80
	s_nop 0
	v_mul_f32_e32 v75, v75, v81
	v_cvt_pk_bf16_f32 v80, v74, v75
	v_mul_f32_e32 v74, 0x3d372713, v76
	v_mul_f32_e32 v74, v76, v74
	v_fma_f32 v74, v76, v74, v76
	v_mul_f32_e32 v74, 0xbfcc422a, v74
	v_mul_f32_e32 v74, 0x3fb8aa3b, v74
	v_exp_f32_e32 v74, v74
	s_nop 0
	v_add_f32_e32 v74, 1.0, v74
	v_rcp_f32_e32 v74, v74
	s_nop 0
	v_mul_f32_e32 v74, v76, v74
	v_mul_f32_e32 v75, 0x3d372713, v77
	v_mul_f32_e32 v75, v77, v75
	v_fma_f32 v75, v77, v75, v77
	v_mul_f32_e32 v75, 0xbfcc422a, v75
	v_mul_f32_e32 v75, 0x3fb8aa3b, v75
	v_exp_f32_e32 v75, v75
	s_nop 0
	v_add_f32_e32 v75, 1.0, v75
	v_rcp_f32_e32 v75, v75
	s_nop 0
	v_mul_f32_e32 v75, v77, v75
	v_cvt_pk_bf16_f32 v81, v74, v75
	v_mul_f32_e32 v74, 0x3d372713, v70
	v_mul_f32_e32 v74, v70, v74
	v_fma_f32 v74, v70, v74, v70
	v_mul_f32_e32 v74, 0xbfcc422a, v74
	v_mul_f32_e32 v74, 0x3fb8aa3b, v74
	v_exp_f32_e32 v74, v74
	global_store_dwordx4 v[82:83], v[78:81], off
	v_add_f32_e32 v74, 1.0, v74
	v_rcp_f32_e32 v75, v74
	s_nop 0
	v_mul_f32_e32 v70, v70, v75
	v_mul_f32_e32 v74, 0x3d372713, v71
	v_mul_f32_e32 v74, v71, v74
	v_fma_f32 v74, v71, v74, v71
	v_mul_f32_e32 v74, 0xbfcc422a, v74
	v_mul_f32_e32 v74, 0x3fb8aa3b, v74
	v_exp_f32_e32 v74, v74
	s_nop 0
	v_add_f32_e32 v74, 1.0, v74
	v_rcp_f32_e32 v75, v74
	s_nop 0
	v_mul_f32_e32 v71, v71, v75
	v_cvt_pk_bf16_f32 v70, v70, v71
	v_mul_f32_e32 v71, 0x3d372713, v72
	v_mul_f32_e32 v71, v72, v71
	v_fma_f32 v71, v72, v71, v72
	v_mul_f32_e32 v71, 0xbfcc422a, v71
	v_mul_f32_e32 v71, 0x3fb8aa3b, v71
	v_exp_f32_e32 v71, v71
	s_nop 0
	v_add_f32_e32 v71, 1.0, v71
	v_rcp_f32_e32 v71, v71
	s_nop 0
	v_mul_f32_e32 v71, v72, v71
	v_mul_f32_e32 v72, 0x3d372713, v73
	v_mul_f32_e32 v72, v73, v72
	v_fma_f32 v72, v73, v72, v73
	v_mul_f32_e32 v72, 0xbfcc422a, v72
	v_mul_f32_e32 v72, 0x3fb8aa3b, v72
	v_exp_f32_e32 v72, v72
	s_nop 0
	v_add_f32_e32 v72, 1.0, v72
	v_rcp_f32_e32 v72, v72
	s_nop 0
	v_mul_f32_e32 v72, v73, v72
	v_cvt_pk_bf16_f32 v71, v71, v72
	v_mul_f32_e32 v72, 0x3d372713, v66
	v_mul_f32_e32 v72, v66, v72
	v_fma_f32 v72, v66, v72, v66
	v_mul_f32_e32 v72, 0xbfcc422a, v72
	v_mul_f32_e32 v72, 0x3fb8aa3b, v72
	v_exp_f32_e32 v72, v72
	s_nop 0
	v_add_f32_e32 v72, 1.0, v72
	v_rcp_f32_e32 v73, v72
	s_nop 0
	v_mul_f32_e32 v66, v66, v73
	v_mul_f32_e32 v72, 0x3d372713, v67
	v_mul_f32_e32 v72, v67, v72
	v_fma_f32 v72, v67, v72, v67
	v_mul_f32_e32 v72, 0xbfcc422a, v72
	v_mul_f32_e32 v72, 0x3fb8aa3b, v72
	v_exp_f32_e32 v72, v72
	s_nop 0
	v_add_f32_e32 v72, 1.0, v72
	v_rcp_f32_e32 v73, v72
	s_nop 0
	v_mul_f32_e32 v67, v67, v73
	v_cvt_pk_bf16_f32 v72, v66, v67
	v_mul_f32_e32 v66, 0x3d372713, v68
	v_mul_f32_e32 v66, v68, v66
	v_fma_f32 v66, v68, v66, v68
	v_mul_f32_e32 v66, 0xbfcc422a, v66
	v_mul_f32_e32 v66, 0x3fb8aa3b, v66
	v_exp_f32_e32 v66, v66
	s_nop 0
	v_add_f32_e32 v66, 1.0, v66
	v_rcp_f32_e32 v66, v66
	s_nop 0
	v_mul_f32_e32 v66, v68, v66
	v_mul_f32_e32 v67, 0x3d372713, v69
	v_mul_f32_e32 v67, v69, v67
	v_fma_f32 v67, v69, v67, v69
	v_mul_f32_e32 v67, 0xbfcc422a, v67
	v_mul_f32_e32 v67, 0x3fb8aa3b, v67
	v_exp_f32_e32 v67, v67
	s_nop 0
	v_add_f32_e32 v67, 1.0, v67
	v_rcp_f32_e32 v67, v67
	s_nop 0
	v_mul_f32_e32 v67, v69, v67
	v_cvt_pk_bf16_f32 v73, v66, v67
	global_store_dwordx4 v[82:83], v[70:73], off offset:256
	v_lshlrev_b64 v[66:67], 12, v[152:153]
	v_lshl_add_u64 v[66:67], v[130:131], 0, v[66:67]
	v_mul_f32_e32 v70, 0x3d372713, v62
	v_mul_f32_e32 v70, v62, v70
	v_fma_f32 v70, v62, v70, v62
	v_mul_f32_e32 v70, 0xbfcc422a, v70
	v_mul_f32_e32 v70, 0x3fb8aa3b, v70
	v_exp_f32_e32 v70, v70
	v_lshl_add_u64 v[68:69], v[66:67], 0, s[0:1]
	v_lshl_add_u64 v[160:161], v[66:67], 0, s[50:51]
	v_add_f32_e32 v70, 1.0, v70
	v_rcp_f32_e32 v71, v70
	s_nop 0
	v_mul_f32_e32 v62, v62, v71
	v_mul_f32_e32 v70, 0x3d372713, v63
	v_mul_f32_e32 v70, v63, v70
	v_fma_f32 v70, v63, v70, v63
	v_mul_f32_e32 v70, 0xbfcc422a, v70
	v_mul_f32_e32 v70, 0x3fb8aa3b, v70
	v_exp_f32_e32 v70, v70
	s_nop 0
	v_add_f32_e32 v70, 1.0, v70
	v_rcp_f32_e32 v71, v70
	s_nop 0
	v_mul_f32_e32 v63, v63, v71
	v_cvt_pk_bf16_f32 v62, v62, v63
	v_mul_f32_e32 v63, 0x3d372713, v64
	v_mul_f32_e32 v63, v64, v63
	v_fma_f32 v63, v64, v63, v64
	v_mul_f32_e32 v63, 0xbfcc422a, v63
	v_mul_f32_e32 v63, 0x3fb8aa3b, v63
	v_exp_f32_e32 v63, v63
	s_nop 0
	v_add_f32_e32 v63, 1.0, v63
	v_rcp_f32_e32 v63, v63
	s_nop 0
	v_mul_f32_e32 v63, v64, v63
	v_mul_f32_e32 v64, 0x3d372713, v65
	v_mul_f32_e32 v64, v65, v64
	v_fma_f32 v64, v65, v64, v65
	v_mul_f32_e32 v64, 0xbfcc422a, v64
	v_mul_f32_e32 v64, 0x3fb8aa3b, v64
	v_exp_f32_e32 v64, v64
	s_nop 0
	v_add_f32_e32 v64, 1.0, v64
; template <int ACT> __device__ __forceinline__ void store_tile_bf16(AccRef acc, bf16_t* dst, int ld, int row0, int col0) {
; #pragma unroll
;     for (int ai = 0; ai < 2; ++ai)
; #pragma unroll
;         for (int m = 0; m < 4; ++m) { bf16_t* rowp = dst + (size_t)(row0 + ai * 128 + m * 16) * ld + col0;
; #pragma unroll
;             for (int bj = 0; bj < 2; ++bj) { const f32x4 v0 = acc[ai][bj][m][0], v1 = acc[ai][bj][m][1];
;                 u32x4 w; w.x = cvt_pk_bf16(actf<ACT>(v0[0]), actf<ACT>(v0[1])); w.y = cvt_pk_bf16(actf<ACT>(v0[2]), actf<ACT>(v0[3]));
;                 w.z = cvt_pk_bf16(actf<ACT>(v1[0]), actf<ACT>(v1[1])); w.w = cvt_pk_bf16(actf<ACT>(v1[2]), actf<ACT>(v1[3]));
;                 *(u32x4*)(rowp + bj * 128) = w; } }
	v_rcp_f32_e32 v64, v64
	s_nop 0
	v_mul_f32_e32 v64, v65, v64
	v_cvt_pk_bf16_f32 v63, v63, v64
	v_mul_f32_e32 v64, 0x3d372713, v58
	v_mul_f32_e32 v64, v58, v64
	v_fma_f32 v64, v58, v64, v58
	v_mul_f32_e32 v64, 0xbfcc422a, v64
	v_mul_f32_e32 v64, 0x3fb8aa3b, v64
	v_exp_f32_e32 v64, v64
	s_nop 0
	v_add_f32_e32 v64, 1.0, v64
	v_rcp_f32_e32 v65, v64
	s_nop 0
	v_mul_f32_e32 v58, v58, v65
	v_mul_f32_e32 v64, 0x3d372713, v59
	v_mul_f32_e32 v64, v59, v64
	v_fma_f32 v64, v59, v64, v59
	v_mul_f32_e32 v64, 0xbfcc422a, v64
	v_mul_f32_e32 v64, 0x3fb8aa3b, v64
	v_exp_f32_e32 v64, v64
	s_nop 0
	v_add_f32_e32 v64, 1.0, v64
	v_rcp_f32_e32 v65, v64
	s_nop 0
	v_mul_f32_e32 v59, v59, v65
	v_cvt_pk_bf16_f32 v64, v58, v59
	v_mul_f32_e32 v58, 0x3d372713, v60
	v_mul_f32_e32 v58, v60, v58
	v_fma_f32 v58, v60, v58, v60
	v_mul_f32_e32 v58, 0xbfcc422a, v58
	v_mul_f32_e32 v58, 0x3fb8aa3b, v58
	v_exp_f32_e32 v58, v58
	s_nop 0
	v_add_f32_e32 v58, 1.0, v58
	v_rcp_f32_e32 v58, v58
	s_nop 0
	v_mul_f32_e32 v58, v60, v58
	v_mul_f32_e32 v59, 0x3d372713, v61
	v_mul_f32_e32 v59, v61, v59
	v_fma_f32 v59, v61, v59, v61
	v_mul_f32_e32 v59, 0xbfcc422a, v59
	v_mul_f32_e32 v59, 0x3fb8aa3b, v59
	v_exp_f32_e32 v59, v59
	s_nop 0
	v_add_f32_e32 v59, 1.0, v59
	v_rcp_f32_e32 v59, v59
	s_nop 0
	v_mul_f32_e32 v59, v61, v59
	v_cvt_pk_bf16_f32 v65, v58, v59
	v_add_co_u32_e32 v58, vcc, s85, v66
	s_nop 1
	v_addc_co_u32_e32 v59, vcc, 0, v67, vcc
	global_store_dwordx4 v[58:59], v[62:65], off
	v_mul_f32_e32 v58, 0x3d372713, v54
	v_mul_f32_e32 v58, v54, v58
	v_fma_f32 v58, v54, v58, v54
	v_mul_f32_e32 v58, 0xbfcc422a, v58
	v_mul_f32_e32 v58, 0x3fb8aa3b, v58
	v_exp_f32_e32 v58, v58
	s_nop 0
	v_add_f32_e32 v58, 1.0, v58
	v_rcp_f32_e32 v59, v58
	s_nop 0
	v_mul_f32_e32 v54, v54, v59
	v_mul_f32_e32 v58, 0x3d372713, v55
	v_mul_f32_e32 v58, v55, v58
	v_fma_f32 v58, v55, v58, v55
	v_mul_f32_e32 v58, 0xbfcc422a, v58
	v_mul_f32_e32 v58, 0x3fb8aa3b, v58
	v_exp_f32_e32 v58, v58
	s_nop 0
	v_add_f32_e32 v58, 1.0, v58
	v_rcp_f32_e32 v59, v58
	s_nop 0
	v_mul_f32_e32 v55, v55, v59
	v_cvt_pk_bf16_f32 v54, v54, v55
	v_mul_f32_e32 v55, 0x3d372713, v56
	v_mul_f32_e32 v55, v56, v55
	v_fma_f32 v55, v56, v55, v56
	v_mul_f32_e32 v55, 0xbfcc422a, v55
	v_mul_f32_e32 v55, 0x3fb8aa3b, v55
	v_exp_f32_e32 v55, v55
	s_nop 0
	v_add_f32_e32 v55, 1.0, v55
	v_rcp_f32_e32 v55, v55
	s_nop 0
	v_mul_f32_e32 v55, v56, v55
	v_mul_f32_e32 v56, 0x3d372713, v57
	v_mul_f32_e32 v56, v57, v56
	v_fma_f32 v56, v57, v56, v57
	v_mul_f32_e32 v56, 0xbfcc422a, v56
	v_mul_f32_e32 v56, 0x3fb8aa3b, v56
	v_exp_f32_e32 v56, v56
	s_nop 0
	v_add_f32_e32 v56, 1.0, v56
	v_rcp_f32_e32 v56, v56
	s_nop 0
	v_mul_f32_e32 v56, v57, v56
	v_cvt_pk_bf16_f32 v55, v55, v56
	v_mul_f32_e32 v56, 0x3d372713, v50
	v_mul_f32_e32 v56, v50, v56
	v_fma_f32 v56, v50, v56, v50
	v_mul_f32_e32 v56, 0xbfcc422a, v56
	v_mul_f32_e32 v56, 0x3fb8aa3b, v56
	v_exp_f32_e32 v56, v56
	s_nop 0
	v_add_f32_e32 v56, 1.0, v56
	v_rcp_f32_e32 v57, v56
	s_nop 0
	v_mul_f32_e32 v50, v50, v57
	v_mul_f32_e32 v56, 0x3d372713, v51
	v_mul_f32_e32 v56, v51, v56
	v_fma_f32 v56, v51, v56, v51
	v_mul_f32_e32 v56, 0xbfcc422a, v56
	v_mul_f32_e32 v56, 0x3fb8aa3b, v56
	v_exp_f32_e32 v56, v56
	s_nop 0
	v_add_f32_e32 v56, 1.0, v56
	v_rcp_f32_e32 v57, v56
	s_nop 0
	v_mul_f32_e32 v51, v51, v57
	v_cvt_pk_bf16_f32 v56, v50, v51
	v_mul_f32_e32 v50, 0x3d372713, v52
	v_mul_f32_e32 v50, v52, v50
	v_fma_f32 v50, v52, v50, v52
	v_mul_f32_e32 v50, 0xbfcc422a, v50
	v_mul_f32_e32 v50, 0x3fb8aa3b, v50
	v_exp_f32_e32 v50, v50
	s_nop 0
	v_add_f32_e32 v50, 1.0, v50
	v_rcp_f32_e32 v50, v50
	s_nop 0
	v_mul_f32_e32 v50, v52, v50
	v_mul_f32_e32 v51, 0x3d372713, v53
	v_mul_f32_e32 v51, v53, v51
	v_fma_f32 v51, v53, v51, v53
	v_mul_f32_e32 v51, 0xbfcc422a, v51
	v_mul_f32_e32 v51, 0x3fb8aa3b, v51
	v_exp_f32_e32 v51, v51
	s_nop 0
	v_add_f32_e32 v51, 1.0, v51
	v_rcp_f32_e32 v51, v51
	s_nop 0
	v_mul_f32_e32 v51, v53, v51
	v_mul_f32_e32 v52, 0x3d372713, v46
	v_mul_f32_e32 v52, v46, v52
	v_fma_f32 v52, v46, v52, v46
	v_mul_f32_e32 v52, 0xbfcc422a, v52
	v_mul_f32_e32 v52, 0x3fb8aa3b, v52
	v_exp_f32_e32 v52, v52
	v_cvt_pk_bf16_f32 v57, v50, v51
	global_store_dwordx4 v[68:69], v[54:57], off offset:256
	v_lshl_add_u64 v[50:51], v[66:67], 0, s[46:47]
	v_add_f32_e32 v52, 1.0, v52
	v_rcp_f32_e32 v53, v52
	s_nop 0
	v_mul_f32_e32 v46, v46, v53
	v_mul_f32_e32 v52, 0x3d372713, v47
	v_mul_f32_e32 v52, v47, v52
	v_fma_f32 v52, v47, v52, v47
	v_mul_f32_e32 v52, 0xbfcc422a, v52
	v_mul_f32_e32 v52, 0x3fb8aa3b, v52
	v_exp_f32_e32 v52, v52
	s_nop 0
	v_add_f32_e32 v52, 1.0, v52
	v_rcp_f32_e32 v53, v52
	s_nop 0
	v_mul_f32_e32 v47, v47, v53
	v_cvt_pk_bf16_f32 v46, v46, v47
	v_mul_f32_e32 v47, 0x3d372713, v48
	v_mul_f32_e32 v47, v48, v47
	v_fma_f32 v47, v48, v47, v48
	v_mul_f32_e32 v47, 0xbfcc422a, v47
	v_mul_f32_e32 v47, 0x3fb8aa3b, v47
	v_exp_f32_e32 v47, v47
	s_nop 0
	v_add_f32_e32 v47, 1.0, v47
	v_rcp_f32_e32 v47, v47
	s_nop 0
	v_mul_f32_e32 v47, v48, v47
	v_mul_f32_e32 v48, 0x3d372713, v49
	v_mul_f32_e32 v48, v49, v48
	v_fma_f32 v48, v49, v48, v49
	v_mul_f32_e32 v48, 0xbfcc422a, v48
	v_mul_f32_e32 v48, 0x3fb8aa3b, v48
	v_exp_f32_e32 v48, v48
	s_nop 0
	v_add_f32_e32 v48, 1.0, v48
	v_rcp_f32_e32 v48, v48
	s_nop 0
	v_mul_f32_e32 v48, v49, v48
	v_cvt_pk_bf16_f32 v47, v47, v48
	v_mul_f32_e32 v48, 0x3d372713, v42
	v_mul_f32_e32 v48, v42, v48
	v_fma_f32 v48, v42, v48, v42
	v_mul_f32_e32 v48, 0xbfcc422a, v48
	v_mul_f32_e32 v48, 0x3fb8aa3b, v48
	v_exp_f32_e32 v48, v48
	s_nop 0
	v_add_f32_e32 v48, 1.0, v48
	v_rcp_f32_e32 v49, v48
	s_nop 0
	v_mul_f32_e32 v42, v42, v49
	v_mul_f32_e32 v48, 0x3d372713, v43
	v_mul_f32_e32 v48, v43, v48
	v_fma_f32 v48, v43, v48, v43
; template <int ACT> __device__ __forceinline__ void store_tile_bf16(AccRef acc, bf16_t* dst, int ld, int row0, int col0) {
; #pragma unroll
;     for (int ai = 0; ai < 2; ++ai)
; #pragma unroll
;         for (int m = 0; m < 4; ++m) { bf16_t* rowp = dst + (size_t)(row0 + ai * 128 + m * 16) * ld + col0;
; #pragma unroll
;             for (int bj = 0; bj < 2; ++bj) { const f32x4 v0 = acc[ai][bj][m][0], v1 = acc[ai][bj][m][1];
;                 u32x4 w; w.x = cvt_pk_bf16(actf<ACT>(v0[0]), actf<ACT>(v0[1])); w.y = cvt_pk_bf16(actf<ACT>(v0[2]), actf<ACT>(v0[3]));
;                 w.z = cvt_pk_bf16(actf<ACT>(v1[0]), actf<ACT>(v1[1])); w.w = cvt_pk_bf16(actf<ACT>(v1[2]), actf<ACT>(v1[3]));
;                 *(u32x4*)(rowp + bj * 128) = w; } }
	v_mul_f32_e32 v48, 0xbfcc422a, v48
	v_mul_f32_e32 v48, 0x3fb8aa3b, v48
	v_exp_f32_e32 v48, v48
	s_nop 0
	v_add_f32_e32 v48, 1.0, v48
	v_rcp_f32_e32 v49, v48
	s_nop 0
	v_mul_f32_e32 v43, v43, v49
	v_cvt_pk_bf16_f32 v48, v42, v43
	v_mul_f32_e32 v42, 0x3d372713, v44
	v_mul_f32_e32 v42, v44, v42
	v_fma_f32 v42, v44, v42, v44
	v_mul_f32_e32 v42, 0xbfcc422a, v42
	v_mul_f32_e32 v42, 0x3fb8aa3b, v42
	v_exp_f32_e32 v42, v42
	s_nop 0
	v_add_f32_e32 v42, 1.0, v42
	v_rcp_f32_e32 v42, v42
	s_nop 0
	v_mul_f32_e32 v42, v44, v42
	v_mul_f32_e32 v43, 0x3d372713, v45
	v_mul_f32_e32 v43, v45, v43
	v_fma_f32 v43, v45, v43, v45
	v_mul_f32_e32 v43, 0xbfcc422a, v43
	v_mul_f32_e32 v43, 0x3fb8aa3b, v43
	v_exp_f32_e32 v43, v43
	s_nop 0
	v_add_f32_e32 v43, 1.0, v43
	v_rcp_f32_e32 v43, v43
	s_nop 0
	v_mul_f32_e32 v43, v45, v43
	v_cvt_pk_bf16_f32 v49, v42, v43
	v_add_co_u32_e32 v42, vcc, s86, v66
	s_nop 1
	v_addc_co_u32_e32 v43, vcc, 0, v67, vcc
	global_store_dwordx4 v[42:43], v[46:49], off
	v_mul_f32_e32 v42, 0x3d372713, v38
	v_mul_f32_e32 v42, v38, v42
	v_fma_f32 v42, v38, v42, v38
	v_mul_f32_e32 v42, 0xbfcc422a, v42
	v_mul_f32_e32 v42, 0x3fb8aa3b, v42
	v_exp_f32_e32 v42, v42
	s_nop 0
	v_add_f32_e32 v42, 1.0, v42
	v_rcp_f32_e32 v43, v42
	s_nop 0
	v_mul_f32_e32 v38, v38, v43
	v_mul_f32_e32 v42, 0x3d372713, v39
	v_mul_f32_e32 v42, v39, v42
	v_fma_f32 v42, v39, v42, v39
	v_mul_f32_e32 v42, 0xbfcc422a, v42
	v_mul_f32_e32 v42, 0x3fb8aa3b, v42
	v_exp_f32_e32 v42, v42
	s_nop 0
	v_add_f32_e32 v42, 1.0, v42
	v_rcp_f32_e32 v43, v42
	s_nop 0
	v_mul_f32_e32 v39, v39, v43
	v_cvt_pk_bf16_f32 v38, v38, v39
	v_mul_f32_e32 v39, 0x3d372713, v40
	v_mul_f32_e32 v39, v40, v39
	v_fma_f32 v39, v40, v39, v40
	v_mul_f32_e32 v39, 0xbfcc422a, v39
	v_mul_f32_e32 v39, 0x3fb8aa3b, v39
	v_exp_f32_e32 v39, v39
	s_nop 0
	v_add_f32_e32 v39, 1.0, v39
	v_rcp_f32_e32 v39, v39
	s_nop 0
	v_mul_f32_e32 v39, v40, v39
	v_mul_f32_e32 v40, 0x3d372713, v41
	v_mul_f32_e32 v40, v41, v40
	v_fma_f32 v40, v41, v40, v41
	v_mul_f32_e32 v40, 0xbfcc422a, v40
	v_mul_f32_e32 v40, 0x3fb8aa3b, v40
	v_exp_f32_e32 v40, v40
	s_nop 0
	v_add_f32_e32 v40, 1.0, v40
	v_rcp_f32_e32 v40, v40
	s_nop 0
	v_mul_f32_e32 v40, v41, v40
	v_cvt_pk_bf16_f32 v39, v39, v40
	v_mul_f32_e32 v40, 0x3d372713, v34
	v_mul_f32_e32 v40, v34, v40
	v_fma_f32 v40, v34, v40, v34
	v_mul_f32_e32 v40, 0xbfcc422a, v40
	v_mul_f32_e32 v40, 0x3fb8aa3b, v40
	v_exp_f32_e32 v40, v40
	s_nop 0
	v_add_f32_e32 v40, 1.0, v40
	v_rcp_f32_e32 v41, v40
	s_nop 0
	v_mul_f32_e32 v34, v34, v41
	v_mul_f32_e32 v40, 0x3d372713, v35
	v_mul_f32_e32 v40, v35, v40
	v_fma_f32 v40, v35, v40, v35
	v_mul_f32_e32 v40, 0xbfcc422a, v40
	v_mul_f32_e32 v40, 0x3fb8aa3b, v40
	v_exp_f32_e32 v40, v40
	s_nop 0
	v_add_f32_e32 v40, 1.0, v40
	v_rcp_f32_e32 v41, v40
	s_nop 0
	v_mul_f32_e32 v35, v35, v41
	v_cvt_pk_bf16_f32 v40, v34, v35
	v_mul_f32_e32 v34, 0x3d372713, v36
	v_mul_f32_e32 v34, v36, v34
	v_fma_f32 v34, v36, v34, v36
	v_mul_f32_e32 v34, 0xbfcc422a, v34
	v_mul_f32_e32 v34, 0x3fb8aa3b, v34
	v_exp_f32_e32 v34, v34
	s_nop 0
	v_add_f32_e32 v34, 1.0, v34
	v_rcp_f32_e32 v34, v34
	s_nop 0
	v_mul_f32_e32 v34, v36, v34
	v_mul_f32_e32 v35, 0x3d372713, v37
	v_mul_f32_e32 v35, v37, v35
	v_fma_f32 v35, v37, v35, v37
	v_mul_f32_e32 v35, 0xbfcc422a, v35
	v_mul_f32_e32 v35, 0x3fb8aa3b, v35
	v_exp_f32_e32 v35, v35
	s_nop 0
	v_add_f32_e32 v35, 1.0, v35
	v_rcp_f32_e32 v35, v35
	s_nop 0
	v_mul_f32_e32 v35, v37, v35
	v_mul_f32_e32 v36, 0x3d372713, v30
	v_mul_f32_e32 v36, v30, v36
	v_fma_f32 v36, v30, v36, v30
	v_mul_f32_e32 v36, 0xbfcc422a, v36
	v_mul_f32_e32 v36, 0x3fb8aa3b, v36
	v_exp_f32_e32 v36, v36
	v_cvt_pk_bf16_f32 v41, v34, v35
	global_store_dwordx4 v[50:51], v[38:41], off offset:256
	v_lshl_add_u64 v[34:35], v[66:67], 0, s[48:49]
	v_add_f32_e32 v36, 1.0, v36
	v_rcp_f32_e32 v37, v36
	s_nop 0
	v_mul_f32_e32 v30, v30, v37
	v_mul_f32_e32 v36, 0x3d372713, v31
	v_mul_f32_e32 v36, v31, v36
	v_fma_f32 v36, v31, v36, v31
	v_mul_f32_e32 v36, 0xbfcc422a, v36
	v_mul_f32_e32 v36, 0x3fb8aa3b, v36
	v_exp_f32_e32 v36, v36
	s_nop 0
	v_add_f32_e32 v36, 1.0, v36
	v_rcp_f32_e32 v37, v36
	s_nop 0
	v_mul_f32_e32 v31, v31, v37
	v_cvt_pk_bf16_f32 v30, v30, v31
	v_mul_f32_e32 v31, 0x3d372713, v32
	v_mul_f32_e32 v31, v32, v31
	v_fma_f32 v31, v32, v31, v32
	v_mul_f32_e32 v31, 0xbfcc422a, v31
	v_mul_f32_e32 v31, 0x3fb8aa3b, v31
	v_exp_f32_e32 v31, v31
	s_nop 0
	v_add_f32_e32 v31, 1.0, v31
	v_rcp_f32_e32 v31, v31
	s_nop 0
	v_mul_f32_e32 v31, v32, v31
	v_mul_f32_e32 v32, 0x3d372713, v33
	v_mul_f32_e32 v32, v33, v32
	v_fma_f32 v32, v33, v32, v33
	v_mul_f32_e32 v32, 0xbfcc422a, v32
	v_mul_f32_e32 v32, 0x3fb8aa3b, v32
	v_exp_f32_e32 v32, v32
	s_nop 0
	v_add_f32_e32 v32, 1.0, v32
	v_rcp_f32_e32 v32, v32
	s_nop 0
	v_mul_f32_e32 v32, v33, v32
	v_cvt_pk_bf16_f32 v31, v31, v32
	v_mul_f32_e32 v32, 0x3d372713, v26
	v_mul_f32_e32 v32, v26, v32
	v_fma_f32 v32, v26, v32, v26
	v_mul_f32_e32 v32, 0xbfcc422a, v32
	v_mul_f32_e32 v32, 0x3fb8aa3b, v32
	v_exp_f32_e32 v32, v32
	s_nop 0
	v_add_f32_e32 v32, 1.0, v32
	v_rcp_f32_e32 v33, v32
	s_nop 0
	v_mul_f32_e32 v26, v26, v33
	v_mul_f32_e32 v32, 0x3d372713, v27
	v_mul_f32_e32 v32, v27, v32
	v_fma_f32 v32, v27, v32, v27
	v_mul_f32_e32 v32, 0xbfcc422a, v32
	v_mul_f32_e32 v32, 0x3fb8aa3b, v32
	v_exp_f32_e32 v32, v32
	s_nop 0
	v_add_f32_e32 v32, 1.0, v32
	v_rcp_f32_e32 v33, v32
	s_nop 0
	v_mul_f32_e32 v27, v27, v33
	v_cvt_pk_bf16_f32 v32, v26, v27
	v_mul_f32_e32 v26, 0x3d372713, v28
	v_mul_f32_e32 v26, v28, v26
	v_fma_f32 v26, v28, v26, v28
	v_mul_f32_e32 v26, 0xbfcc422a, v26
	v_mul_f32_e32 v26, 0x3fb8aa3b, v26
	v_exp_f32_e32 v26, v26
	s_nop 0
	v_add_f32_e32 v26, 1.0, v26
	v_rcp_f32_e32 v26, v26
	s_nop 0
; template <int ACT> __device__ __forceinline__ void store_tile_bf16(AccRef acc, bf16_t* dst, int ld, int row0, int col0) {
; #pragma unroll
;     for (int ai = 0; ai < 2; ++ai)
; #pragma unroll
;         for (int m = 0; m < 4; ++m) { bf16_t* rowp = dst + (size_t)(row0 + ai * 128 + m * 16) * ld + col0;
; #pragma unroll
;             for (int bj = 0; bj < 2; ++bj) { const f32x4 v0 = acc[ai][bj][m][0], v1 = acc[ai][bj][m][1];
;                 u32x4 w; w.x = cvt_pk_bf16(actf<ACT>(v0[0]), actf<ACT>(v0[1])); w.y = cvt_pk_bf16(actf<ACT>(v0[2]), actf<ACT>(v0[3]));
;                 w.z = cvt_pk_bf16(actf<ACT>(v1[0]), actf<ACT>(v1[1])); w.w = cvt_pk_bf16(actf<ACT>(v1[2]), actf<ACT>(v1[3]));
;                 *(u32x4*)(rowp + bj * 128) = w; } }
	v_mul_f32_e32 v26, v28, v26
	v_mul_f32_e32 v27, 0x3d372713, v29
	v_mul_f32_e32 v27, v29, v27
	v_fma_f32 v27, v29, v27, v29
	v_mul_f32_e32 v27, 0xbfcc422a, v27
	v_mul_f32_e32 v27, 0x3fb8aa3b, v27
	v_exp_f32_e32 v27, v27
	s_nop 0
	v_add_f32_e32 v27, 1.0, v27
	v_rcp_f32_e32 v27, v27
	s_nop 0
	v_mul_f32_e32 v27, v29, v27
	v_cvt_pk_bf16_f32 v33, v26, v27
	v_add_co_u32_e32 v26, vcc, s87, v66
	s_nop 1
	v_addc_co_u32_e32 v27, vcc, 0, v67, vcc
	global_store_dwordx4 v[26:27], v[30:33], off
	v_mul_f32_e32 v26, 0x3d372713, v22
	v_mul_f32_e32 v26, v22, v26
	v_fma_f32 v26, v22, v26, v22
	v_mul_f32_e32 v26, 0xbfcc422a, v26
	v_mul_f32_e32 v26, 0x3fb8aa3b, v26
	v_exp_f32_e32 v26, v26
	s_nop 0
	v_add_f32_e32 v26, 1.0, v26
	v_rcp_f32_e32 v27, v26
	s_nop 0
	v_mul_f32_e32 v22, v22, v27
	v_mul_f32_e32 v26, 0x3d372713, v23
	v_mul_f32_e32 v26, v23, v26
	v_fma_f32 v26, v23, v26, v23
	v_mul_f32_e32 v26, 0xbfcc422a, v26
	v_mul_f32_e32 v26, 0x3fb8aa3b, v26
	v_exp_f32_e32 v26, v26
	s_nop 0
	v_add_f32_e32 v26, 1.0, v26
	v_rcp_f32_e32 v27, v26
	s_nop 0
	v_mul_f32_e32 v23, v23, v27
	v_cvt_pk_bf16_f32 v22, v22, v23
	v_mul_f32_e32 v23, 0x3d372713, v24
	v_mul_f32_e32 v23, v24, v23
	v_fma_f32 v23, v24, v23, v24
	v_mul_f32_e32 v23, 0xbfcc422a, v23
	v_mul_f32_e32 v23, 0x3fb8aa3b, v23
	v_exp_f32_e32 v23, v23
	s_nop 0
	v_add_f32_e32 v23, 1.0, v23
	v_rcp_f32_e32 v23, v23
	s_nop 0
	v_mul_f32_e32 v23, v24, v23
	v_mul_f32_e32 v24, 0x3d372713, v25
	v_mul_f32_e32 v24, v25, v24
	v_fma_f32 v24, v25, v24, v25
	v_mul_f32_e32 v24, 0xbfcc422a, v24
	v_mul_f32_e32 v24, 0x3fb8aa3b, v24
	v_exp_f32_e32 v24, v24
	s_nop 0
	v_add_f32_e32 v24, 1.0, v24
	v_rcp_f32_e32 v24, v24
	s_nop 0
	v_mul_f32_e32 v24, v25, v24
	v_cvt_pk_bf16_f32 v23, v23, v24
	v_mul_f32_e32 v24, 0x3d372713, v18
	v_mul_f32_e32 v24, v18, v24
	v_fma_f32 v24, v18, v24, v18
	v_mul_f32_e32 v24, 0xbfcc422a, v24
	v_mul_f32_e32 v24, 0x3fb8aa3b, v24
	v_exp_f32_e32 v24, v24
	s_nop 0
	v_add_f32_e32 v24, 1.0, v24
	v_rcp_f32_e32 v25, v24
	s_nop 0
	v_mul_f32_e32 v18, v18, v25
	v_mul_f32_e32 v24, 0x3d372713, v19
	v_mul_f32_e32 v24, v19, v24
	v_fma_f32 v24, v19, v24, v19
	v_mul_f32_e32 v24, 0xbfcc422a, v24
	v_mul_f32_e32 v24, 0x3fb8aa3b, v24
	v_exp_f32_e32 v24, v24
	s_nop 0
	v_add_f32_e32 v24, 1.0, v24
	v_rcp_f32_e32 v25, v24
	s_nop 0
	v_mul_f32_e32 v19, v19, v25
	v_cvt_pk_bf16_f32 v24, v18, v19
	v_mul_f32_e32 v18, 0x3d372713, v20
	v_mul_f32_e32 v18, v20, v18
	v_fma_f32 v18, v20, v18, v20
	v_mul_f32_e32 v18, 0xbfcc422a, v18
	v_mul_f32_e32 v18, 0x3fb8aa3b, v18
	v_exp_f32_e32 v18, v18
	s_nop 0
	v_add_f32_e32 v18, 1.0, v18
	v_rcp_f32_e32 v18, v18
	s_nop 0
	v_mul_f32_e32 v18, v20, v18
	v_mul_f32_e32 v19, 0x3d372713, v21
	v_mul_f32_e32 v19, v21, v19
	v_fma_f32 v19, v21, v19, v21
	v_mul_f32_e32 v19, 0xbfcc422a, v19
	v_mul_f32_e32 v19, 0x3fb8aa3b, v19
	v_exp_f32_e32 v19, v19
	s_nop 0
	v_add_f32_e32 v19, 1.0, v19
	v_rcp_f32_e32 v19, v19
	s_nop 0
	v_mul_f32_e32 v19, v21, v19
	v_cvt_pk_bf16_f32 v25, v18, v19
	v_mul_f32_e32 v18, 0x3d372713, v14
	v_mul_f32_e32 v18, v14, v18
	v_fma_f32 v18, v14, v18, v14
	v_mul_f32_e32 v18, 0xbfcc422a, v18
	v_mul_f32_e32 v18, 0x3fb8aa3b, v18
	v_exp_f32_e32 v18, v18
	global_store_dwordx4 v[34:35], v[22:25], off offset:256
	v_add_f32_e32 v18, 1.0, v18
	v_rcp_f32_e32 v19, v18
	s_nop 0
	v_mul_f32_e32 v14, v14, v19
	v_mul_f32_e32 v18, 0x3d372713, v15
	v_mul_f32_e32 v18, v15, v18
	v_fma_f32 v18, v15, v18, v15
	v_mul_f32_e32 v18, 0xbfcc422a, v18
	v_mul_f32_e32 v18, 0x3fb8aa3b, v18
	v_exp_f32_e32 v18, v18
	s_nop 0
	v_add_f32_e32 v18, 1.0, v18
	v_rcp_f32_e32 v19, v18
	s_nop 0
	v_mul_f32_e32 v15, v15, v19
	v_cvt_pk_bf16_f32 v14, v14, v15
	v_mul_f32_e32 v15, 0x3d372713, v16
	v_mul_f32_e32 v15, v16, v15
	v_fma_f32 v15, v16, v15, v16
	v_mul_f32_e32 v15, 0xbfcc422a, v15
	v_mul_f32_e32 v15, 0x3fb8aa3b, v15
	v_exp_f32_e32 v15, v15
	s_nop 0
	v_add_f32_e32 v15, 1.0, v15
	v_rcp_f32_e32 v15, v15
	s_nop 0
	v_mul_f32_e32 v15, v16, v15
	v_mul_f32_e32 v16, 0x3d372713, v17
; template <int ACT> __device__ __forceinline__ void store_tile_bf16(AccRef acc, bf16_t* dst, int ld, int row0, int col0) {
; #pragma unroll
;     for (int ai = 0; ai < 2; ++ai)
; #pragma unroll
;         for (int m = 0; m < 4; ++m) { bf16_t* rowp = dst + (size_t)(row0 + ai * 128 + m * 16) * ld + col0;
; #pragma unroll
;             for (int bj = 0; bj < 2; ++bj) { const f32x4 v0 = acc[ai][bj][m][0], v1 = acc[ai][bj][m][1];
;                 u32x4 w; w.x = cvt_pk_bf16(actf<ACT>(v0[0]), actf<ACT>(v0[1])); w.y = cvt_pk_bf16(actf<ACT>(v0[2]), actf<ACT>(v0[3]));
;                 w.z = cvt_pk_bf16(actf<ACT>(v1[0]), actf<ACT>(v1[1])); w.w = cvt_pk_bf16(actf<ACT>(v1[2]), actf<ACT>(v1[3]));
;                 *(u32x4*)(rowp + bj * 128) = w; } }
	v_mul_f32_e32 v16, v17, v16
	v_fma_f32 v16, v17, v16, v17
	v_mul_f32_e32 v16, 0xbfcc422a, v16
	v_mul_f32_e32 v16, 0x3fb8aa3b, v16
	v_exp_f32_e32 v16, v16
	s_nop 0
	v_add_f32_e32 v16, 1.0, v16
	v_rcp_f32_e32 v16, v16
	s_nop 0
	v_mul_f32_e32 v16, v17, v16
	v_cvt_pk_bf16_f32 v15, v15, v16
	v_mul_f32_e32 v16, 0x3d372713, v10
	v_mul_f32_e32 v16, v10, v16
	v_fma_f32 v16, v10, v16, v10
	v_mul_f32_e32 v16, 0xbfcc422a, v16
	v_mul_f32_e32 v16, 0x3fb8aa3b, v16
	v_exp_f32_e32 v16, v16
	s_nop 0
	v_add_f32_e32 v16, 1.0, v16
	v_rcp_f32_e32 v17, v16
	s_nop 0
	v_mul_f32_e32 v10, v10, v17
	v_mul_f32_e32 v16, 0x3d372713, v11
	v_mul_f32_e32 v16, v11, v16
	v_fma_f32 v16, v11, v16, v11
	v_mul_f32_e32 v16, 0xbfcc422a, v16
	v_mul_f32_e32 v16, 0x3fb8aa3b, v16
	v_exp_f32_e32 v16, v16
	s_nop 0
	v_add_f32_e32 v16, 1.0, v16
	v_rcp_f32_e32 v17, v16
	s_nop 0
	v_mul_f32_e32 v11, v11, v17
	v_cvt_pk_bf16_f32 v16, v10, v11
	v_mul_f32_e32 v10, 0x3d372713, v12
	v_mul_f32_e32 v10, v12, v10
	v_fma_f32 v10, v12, v10, v12
	v_mul_f32_e32 v10, 0xbfcc422a, v10
	v_mul_f32_e32 v10, 0x3fb8aa3b, v10
	v_exp_f32_e32 v10, v10
	s_nop 0
	v_add_f32_e32 v10, 1.0, v10
	v_rcp_f32_e32 v10, v10
	s_nop 0
	v_mul_f32_e32 v10, v12, v10
	v_mul_f32_e32 v11, 0x3d372713, v13
	v_mul_f32_e32 v11, v13, v11
	v_fma_f32 v11, v13, v11, v13
	v_mul_f32_e32 v11, 0xbfcc422a, v11
	v_mul_f32_e32 v11, 0x3fb8aa3b, v11
	v_exp_f32_e32 v11, v11
	s_nop 0
	v_add_f32_e32 v11, 1.0, v11
	v_rcp_f32_e32 v11, v11
	s_nop 0
	v_mul_f32_e32 v11, v13, v11
	v_cvt_pk_bf16_f32 v17, v10, v11
	v_add_co_u32_e32 v10, vcc, s3, v66
	s_nop 1
	v_addc_co_u32_e32 v11, vcc, 0, v67, vcc
	global_store_dwordx4 v[10:11], v[14:17], off
	v_mul_f32_e32 v10, 0x3d372713, v6
	v_mul_f32_e32 v10, v6, v10
	v_fma_f32 v10, v6, v10, v6
	v_mul_f32_e32 v10, 0xbfcc422a, v10
	v_mul_f32_e32 v10, 0x3fb8aa3b, v10
	v_exp_f32_e32 v10, v10
	s_nop 0
	v_add_f32_e32 v10, 1.0, v10
	v_rcp_f32_e32 v11, v10
	s_nop 0
	v_mul_f32_e32 v6, v6, v11
	v_mul_f32_e32 v10, 0x3d372713, v7
	v_mul_f32_e32 v10, v7, v10
	v_fma_f32 v10, v7, v10, v7
	v_mul_f32_e32 v10, 0xbfcc422a, v10
	v_mul_f32_e32 v10, 0x3fb8aa3b, v10
	v_exp_f32_e32 v10, v10
	s_nop 0
	v_add_f32_e32 v10, 1.0, v10
	v_rcp_f32_e32 v11, v10
	s_nop 0
	v_mul_f32_e32 v7, v7, v11
	v_cvt_pk_bf16_f32 v130, v6, v7
	v_mul_f32_e32 v6, 0x3d372713, v8
	v_mul_f32_e32 v6, v8, v6
	v_fma_f32 v6, v8, v6, v8
	v_mul_f32_e32 v6, 0xbfcc422a, v6
	v_mul_f32_e32 v6, 0x3fb8aa3b, v6
	v_exp_f32_e32 v6, v6
	s_nop 0
	v_add_f32_e32 v6, 1.0, v6
	v_rcp_f32_e32 v6, v6
	s_nop 0
	v_mul_f32_e32 v6, v8, v6
	v_mul_f32_e32 v7, 0x3d372713, v9
	v_mul_f32_e32 v7, v9, v7
	v_fma_f32 v7, v9, v7, v9
	v_mul_f32_e32 v7, 0xbfcc422a, v7
	v_mul_f32_e32 v7, 0x3fb8aa3b, v7
	v_exp_f32_e32 v7, v7
	s_nop 0
	v_add_f32_e32 v7, 1.0, v7
	v_rcp_f32_e32 v7, v7
	s_nop 0
	v_mul_f32_e32 v7, v9, v7
	v_cvt_pk_bf16_f32 v131, v6, v7
	v_mul_f32_e32 v6, 0x3d372713, v2
	v_mul_f32_e32 v6, v2, v6
	v_fma_f32 v6, v2, v6, v2
	v_mul_f32_e32 v6, 0xbfcc422a, v6
	v_mul_f32_e32 v6, 0x3fb8aa3b, v6
	v_exp_f32_e32 v6, v6
	s_nop 0
	v_add_f32_e32 v6, 1.0, v6
	v_rcp_f32_e32 v7, v6
	s_nop 0
	v_mul_f32_e32 v2, v2, v7
	v_mul_f32_e32 v6, 0x3d372713, v3
	v_mul_f32_e32 v6, v3, v6
	v_fma_f32 v6, v3, v6, v3
	v_mul_f32_e32 v6, 0xbfcc422a, v6
	v_mul_f32_e32 v6, 0x3fb8aa3b, v6
	v_exp_f32_e32 v6, v6
	s_nop 0
	v_add_f32_e32 v6, 1.0, v6
	v_rcp_f32_e32 v7, v6
	s_nop 0
	v_mul_f32_e32 v3, v3, v7
	v_cvt_pk_bf16_f32 v132, v2, v3
	v_mul_f32_e32 v2, 0x3d372713, v4
	v_mul_f32_e32 v3, 0x3d372713, v5
	v_mul_f32_e32 v2, v4, v2
	v_mul_f32_e32 v3, v5, v3
	v_fma_f32 v2, v4, v2, v4
	v_fma_f32 v3, v5, v3, v5
	v_mul_f32_e32 v2, 0xbfcc422a, v2
	v_mul_f32_e32 v3, 0xbfcc422a, v3
	v_mul_f32_e32 v2, 0x3fb8aa3b, v2
	v_mul_f32_e32 v3, 0x3fb8aa3b, v3
	v_exp_f32_e32 v2, v2
	v_exp_f32_e32 v3, v3
	s_nop 0
	v_pk_add_f32 v[2:3], v[2:3], 1.0 op_sel_hi:[1,0]
	s_nop 0
	v_rcp_f32_e32 v6, v2
	s_nop 0
	v_mul_f32_e32 v4, v4, v6
	v_rcp_f32_e32 v2, v3
	s_nop 0
	v_mul_f32_e32 v5, v5, v2
	s_branch .LBB0_413

; #define PG8_STAGE(bufoff, gbase, voff) do { _Pragma("unroll") for (int _i = 0; _i < 2; ++_i) \
;         __builtin_amdgcn_global_load_lds((const unsigned*)((const char*)(gbase) + (voff)[_i]), (LAS unsigned*)(lds + (bufoff) + ldsw + _i * 8192), 16, 0, 0); } while (0)
; #define PG8_LDA(dst, b, h) do { _Pragma("unroll") for (int m = 0; m < 4; ++m) _Pragma("unroll") for (int k = 0; k < 2; ++k) dst[m][k] = *(const LAS bf16x8*)(lds + PG8_SA(b, h) + aoff + m * 2048 + k * 1024); } while (0)
; #define PG8_LDB(dst, b, h) do { _Pragma("unroll") for (int n = 0; n < 2; ++n) _Pragma("unroll") for (int k = 0; k < 2; ++k) dst[n][k] = *(const LAS bf16x8*)(lds + PG8_SB(b, h) + boff + n * 2048 + k * 1024); } while (0)
; #define PG8_WAIT_V(n) asm volatile("s_waitcnt vmcnt(" #n ")" ::: "memory")
; #define PG8_WAIT_L(n) asm volatile("s_waitcnt lgkmcnt(" #n ")" ::: "memory")
; #define PG8_BAR __builtin_amdgcn_s_barrier()
; #define PG8_SCHED __builtin_amdgcn_sched_barrier(0)
; template <class Epi, class GT>
; __device__ __forceinline__ void gemm_phase(LAS unsigned char* lds, const GT g, const StaticOrder& S, const Epi& E) {
;     ...
;         for (int t = 0; t < nt; t += 2) {
;             const bool last = (t == nt - 2);
;             const char* a1 = cA + (size_t)(t + 1) * kstep;
;             const char* a2 = last ? nA : cA + (size_t)(t + 2) * kstep; const char* b2 = last ? nB : cB + (size_t)(t + 2) * kstep;
;             const char* a3 = a2 + kstep; const char* b3 = b2 + kstep;
;             PG8_LDB(B0, 0, 0); PG8_SCHED; PG8_LDA(At, 0, 0); PG8_STAGE(PG8_SA(1, 1), a1 + hstepA, voffA);
;             PG8_WAIT_L(8); PG8_BAR; PG8_WAIT_L(0); PG8_MMA(0, 0, At, B0); PG8_BAR; PG8_SCHED;
;             PG8_LDB(B1, 0, 1); PG8_STAGE(PG8_SB(0, 0), b2, voffB);
;             PG8_BAR; PG8_WAIT_L(0); PG8_MMA(0, 1, At, B1); PG8_BAR;
;             PG8_LDA(At, 0, 1); PG8_STAGE(PG8_SA(0, 0), a2, voffA);
;             PG8_BAR; PG8_WAIT_L(0); PG8_MMA(1, 0, At, B0); PG8_BAR; PG8_SCHED;
;             PG8_STAGE(PG8_SB(0, 1), b2 + hstepB, voffB);
;             PG8_WAIT_V(6); PG8_BAR; PG8_MMA(1, 1, At, B1); PG8_BAR;
;             PG8_LDB(B0, 1, 0); PG8_SCHED; PG8_LDA(At, 1, 0); PG8_STAGE(PG8_SA(0, 1), a2 + hstepA, voffA);
;             PG8_WAIT_L(8); PG8_BAR; PG8_WAIT_L(0); PG8_MMA(0, 0, At, B0); PG8_BAR; PG8_SCHED;
.LBB0_565:
	s_add_u32 s16, s62, s12
	s_addc_u32 s17, s63, 0
	s_add_u32 s13, s16, 0x100
	s_addc_u32 s18, s17, 0
	s_and_b64 s[14:15], s[66:67], exec
	s_cselect_b32 s73, s8, s18
	s_cselect_b32 s72, s9, s13
	s_add_u32 s12, s60, s12
	s_addc_u32 s13, s61, 0
	s_add_u32 s14, s12, 0x100
	s_addc_u32 s15, s13, 0
	s_and_b64 s[12:13], s[66:67], exec
	s_cselect_b32 s75, s10, s15
	s_cselect_b32 s74, s11, s14
	s_add_u32 s76, s16, 0x80080
	s_addc_u32 s77, s17, 0
	s_add_i32 s21, s90, s81
	s_add_i32 m0, s83, 0xc000
	s_add_i32 s22, s83, 0xe000
	s_add_i32 s20, s21, 0x2000
	s_add_u32 s70, s74, 0x10000
	s_addc_u32 s71, s75, 0
	s_add_i32 s19, s91, s81
	s_add_i32 s18, s19, 0x2000
	s_add_i32 s17, 0, 0x18000
	ds_read_b128 v[2:5], v218
	ds_read_b128 v[26:29], v218 offset:1024
	ds_read_b128 v[30:33], v218 offset:2048
	ds_read_b128 v[34:37], v218 offset:3072
	s_add_u32 s68, s72, 0x80000
	s_addc_u32 s69, s73, 0
	s_add_i32 s16, s17, s81
	s_add_i32 s15, 0, 0x1c000
	s_add_i32 s14, s16, 0x2000
	s_add_u32 s66, s74, 0x10080
	s_addc_u32 s67, s75, 0
	s_add_i32 s13, s15, s81
	s_add_i32 s12, s13, 0x2000
	v_lshl_add_u64 v[192:193], s[76:77], 0, v[184:185]
	ds_read_b128 v[38:41], v219
	ds_read_b128 v[46:49], v219 offset:1024
	ds_read_b128 v[66:69], v219 offset:2048
	ds_read_b128 v[86:89], v219 offset:3072
	ds_read_b128 v[106:109], v219 offset:4096
	ds_read_b128 v[126:129], v219 offset:5120
	ds_read_b128 v[146:149], v219 offset:6144
	ds_read_b128 v[166:169], v219 offset:7168
	global_load_lds_dwordx4 v[192:193], off
	v_lshl_add_u64 v[192:193], s[76:77], 0, v[180:181]
	s_mov_b32 m0, s22
	s_nop 0
	global_load_lds_dwordx4 v[192:193], off
	s_waitcnt lgkmcnt(8)
	s_barrier
	s_waitcnt lgkmcnt(0)
	s_setprio 1
	s_waitcnt lgkmcnt(0)
	v_mfma_f32_16x16x32_bf16 v[174:177], v[2:5], v[38:41], v[174:177]
	v_mfma_f32_16x16x32_bf16 v[170:173], v[30:33], v[38:41], v[170:173]
	v_mfma_f32_16x16x32_bf16 v[162:165], v[2:5], v[66:69], v[162:165]
	v_mfma_f32_16x16x32_bf16 v[158:161], v[30:33], v[66:69], v[158:161]
	v_mfma_f32_16x16x32_bf16 v[142:145], v[2:5], v[106:109], v[142:145]
	v_mfma_f32_16x16x32_bf16 v[138:141], v[30:33], v[106:109], v[138:141]
	v_mfma_f32_16x16x32_bf16 v[122:125], v[2:5], v[146:149], v[122:125]
	v_mfma_f32_16x16x32_bf16 v[118:121], v[30:33], v[146:149], v[118:121]
	v_mfma_f32_16x16x32_bf16 v[174:177], v[26:29], v[46:49], v[174:177]
	v_mfma_f32_16x16x32_bf16 v[170:173], v[34:37], v[46:49], v[170:173]
	v_mfma_f32_16x16x32_bf16 v[162:165], v[26:29], v[86:89], v[162:165]
	v_mfma_f32_16x16x32_bf16 v[158:161], v[34:37], v[86:89], v[158:161]
	v_mfma_f32_16x16x32_bf16 v[142:145], v[26:29], v[126:129], v[142:145]
	v_mfma_f32_16x16x32_bf16 v[138:141], v[34:37], v[126:129], v[138:141]
	v_mfma_f32_16x16x32_bf16 v[122:125], v[26:29], v[166:169], v[122:125]
	v_mfma_f32_16x16x32_bf16 v[118:121], v[34:37], v[166:169], v[118:121]
	s_setprio 0
	s_barrier
	s_mov_b32 m0, s21
	v_lshl_add_u64 v[222:223], s[74:75], 0, v[182:183]
	ds_read_b128 v[192:195], v220
	ds_read_b128 v[196:199], v220 offset:1024
	ds_read_b128 v[200:203], v220 offset:2048
	ds_read_b128 v[204:207], v220 offset:3072
	global_load_lds_dwordx4 v[222:223], off
	v_lshl_add_u64 v[224:225], s[74:75], 0, v[178:179]
	s_mov_b32 m0, s20
	s_nop 0
	global_load_lds_dwordx4 v[224:225], off
	s_barrier
	s_waitcnt lgkmcnt(0)
	s_setprio 1
	s_waitcnt lgkmcnt(0)
	v_mfma_f32_16x16x32_bf16 v[42:45], v[192:195], v[38:41], v[42:45]
	v_mfma_f32_16x16x32_bf16 v[22:25], v[200:203], v[38:41], v[22:25]
	v_mfma_f32_16x16x32_bf16 v[42:45], v[196:199], v[46:49], v[42:45]
	v_mfma_f32_16x16x32_bf16 v[22:25], v[204:207], v[46:49], v[22:25]
	v_mfma_f32_16x16x32_bf16 v[38:41], v[192:195], v[66:69], v[154:157]
	v_mfma_f32_16x16x32_bf16 v[46:49], v[200:203], v[66:69], v[150:153]
	v_mfma_f32_16x16x32_bf16 v[110:113], v[200:203], v[146:149], v[110:113]
	v_mfma_f32_16x16x32_bf16 v[38:41], v[196:199], v[86:89], v[38:41]
	v_mfma_f32_16x16x32_bf16 v[46:49], v[204:207], v[86:89], v[46:49]
	v_mfma_f32_16x16x32_bf16 v[66:69], v[192:195], v[106:109], v[134:137]
	v_mfma_f32_16x16x32_bf16 v[86:89], v[200:203], v[106:109], v[130:133]
	v_mfma_f32_16x16x32_bf16 v[106:109], v[192:195], v[146:149], v[114:117]
	v_mfma_f32_16x16x32_bf16 v[110:113], v[204:207], v[166:169], v[110:113]
	v_mfma_f32_16x16x32_bf16 v[66:69], v[196:199], v[126:129], v[66:69]
	v_mfma_f32_16x16x32_bf16 v[86:89], v[204:207], v[126:129], v[86:89]
	v_mfma_f32_16x16x32_bf16 v[106:109], v[196:199], v[166:169], v[106:109]
	s_setprio 0
	s_mov_b32 m0, s83
	v_lshl_add_u64 v[226:227], s[72:73], 0, v[184:185]
	s_barrier
	ds_read_b128 v[114:117], v219 offset:16384
	ds_read_b128 v[126:129], v219 offset:17408
	ds_read_b128 v[130:133], v219 offset:18432
	ds_read_b128 v[134:137], v219 offset:19456
	ds_read_b128 v[146:149], v219 offset:20480
	ds_read_b128 v[150:153], v219 offset:21504
	ds_read_b128 v[154:157], v219 offset:22528
	ds_read_b128 v[166:169], v219 offset:23552
	global_load_lds_dwordx4 v[226:227], off
	v_lshl_add_u64 v[228:229], s[72:73], 0, v[180:181]
	s_mov_b32 m0, s84
	s_nop 0
	global_load_lds_dwordx4 v[228:229], off
	s_barrier
	s_waitcnt lgkmcnt(0)
	s_setprio 1
	s_waitcnt lgkmcnt(0)
	v_mfma_f32_16x16x32_bf16 v[102:105], v[2:5], v[114:117], v[102:105]
	v_mfma_f32_16x16x32_bf16 v[98:101], v[30:33], v[114:117], v[98:101]
	v_mfma_f32_16x16x32_bf16 v[82:85], v[2:5], v[130:133], v[82:85]
	v_mfma_f32_16x16x32_bf16 v[78:81], v[30:33], v[130:133], v[78:81]
	v_mfma_f32_16x16x32_bf16 v[62:65], v[2:5], v[146:149], v[62:65]
	v_mfma_f32_16x16x32_bf16 v[58:61], v[30:33], v[146:149], v[58:61]
	v_mfma_f32_16x16x32_bf16 v[14:17], v[30:33], v[154:157], v[14:17]
	v_mfma_f32_16x16x32_bf16 v[102:105], v[26:29], v[126:129], v[102:105]
	v_mfma_f32_16x16x32_bf16 v[98:101], v[34:37], v[126:129], v[98:101]
	v_mfma_f32_16x16x32_bf16 v[82:85], v[26:29], v[134:137], v[82:85]
	v_mfma_f32_16x16x32_bf16 v[78:81], v[34:37], v[134:137], v[78:81]
	v_mfma_f32_16x16x32_bf16 v[62:65], v[26:29], v[150:153], v[62:65]
	v_mfma_f32_16x16x32_bf16 v[58:61], v[34:37], v[150:153], v[58:61]
	v_mfma_f32_16x16x32_bf16 v[2:5], v[2:5], v[154:157], v[18:21]
	v_mfma_f32_16x16x32_bf16 v[14:17], v[34:37], v[166:169], v[14:17]
	v_mfma_f32_16x16x32_bf16 v[2:5], v[26:29], v[166:169], v[2:5]
	s_setprio 0
	s_barrier
; #define PG8_STAGE(bufoff, gbase, voff) do { _Pragma("unroll") for (int _i = 0; _i < 2; ++_i) \
;         __builtin_amdgcn_global_load_lds((const unsigned*)((const char*)(gbase) + (voff)[_i]), (LAS unsigned*)(lds + (bufoff) + ldsw + _i * 8192), 16, 0, 0); } while (0)
; #define PG8_LDA(dst, b, h) do { _Pragma("unroll") for (int m = 0; m < 4; ++m) _Pragma("unroll") for (int k = 0; k < 2; ++k) dst[m][k] = *(const LAS bf16x8*)(lds + PG8_SA(b, h) + aoff + m * 2048 + k * 1024); } while (0)
; #define PG8_LDB(dst, b, h) do { _Pragma("unroll") for (int n = 0; n < 2; ++n) _Pragma("unroll") for (int k = 0; k < 2; ++k) dst[n][k] = *(const LAS bf16x8*)(lds + PG8_SB(b, h) + boff + n * 2048 + k * 1024); } while (0)
; #define PG8_MMA(ai, bj, At, Bt) do { __builtin_amdgcn_s_setprio(1); _Pragma("unroll") for (int m = 0; m < 4; ++m) _Pragma("unroll") for (int n = 0; n < 2; ++n) _Pragma("unroll") for (int k = 0; k < 2; ++k) \
;         acc[ai][bj][m][n] = __builtin_amdgcn_mfma_f32_16x16x32_bf16(Bt[n][k], At[m][k], acc[ai][bj][m][n], 0, 0, 0); __builtin_amdgcn_s_setprio(0); } while (0)
; #define PG8_WAIT_V(n) asm volatile("s_waitcnt vmcnt(" #n ")" ::: "memory")
; #define PG8_WAIT_L(n) asm volatile("s_waitcnt lgkmcnt(" #n ")" ::: "memory")
; #define PG8_BAR __builtin_amdgcn_s_barrier()
; #define PG8_SCHED __builtin_amdgcn_sched_barrier(0)
; template <class Epi, class GT>
; __device__ __forceinline__ void gemm_phase(LAS unsigned char* lds, const GT g, const StaticOrder& S, const Epi& E) {
;     ...
;             PG8_WAIT_V(6); PG8_BAR; PG8_MMA(1, 1, At, B1); PG8_BAR;
;             PG8_LDB(B0, 1, 0); PG8_SCHED; PG8_LDA(At, 1, 0); PG8_STAGE(PG8_SA(0, 1), a2 + hstepA, voffA);
;             PG8_WAIT_L(8); PG8_BAR; PG8_WAIT_L(0); PG8_MMA(0, 0, At, B0); PG8_BAR; PG8_SCHED;
;             PG8_LDB(B1, 1, 1); PG8_STAGE(PG8_SB(1, 0), b3, voffB);
;             PG8_BAR; PG8_WAIT_L(0); PG8_MMA(0, 1, At, B1); PG8_BAR;
;             PG8_LDA(At, 1, 1); PG8_STAGE(PG8_SA(1, 0), a3, voffA);
;             PG8_BAR; PG8_WAIT_L(0); PG8_MMA(1, 0, At, B0); PG8_BAR; PG8_SCHED;
	s_mov_b32 m0, s19
	v_lshl_add_u64 v[18:19], s[70:71], 0, v[182:183]
	global_load_lds_dwordx4 v[18:19], off
	v_lshl_add_u64 v[18:19], s[70:71], 0, v[178:179]
	s_mov_b32 m0, s18
	s_nop 0
	global_load_lds_dwordx4 v[18:19], off
	s_waitcnt vmcnt(6)
	s_barrier
	s_setprio 1
	v_mfma_f32_16x16x32_bf16 v[18:21], v[192:195], v[114:117], v[94:97]
	v_mfma_f32_16x16x32_bf16 v[26:29], v[196:199], v[126:129], v[18:21]
	v_mfma_f32_16x16x32_bf16 v[18:21], v[200:203], v[114:117], v[90:93]
	v_mfma_f32_16x16x32_bf16 v[30:33], v[204:207], v[126:129], v[18:21]
	v_mfma_f32_16x16x32_bf16 v[18:21], v[192:195], v[130:133], v[74:77]
	v_mfma_f32_16x16x32_bf16 v[34:37], v[196:199], v[134:137], v[18:21]
	v_mfma_f32_16x16x32_bf16 v[18:21], v[200:203], v[130:133], v[70:73]
	v_mfma_f32_16x16x32_bf16 v[70:73], v[204:207], v[134:137], v[18:21]
	v_mfma_f32_16x16x32_bf16 v[18:21], v[192:195], v[146:149], v[54:57]
	v_mfma_f32_16x16x32_bf16 v[54:57], v[196:199], v[150:153], v[18:21]
	v_mfma_f32_16x16x32_bf16 v[18:21], v[200:203], v[146:149], v[50:53]
	v_mfma_f32_16x16x32_bf16 v[10:13], v[192:195], v[154:157], v[10:13]
	v_mfma_f32_16x16x32_bf16 v[6:9], v[200:203], v[154:157], v[6:9]
	v_mfma_f32_16x16x32_bf16 v[50:53], v[204:207], v[150:153], v[18:21]
	v_mfma_f32_16x16x32_bf16 v[10:13], v[196:199], v[166:169], v[10:13]
	v_mfma_f32_16x16x32_bf16 v[6:9], v[204:207], v[166:169], v[6:9]
	s_setprio 0
	v_add_u32_e32 v94, s17, v216
	s_barrier
	ds_read_b128 v[18:21], v94
	ds_read_b128 v[74:77], v94 offset:1024
	ds_read_b128 v[90:93], v94 offset:2048
	ds_read_b128 v[94:97], v94 offset:3072
	s_mov_b32 m0, s85
	v_lshl_add_u64 v[150:151], s[68:69], 0, v[184:185]
	ds_read_b128 v[114:117], v219 offset:32768
	ds_read_b128 v[126:129], v219 offset:33792
	ds_read_b128 v[130:133], v219 offset:34816
	ds_read_b128 v[134:137], v219 offset:35840
	ds_read_b128 v[146:149], v219 offset:36864
	ds_read_b128 v[166:169], v219 offset:37888
	ds_read_b128 v[192:195], v219 offset:38912
	ds_read_b128 v[196:199], v219 offset:39936
	global_load_lds_dwordx4 v[150:151], off
	v_lshl_add_u64 v[150:151], s[68:69], 0, v[180:181]
	s_mov_b32 m0, s86
	s_nop 0
	global_load_lds_dwordx4 v[150:151], off
	s_waitcnt lgkmcnt(8)
	s_barrier
	s_waitcnt lgkmcnt(0)
	s_setprio 1
	s_waitcnt lgkmcnt(0)
	v_mfma_f32_16x16x32_bf16 v[150:153], v[18:21], v[114:117], v[174:177]
	v_mfma_f32_16x16x32_bf16 v[174:177], v[74:77], v[126:129], v[150:153]
	v_mfma_f32_16x16x32_bf16 v[150:153], v[90:93], v[114:117], v[170:173]
	v_mfma_f32_16x16x32_bf16 v[170:173], v[94:97], v[126:129], v[150:153]
	v_mfma_f32_16x16x32_bf16 v[150:153], v[18:21], v[130:133], v[162:165]
	v_mfma_f32_16x16x32_bf16 v[162:165], v[74:77], v[134:137], v[150:153]
	v_mfma_f32_16x16x32_bf16 v[150:153], v[90:93], v[130:133], v[158:161]
	v_mfma_f32_16x16x32_bf16 v[142:145], v[18:21], v[146:149], v[142:145]
	v_mfma_f32_16x16x32_bf16 v[138:141], v[90:93], v[146:149], v[138:141]
	v_mfma_f32_16x16x32_bf16 v[122:125], v[18:21], v[192:195], v[122:125]
	v_mfma_f32_16x16x32_bf16 v[118:121], v[90:93], v[192:195], v[118:121]
	v_mfma_f32_16x16x32_bf16 v[158:161], v[94:97], v[134:137], v[150:153]
	v_mfma_f32_16x16x32_bf16 v[142:145], v[74:77], v[166:169], v[142:145]
	v_mfma_f32_16x16x32_bf16 v[138:141], v[94:97], v[166:169], v[138:141]
	v_mfma_f32_16x16x32_bf16 v[122:125], v[74:77], v[196:199], v[122:125]
	v_mfma_f32_16x16x32_bf16 v[118:121], v[94:97], v[196:199], v[118:121]
	s_setprio 0
	s_barrier
	v_add_u32_e32 v150, s15, v216
	s_mov_b32 m0, s16
	ds_read_b128 v[200:203], v150
	ds_read_b128 v[204:207], v150 offset:1024
	ds_read_b128 v[208:211], v150 offset:2048
	ds_read_b128 v[212:215], v150 offset:3072
	v_lshl_add_u64 v[150:151], v[222:223], 0, s[50:51]
	global_load_lds_dwordx4 v[150:151], off
	v_lshl_add_u64 v[150:151], v[224:225], 0, s[50:51]
	s_mov_b32 m0, s14
	s_nop 0
	global_load_lds_dwordx4 v[150:151], off
	s_barrier
	s_waitcnt lgkmcnt(0)
	s_setprio 1
	s_waitcnt lgkmcnt(0)
	v_mfma_f32_16x16x32_bf16 v[38:41], v[200:203], v[130:133], v[38:41]
	v_mfma_f32_16x16x32_bf16 v[154:157], v[204:207], v[134:137], v[38:41]
	v_mfma_f32_16x16x32_bf16 v[38:41], v[208:211], v[130:133], v[46:49]
	v_mfma_f32_16x16x32_bf16 v[150:153], v[212:215], v[134:137], v[38:41]
	v_mfma_f32_16x16x32_bf16 v[38:41], v[200:203], v[146:149], v[66:69]
	v_mfma_f32_16x16x32_bf16 v[134:137], v[204:207], v[166:169], v[38:41]
	v_mfma_f32_16x16x32_bf16 v[38:41], v[208:211], v[146:149], v[86:89]
	v_mfma_f32_16x16x32_bf16 v[130:133], v[212:215], v[166:169], v[38:41]
	v_mfma_f32_16x16x32_bf16 v[38:41], v[200:203], v[192:195], v[106:109]
	v_mfma_f32_16x16x32_bf16 v[42:45], v[200:203], v[114:117], v[42:45]
	v_mfma_f32_16x16x32_bf16 v[22:25], v[208:211], v[114:117], v[22:25]
	v_mfma_f32_16x16x32_bf16 v[114:117], v[204:207], v[196:199], v[38:41]
	v_mfma_f32_16x16x32_bf16 v[38:41], v[208:211], v[192:195], v[110:113]
	v_mfma_f32_16x16x32_bf16 v[42:45], v[204:207], v[126:129], v[42:45]
	v_mfma_f32_16x16x32_bf16 v[22:25], v[212:215], v[126:129], v[22:25]
	v_mfma_f32_16x16x32_bf16 v[110:113], v[212:215], v[196:199], v[38:41]
	s_setprio 0
	s_mov_b32 m0, s88
	v_lshl_add_u64 v[192:193], v[226:227], 0, s[50:51]
	s_barrier
	s_nop 0
	ds_read_b128 v[38:41], v219 offset:49152
	ds_read_b128 v[46:49], v219 offset:50176
	ds_read_b128 v[66:69], v219 offset:51200
	ds_read_b128 v[86:89], v219 offset:52224
	ds_read_b128 v[106:109], v219 offset:53248
	ds_read_b128 v[126:129], v219 offset:54272
	ds_read_b128 v[146:149], v219 offset:55296
	ds_read_b128 v[166:169], v219 offset:56320
	global_load_lds_dwordx4 v[192:193], off
	v_lshl_add_u64 v[192:193], v[228:229], 0, s[50:51]
	s_mov_b32 m0, s89
	s_nop 0
	global_load_lds_dwordx4 v[192:193], off
	s_barrier
; #define PG8_STAGE(bufoff, gbase, voff) do { _Pragma("unroll") for (int _i = 0; _i < 2; ++_i) \
;         __builtin_amdgcn_global_load_lds((const unsigned*)((const char*)(gbase) + (voff)[_i]), (LAS unsigned*)(lds + (bufoff) + ldsw + _i * 8192), 16, 0, 0); } while (0)
; #define PG8_MMA(ai, bj, At, Bt) do { __builtin_amdgcn_s_setprio(1); _Pragma("unroll") for (int m = 0; m < 4; ++m) _Pragma("unroll") for (int n = 0; n < 2; ++n) _Pragma("unroll") for (int k = 0; k < 2; ++k) \
;         acc[ai][bj][m][n] = __builtin_amdgcn_mfma_f32_16x16x32_bf16(Bt[n][k], At[m][k], acc[ai][bj][m][n], 0, 0, 0); __builtin_amdgcn_s_setprio(0); } while (0)
; #define PG8_WAIT_V(n) asm volatile("s_waitcnt vmcnt(" #n ")" ::: "memory")
; #define PG8_WAIT_L(n) asm volatile("s_waitcnt lgkmcnt(" #n ")" ::: "memory")
; #define PG8_BAR __builtin_amdgcn_s_barrier()
; #define PG8_SCHED __builtin_amdgcn_sched_barrier(0)
; template <class Epi, class GT>
; __device__ __forceinline__ void gemm_phase(LAS unsigned char* lds, const GT g, const StaticOrder& S, const Epi& E) {
;     ...
;             PG8_BAR; PG8_WAIT_L(0); PG8_MMA(1, 0, At, B0); PG8_BAR; PG8_SCHED;
;             PG8_STAGE(PG8_SB(1, 1), b3 + hstepB, voffB);
;             PG8_WAIT_V(6); PG8_BAR; PG8_MMA(1, 1, At, B1); PG8_BAR;
	s_waitcnt lgkmcnt(0)
	s_setprio 1
	s_waitcnt lgkmcnt(0)
	v_mfma_f32_16x16x32_bf16 v[2:5], v[18:21], v[146:149], v[2:5]
	v_mfma_f32_16x16x32_bf16 v[102:105], v[18:21], v[38:41], v[102:105]
	v_mfma_f32_16x16x32_bf16 v[98:101], v[90:93], v[38:41], v[98:101]
	v_mfma_f32_16x16x32_bf16 v[82:85], v[18:21], v[66:69], v[82:85]
	v_mfma_f32_16x16x32_bf16 v[78:81], v[90:93], v[66:69], v[78:81]
	v_mfma_f32_16x16x32_bf16 v[62:65], v[18:21], v[106:109], v[62:65]
	v_mfma_f32_16x16x32_bf16 v[58:61], v[90:93], v[106:109], v[58:61]
	v_mfma_f32_16x16x32_bf16 v[18:21], v[74:77], v[166:169], v[2:5]
	v_mfma_f32_16x16x32_bf16 v[2:5], v[90:93], v[146:149], v[14:17]
	v_mfma_f32_16x16x32_bf16 v[102:105], v[74:77], v[46:49], v[102:105]
	v_mfma_f32_16x16x32_bf16 v[98:101], v[94:97], v[46:49], v[98:101]
	v_mfma_f32_16x16x32_bf16 v[82:85], v[74:77], v[86:89], v[82:85]
	v_mfma_f32_16x16x32_bf16 v[78:81], v[94:97], v[86:89], v[78:81]
	v_mfma_f32_16x16x32_bf16 v[62:65], v[74:77], v[126:129], v[62:65]
	v_mfma_f32_16x16x32_bf16 v[58:61], v[94:97], v[126:129], v[58:61]
	v_mfma_f32_16x16x32_bf16 v[14:17], v[94:97], v[166:169], v[2:5]
	s_setprio 0
	s_barrier
	s_mov_b32 m0, s13
	v_lshl_add_u64 v[2:3], s[66:67], 0, v[182:183]
	global_load_lds_dwordx4 v[2:3], off
	v_lshl_add_u64 v[2:3], s[66:67], 0, v[178:179]
	s_mov_b32 m0, s12
	s_nop 0
	global_load_lds_dwordx4 v[2:3], off
	s_waitcnt vmcnt(6)
	s_barrier
	s_setprio 1
	v_mfma_f32_16x16x32_bf16 v[2:5], v[200:203], v[38:41], v[26:29]
	v_mfma_f32_16x16x32_bf16 v[94:97], v[204:207], v[46:49], v[2:5]
	v_mfma_f32_16x16x32_bf16 v[2:5], v[208:211], v[38:41], v[30:33]
	v_mfma_f32_16x16x32_bf16 v[90:93], v[212:215], v[46:49], v[2:5]
	v_mfma_f32_16x16x32_bf16 v[2:5], v[200:203], v[66:69], v[34:37]
	v_mfma_f32_16x16x32_bf16 v[74:77], v[204:207], v[86:89], v[2:5]
	v_mfma_f32_16x16x32_bf16 v[2:5], v[208:211], v[66:69], v[70:73]
	v_mfma_f32_16x16x32_bf16 v[70:73], v[212:215], v[86:89], v[2:5]
	v_mfma_f32_16x16x32_bf16 v[2:5], v[200:203], v[106:109], v[54:57]
	v_mfma_f32_16x16x32_bf16 v[54:57], v[204:207], v[126:129], v[2:5]
	v_mfma_f32_16x16x32_bf16 v[2:5], v[208:211], v[106:109], v[50:53]
	v_mfma_f32_16x16x32_bf16 v[50:53], v[212:215], v[126:129], v[2:5]
	v_mfma_f32_16x16x32_bf16 v[2:5], v[200:203], v[146:149], v[10:13]
	v_mfma_f32_16x16x32_bf16 v[10:13], v[204:207], v[166:169], v[2:5]
	v_mfma_f32_16x16x32_bf16 v[2:5], v[208:211], v[146:149], v[6:9]
	v_mfma_f32_16x16x32_bf16 v[6:9], v[212:215], v[166:169], v[2:5]
	s_setprio 0
	s_movk_i32 s12, 0x100
	s_andn2_b64 vcc, exec, s[64:65]
	s_mov_b64 s[66:67], -1
	s_mov_b64 s[64:65], 0
	s_barrier
	s_cbranch_vccz .LBB0_565
	s_ashr_i32 s60, s3, 4
	s_lshl_b32 s3, s3, 7
	s_and_b32 s3, s3, 0x780
	v_or_b32_e32 v46, s3, v217
	v_lshl_or_b32 v2, s60, 12, v46
	v_ashrrev_i32_e32 v3, 31, v2
	v_lshl_add_u64 v[2:3], v[2:3], 2, s[0:1]
	s_mov_b64 s[8:9], 0x2000
	s_movk_i32 s3, 0x2000
	global_load_dwordx4 v[26:29], v[2:3], off offset:16
	global_load_dwordx4 v[34:37], v[2:3], off
	v_lshl_add_u64 v[30:31], v[2:3], 0, s[8:9]
	v_add_co_u32_e32 v2, vcc, s3, v2
	v_lshl_or_b32 v4, s60, 11, v46
	s_nop 0
	v_addc_co_u32_e32 v3, vcc, 0, v3, vcc
	global_load_dwordx4 v[38:41], v[2:3], off
	global_load_dwordx4 v[30:33], v[30:31], off offset:16
	v_lshl_add_u32 v2, s40, 8, v1
	v_ashrrev_i32_e32 v5, 31, v4
	v_lshlrev_b32_e32 v186, 1, v46
	v_ashrrev_i32_e32 v3, 31, v2
	v_lshl_add_u64 v[210:211], v[4:5], 2, s[48:49]
	v_lshl_add_u64 v[4:5], s[42:43], 0, v[186:187]
	v_lshlrev_b64 v[200:201], 12, v[2:3]
	v_lshl_add_u64 v[46:47], v[4:5], 0, v[200:201]
	global_load_dwordx4 v[166:169], v[46:47], off
	v_or_b32_e32 v46, 16, v2
	v_ashrrev_i32_e32 v47, 31, v46
	v_lshlrev_b64 v[198:199], 12, v[46:47]
	v_lshl_add_u64 v[46:47], v[4:5], 0, v[198:199]
	global_load_dwordx4 v[146:149], v[46:47], off
	v_or_b32_e32 v46, 32, v2
	v_ashrrev_i32_e32 v47, 31, v46
	v_lshlrev_b64 v[196:197], 12, v[46:47]
	v_lshl_add_u64 v[46:47], v[4:5], 0, v[196:197]
	global_load_dwordx4 v[126:129], v[46:47], off
	v_or_b32_e32 v46, 48, v2
	v_ashrrev_i32_e32 v47, 31, v46
	v_lshlrev_b64 v[194:195], 12, v[46:47]
	s_mov_b64 s[8:9], 0x80000
	v_lshl_add_u64 v[46:47], v[4:5], 0, v[194:195]
	v_lshl_add_u64 v[192:193], v[200:201], 0, s[8:9]
	global_load_dwordx4 v[106:109], v[46:47], off
	v_lshl_add_u64 v[46:47], v[4:5], 0, v[192:193]
	global_load_dwordx4 v[86:89], v[46:47], off
	v_add_u32_e32 v46, 0x90, v2
	v_ashrrev_i32_e32 v47, 31, v46
	v_lshlrev_b64 v[46:47], 12, v[46:47]
	v_lshl_add_u64 v[46:47], v[4:5], 0, v[46:47]
	global_load_dwordx4 v[66:69], v[46:47], off
	v_add_u32_e32 v46, 0xa0, v2
	v_add_u32_e32 v2, 0xb0, v2
	v_ashrrev_i32_e32 v47, 31, v46
	v_ashrrev_i32_e32 v3, 31, v2
	v_lshlrev_b64 v[46:47], 12, v[46:47]
	v_lshlrev_b64 v[2:3], 12, v[2:3]
	v_lshl_add_u64 v[46:47], v[4:5], 0, v[46:47]
	v_lshl_add_u64 v[2:3], v[4:5], 0, v[2:3]
	global_load_dwordx4 v[46:49], v[46:47], off
	s_ashr_i32 s61, s60, 31
	global_load_dwordx4 v[2:5], v[2:3], off
	s_lshl_b64 s[60:61], s[60:61], 11
	s_mov_b32 s3, s52
	s_mov_b64 s[62:63], s[56:57]
	s_waitcnt vmcnt(0)
; __device__ __forceinline__ float sigmoidf_(float x) { return 1.0f / (1.0f + __expf(-x)); }
	v_add_f32_e32 v174, v174, v34
	v_mul_f32_e32 v174, 0xbfb8aa3b, v174
	v_exp_f32_e32 v214, v174
	v_add_f32_e32 v162, v162, v34
	v_mul_f32_e32 v162, 0xbfb8aa3b, v162
	v_add_f32_e32 v142, v142, v34
	v_add_f32_e32 v42, v42, v38
	v_mul_f32_e32 v42, 0xbfb8aa3b, v42
	v_exp_f32_e32 v206, v42
	v_add_f32_e32 v42, v175, v35
	v_add_f32_e32 v22, v22, v30
	v_mul_f32_e32 v42, 0xbfb8aa3b, v42
	v_mul_f32_e32 v22, 0xbfb8aa3b, v22
	v_exp_f32_e32 v215, v42
	v_add_f32_e32 v42, v43, v39
	v_exp_f32_e32 v202, v22
	v_add_f32_e32 v22, v171, v27
	v_mul_f32_e32 v42, 0xbfb8aa3b, v42
	v_mul_f32_e32 v22, 0xbfb8aa3b, v22
	v_exp_f32_e32 v207, v42
	v_add_f32_e32 v42, v176, v36
	v_exp_f32_e32 v209, v22
	v_add_f32_e32 v22, v23, v31
	v_mul_f32_e32 v42, 0xbfb8aa3b, v42
	v_mul_f32_e32 v22, 0xbfb8aa3b, v22
	v_exp_f32_e32 v212, v42
	v_add_f32_e32 v42, v44, v40
	v_exp_f32_e32 v203, v22
	v_add_f32_e32 v22, v172, v28
	v_mul_f32_e32 v42, 0xbfb8aa3b, v42
	v_mul_f32_e32 v22, 0xbfb8aa3b, v22
	v_exp_f32_e32 v204, v42
	v_add_f32_e32 v42, v177, v37
	v_exp_f32_e32 v174, v22
	v_add_f32_e32 v22, v24, v32
	v_mul_f32_e32 v42, 0xbfb8aa3b, v42
	v_mul_f32_e32 v22, 0xbfb8aa3b, v22
	v_exp_f32_e32 v213, v42
	v_add_f32_e32 v42, v45, v41
	v_exp_f32_e32 v176, v22
	v_add_f32_e32 v22, v173, v29
	v_mul_f32_e32 v42, 0xbfb8aa3b, v42
	v_mul_f32_e32 v22, 0xbfb8aa3b, v22
	v_exp_f32_e32 v205, v42
	v_add_f32_e32 v42, v170, v26
	v_exp_f32_e32 v175, v22
	v_add_f32_e32 v22, v25, v33
	v_mul_f32_e32 v42, 0xbfb8aa3b, v42
	v_mul_f32_e32 v22, 0xbfb8aa3b, v22
	v_exp_f32_e32 v208, v42
	v_exp_f32_e32 v177, v22
	global_load_dwordx4 v[22:25], v[210:211], off offset:16
	global_load_dwordx4 v[42:45], v[210:211], off
	v_pk_add_f32 v[170:171], v[214:215], 1.0 op_sel_hi:[1,0]
	v_pk_add_f32 v[174:175], v[174:175], 1.0 op_sel_hi:[1,0]
	v_add_f32_e32 v154, v154, v38
	v_mul_f32_e32 v154, 0xbfb8aa3b, v154
	v_add_f32_e32 v150, v150, v30
	v_rcp_f32_e32 v171, v171
	v_mul_f32_e32 v150, 0xbfb8aa3b, v150
	v_add_f32_e32 v134, v134, v38
	v_mul_f32_e32 v134, 0xbfb8aa3b, v134
	v_rcp_f32_e32 v170, v170
	v_add_f32_e32 v130, v130, v30
	v_mul_f32_e32 v130, 0xbfb8aa3b, v130
	v_mul_f32_e32 v142, 0xbfb8aa3b, v142
	v_add_f32_e32 v114, v114, v38
	v_mul_f32_e32 v114, 0xbfb8aa3b, v114
	v_add_f32_e32 v110, v110, v30
	v_mul_f32_e32 v110, 0xbfb8aa3b, v110
	v_add_f32_e32 v122, v122, v34
	v_mul_f32_e32 v122, 0xbfb8aa3b, v122
	v_add_f32_e32 v94, v94, v38
	v_mul_f32_e32 v94, 0xbfb8aa3b, v94
	v_add_f32_e32 v90, v90, v30
	v_mul_f32_e32 v90, 0xbfb8aa3b, v90
	v_add_f32_e32 v102, v102, v34
	v_mul_f32_e32 v102, 0xbfb8aa3b, v102
	v_add_f32_e32 v74, v74, v38
	v_mul_f32_e32 v74, 0xbfb8aa3b, v74
	v_add_f32_e32 v70, v70, v30
	v_mul_f32_e32 v70, 0xbfb8aa3b, v70
	v_add_f32_e32 v82, v82, v34
	v_mul_f32_e32 v82, 0xbfb8aa3b, v82
	v_add_f32_e32 v54, v54, v38
	v_mul_f32_e32 v54, 0xbfb8aa3b, v54
	v_add_f32_e32 v50, v50, v30
	v_mul_f32_e32 v50, 0xbfb8aa3b, v50
	v_add_f32_e32 v62, v62, v34
	v_mul_f32_e32 v62, 0xbfb8aa3b, v62
	v_add_f32_e32 v10, v10, v38
	v_mul_f32_e32 v10, 0xbfb8aa3b, v10
	v_add_f32_e32 v18, v18, v34
	v_exp_f32_e32 v34, v10
	v_add_f32_e32 v10, v19, v35
	v_mul_f32_e32 v10, 0xbfb8aa3b, v10
	v_add_f32_e32 v6, v6, v30
	v_mul_f32_e32 v6, 0xbfb8aa3b, v6
	v_mul_f32_e32 v18, 0xbfb8aa3b, v18
	s_waitcnt vmcnt(0)
	v_pk_mul_f32 v[170:171], v[42:43], v[170:171]
	s_nop 0
	v_add_f32_e32 v172, v170, v170
	v_mul_f32_e32 v172, 0x3fb8aa3b, v172
	v_exp_f32_e32 v172, v172
	v_cvt_pk_bf16_f32 v170, v170, v171
	v_sub_f32_e32 v172, 1.0, v172
	v_sqrt_f32_e32 v210, v172
	v_add_f32_e32 v172, v171, v171
	v_mul_f32_e32 v172, 0x3fb8aa3b, v172
	v_exp_f32_e32 v172, v172
	s_nop 0
	v_sub_f32_e32 v172, 1.0, v172
	v_sqrt_f32_e32 v211, v172
	v_pk_add_f32 v[172:173], v[212:213], 1.0 op_sel_hi:[1,0]
	s_nop 0
	v_rcp_f32_e32 v173, v173
	v_rcp_f32_e32 v172, v172
	s_nop 0
	v_pk_mul_f32 v[172:173], v[44:45], v[172:173]
	s_nop 0
	v_add_f32_e32 v171, v172, v172
	v_mul_f32_e32 v171, 0x3fb8aa3b, v171
	v_exp_f32_e32 v171, v171
	s_nop 0
	v_sub_f32_e32 v171, 1.0, v171
	v_sqrt_f32_e32 v212, v171
	v_add_f32_e32 v171, v173, v173
	v_mul_f32_e32 v171, 0x3fb8aa3b, v171
	v_exp_f32_e32 v171, v171
	s_nop 0
	v_sub_f32_e32 v171, 1.0, v171
	v_sqrt_f32_e32 v213, v171
	v_cvt_pk_bf16_f32 v171, v172, v173
	v_pk_add_f32 v[172:173], v[208:209], 1.0 op_sel_hi:[1,0]
	s_nop 0
	v_rcp_f32_e32 v173, v173
	v_rcp_f32_e32 v172, v172
	s_nop 0
	v_pk_mul_f32 v[172:173], v[22:23], v[172:173]
	s_nop 0
	v_add_f32_e32 v208, v172, v172
	v_mul_f32_e32 v208, 0x3fb8aa3b, v208
	v_exp_f32_e32 v208, v208
	v_cvt_pk_bf16_f32 v172, v172, v173
	v_sub_f32_e32 v208, 1.0, v208
	v_sqrt_f32_e32 v208, v208
	v_add_f32_e32 v209, v173, v173
	v_mul_f32_e32 v209, 0x3fb8aa3b, v209
	v_exp_f32_e32 v209, v209
	s_nop 0
	v_sub_f32_e32 v209, 1.0, v209
	v_sqrt_f32_e32 v209, v209
	v_rcp_f32_e32 v175, v175
	v_rcp_f32_e32 v174, v174
	s_nop 0
	v_pk_mul_f32 v[174:175], v[24:25], v[174:175]
	s_nop 0
	v_add_f32_e32 v173, v174, v174
	v_mul_f32_e32 v173, 0x3fb8aa3b, v173
	v_exp_f32_e32 v173, v173
	s_nop 0
	v_sub_f32_e32 v173, 1.0, v173
	v_sqrt_f32_e32 v214, v173
	v_add_f32_e32 v173, v175, v175
	v_mul_f32_e32 v173, 0x3fb8aa3b, v173
	v_exp_f32_e32 v173, v173
	s_nop 0
	v_sub_f32_e32 v173, 1.0, v173
	v_sqrt_f32_e32 v215, v173
	v_cvt_pk_bf16_f32 v173, v174, v175
	v_lshl_add_u64 v[174:175], v[200:201], 0, s[60:61]
	v_lshlrev_b64 v[174:175], 1, v[174:175]
	v_lshl_add_u64 v[200:201], s[44:45], 0, v[174:175]
	v_lshl_add_u64 v[200:201], v[200:201], 0, v[186:187]
	global_store_dwordx4 v[200:201], v[170:173], off
	s_nop 1
	v_pk_add_f32 v[172:173], v[206:207], 1.0 op_sel_hi:[1,0]
	v_lshlrev_b32_e32 v170, 16, v166
	v_and_b32_e32 v171, 0xffff0000, v166
	v_rcp_f32_e32 v173, v173
	v_rcp_f32_e32 v172, v172
; __device__ __forceinline__ float sigmoidf_(float x) { return 1.0f / (1.0f + __expf(-x)); }
	s_nop 0
	v_pk_mul_f32 v[170:171], v[172:173], v[170:171]
	v_pk_add_f32 v[172:173], v[204:205], 1.0 op_sel_hi:[1,0]
	v_pk_mul_f32 v[170:171], v[210:211], v[170:171]
	s_nop 0
	v_cvt_pk_bf16_f32 v166, v170, v171
	v_lshlrev_b32_e32 v170, 16, v167
	v_and_b32_e32 v171, 0xffff0000, v167
	v_rcp_f32_e32 v173, v173
	v_rcp_f32_e32 v172, v172
	s_nop 0
	v_pk_mul_f32 v[170:171], v[172:173], v[170:171]
	v_pk_add_f32 v[172:173], v[202:203], 1.0 op_sel_hi:[1,0]
	v_pk_mul_f32 v[170:171], v[212:213], v[170:171]
	s_nop 0
	v_cvt_pk_bf16_f32 v167, v170, v171
	v_lshlrev_b32_e32 v170, 16, v168
	v_and_b32_e32 v171, 0xffff0000, v168
	v_rcp_f32_e32 v173, v173
	v_rcp_f32_e32 v172, v172
	s_nop 0
	v_pk_mul_f32 v[170:171], v[172:173], v[170:171]
	v_pk_add_f32 v[172:173], v[176:177], 1.0 op_sel_hi:[1,0]
	v_pk_mul_f32 v[170:171], v[208:209], v[170:171]
	s_nop 0
	v_cvt_pk_bf16_f32 v168, v170, v171
	v_lshlrev_b32_e32 v170, 16, v169
	v_and_b32_e32 v171, 0xffff0000, v169
	v_rcp_f32_e32 v173, v173
	v_rcp_f32_e32 v172, v172
	s_nop 0
	v_pk_mul_f32 v[170:171], v[172:173], v[170:171]
	s_nop 0
	v_pk_mul_f32 v[170:171], v[170:171], v[214:215]
	s_nop 0
	v_cvt_pk_bf16_f32 v169, v170, v171
	v_lshl_add_u64 v[170:171], s[46:47], 0, v[174:175]
	v_lshl_add_u64 v[170:171], v[170:171], 0, v[186:187]
	global_store_dwordx4 v[170:171], v[166:169], off
	v_exp_f32_e32 v170, v162
	s_nop 0
	v_exp_f32_e32 v166, v154
	v_add_f32_e32 v154, v163, v35
	v_mul_f32_e32 v154, 0xbfb8aa3b, v154
	v_exp_f32_e32 v171, v154
	v_add_f32_e32 v154, v155, v39
	v_mul_f32_e32 v154, 0xbfb8aa3b, v154
	v_exp_f32_e32 v167, v154
	v_add_f32_e32 v154, v164, v36
	v_mul_f32_e32 v154, 0xbfb8aa3b, v154
	v_exp_f32_e32 v164, v154
	v_add_f32_e32 v154, v156, v40
	v_exp_f32_e32 v156, v150
	v_add_f32_e32 v150, v159, v27
	v_mul_f32_e32 v154, 0xbfb8aa3b, v154
	v_mul_f32_e32 v150, 0xbfb8aa3b, v150
	v_exp_f32_e32 v162, v154
	v_add_f32_e32 v154, v165, v37
	v_exp_f32_e32 v169, v150
	v_add_f32_e32 v150, v151, v31
	v_mul_f32_e32 v154, 0xbfb8aa3b, v154
	v_mul_f32_e32 v150, 0xbfb8aa3b, v150
	v_exp_f32_e32 v165, v154
	v_add_f32_e32 v154, v157, v41
	v_exp_f32_e32 v157, v150
	v_add_f32_e32 v150, v160, v28
	v_mul_f32_e32 v154, 0xbfb8aa3b, v154
	v_mul_f32_e32 v150, 0xbfb8aa3b, v150
	v_exp_f32_e32 v163, v154
	v_add_f32_e32 v154, v158, v26
	v_exp_f32_e32 v160, v150
	v_add_f32_e32 v150, v152, v32
	v_mul_f32_e32 v154, 0xbfb8aa3b, v154
	v_mul_f32_e32 v150, 0xbfb8aa3b, v150
	v_exp_f32_e32 v168, v154
	v_exp_f32_e32 v154, v150
	v_add_f32_e32 v150, v161, v29
	v_mul_f32_e32 v150, 0xbfb8aa3b, v150
	v_exp_f32_e32 v161, v150
	v_add_f32_e32 v150, v153, v33
	v_mul_f32_e32 v150, 0xbfb8aa3b, v150
	v_exp_f32_e32 v155, v150
	v_pk_add_f32 v[150:151], v[170:171], 1.0 op_sel_hi:[1,0]
	v_pk_add_f32 v[160:161], v[160:161], 1.0 op_sel_hi:[1,0]
	v_rcp_f32_e32 v151, v151
	v_rcp_f32_e32 v150, v150
	s_nop 0
	v_pk_mul_f32 v[150:151], v[42:43], v[150:151]
	s_nop 0
	v_add_f32_e32 v152, v150, v150
	v_mul_f32_e32 v152, 0x3fb8aa3b, v152
	v_exp_f32_e32 v152, v152
	v_cvt_pk_bf16_f32 v150, v150, v151
	v_sub_f32_e32 v152, 1.0, v152
	v_sqrt_f32_e32 v158, v152
	v_add_f32_e32 v152, v151, v151
	v_mul_f32_e32 v152, 0x3fb8aa3b, v152
	v_exp_f32_e32 v152, v152
	s_nop 0
	v_sub_f32_e32 v152, 1.0, v152
	v_sqrt_f32_e32 v159, v152
	v_pk_add_f32 v[152:153], v[164:165], 1.0 op_sel_hi:[1,0]
	s_nop 0
	v_rcp_f32_e32 v153, v153
	v_rcp_f32_e32 v152, v152
	s_nop 0
	v_pk_mul_f32 v[152:153], v[44:45], v[152:153]
	s_nop 0
	v_add_f32_e32 v151, v152, v152
	v_mul_f32_e32 v151, 0x3fb8aa3b, v151
	v_exp_f32_e32 v151, v151
	s_nop 0
	v_sub_f32_e32 v151, 1.0, v151
	v_sqrt_f32_e32 v164, v151
	v_add_f32_e32 v151, v153, v153
	v_mul_f32_e32 v151, 0x3fb8aa3b, v151
	v_exp_f32_e32 v151, v151
	s_nop 0
	v_sub_f32_e32 v151, 1.0, v151
	v_sqrt_f32_e32 v165, v151
	v_cvt_pk_bf16_f32 v151, v152, v153
	v_pk_add_f32 v[152:153], v[168:169], 1.0 op_sel_hi:[1,0]
	s_nop 0
	v_rcp_f32_e32 v153, v153
	v_rcp_f32_e32 v152, v152
	s_nop 0
	v_pk_mul_f32 v[152:153], v[22:23], v[152:153]
	s_nop 0
	v_add_f32_e32 v168, v152, v152
	v_mul_f32_e32 v168, 0x3fb8aa3b, v168
	v_exp_f32_e32 v168, v168
	v_cvt_pk_bf16_f32 v152, v152, v153
	v_sub_f32_e32 v168, 1.0, v168
	v_sqrt_f32_e32 v168, v168
	v_add_f32_e32 v169, v153, v153
	v_mul_f32_e32 v169, 0x3fb8aa3b, v169
	v_exp_f32_e32 v169, v169
	s_nop 0
	v_sub_f32_e32 v169, 1.0, v169
	v_sqrt_f32_e32 v169, v169
	v_rcp_f32_e32 v161, v161
	v_rcp_f32_e32 v160, v160
	s_nop 0
	v_pk_mul_f32 v[170:171], v[24:25], v[160:161]
	s_nop 0
	v_add_f32_e32 v153, v170, v170
	v_mul_f32_e32 v153, 0x3fb8aa3b, v153
	v_exp_f32_e32 v153, v153
	s_nop 0
	v_sub_f32_e32 v153, 1.0, v153
	v_sqrt_f32_e32 v160, v153
	v_add_f32_e32 v153, v171, v171
	v_mul_f32_e32 v153, 0x3fb8aa3b, v153
	v_exp_f32_e32 v153, v153
	s_nop 0
	v_sub_f32_e32 v153, 1.0, v153
	v_sqrt_f32_e32 v161, v153
	v_cvt_pk_bf16_f32 v153, v170, v171
	v_lshl_add_u64 v[170:171], v[198:199], 0, s[60:61]
	v_lshlrev_b64 v[170:171], 1, v[170:171]
	v_lshl_add_u64 v[172:173], s[44:45], 0, v[170:171]
	v_lshl_add_u64 v[172:173], v[172:173], 0, v[186:187]
	global_store_dwordx4 v[172:173], v[150:153], off
	s_nop 1
	v_pk_add_f32 v[152:153], v[166:167], 1.0 op_sel_hi:[1,0]
	v_lshlrev_b32_e32 v150, 16, v146
	v_and_b32_e32 v151, 0xffff0000, v146
	v_rcp_f32_e32 v153, v153
	v_rcp_f32_e32 v152, v152
	s_nop 0
	v_pk_mul_f32 v[150:151], v[152:153], v[150:151]
	v_pk_add_f32 v[152:153], v[162:163], 1.0 op_sel_hi:[1,0]
	v_pk_mul_f32 v[150:151], v[158:159], v[150:151]
	s_nop 0
	v_cvt_pk_bf16_f32 v146, v150, v151
	v_lshlrev_b32_e32 v150, 16, v147
	v_and_b32_e32 v151, 0xffff0000, v147
	v_rcp_f32_e32 v153, v153
	v_rcp_f32_e32 v152, v152
	s_nop 0
	v_pk_mul_f32 v[150:151], v[152:153], v[150:151]
	v_pk_add_f32 v[152:153], v[156:157], 1.0 op_sel_hi:[1,0]
	v_pk_mul_f32 v[150:151], v[164:165], v[150:151]
	s_nop 0
	v_cvt_pk_bf16_f32 v147, v150, v151
	v_lshlrev_b32_e32 v150, 16, v148
	v_and_b32_e32 v151, 0xffff0000, v148
	v_rcp_f32_e32 v153, v153
	v_rcp_f32_e32 v152, v152
	s_nop 0
	v_pk_mul_f32 v[150:151], v[152:153], v[150:151]
	v_pk_add_f32 v[152:153], v[154:155], 1.0 op_sel_hi:[1,0]
	v_pk_mul_f32 v[150:151], v[168:169], v[150:151]
	s_nop 0
	v_cvt_pk_bf16_f32 v148, v150, v151
	v_lshlrev_b32_e32 v150, 16, v149
	v_and_b32_e32 v151, 0xffff0000, v149
	v_rcp_f32_e32 v153, v153
	v_rcp_f32_e32 v152, v152
	s_nop 0
	v_pk_mul_f32 v[150:151], v[152:153], v[150:151]
	s_nop 0
	v_pk_mul_f32 v[150:151], v[160:161], v[150:151]
	s_nop 0
	v_cvt_pk_bf16_f32 v149, v150, v151
	v_lshl_add_u64 v[150:151], s[46:47], 0, v[170:171]
	v_lshl_add_u64 v[150:151], v[150:151], 0, v[186:187]
	global_store_dwordx4 v[150:151], v[146:149], off
	v_exp_f32_e32 v150, v142
	s_nop 0
	v_exp_f32_e32 v146, v134
	v_add_f32_e32 v134, v143, v35
	v_mul_f32_e32 v134, 0xbfb8aa3b, v134
	v_exp_f32_e32 v151, v134
	v_add_f32_e32 v134, v135, v39
	v_mul_f32_e32 v134, 0xbfb8aa3b, v134
	v_exp_f32_e32 v147, v134
	v_add_f32_e32 v134, v144, v36
	v_mul_f32_e32 v134, 0xbfb8aa3b, v134
	v_exp_f32_e32 v144, v134
	v_add_f32_e32 v134, v136, v40
	v_exp_f32_e32 v136, v130
	v_add_f32_e32 v130, v139, v27
	v_mul_f32_e32 v134, 0xbfb8aa3b, v134
	v_mul_f32_e32 v130, 0xbfb8aa3b, v130
	v_exp_f32_e32 v142, v134
	v_add_f32_e32 v134, v145, v37
	v_exp_f32_e32 v149, v130
	v_add_f32_e32 v130, v131, v31
	v_mul_f32_e32 v134, 0xbfb8aa3b, v134
	v_mul_f32_e32 v130, 0xbfb8aa3b, v130
	v_exp_f32_e32 v145, v134
	v_add_f32_e32 v134, v137, v41
	v_exp_f32_e32 v137, v130
	v_add_f32_e32 v130, v140, v28
	v_mul_f32_e32 v134, 0xbfb8aa3b, v134
	v_mul_f32_e32 v130, 0xbfb8aa3b, v130
	v_exp_f32_e32 v143, v134
	v_add_f32_e32 v134, v138, v26
	v_exp_f32_e32 v140, v130
	v_add_f32_e32 v130, v132, v32
	v_mul_f32_e32 v134, 0xbfb8aa3b, v134
	v_mul_f32_e32 v130, 0xbfb8aa3b, v130
	v_exp_f32_e32 v148, v134
	v_exp_f32_e32 v134, v130
	v_add_f32_e32 v130, v141, v29
	v_mul_f32_e32 v130, 0xbfb8aa3b, v130
	v_exp_f32_e32 v141, v130
	v_add_f32_e32 v130, v133, v33
	v_mul_f32_e32 v130, 0xbfb8aa3b, v130
	v_exp_f32_e32 v135, v130
	v_pk_add_f32 v[130:131], v[150:151], 1.0 op_sel_hi:[1,0]
	v_pk_add_f32 v[140:141], v[140:141], 1.0 op_sel_hi:[1,0]
	v_rcp_f32_e32 v131, v131
	v_rcp_f32_e32 v130, v130
	s_nop 0
	v_pk_mul_f32 v[130:131], v[42:43], v[130:131]
	s_nop 0
	v_add_f32_e32 v132, v130, v130
	v_mul_f32_e32 v132, 0x3fb8aa3b, v132
	v_exp_f32_e32 v132, v132
	v_cvt_pk_bf16_f32 v130, v130, v131
	v_sub_f32_e32 v132, 1.0, v132
	v_sqrt_f32_e32 v138, v132
	v_add_f32_e32 v132, v131, v131
	v_mul_f32_e32 v132, 0x3fb8aa3b, v132
	v_exp_f32_e32 v132, v132
	s_nop 0
	v_sub_f32_e32 v132, 1.0, v132
	v_sqrt_f32_e32 v139, v132
	v_pk_add_f32 v[132:133], v[144:145], 1.0 op_sel_hi:[1,0]
	s_nop 0
	v_rcp_f32_e32 v133, v133
	v_rcp_f32_e32 v132, v132
	s_nop 0
	v_pk_mul_f32 v[132:133], v[44:45], v[132:133]
	s_nop 0
	v_add_f32_e32 v131, v132, v132
	v_mul_f32_e32 v131, 0x3fb8aa3b, v131
	v_exp_f32_e32 v131, v131
	s_nop 0
	v_sub_f32_e32 v131, 1.0, v131
	v_sqrt_f32_e32 v144, v131
	v_add_f32_e32 v131, v133, v133
	v_mul_f32_e32 v131, 0x3fb8aa3b, v131
	v_exp_f32_e32 v131, v131
	s_nop 0
	v_sub_f32_e32 v131, 1.0, v131
	v_sqrt_f32_e32 v145, v131
	v_cvt_pk_bf16_f32 v131, v132, v133
	v_pk_add_f32 v[132:133], v[148:149], 1.0 op_sel_hi:[1,0]
	s_nop 0
	v_rcp_f32_e32 v133, v133
	v_rcp_f32_e32 v132, v132
	s_nop 0
	v_pk_mul_f32 v[132:133], v[22:23], v[132:133]
	s_nop 0
	v_add_f32_e32 v148, v132, v132
	v_mul_f32_e32 v148, 0x3fb8aa3b, v148
	v_exp_f32_e32 v148, v148
	v_cvt_pk_bf16_f32 v132, v132, v133
	v_sub_f32_e32 v148, 1.0, v148
	v_sqrt_f32_e32 v148, v148
	v_add_f32_e32 v149, v133, v133
	v_mul_f32_e32 v149, 0x3fb8aa3b, v149
	v_exp_f32_e32 v149, v149
	s_nop 0
	v_sub_f32_e32 v149, 1.0, v149
	v_sqrt_f32_e32 v149, v149
	v_rcp_f32_e32 v141, v141
	v_rcp_f32_e32 v140, v140
	s_nop 0
	v_pk_mul_f32 v[150:151], v[24:25], v[140:141]
	s_nop 0
	v_add_f32_e32 v133, v150, v150
	v_mul_f32_e32 v133, 0x3fb8aa3b, v133
	v_exp_f32_e32 v133, v133
	s_nop 0
	v_sub_f32_e32 v133, 1.0, v133
	v_sqrt_f32_e32 v140, v133
	v_add_f32_e32 v133, v151, v151
	v_mul_f32_e32 v133, 0x3fb8aa3b, v133
	v_exp_f32_e32 v133, v133
	s_nop 0
	v_sub_f32_e32 v133, 1.0, v133
	v_sqrt_f32_e32 v141, v133
	v_cvt_pk_bf16_f32 v133, v150, v151
	v_lshl_add_u64 v[150:151], v[196:197], 0, s[60:61]
	v_lshlrev_b64 v[150:151], 1, v[150:151]
	v_lshl_add_u64 v[152:153], s[44:45], 0, v[150:151]
	v_lshl_add_u64 v[152:153], v[152:153], 0, v[186:187]
	global_store_dwordx4 v[152:153], v[130:133], off
	s_nop 1
	v_pk_add_f32 v[132:133], v[146:147], 1.0 op_sel_hi:[1,0]
	v_lshlrev_b32_e32 v130, 16, v126
	v_and_b32_e32 v131, 0xffff0000, v126
	v_rcp_f32_e32 v133, v133
	v_rcp_f32_e32 v132, v132
	s_nop 0
	v_pk_mul_f32 v[130:131], v[132:133], v[130:131]
	v_pk_add_f32 v[132:133], v[142:143], 1.0 op_sel_hi:[1,0]
	v_pk_mul_f32 v[130:131], v[138:139], v[130:131]
	s_nop 0
	v_cvt_pk_bf16_f32 v126, v130, v131
	v_lshlrev_b32_e32 v130, 16, v127
	v_and_b32_e32 v131, 0xffff0000, v127
	v_rcp_f32_e32 v133, v133
	v_rcp_f32_e32 v132, v132
	s_nop 0
	v_pk_mul_f32 v[130:131], v[132:133], v[130:131]
	v_pk_add_f32 v[132:133], v[136:137], 1.0 op_sel_hi:[1,0]
	v_pk_mul_f32 v[130:131], v[144:145], v[130:131]
	s_nop 0
	v_cvt_pk_bf16_f32 v127, v130, v131
	v_lshlrev_b32_e32 v130, 16, v128
	v_and_b32_e32 v131, 0xffff0000, v128
	v_rcp_f32_e32 v133, v133
	v_rcp_f32_e32 v132, v132
	s_nop 0
	v_pk_mul_f32 v[130:131], v[132:133], v[130:131]
	v_pk_add_f32 v[132:133], v[134:135], 1.0 op_sel_hi:[1,0]
	v_pk_mul_f32 v[130:131], v[148:149], v[130:131]
	s_nop 0
	v_cvt_pk_bf16_f32 v128, v130, v131
	v_lshlrev_b32_e32 v130, 16, v129
	v_and_b32_e32 v131, 0xffff0000, v129
	v_rcp_f32_e32 v133, v133
	v_rcp_f32_e32 v132, v132
	s_nop 0
	v_pk_mul_f32 v[130:131], v[132:133], v[130:131]
	s_nop 0
	v_pk_mul_f32 v[130:131], v[140:141], v[130:131]
	s_nop 0
	v_cvt_pk_bf16_f32 v129, v130, v131
	v_lshl_add_u64 v[130:131], s[46:47], 0, v[150:151]
	v_lshl_add_u64 v[130:131], v[130:131], 0, v[186:187]
	global_store_dwordx4 v[130:131], v[126:129], off
	v_exp_f32_e32 v130, v122
	s_nop 0
	v_exp_f32_e32 v126, v114
	v_add_f32_e32 v114, v123, v35
	v_mul_f32_e32 v114, 0xbfb8aa3b, v114
	v_exp_f32_e32 v131, v114
	v_add_f32_e32 v114, v115, v39
	v_mul_f32_e32 v114, 0xbfb8aa3b, v114
	v_exp_f32_e32 v127, v114
	v_add_f32_e32 v114, v124, v36
	v_mul_f32_e32 v114, 0xbfb8aa3b, v114
	v_exp_f32_e32 v124, v114
	v_add_f32_e32 v114, v116, v40
	v_exp_f32_e32 v116, v110
	v_add_f32_e32 v110, v119, v27
	v_mul_f32_e32 v114, 0xbfb8aa3b, v114
	v_mul_f32_e32 v110, 0xbfb8aa3b, v110
	v_exp_f32_e32 v122, v114
	v_add_f32_e32 v114, v125, v37
	v_exp_f32_e32 v129, v110
	v_add_f32_e32 v110, v111, v31
	v_mul_f32_e32 v114, 0xbfb8aa3b, v114
	v_mul_f32_e32 v110, 0xbfb8aa3b, v110
	v_exp_f32_e32 v125, v114
	v_add_f32_e32 v114, v117, v41
	v_exp_f32_e32 v117, v110
	v_add_f32_e32 v110, v120, v28
	v_mul_f32_e32 v114, 0xbfb8aa3b, v114
	v_mul_f32_e32 v110, 0xbfb8aa3b, v110
	v_exp_f32_e32 v123, v114
	v_add_f32_e32 v114, v118, v26
	v_exp_f32_e32 v120, v110
	v_add_f32_e32 v110, v112, v32
	v_mul_f32_e32 v114, 0xbfb8aa3b, v114
	v_mul_f32_e32 v110, 0xbfb8aa3b, v110
	v_exp_f32_e32 v128, v114
	v_exp_f32_e32 v114, v110
	v_add_f32_e32 v110, v121, v29
	v_mul_f32_e32 v110, 0xbfb8aa3b, v110
	v_exp_f32_e32 v121, v110
	v_add_f32_e32 v110, v113, v33
	v_mul_f32_e32 v110, 0xbfb8aa3b, v110
	v_exp_f32_e32 v115, v110
	v_pk_add_f32 v[110:111], v[130:131], 1.0 op_sel_hi:[1,0]
	v_pk_add_f32 v[120:121], v[120:121], 1.0 op_sel_hi:[1,0]
	v_rcp_f32_e32 v111, v111
	v_rcp_f32_e32 v110, v110
	s_nop 0
	v_pk_mul_f32 v[110:111], v[42:43], v[110:111]
	s_nop 0
	v_add_f32_e32 v112, v110, v110
	v_mul_f32_e32 v112, 0x3fb8aa3b, v112
	v_exp_f32_e32 v112, v112
	v_cvt_pk_bf16_f32 v110, v110, v111
	v_sub_f32_e32 v112, 1.0, v112
	v_sqrt_f32_e32 v118, v112
	v_add_f32_e32 v112, v111, v111
	v_mul_f32_e32 v112, 0x3fb8aa3b, v112
	v_exp_f32_e32 v112, v112
	s_nop 0
	v_sub_f32_e32 v112, 1.0, v112
	v_sqrt_f32_e32 v119, v112
	v_pk_add_f32 v[112:113], v[124:125], 1.0 op_sel_hi:[1,0]
	s_nop 0
	v_rcp_f32_e32 v113, v113
	v_rcp_f32_e32 v112, v112
	s_nop 0
	v_pk_mul_f32 v[112:113], v[44:45], v[112:113]
	s_nop 0
	v_add_f32_e32 v111, v112, v112
	v_mul_f32_e32 v111, 0x3fb8aa3b, v111
	v_exp_f32_e32 v111, v111
	s_nop 0
	v_sub_f32_e32 v111, 1.0, v111
	v_sqrt_f32_e32 v124, v111
	v_add_f32_e32 v111, v113, v113
	v_mul_f32_e32 v111, 0x3fb8aa3b, v111
	v_exp_f32_e32 v111, v111
	s_nop 0
	v_sub_f32_e32 v111, 1.0, v111
	v_sqrt_f32_e32 v125, v111
	v_cvt_pk_bf16_f32 v111, v112, v113
	v_pk_add_f32 v[112:113], v[128:129], 1.0 op_sel_hi:[1,0]
	s_nop 0
	v_rcp_f32_e32 v113, v113
	v_rcp_f32_e32 v112, v112
	s_nop 0
	v_pk_mul_f32 v[112:113], v[22:23], v[112:113]
	s_nop 0
	v_add_f32_e32 v128, v112, v112
	v_mul_f32_e32 v128, 0x3fb8aa3b, v128
	v_exp_f32_e32 v128, v128
	v_cvt_pk_bf16_f32 v112, v112, v113
	v_sub_f32_e32 v128, 1.0, v128
	v_sqrt_f32_e32 v128, v128
	v_add_f32_e32 v129, v113, v113
	v_mul_f32_e32 v129, 0x3fb8aa3b, v129
	v_exp_f32_e32 v129, v129
	s_nop 0
	v_sub_f32_e32 v129, 1.0, v129
	v_sqrt_f32_e32 v129, v129
	v_rcp_f32_e32 v121, v121
	v_rcp_f32_e32 v120, v120
	s_nop 0
	v_pk_mul_f32 v[130:131], v[24:25], v[120:121]
	s_nop 0
	v_add_f32_e32 v113, v130, v130
	v_mul_f32_e32 v113, 0x3fb8aa3b, v113
	v_exp_f32_e32 v113, v113
	s_nop 0
	v_sub_f32_e32 v113, 1.0, v113
	v_sqrt_f32_e32 v120, v113
	v_add_f32_e32 v113, v131, v131
	v_mul_f32_e32 v113, 0x3fb8aa3b, v113
	v_exp_f32_e32 v113, v113
	s_nop 0
	v_sub_f32_e32 v113, 1.0, v113
	v_sqrt_f32_e32 v121, v113
	v_cvt_pk_bf16_f32 v113, v130, v131
	v_lshl_add_u64 v[130:131], v[194:195], 0, s[60:61]
	v_lshlrev_b64 v[130:131], 1, v[130:131]
	v_lshl_add_u64 v[132:133], s[44:45], 0, v[130:131]
	v_lshl_add_u64 v[132:133], v[132:133], 0, v[186:187]
	global_store_dwordx4 v[132:133], v[110:113], off
	s_nop 1
	v_pk_add_f32 v[112:113], v[126:127], 1.0 op_sel_hi:[1,0]
	v_lshlrev_b32_e32 v110, 16, v106
	v_and_b32_e32 v111, 0xffff0000, v106
	v_rcp_f32_e32 v113, v113
	v_rcp_f32_e32 v112, v112
	s_nop 0
	v_pk_mul_f32 v[110:111], v[112:113], v[110:111]
	v_pk_add_f32 v[112:113], v[122:123], 1.0 op_sel_hi:[1,0]
	v_pk_mul_f32 v[110:111], v[118:119], v[110:111]
	s_nop 0
	v_cvt_pk_bf16_f32 v106, v110, v111
	v_lshlrev_b32_e32 v110, 16, v107
	v_and_b32_e32 v111, 0xffff0000, v107
	v_rcp_f32_e32 v113, v113
	v_rcp_f32_e32 v112, v112
	s_nop 0
	v_pk_mul_f32 v[110:111], v[112:113], v[110:111]
	v_pk_add_f32 v[112:113], v[116:117], 1.0 op_sel_hi:[1,0]
	v_pk_mul_f32 v[110:111], v[124:125], v[110:111]
	s_nop 0
	v_cvt_pk_bf16_f32 v107, v110, v111
	v_lshlrev_b32_e32 v110, 16, v108
	v_and_b32_e32 v111, 0xffff0000, v108
	v_rcp_f32_e32 v113, v113
	v_rcp_f32_e32 v112, v112
	s_nop 0
	v_pk_mul_f32 v[110:111], v[112:113], v[110:111]
	v_pk_add_f32 v[112:113], v[114:115], 1.0 op_sel_hi:[1,0]
	v_pk_mul_f32 v[110:111], v[128:129], v[110:111]
	s_nop 0
	v_cvt_pk_bf16_f32 v108, v110, v111
	v_lshlrev_b32_e32 v110, 16, v109
	v_and_b32_e32 v111, 0xffff0000, v109
	v_rcp_f32_e32 v113, v113
	v_rcp_f32_e32 v112, v112
	s_nop 0
	v_pk_mul_f32 v[110:111], v[112:113], v[110:111]
	s_nop 0
	v_pk_mul_f32 v[110:111], v[120:121], v[110:111]
	s_nop 0
	v_cvt_pk_bf16_f32 v109, v110, v111
	v_lshl_add_u64 v[110:111], s[46:47], 0, v[130:131]
	v_lshl_add_u64 v[110:111], v[110:111], 0, v[186:187]
	global_store_dwordx4 v[110:111], v[106:109], off
	v_exp_f32_e32 v110, v102
	s_nop 0
	v_exp_f32_e32 v106, v94
	v_add_f32_e32 v94, v103, v35
	v_mul_f32_e32 v94, 0xbfb8aa3b, v94
	v_exp_f32_e32 v111, v94
	v_add_f32_e32 v94, v95, v39
	v_mul_f32_e32 v94, 0xbfb8aa3b, v94
	v_exp_f32_e32 v107, v94
	v_add_f32_e32 v94, v104, v36
	v_mul_f32_e32 v94, 0xbfb8aa3b, v94
	v_exp_f32_e32 v104, v94
	v_add_f32_e32 v94, v96, v40
	v_exp_f32_e32 v96, v90
	v_add_f32_e32 v90, v99, v27
	v_mul_f32_e32 v94, 0xbfb8aa3b, v94
	v_mul_f32_e32 v90, 0xbfb8aa3b, v90
	v_exp_f32_e32 v102, v94
	v_add_f32_e32 v94, v105, v37
	v_exp_f32_e32 v109, v90
	v_add_f32_e32 v90, v91, v31
	v_mul_f32_e32 v94, 0xbfb8aa3b, v94
	v_mul_f32_e32 v90, 0xbfb8aa3b, v90
	v_exp_f32_e32 v105, v94
	v_add_f32_e32 v94, v97, v41
	v_exp_f32_e32 v97, v90
	v_add_f32_e32 v90, v100, v28
	v_mul_f32_e32 v94, 0xbfb8aa3b, v94
	v_mul_f32_e32 v90, 0xbfb8aa3b, v90
	v_exp_f32_e32 v103, v94
	v_add_f32_e32 v94, v98, v26
	v_exp_f32_e32 v100, v90
	v_add_f32_e32 v90, v92, v32
	v_mul_f32_e32 v94, 0xbfb8aa3b, v94
	v_mul_f32_e32 v90, 0xbfb8aa3b, v90
	v_exp_f32_e32 v108, v94
	v_exp_f32_e32 v94, v90
	v_add_f32_e32 v90, v101, v29
	v_mul_f32_e32 v90, 0xbfb8aa3b, v90
	v_exp_f32_e32 v101, v90
	v_add_f32_e32 v90, v93, v33
	v_mul_f32_e32 v90, 0xbfb8aa3b, v90
	v_exp_f32_e32 v95, v90
	v_pk_add_f32 v[90:91], v[110:111], 1.0 op_sel_hi:[1,0]
	v_pk_add_f32 v[100:101], v[100:101], 1.0 op_sel_hi:[1,0]
	v_rcp_f32_e32 v91, v91
	v_rcp_f32_e32 v90, v90
	s_nop 0
	v_pk_mul_f32 v[90:91], v[42:43], v[90:91]
	s_nop 0
	v_add_f32_e32 v92, v90, v90
	v_mul_f32_e32 v92, 0x3fb8aa3b, v92
	v_exp_f32_e32 v92, v92
	v_cvt_pk_bf16_f32 v90, v90, v91
	v_sub_f32_e32 v92, 1.0, v92
	v_sqrt_f32_e32 v98, v92
	v_add_f32_e32 v92, v91, v91
	v_mul_f32_e32 v92, 0x3fb8aa3b, v92
	v_exp_f32_e32 v92, v92
	s_nop 0
	v_sub_f32_e32 v92, 1.0, v92
	v_sqrt_f32_e32 v99, v92
	v_pk_add_f32 v[92:93], v[104:105], 1.0 op_sel_hi:[1,0]
	s_nop 0
	v_rcp_f32_e32 v93, v93
	v_rcp_f32_e32 v92, v92
	s_nop 0
	v_pk_mul_f32 v[92:93], v[44:45], v[92:93]
	s_nop 0
	v_add_f32_e32 v91, v92, v92
	v_mul_f32_e32 v91, 0x3fb8aa3b, v91
	v_exp_f32_e32 v91, v91
	s_nop 0
	v_sub_f32_e32 v91, 1.0, v91
	v_sqrt_f32_e32 v104, v91
	v_add_f32_e32 v91, v93, v93
	v_mul_f32_e32 v91, 0x3fb8aa3b, v91
	v_exp_f32_e32 v91, v91
	s_nop 0
	v_sub_f32_e32 v91, 1.0, v91
	v_sqrt_f32_e32 v105, v91
	v_cvt_pk_bf16_f32 v91, v92, v93
	v_pk_add_f32 v[92:93], v[108:109], 1.0 op_sel_hi:[1,0]
	s_nop 0
	v_rcp_f32_e32 v93, v93
	v_rcp_f32_e32 v92, v92
	s_nop 0
	v_pk_mul_f32 v[92:93], v[22:23], v[92:93]
	s_nop 0
	v_add_f32_e32 v108, v92, v92
	v_mul_f32_e32 v108, 0x3fb8aa3b, v108
	v_exp_f32_e32 v108, v108
	v_cvt_pk_bf16_f32 v92, v92, v93
	v_sub_f32_e32 v108, 1.0, v108
	v_sqrt_f32_e32 v108, v108
	v_add_f32_e32 v109, v93, v93
	v_mul_f32_e32 v109, 0x3fb8aa3b, v109
	v_exp_f32_e32 v109, v109
	s_nop 0
	v_sub_f32_e32 v109, 1.0, v109
	v_sqrt_f32_e32 v109, v109
	v_rcp_f32_e32 v101, v101
	v_rcp_f32_e32 v100, v100
	s_nop 0
	v_pk_mul_f32 v[110:111], v[24:25], v[100:101]
	s_nop 0
	v_add_f32_e32 v93, v110, v110
	v_mul_f32_e32 v93, 0x3fb8aa3b, v93
	v_exp_f32_e32 v93, v93
	s_nop 0
	v_sub_f32_e32 v93, 1.0, v93
	v_sqrt_f32_e32 v100, v93
	v_add_f32_e32 v93, v111, v111
	v_mul_f32_e32 v93, 0x3fb8aa3b, v93
	v_exp_f32_e32 v93, v93
	s_nop 0
	v_sub_f32_e32 v93, 1.0, v93
	v_sqrt_f32_e32 v101, v93
	v_cvt_pk_bf16_f32 v93, v110, v111
	v_lshl_add_u64 v[110:111], v[192:193], 0, s[60:61]
	v_lshlrev_b64 v[110:111], 1, v[110:111]
	v_lshl_add_u64 v[112:113], s[44:45], 0, v[110:111]
	v_lshl_add_u64 v[112:113], v[112:113], 0, v[186:187]
	global_store_dwordx4 v[112:113], v[90:93], off
	s_mov_b64 s[60:61], s[58:59]
	s_nop 0
	v_pk_add_f32 v[92:93], v[106:107], 1.0 op_sel_hi:[1,0]
	v_lshlrev_b32_e32 v90, 16, v86
	v_and_b32_e32 v91, 0xffff0000, v86
	v_rcp_f32_e32 v93, v93
	v_rcp_f32_e32 v92, v92
	s_nop 0
	v_pk_mul_f32 v[90:91], v[92:93], v[90:91]
	v_pk_add_f32 v[92:93], v[102:103], 1.0 op_sel_hi:[1,0]
	v_pk_mul_f32 v[90:91], v[98:99], v[90:91]
	s_nop 0
	v_cvt_pk_bf16_f32 v86, v90, v91
	v_lshlrev_b32_e32 v90, 16, v87
	v_and_b32_e32 v91, 0xffff0000, v87
	v_rcp_f32_e32 v93, v93
	v_rcp_f32_e32 v92, v92
	s_nop 0
	v_pk_mul_f32 v[90:91], v[92:93], v[90:91]
	v_pk_add_f32 v[92:93], v[96:97], 1.0 op_sel_hi:[1,0]
	v_pk_mul_f32 v[90:91], v[104:105], v[90:91]
	s_nop 0
	v_cvt_pk_bf16_f32 v87, v90, v91
	v_lshlrev_b32_e32 v90, 16, v88
	v_and_b32_e32 v91, 0xffff0000, v88
	v_rcp_f32_e32 v93, v93
	v_rcp_f32_e32 v92, v92
	s_nop 0
	v_pk_mul_f32 v[90:91], v[92:93], v[90:91]
	v_pk_add_f32 v[92:93], v[94:95], 1.0 op_sel_hi:[1,0]
	v_pk_mul_f32 v[90:91], v[108:109], v[90:91]
	s_nop 0
	v_cvt_pk_bf16_f32 v88, v90, v91
	v_lshlrev_b32_e32 v90, 16, v89
	v_and_b32_e32 v91, 0xffff0000, v89
	v_rcp_f32_e32 v93, v93
	v_rcp_f32_e32 v92, v92
	s_nop 0
	v_pk_mul_f32 v[90:91], v[92:93], v[90:91]
	s_nop 0
	v_pk_mul_f32 v[90:91], v[100:101], v[90:91]
	s_nop 0
	v_cvt_pk_bf16_f32 v89, v90, v91
	v_lshl_add_u64 v[90:91], s[46:47], 0, v[110:111]
	v_lshl_add_u64 v[90:91], v[90:91], 0, v[186:187]
	global_store_dwordx4 v[90:91], v[86:89], off
	v_exp_f32_e32 v90, v82
	s_nop 0
	v_exp_f32_e32 v86, v74
	v_add_f32_e32 v74, v83, v35
	v_mul_f32_e32 v74, 0xbfb8aa3b, v74
	v_exp_f32_e32 v91, v74
	v_add_f32_e32 v74, v75, v39
	v_mul_f32_e32 v74, 0xbfb8aa3b, v74
	v_exp_f32_e32 v87, v74
	v_add_f32_e32 v74, v84, v36
	v_mul_f32_e32 v74, 0xbfb8aa3b, v74
	v_exp_f32_e32 v84, v74
	v_add_f32_e32 v74, v76, v40
	v_exp_f32_e32 v76, v70
	v_add_f32_e32 v70, v79, v27
	v_mul_f32_e32 v74, 0xbfb8aa3b, v74
	v_mul_f32_e32 v70, 0xbfb8aa3b, v70
	v_exp_f32_e32 v82, v74
	v_add_f32_e32 v74, v85, v37
	v_exp_f32_e32 v89, v70
	v_add_f32_e32 v70, v71, v31
	v_mul_f32_e32 v74, 0xbfb8aa3b, v74
	v_mul_f32_e32 v70, 0xbfb8aa3b, v70
	v_exp_f32_e32 v85, v74
	v_add_f32_e32 v74, v77, v41
	v_exp_f32_e32 v77, v70
	v_add_f32_e32 v70, v80, v28
	v_mul_f32_e32 v74, 0xbfb8aa3b, v74
	v_mul_f32_e32 v70, 0xbfb8aa3b, v70
	v_exp_f32_e32 v83, v74
	v_add_f32_e32 v74, v78, v26
	v_exp_f32_e32 v80, v70
	v_add_f32_e32 v70, v72, v32
	v_mul_f32_e32 v74, 0xbfb8aa3b, v74
	v_mul_f32_e32 v70, 0xbfb8aa3b, v70
	v_exp_f32_e32 v88, v74
	v_exp_f32_e32 v74, v70
	v_add_f32_e32 v70, v81, v29
	v_mul_f32_e32 v70, 0xbfb8aa3b, v70
	v_exp_f32_e32 v81, v70
	v_add_f32_e32 v70, v73, v33
	v_mul_f32_e32 v70, 0xbfb8aa3b, v70
	v_exp_f32_e32 v75, v70
	v_pk_add_f32 v[70:71], v[90:91], 1.0 op_sel_hi:[1,0]
	v_pk_add_f32 v[80:81], v[80:81], 1.0 op_sel_hi:[1,0]
	v_rcp_f32_e32 v71, v71
	v_rcp_f32_e32 v70, v70
	s_nop 0
	v_pk_mul_f32 v[70:71], v[42:43], v[70:71]
	s_nop 0
	v_add_f32_e32 v72, v70, v70
	v_mul_f32_e32 v72, 0x3fb8aa3b, v72
	v_exp_f32_e32 v72, v72
	v_cvt_pk_bf16_f32 v70, v70, v71
	v_sub_f32_e32 v72, 1.0, v72
	v_sqrt_f32_e32 v78, v72
	v_add_f32_e32 v72, v71, v71
	v_mul_f32_e32 v72, 0x3fb8aa3b, v72
	v_exp_f32_e32 v72, v72
	s_nop 0
	v_sub_f32_e32 v72, 1.0, v72
	v_sqrt_f32_e32 v79, v72
	v_pk_add_f32 v[72:73], v[84:85], 1.0 op_sel_hi:[1,0]
	s_nop 0
	v_rcp_f32_e32 v73, v73
	v_rcp_f32_e32 v72, v72
	s_nop 0
	v_pk_mul_f32 v[72:73], v[44:45], v[72:73]
	s_nop 0
	v_add_f32_e32 v71, v72, v72
	v_mul_f32_e32 v71, 0x3fb8aa3b, v71
	v_exp_f32_e32 v71, v71
	s_nop 0
	v_sub_f32_e32 v71, 1.0, v71
	v_sqrt_f32_e32 v84, v71
	v_add_f32_e32 v71, v73, v73
	v_mul_f32_e32 v71, 0x3fb8aa3b, v71
	v_exp_f32_e32 v71, v71
	s_nop 0
	v_sub_f32_e32 v71, 1.0, v71
	v_sqrt_f32_e32 v85, v71
	v_cvt_pk_bf16_f32 v71, v72, v73
	v_pk_add_f32 v[72:73], v[88:89], 1.0 op_sel_hi:[1,0]
	s_nop 0
	v_rcp_f32_e32 v73, v73
	v_rcp_f32_e32 v72, v72
	s_nop 0
	v_pk_mul_f32 v[72:73], v[22:23], v[72:73]
	s_nop 0
	v_add_f32_e32 v88, v72, v72
	v_mul_f32_e32 v88, 0x3fb8aa3b, v88
	v_exp_f32_e32 v88, v88
	v_cvt_pk_bf16_f32 v72, v72, v73
	v_sub_f32_e32 v88, 1.0, v88
	v_sqrt_f32_e32 v88, v88
	v_add_f32_e32 v89, v73, v73
	v_mul_f32_e32 v89, 0x3fb8aa3b, v89
	v_exp_f32_e32 v89, v89
	s_nop 0
	v_sub_f32_e32 v89, 1.0, v89
	v_sqrt_f32_e32 v89, v89
	v_rcp_f32_e32 v81, v81
	s_mov_b64 s[8:9], 0x120000
	v_rcp_f32_e32 v80, v80
	s_nop 0
	v_pk_mul_f32 v[90:91], v[24:25], v[80:81]
	s_nop 0
	v_add_f32_e32 v73, v90, v90
	v_mul_f32_e32 v73, 0x3fb8aa3b, v73
	v_exp_f32_e32 v73, v73
	s_nop 0
	v_sub_f32_e32 v73, 1.0, v73
	v_sqrt_f32_e32 v80, v73
	v_add_f32_e32 v73, v91, v91
	v_mul_f32_e32 v73, 0x3fb8aa3b, v73
	v_exp_f32_e32 v73, v73
	s_nop 0
	v_sub_f32_e32 v73, 1.0, v73
	v_sqrt_f32_e32 v81, v73
	v_cvt_pk_bf16_f32 v73, v90, v91
	v_lshl_add_u64 v[90:91], v[174:175], 0, s[8:9]
	v_lshl_add_u64 v[92:93], s[44:45], 0, v[90:91]
	v_lshl_add_u64 v[92:93], v[92:93], 0, v[186:187]
	global_store_dwordx4 v[92:93], v[70:73], off
	s_nop 1
	v_pk_add_f32 v[72:73], v[86:87], 1.0 op_sel_hi:[1,0]
	v_lshlrev_b32_e32 v70, 16, v66
	v_and_b32_e32 v71, 0xffff0000, v66
	v_rcp_f32_e32 v73, v73
	v_rcp_f32_e32 v72, v72
	s_nop 0
	v_pk_mul_f32 v[70:71], v[72:73], v[70:71]
	v_pk_add_f32 v[72:73], v[82:83], 1.0 op_sel_hi:[1,0]
	v_pk_mul_f32 v[70:71], v[78:79], v[70:71]
	s_nop 0
	v_cvt_pk_bf16_f32 v66, v70, v71
	v_lshlrev_b32_e32 v70, 16, v67
	v_and_b32_e32 v71, 0xffff0000, v67
	v_rcp_f32_e32 v73, v73
	v_rcp_f32_e32 v72, v72
	s_nop 0
	v_pk_mul_f32 v[70:71], v[72:73], v[70:71]
	v_pk_add_f32 v[72:73], v[76:77], 1.0 op_sel_hi:[1,0]
	v_pk_mul_f32 v[70:71], v[84:85], v[70:71]
	s_nop 0
	v_cvt_pk_bf16_f32 v67, v70, v71
	v_lshlrev_b32_e32 v70, 16, v68
	v_and_b32_e32 v71, 0xffff0000, v68
	v_rcp_f32_e32 v73, v73
	v_rcp_f32_e32 v72, v72
	s_nop 0
	v_pk_mul_f32 v[70:71], v[72:73], v[70:71]
	v_pk_add_f32 v[72:73], v[74:75], 1.0 op_sel_hi:[1,0]
	v_pk_mul_f32 v[70:71], v[88:89], v[70:71]
	s_nop 0
	v_cvt_pk_bf16_f32 v68, v70, v71
	v_lshlrev_b32_e32 v70, 16, v69
	v_and_b32_e32 v71, 0xffff0000, v69
	v_rcp_f32_e32 v73, v73
	v_rcp_f32_e32 v72, v72
	s_nop 0
	v_pk_mul_f32 v[70:71], v[72:73], v[70:71]
	s_nop 0
	v_pk_mul_f32 v[70:71], v[80:81], v[70:71]
	s_nop 0
	v_cvt_pk_bf16_f32 v69, v70, v71
	v_lshl_add_u64 v[70:71], s[46:47], 0, v[90:91]
	v_lshl_add_u64 v[70:71], v[70:71], 0, v[186:187]
	global_store_dwordx4 v[70:71], v[66:69], off
	v_exp_f32_e32 v70, v62
	s_nop 0
	v_exp_f32_e32 v66, v54
	v_add_f32_e32 v54, v63, v35
	v_mul_f32_e32 v54, 0xbfb8aa3b, v54
	v_exp_f32_e32 v71, v54
	v_add_f32_e32 v54, v55, v39
	v_mul_f32_e32 v54, 0xbfb8aa3b, v54
	v_exp_f32_e32 v67, v54
	v_add_f32_e32 v54, v64, v36
	v_mul_f32_e32 v54, 0xbfb8aa3b, v54
	v_exp_f32_e32 v64, v54
	v_add_f32_e32 v54, v56, v40
	v_exp_f32_e32 v56, v50
	v_add_f32_e32 v50, v59, v27
	v_mul_f32_e32 v54, 0xbfb8aa3b, v54
	v_mul_f32_e32 v50, 0xbfb8aa3b, v50
	v_exp_f32_e32 v62, v54
	v_add_f32_e32 v54, v65, v37
	v_exp_f32_e32 v69, v50
	v_add_f32_e32 v50, v51, v31
	v_mul_f32_e32 v54, 0xbfb8aa3b, v54
	v_mul_f32_e32 v50, 0xbfb8aa3b, v50
	v_exp_f32_e32 v65, v54
	v_add_f32_e32 v54, v57, v41
	v_exp_f32_e32 v57, v50
	v_add_f32_e32 v50, v60, v28
	v_mul_f32_e32 v54, 0xbfb8aa3b, v54
	v_mul_f32_e32 v50, 0xbfb8aa3b, v50
	v_exp_f32_e32 v63, v54
	v_add_f32_e32 v54, v58, v26
	v_exp_f32_e32 v60, v50
	v_add_f32_e32 v50, v52, v32
	v_mul_f32_e32 v54, 0xbfb8aa3b, v54
	v_mul_f32_e32 v50, 0xbfb8aa3b, v50
	v_exp_f32_e32 v68, v54
	v_exp_f32_e32 v54, v50
	v_add_f32_e32 v50, v61, v29
	v_mul_f32_e32 v50, 0xbfb8aa3b, v50
	v_exp_f32_e32 v61, v50
	v_add_f32_e32 v50, v53, v33
	v_mul_f32_e32 v50, 0xbfb8aa3b, v50
	v_exp_f32_e32 v55, v50
	v_pk_add_f32 v[50:51], v[70:71], 1.0 op_sel_hi:[1,0]
	v_pk_add_f32 v[60:61], v[60:61], 1.0 op_sel_hi:[1,0]
	v_rcp_f32_e32 v51, v51
	v_rcp_f32_e32 v50, v50
	s_nop 0
	v_pk_mul_f32 v[50:51], v[42:43], v[50:51]
	s_nop 0
	v_add_f32_e32 v52, v50, v50
	v_mul_f32_e32 v52, 0x3fb8aa3b, v52
	v_exp_f32_e32 v52, v52
	v_cvt_pk_bf16_f32 v50, v50, v51
	v_sub_f32_e32 v52, 1.0, v52
	v_sqrt_f32_e32 v58, v52
	v_add_f32_e32 v52, v51, v51
	v_mul_f32_e32 v52, 0x3fb8aa3b, v52
	v_exp_f32_e32 v52, v52
	s_nop 0
	v_sub_f32_e32 v52, 1.0, v52
	v_sqrt_f32_e32 v59, v52
	v_pk_add_f32 v[52:53], v[64:65], 1.0 op_sel_hi:[1,0]
	s_nop 0
	v_rcp_f32_e32 v53, v53
	v_rcp_f32_e32 v52, v52
	s_nop 0
	v_pk_mul_f32 v[52:53], v[44:45], v[52:53]
	s_nop 0
	v_add_f32_e32 v51, v52, v52
	v_mul_f32_e32 v51, 0x3fb8aa3b, v51
	v_exp_f32_e32 v51, v51
	s_nop 0
	v_sub_f32_e32 v51, 1.0, v51
	v_sqrt_f32_e32 v64, v51
	v_add_f32_e32 v51, v53, v53
	v_mul_f32_e32 v51, 0x3fb8aa3b, v51
	v_exp_f32_e32 v51, v51
	s_nop 0
	v_sub_f32_e32 v51, 1.0, v51
	v_sqrt_f32_e32 v65, v51
	v_cvt_pk_bf16_f32 v51, v52, v53
	v_pk_add_f32 v[52:53], v[68:69], 1.0 op_sel_hi:[1,0]
	s_nop 0
	v_rcp_f32_e32 v53, v53
	v_rcp_f32_e32 v52, v52
	s_nop 0
	v_pk_mul_f32 v[52:53], v[22:23], v[52:53]
	s_nop 0
	v_add_f32_e32 v68, v52, v52
	v_mul_f32_e32 v68, 0x3fb8aa3b, v68
	v_exp_f32_e32 v68, v68
	v_cvt_pk_bf16_f32 v52, v52, v53
	v_sub_f32_e32 v68, 1.0, v68
	v_sqrt_f32_e32 v68, v68
	v_add_f32_e32 v69, v53, v53
	v_mul_f32_e32 v69, 0x3fb8aa3b, v69
	v_exp_f32_e32 v69, v69
	s_nop 0
	v_sub_f32_e32 v69, 1.0, v69
	v_sqrt_f32_e32 v69, v69
	v_rcp_f32_e32 v61, v61
	s_mov_b64 s[8:9], 0x140000
	v_rcp_f32_e32 v60, v60
	s_nop 0
	v_pk_mul_f32 v[70:71], v[24:25], v[60:61]
	s_nop 0
	v_add_f32_e32 v53, v70, v70
	v_mul_f32_e32 v53, 0x3fb8aa3b, v53
	v_exp_f32_e32 v53, v53
	s_nop 0
	v_sub_f32_e32 v53, 1.0, v53
	v_sqrt_f32_e32 v60, v53
	v_add_f32_e32 v53, v71, v71
	v_mul_f32_e32 v53, 0x3fb8aa3b, v53
	v_exp_f32_e32 v53, v53
	s_nop 0
	v_sub_f32_e32 v53, 1.0, v53
	v_sqrt_f32_e32 v61, v53
	v_cvt_pk_bf16_f32 v53, v70, v71
	v_lshl_add_u64 v[70:71], v[174:175], 0, s[8:9]
	v_lshl_add_u64 v[72:73], s[44:45], 0, v[70:71]
	v_lshl_add_u64 v[72:73], v[72:73], 0, v[186:187]
	global_store_dwordx4 v[72:73], v[50:53], off
	s_nop 1
	v_pk_add_f32 v[52:53], v[66:67], 1.0 op_sel_hi:[1,0]
	v_lshlrev_b32_e32 v50, 16, v46
	v_and_b32_e32 v51, 0xffff0000, v46
	v_rcp_f32_e32 v53, v53
	v_rcp_f32_e32 v52, v52
	s_nop 0
	v_pk_mul_f32 v[50:51], v[52:53], v[50:51]
	v_pk_add_f32 v[52:53], v[62:63], 1.0 op_sel_hi:[1,0]
	v_pk_mul_f32 v[50:51], v[58:59], v[50:51]
	s_nop 0
	v_cvt_pk_bf16_f32 v46, v50, v51
	v_lshlrev_b32_e32 v50, 16, v47
	v_and_b32_e32 v51, 0xffff0000, v47
	v_rcp_f32_e32 v53, v53
	v_rcp_f32_e32 v52, v52
	s_nop 0
	v_pk_mul_f32 v[50:51], v[52:53], v[50:51]
	v_pk_add_f32 v[52:53], v[56:57], 1.0 op_sel_hi:[1,0]
	v_pk_mul_f32 v[50:51], v[64:65], v[50:51]
	s_nop 0
	v_cvt_pk_bf16_f32 v47, v50, v51
	v_lshlrev_b32_e32 v50, 16, v48
	v_and_b32_e32 v51, 0xffff0000, v48
	v_rcp_f32_e32 v53, v53
	v_rcp_f32_e32 v52, v52
	s_nop 0
	v_pk_mul_f32 v[50:51], v[52:53], v[50:51]
	v_pk_add_f32 v[52:53], v[54:55], 1.0 op_sel_hi:[1,0]
	v_pk_mul_f32 v[50:51], v[68:69], v[50:51]
	s_nop 0
	v_cvt_pk_bf16_f32 v48, v50, v51
	v_lshlrev_b32_e32 v50, 16, v49
	v_and_b32_e32 v51, 0xffff0000, v49
	v_rcp_f32_e32 v53, v53
	v_rcp_f32_e32 v52, v52
	s_nop 0
	v_pk_mul_f32 v[50:51], v[52:53], v[50:51]
	s_nop 0
	v_pk_mul_f32 v[50:51], v[60:61], v[50:51]
	s_nop 0
	v_cvt_pk_bf16_f32 v49, v50, v51
	v_lshl_add_u64 v[50:51], s[46:47], 0, v[70:71]
	v_lshl_add_u64 v[50:51], v[50:51], 0, v[186:187]
	global_store_dwordx4 v[50:51], v[46:49], off
	s_nop 1
	v_exp_f32_e32 v47, v10
	v_add_f32_e32 v10, v11, v39
	v_mul_f32_e32 v10, 0xbfb8aa3b, v10
	v_exp_f32_e32 v35, v10
	v_add_f32_e32 v10, v20, v36
	v_mul_f32_e32 v10, 0xbfb8aa3b, v10
	v_exp_f32_e32 v20, v10
	v_add_f32_e32 v10, v12, v40
	v_exp_f32_e32 v12, v6
	v_add_f32_e32 v6, v15, v27
	v_mul_f32_e32 v10, 0xbfb8aa3b, v10
	v_mul_f32_e32 v6, 0xbfb8aa3b, v6
	v_exp_f32_e32 v46, v18
	v_exp_f32_e32 v18, v10
	v_add_f32_e32 v10, v21, v37
	v_exp_f32_e32 v27, v6
	v_add_f32_e32 v6, v7, v31
	v_mul_f32_e32 v10, 0xbfb8aa3b, v10
	v_mul_f32_e32 v6, 0xbfb8aa3b, v6
	v_exp_f32_e32 v21, v10
	v_add_f32_e32 v10, v13, v41
	v_exp_f32_e32 v13, v6
	v_add_f32_e32 v6, v16, v28
	v_mul_f32_e32 v10, 0xbfb8aa3b, v10
	v_mul_f32_e32 v6, 0xbfb8aa3b, v6
	v_exp_f32_e32 v19, v10
	v_add_f32_e32 v10, v14, v26
	v_exp_f32_e32 v16, v6
	v_add_f32_e32 v6, v8, v32
	v_mul_f32_e32 v10, 0xbfb8aa3b, v10
; #define PG8_STAGE(bufoff, gbase, voff) do { _Pragma("unroll") for (int _i = 0; _i < 2; ++_i) \
;         __builtin_amdgcn_global_load_lds((const unsigned*)((const char*)(gbase) + (voff)[_i]), (LAS unsigned*)(lds + (bufoff) + ldsw + _i * 8192), 16, 0, 0); } while (0)
; #define PG8_WAIT_V(n) asm volatile("s_waitcnt vmcnt(" #n ")" ::: "memory")
; template <class Epi, class GT>
; __device__ __forceinline__ void gemm_phase(LAS unsigned char* lds, const GT g, const StaticOrder& S, const Epi& E) {
;     ...
;     for (;;) {
;         const bool has_next = S.next(ui + 1, nxt);
;         const char* nA = has_next ? g.a_ptr(nxt) : cA; const char* nB = has_next ? g.b_ptr(nxt) : cB;
;         for (int t = 0; t < nt; t += 2) {
;             const bool last = (t == nt - 2);
;             const char* a1 = cA + (size_t)(t + 1) * kstep;
;             const char* a2 = last ? nA : cA + (size_t)(t + 2) * kstep; const char* b2 = last ? nB : cB + (size_t)(t + 2) * kstep;
;             const char* a3 = a2 + kstep; const char* b3 = b2 + kstep;
;             PG8_LDB(B0, 0, 0); PG8_SCHED; PG8_LDA(At, 0, 0); PG8_STAGE(PG8_SA(1, 1), a1 + hstepA, voffA);
;             PG8_WAIT_L(8); PG8_BAR; PG8_WAIT_L(0); PG8_MMA(0, 0, At, B0); PG8_BAR; PG8_SCHED;
;             PG8_LDB(B1, 0, 1); PG8_STAGE(PG8_SB(0, 0), b2, voffB);
;             PG8_BAR; PG8_WAIT_L(0); PG8_MMA(0, 1, At, B1); PG8_BAR;
;             PG8_LDA(At, 0, 1); PG8_STAGE(PG8_SA(0, 0), a2, voffA);
;             PG8_BAR; PG8_WAIT_L(0); PG8_MMA(1, 0, At, B0); PG8_BAR; PG8_SCHED;
;             PG8_STAGE(PG8_SB(0, 1), b2 + hstepB, voffB);
;             PG8_WAIT_V(6); PG8_BAR; PG8_MMA(1, 1, At, B1); PG8_BAR;
;             PG8_LDB(B0, 1, 0); PG8_SCHED; PG8_LDA(At, 1, 0); PG8_STAGE(PG8_SA(0, 1), a2 + hstepA, voffA);
;             PG8_WAIT_L(8); PG8_BAR; PG8_WAIT_L(0); PG8_MMA(0, 0, At, B0); PG8_BAR; PG8_SCHED;
;             PG8_LDB(B1, 1, 1); PG8_STAGE(PG8_SB(1, 0), b3, voffB);
;             PG8_BAR; PG8_WAIT_L(0); PG8_MMA(0, 1, At, B1); PG8_BAR;
;             PG8_LDA(At, 1, 1); PG8_STAGE(PG8_SA(1, 0), a3, voffA);
;             PG8_BAR; PG8_WAIT_L(0); PG8_MMA(1, 0, At, B0); PG8_BAR; PG8_SCHED;
;             PG8_STAGE(PG8_SB(1, 1), b3 + hstepB, voffB);
;             PG8_WAIT_V(6); PG8_BAR; PG8_MMA(1, 1, At, B1); PG8_BAR;
;         }
;         E(acc, cur, wr, wc, fr, fq);
;         if (!has_next) break;
	v_mul_f32_e32 v6, 0xbfb8aa3b, v6
	v_exp_f32_e32 v26, v10
	v_exp_f32_e32 v10, v6
	v_add_f32_e32 v6, v17, v29
	v_mul_f32_e32 v6, 0xbfb8aa3b, v6
	v_exp_f32_e32 v17, v6
	v_add_f32_e32 v6, v9, v33
	v_mul_f32_e32 v6, 0xbfb8aa3b, v6
	v_exp_f32_e32 v11, v6
	v_pk_add_f32 v[6:7], v[46:47], 1.0 op_sel_hi:[1,0]
	v_pk_add_f32 v[16:17], v[16:17], 1.0 op_sel_hi:[1,0]
	v_rcp_f32_e32 v7, v7
	v_rcp_f32_e32 v6, v6
	s_nop 0
	v_pk_mul_f32 v[6:7], v[42:43], v[6:7]
	s_nop 0
	v_add_f32_e32 v8, v6, v6
	v_mul_f32_e32 v8, 0x3fb8aa3b, v8
	v_exp_f32_e32 v8, v8
	v_cvt_pk_bf16_f32 v6, v6, v7
	v_sub_f32_e32 v8, 1.0, v8
	v_sqrt_f32_e32 v14, v8
	v_add_f32_e32 v8, v7, v7
	v_mul_f32_e32 v8, 0x3fb8aa3b, v8
	v_exp_f32_e32 v8, v8
	s_nop 0
	v_sub_f32_e32 v8, 1.0, v8
	v_sqrt_f32_e32 v15, v8
	v_pk_add_f32 v[8:9], v[20:21], 1.0 op_sel_hi:[1,0]
	s_nop 0
	v_rcp_f32_e32 v9, v9
	v_rcp_f32_e32 v8, v8
	s_nop 0
	v_pk_mul_f32 v[8:9], v[44:45], v[8:9]
	s_nop 0
	v_add_f32_e32 v7, v8, v8
	v_mul_f32_e32 v7, 0x3fb8aa3b, v7
	v_exp_f32_e32 v7, v7
	s_nop 0
	v_sub_f32_e32 v7, 1.0, v7
	v_sqrt_f32_e32 v20, v7
	v_add_f32_e32 v7, v9, v9
	v_mul_f32_e32 v7, 0x3fb8aa3b, v7
	v_exp_f32_e32 v7, v7
	s_nop 0
	v_sub_f32_e32 v7, 1.0, v7
	v_sqrt_f32_e32 v21, v7
	v_cvt_pk_bf16_f32 v7, v8, v9
	v_pk_add_f32 v[8:9], v[26:27], 1.0 op_sel_hi:[1,0]
	s_nop 0
	v_rcp_f32_e32 v9, v9
	v_rcp_f32_e32 v8, v8
	s_nop 0
	v_pk_mul_f32 v[8:9], v[22:23], v[8:9]
	s_nop 0
	v_add_f32_e32 v22, v8, v8
	v_mul_f32_e32 v22, 0x3fb8aa3b, v22
	v_exp_f32_e32 v22, v22
	v_cvt_pk_bf16_f32 v8, v8, v9
	v_sub_f32_e32 v22, 1.0, v22
	v_sqrt_f32_e32 v22, v22
	v_add_f32_e32 v23, v9, v9
	v_mul_f32_e32 v23, 0x3fb8aa3b, v23
	v_exp_f32_e32 v23, v23
	s_nop 0
	v_sub_f32_e32 v23, 1.0, v23
	v_sqrt_f32_e32 v23, v23
	v_rcp_f32_e32 v17, v17
	s_mov_b64 s[8:9], 0x160000
	v_rcp_f32_e32 v16, v16
	s_nop 0
	v_pk_mul_f32 v[24:25], v[24:25], v[16:17]
	s_nop 0
	v_add_f32_e32 v9, v24, v24
	v_mul_f32_e32 v9, 0x3fb8aa3b, v9
	v_exp_f32_e32 v9, v9
	s_nop 0
	v_sub_f32_e32 v9, 1.0, v9
	v_sqrt_f32_e32 v16, v9
	v_add_f32_e32 v9, v25, v25
	v_mul_f32_e32 v9, 0x3fb8aa3b, v9
	v_exp_f32_e32 v9, v9
	s_nop 0
	v_sub_f32_e32 v9, 1.0, v9
	v_cmp_gt_f32_e32 vcc, s96, v9
	v_mul_f32_e32 v17, 0x4f800000, v9
	s_nop 0
	v_cndmask_b32_e32 v9, v9, v17, vcc
	v_sqrt_f32_e32 v17, v9
	s_nop 0
	v_add_u32_e32 v26, -1, v17
	v_fma_f32 v27, -v26, v17, v9
	v_cmp_ge_f32_e64 s[40:41], 0, v27
	v_add_u32_e32 v27, 1, v17
	s_nop 0
	v_cndmask_b32_e64 v26, v17, v26, s[40:41]
	v_fma_f32 v17, -v27, v17, v9
	v_cmp_lt_f32_e64 s[40:41], 0, v17
	s_nop 1
	v_cndmask_b32_e64 v17, v26, v27, s[40:41]
	v_mul_f32_e32 v26, 0x37800000, v17
	v_cndmask_b32_e32 v17, v17, v26, vcc
	v_cmp_class_f32_e32 vcc, v9, v221
	s_mov_b32 s40, s54
	s_nop 0
	v_cndmask_b32_e32 v17, v17, v9, vcc
	v_cvt_pk_bf16_f32 v9, v24, v25
	v_lshl_add_u64 v[24:25], v[174:175], 0, s[8:9]
	v_lshl_add_u64 v[26:27], s[44:45], 0, v[24:25]
	v_lshl_add_u64 v[26:27], v[26:27], 0, v[186:187]
	global_store_dwordx4 v[26:27], v[6:9], off
	s_nop 1
	v_pk_add_f32 v[8:9], v[34:35], 1.0 op_sel_hi:[1,0]
	v_lshlrev_b32_e32 v6, 16, v2
	v_and_b32_e32 v7, 0xffff0000, v2
	v_rcp_f32_e32 v9, v9
	v_rcp_f32_e32 v8, v8
	s_nop 0
	v_pk_mul_f32 v[6:7], v[8:9], v[6:7]
	v_pk_add_f32 v[8:9], v[18:19], 1.0 op_sel_hi:[1,0]
	v_pk_mul_f32 v[6:7], v[14:15], v[6:7]
	s_nop 0
	v_cvt_pk_bf16_f32 v2, v6, v7
	v_lshlrev_b32_e32 v6, 16, v3
	v_and_b32_e32 v7, 0xffff0000, v3
	v_rcp_f32_e32 v9, v9
	v_rcp_f32_e32 v8, v8
	s_nop 0
	v_pk_mul_f32 v[6:7], v[8:9], v[6:7]
	v_pk_add_f32 v[8:9], v[12:13], 1.0 op_sel_hi:[1,0]
	v_pk_mul_f32 v[6:7], v[20:21], v[6:7]
	s_nop 0
	v_cvt_pk_bf16_f32 v3, v6, v7
	v_lshlrev_b32_e32 v6, 16, v4
	v_and_b32_e32 v7, 0xffff0000, v4
	v_rcp_f32_e32 v9, v9
	v_rcp_f32_e32 v8, v8
	s_nop 0
	v_pk_mul_f32 v[6:7], v[8:9], v[6:7]
	v_pk_add_f32 v[8:9], v[10:11], 1.0 op_sel_hi:[1,0]
	v_pk_mul_f32 v[6:7], v[22:23], v[6:7]
	s_nop 0
	v_cvt_pk_bf16_f32 v4, v6, v7
	v_lshlrev_b32_e32 v6, 16, v5
	v_and_b32_e32 v7, 0xffff0000, v5
	v_rcp_f32_e32 v9, v9
	v_rcp_f32_e32 v8, v8
	s_nop 0
	v_pk_mul_f32 v[6:7], v[8:9], v[6:7]
	s_and_b64 vcc, exec, s[38:39]
	v_pk_mul_f32 v[6:7], v[16:17], v[6:7]
	s_nop 0
	v_cvt_pk_bf16_f32 v5, v6, v7
	v_lshl_add_u64 v[6:7], s[46:47], 0, v[24:25]
	v_lshl_add_u64 v[6:7], v[6:7], 0, v[186:187]
	global_store_dwordx4 v[6:7], v[2:5], off
	s_cbranch_vccz .LBB0_562
	s_waitcnt vmcnt(0)
	s_cmpk_gt_u32 s78, 0xff
	s_cbranch_scc1 .LBB0_569
	s_barrier

; #define PG8_STAGE(bufoff, gbase, voff) do { _Pragma("unroll") for (int _i = 0; _i < 2; ++_i) \
;         __builtin_amdgcn_global_load_lds((const unsigned*)((const char*)(gbase) + (voff)[_i]), (LAS unsigned*)(lds + (bufoff) + ldsw + _i * 8192), 16, 0, 0); } while (0)
; #define PG8_LDA(dst, b, h) do { _Pragma("unroll") for (int m = 0; m < 4; ++m) _Pragma("unroll") for (int k = 0; k < 2; ++k) dst[m][k] = *(const LAS bf16x8*)(lds + PG8_SA(b, h) + aoff + m * 2048 + k * 1024); } while (0)
; #define PG8_LDB(dst, b, h) do { _Pragma("unroll") for (int n = 0; n < 2; ++n) _Pragma("unroll") for (int k = 0; k < 2; ++k) dst[n][k] = *(const LAS bf16x8*)(lds + PG8_SB(b, h) + boff + n * 2048 + k * 1024); } while (0)
; #define PG8_MMA(ai, bj, At, Bt) do { __builtin_amdgcn_s_setprio(1); _Pragma("unroll") for (int m = 0; m < 4; ++m) _Pragma("unroll") for (int n = 0; n < 2; ++n) _Pragma("unroll") for (int k = 0; k < 2; ++k) \
;         acc[ai][bj][m][n] = __builtin_amdgcn_mfma_f32_16x16x32_bf16(Bt[n][k], At[m][k], acc[ai][bj][m][n], 0, 0, 0); __builtin_amdgcn_s_setprio(0); } while (0)
; #define PG8_WAIT_V(n) asm volatile("s_waitcnt vmcnt(" #n ")" ::: "memory")
; #define PG8_WAIT_L(n) asm volatile("s_waitcnt lgkmcnt(" #n ")" ::: "memory")
; #define PG8_BAR __builtin_amdgcn_s_barrier()
; #define PG8_SCHED __builtin_amdgcn_sched_barrier(0)
; template <class Epi, class GT>
; __device__ __forceinline__ void gemm_phase(LAS unsigned char* lds, const GT g, const StaticOrder& S, const Epi& E) {
;     ...
;             PG8_LDB(B0, 0, 0); PG8_SCHED; PG8_LDA(At, 0, 0); PG8_STAGE(PG8_SA(1, 1), a1 + hstepA, voffA);
;             PG8_WAIT_L(8); PG8_BAR; PG8_WAIT_L(0); PG8_MMA(0, 0, At, B0); PG8_BAR; PG8_SCHED;
;             PG8_LDB(B1, 0, 1); PG8_STAGE(PG8_SB(0, 0), b2, voffB);
;             PG8_BAR; PG8_WAIT_L(0); PG8_MMA(0, 1, At, B1); PG8_BAR;
;             PG8_LDA(At, 0, 1); PG8_STAGE(PG8_SA(0, 0), a2, voffA);
;             PG8_BAR; PG8_WAIT_L(0); PG8_MMA(1, 0, At, B0); PG8_BAR; PG8_SCHED;
;             PG8_STAGE(PG8_SB(0, 1), b2 + hstepB, voffB);
;             PG8_WAIT_V(6); PG8_BAR; PG8_MMA(1, 1, At, B1); PG8_BAR;
.LBB0_1608:
	ds_read_b128 v[130:133], v165
	ds_read_b128 v[154:157], v165 offset:1024
	ds_read_b128 v[158:161], v165 offset:2048
	ds_read_b128 v[168:171], v165 offset:3072
	s_add_u32 s40, s38, 0x100
	s_addc_u32 s41, s39, 0
	s_cmp_eq_u32 s8, 28
	s_cselect_b32 s55, s51, s41
	s_cselect_b32 s54, s50, s40
	s_cselect_b32 s45, s0, s5
	s_cselect_b32 s44, s1, s4
	v_lshl_add_u64 v[204:205], s[38:39], 0, v[148:149]
	s_add_i32 m0, s62, 0xc000
	ds_read_b128 v[172:175], v166
	ds_read_b128 v[176:179], v166 offset:1024
	ds_read_b128 v[180:183], v166 offset:2048
	ds_read_b128 v[184:187], v166 offset:3072
	ds_read_b128 v[188:191], v166 offset:4096
	ds_read_b128 v[192:195], v166 offset:5120
	ds_read_b128 v[196:199], v166 offset:6144
	ds_read_b128 v[200:203], v166 offset:7168
	global_load_lds_dwordx4 v[204:205], off
	v_lshl_add_u64 v[204:205], s[38:39], 0, v[146:147]
	s_add_i32 m0, s62, 0xe000
	s_nop 0
	global_load_lds_dwordx4 v[204:205], off
	s_waitcnt lgkmcnt(8)
	s_barrier
	s_waitcnt lgkmcnt(0)
	s_setprio 1
	s_waitcnt lgkmcnt(0)
	v_mfma_f32_16x16x32_bf16 v[126:129], v[130:133], v[172:175], v[126:129]
	v_mfma_f32_16x16x32_bf16 v[122:125], v[158:161], v[172:175], v[122:125]
	v_mfma_f32_16x16x32_bf16 v[118:121], v[130:133], v[180:183], v[118:121]
	v_mfma_f32_16x16x32_bf16 v[114:117], v[158:161], v[180:183], v[114:117]
	v_mfma_f32_16x16x32_bf16 v[102:105], v[130:133], v[188:191], v[102:105]
	v_mfma_f32_16x16x32_bf16 v[98:101], v[158:161], v[188:191], v[98:101]
	v_mfma_f32_16x16x32_bf16 v[86:89], v[130:133], v[196:199], v[86:89]
	v_mfma_f32_16x16x32_bf16 v[82:85], v[158:161], v[196:199], v[82:85]
	v_mfma_f32_16x16x32_bf16 v[126:129], v[154:157], v[176:179], v[126:129]
	v_mfma_f32_16x16x32_bf16 v[122:125], v[168:171], v[176:179], v[122:125]
	v_mfma_f32_16x16x32_bf16 v[118:121], v[154:157], v[184:187], v[118:121]
	v_mfma_f32_16x16x32_bf16 v[114:117], v[168:171], v[184:187], v[114:117]
	v_mfma_f32_16x16x32_bf16 v[102:105], v[154:157], v[192:195], v[102:105]
	v_mfma_f32_16x16x32_bf16 v[98:101], v[168:171], v[192:195], v[98:101]
	v_mfma_f32_16x16x32_bf16 v[86:89], v[154:157], v[200:203], v[86:89]
	v_mfma_f32_16x16x32_bf16 v[82:85], v[168:171], v[200:203], v[82:85]
	s_setprio 0
	s_barrier
	s_add_i32 s9, s72, s61
	v_lshl_add_u64 v[220:221], s[44:45], 0, v[138:139]
	s_mov_b32 m0, s9
	ds_read_b128 v[204:207], v167
	ds_read_b128 v[208:211], v167 offset:1024
	ds_read_b128 v[212:215], v167 offset:2048
	ds_read_b128 v[216:219], v167 offset:3072
	global_load_lds_dwordx4 v[220:221], off
	v_lshl_add_u64 v[222:223], s[44:45], 0, v[134:135]
	s_add_i32 m0, s9, 0x2000
	s_nop 0
	global_load_lds_dwordx4 v[222:223], off
	s_barrier
	s_waitcnt lgkmcnt(0)
	s_setprio 1
	s_waitcnt lgkmcnt(0)
	v_mfma_f32_16x16x32_bf16 v[110:113], v[204:207], v[172:175], v[110:113]
	v_mfma_f32_16x16x32_bf16 v[106:109], v[212:215], v[172:175], v[106:109]
	v_mfma_f32_16x16x32_bf16 v[94:97], v[204:207], v[180:183], v[94:97]
	v_mfma_f32_16x16x32_bf16 v[90:93], v[212:215], v[180:183], v[90:93]
	v_mfma_f32_16x16x32_bf16 v[78:81], v[204:207], v[188:191], v[78:81]
	v_mfma_f32_16x16x32_bf16 v[74:77], v[212:215], v[188:191], v[74:77]
	v_mfma_f32_16x16x32_bf16 v[70:73], v[204:207], v[196:199], v[70:73]
	v_mfma_f32_16x16x32_bf16 v[66:69], v[212:215], v[196:199], v[66:69]
	v_mfma_f32_16x16x32_bf16 v[110:113], v[208:211], v[176:179], v[110:113]
	v_mfma_f32_16x16x32_bf16 v[106:109], v[216:219], v[176:179], v[106:109]
	v_mfma_f32_16x16x32_bf16 v[94:97], v[208:211], v[184:187], v[94:97]
	v_mfma_f32_16x16x32_bf16 v[90:93], v[216:219], v[184:187], v[90:93]
	v_mfma_f32_16x16x32_bf16 v[78:81], v[208:211], v[192:195], v[78:81]
	v_mfma_f32_16x16x32_bf16 v[74:77], v[216:219], v[192:195], v[74:77]
	v_mfma_f32_16x16x32_bf16 v[70:73], v[208:211], v[200:203], v[70:73]
	v_mfma_f32_16x16x32_bf16 v[66:69], v[216:219], v[200:203], v[66:69]
	s_setprio 0
	s_mov_b32 m0, s62
	v_lshl_add_u64 v[224:225], s[54:55], 0, v[140:141]
	s_barrier
	ds_read_b128 v[172:175], v166 offset:16384
	ds_read_b128 v[176:179], v166 offset:17408
	ds_read_b128 v[180:183], v166 offset:18432
	ds_read_b128 v[184:187], v166 offset:19456
	ds_read_b128 v[188:191], v166 offset:20480
	ds_read_b128 v[192:195], v166 offset:21504
	ds_read_b128 v[196:199], v166 offset:22528
	ds_read_b128 v[200:203], v166 offset:23552
	global_load_lds_dwordx4 v[224:225], off
	v_lshl_add_u64 v[226:227], s[54:55], 0, v[136:137]
	s_mov_b32 m0, s63
	s_nop 0
	global_load_lds_dwordx4 v[226:227], off
	s_barrier
	s_waitcnt lgkmcnt(0)
	s_setprio 1
	s_waitcnt lgkmcnt(0)
	v_mfma_f32_16x16x32_bf16 v[62:65], v[130:133], v[172:175], v[62:65]
	v_mfma_f32_16x16x32_bf16 v[58:61], v[158:161], v[172:175], v[58:61]
	v_mfma_f32_16x16x32_bf16 v[54:57], v[130:133], v[180:183], v[54:57]
	v_mfma_f32_16x16x32_bf16 v[50:53], v[158:161], v[180:183], v[50:53]
	v_mfma_f32_16x16x32_bf16 v[38:41], v[130:133], v[188:191], v[38:41]
	v_mfma_f32_16x16x32_bf16 v[34:37], v[158:161], v[188:191], v[34:37]
	v_mfma_f32_16x16x32_bf16 v[22:25], v[130:133], v[196:199], v[22:25]
	v_mfma_f32_16x16x32_bf16 v[18:21], v[158:161], v[196:199], v[18:21]
	v_mfma_f32_16x16x32_bf16 v[62:65], v[154:157], v[176:179], v[62:65]
	v_mfma_f32_16x16x32_bf16 v[58:61], v[168:171], v[176:179], v[58:61]
	v_mfma_f32_16x16x32_bf16 v[54:57], v[154:157], v[184:187], v[54:57]
	v_mfma_f32_16x16x32_bf16 v[50:53], v[168:171], v[184:187], v[50:53]
	v_mfma_f32_16x16x32_bf16 v[38:41], v[154:157], v[192:195], v[38:41]
	v_mfma_f32_16x16x32_bf16 v[34:37], v[168:171], v[192:195], v[34:37]
	v_mfma_f32_16x16x32_bf16 v[22:25], v[154:157], v[200:203], v[22:25]
	v_mfma_f32_16x16x32_bf16 v[18:21], v[168:171], v[200:203], v[18:21]
	s_setprio 0
	s_barrier
; #define PG8_STAGE(bufoff, gbase, voff) do { _Pragma("unroll") for (int _i = 0; _i < 2; ++_i) \
;         __builtin_amdgcn_global_load_lds((const unsigned*)((const char*)(gbase) + (voff)[_i]), (LAS unsigned*)(lds + (bufoff) + ldsw + _i * 8192), 16, 0, 0); } while (0)
; #define PG8_LDA(dst, b, h) do { _Pragma("unroll") for (int m = 0; m < 4; ++m) _Pragma("unroll") for (int k = 0; k < 2; ++k) dst[m][k] = *(const LAS bf16x8*)(lds + PG8_SA(b, h) + aoff + m * 2048 + k * 1024); } while (0)
; #define PG8_LDB(dst, b, h) do { _Pragma("unroll") for (int n = 0; n < 2; ++n) _Pragma("unroll") for (int k = 0; k < 2; ++k) dst[n][k] = *(const LAS bf16x8*)(lds + PG8_SB(b, h) + boff + n * 2048 + k * 1024); } while (0)
; #define PG8_MMA(ai, bj, At, Bt) do { __builtin_amdgcn_s_setprio(1); _Pragma("unroll") for (int m = 0; m < 4; ++m) _Pragma("unroll") for (int n = 0; n < 2; ++n) _Pragma("unroll") for (int k = 0; k < 2; ++k) \
;         acc[ai][bj][m][n] = __builtin_amdgcn_mfma_f32_16x16x32_bf16(Bt[n][k], At[m][k], acc[ai][bj][m][n], 0, 0, 0); __builtin_amdgcn_s_setprio(0); } while (0)
; #define PG8_WAIT_V(n) asm volatile("s_waitcnt vmcnt(" #n ")" ::: "memory")
; #define PG8_WAIT_L(n) asm volatile("s_waitcnt lgkmcnt(" #n ")" ::: "memory")
; #define PG8_BAR __builtin_amdgcn_s_barrier()
; #define PG8_SCHED __builtin_amdgcn_sched_barrier(0)
; template <class Epi, class GT>
; __device__ __forceinline__ void gemm_phase(LAS unsigned char* lds, const GT g, const StaticOrder& S, const Epi& E) {
;     ...
;             PG8_WAIT_V(6); PG8_BAR; PG8_MMA(1, 1, At, B1); PG8_BAR;
;             PG8_LDB(B0, 1, 0); PG8_SCHED; PG8_LDA(At, 1, 0); PG8_STAGE(PG8_SA(0, 1), a2 + hstepA, voffA);
;             PG8_WAIT_L(8); PG8_BAR; PG8_WAIT_L(0); PG8_MMA(0, 0, At, B0); PG8_BAR; PG8_SCHED;
;             PG8_LDB(B1, 1, 1); PG8_STAGE(PG8_SB(1, 0), b3, voffB);
;             PG8_BAR; PG8_WAIT_L(0); PG8_MMA(0, 1, At, B1); PG8_BAR;
;             PG8_LDA(At, 1, 1); PG8_STAGE(PG8_SA(1, 0), a3, voffA);
;             PG8_BAR; PG8_WAIT_L(0); PG8_MMA(1, 0, At, B0); PG8_BAR; PG8_SCHED;
;             PG8_STAGE(PG8_SB(1, 1), b3 + hstepB, voffB);
;             PG8_WAIT_V(6); PG8_BAR; PG8_MMA(1, 1, At, B1); PG8_BAR;
	s_add_u32 s10, s44, 0x80000
	s_addc_u32 s11, s45, 0
	s_add_i32 s9, s73, s61
	v_lshl_add_u64 v[130:131], s[10:11], 0, v[138:139]
	s_mov_b32 m0, s9
	s_nop 0
	global_load_lds_dwordx4 v[130:131], off
	v_lshl_add_u64 v[130:131], s[10:11], 0, v[134:135]
	s_add_i32 m0, s9, 0x2000
	s_nop 0
	global_load_lds_dwordx4 v[130:131], off
	s_waitcnt vmcnt(6)
	s_barrier
	s_setprio 1
	v_mfma_f32_16x16x32_bf16 v[46:49], v[204:207], v[172:175], v[46:49]
	v_mfma_f32_16x16x32_bf16 v[42:45], v[212:215], v[172:175], v[42:45]
	v_mfma_f32_16x16x32_bf16 v[30:33], v[204:207], v[180:183], v[30:33]
	v_mfma_f32_16x16x32_bf16 v[26:29], v[212:215], v[180:183], v[26:29]
	v_mfma_f32_16x16x32_bf16 v[14:17], v[204:207], v[188:191], v[14:17]
	v_mfma_f32_16x16x32_bf16 v[10:13], v[212:215], v[188:191], v[10:13]
	v_mfma_f32_16x16x32_bf16 v[6:9], v[204:207], v[196:199], v[6:9]
	v_mfma_f32_16x16x32_bf16 v[2:5], v[212:215], v[196:199], v[2:5]
	v_mfma_f32_16x16x32_bf16 v[46:49], v[208:211], v[176:179], v[46:49]
	v_mfma_f32_16x16x32_bf16 v[42:45], v[216:219], v[176:179], v[42:45]
	v_mfma_f32_16x16x32_bf16 v[30:33], v[208:211], v[184:187], v[30:33]
	v_mfma_f32_16x16x32_bf16 v[26:29], v[216:219], v[184:187], v[26:29]
	v_mfma_f32_16x16x32_bf16 v[14:17], v[208:211], v[192:195], v[14:17]
	v_mfma_f32_16x16x32_bf16 v[10:13], v[216:219], v[192:195], v[10:13]
	v_mfma_f32_16x16x32_bf16 v[6:9], v[208:211], v[200:203], v[6:9]
	v_mfma_f32_16x16x32_bf16 v[2:5], v[216:219], v[200:203], v[2:5]
	s_setprio 0
	s_add_i32 s9, 0, 0x18000
	v_add_u32_e32 v142, s9, v163
	s_barrier
	ds_read_b128 v[130:133], v142
	ds_read_b128 v[154:157], v142 offset:1024
	ds_read_b128 v[158:161], v142 offset:2048
	ds_read_b128 v[168:171], v142 offset:3072
	s_add_u32 s10, s54, 0x300000
	s_addc_u32 s11, s55, 0
	s_mov_b32 m0, s64
	v_lshl_add_u64 v[204:205], s[10:11], 0, v[140:141]
	ds_read_b128 v[172:175], v166 offset:32768
	ds_read_b128 v[176:179], v166 offset:33792
	ds_read_b128 v[180:183], v166 offset:34816
	ds_read_b128 v[184:187], v166 offset:35840
	ds_read_b128 v[188:191], v166 offset:36864
	ds_read_b128 v[192:195], v166 offset:37888
	ds_read_b128 v[196:199], v166 offset:38912
	ds_read_b128 v[200:203], v166 offset:39936
	global_load_lds_dwordx4 v[204:205], off
	v_lshl_add_u64 v[204:205], s[10:11], 0, v[136:137]
	s_mov_b32 m0, s65
	s_nop 0
	global_load_lds_dwordx4 v[204:205], off
	s_waitcnt lgkmcnt(8)
	s_barrier
	s_waitcnt lgkmcnt(0)
	s_setprio 1
	s_waitcnt lgkmcnt(0)
	v_mfma_f32_16x16x32_bf16 v[126:129], v[130:133], v[172:175], v[126:129]
	v_mfma_f32_16x16x32_bf16 v[122:125], v[158:161], v[172:175], v[122:125]
	v_mfma_f32_16x16x32_bf16 v[118:121], v[130:133], v[180:183], v[118:121]
	v_mfma_f32_16x16x32_bf16 v[114:117], v[158:161], v[180:183], v[114:117]
	v_mfma_f32_16x16x32_bf16 v[102:105], v[130:133], v[188:191], v[102:105]
	v_mfma_f32_16x16x32_bf16 v[98:101], v[158:161], v[188:191], v[98:101]
	v_mfma_f32_16x16x32_bf16 v[86:89], v[130:133], v[196:199], v[86:89]
	v_mfma_f32_16x16x32_bf16 v[82:85], v[158:161], v[196:199], v[82:85]
	v_mfma_f32_16x16x32_bf16 v[126:129], v[154:157], v[176:179], v[126:129]
	v_mfma_f32_16x16x32_bf16 v[122:125], v[168:171], v[176:179], v[122:125]
	v_mfma_f32_16x16x32_bf16 v[118:121], v[154:157], v[184:187], v[118:121]
	v_mfma_f32_16x16x32_bf16 v[114:117], v[168:171], v[184:187], v[114:117]
	v_mfma_f32_16x16x32_bf16 v[102:105], v[154:157], v[192:195], v[102:105]
	v_mfma_f32_16x16x32_bf16 v[98:101], v[168:171], v[192:195], v[98:101]
	v_mfma_f32_16x16x32_bf16 v[86:89], v[154:157], v[200:203], v[86:89]
	v_mfma_f32_16x16x32_bf16 v[82:85], v[168:171], v[200:203], v[82:85]
	s_setprio 0
	s_barrier
	s_add_i32 s12, 0, 0x1c000
	s_add_i32 s9, s9, s61
	v_add_u32_e32 v142, s12, v163
	v_lshl_add_u64 v[220:221], v[220:221], 0, s[46:47]
	s_mov_b32 m0, s9
	ds_read_b128 v[204:207], v142
	ds_read_b128 v[208:211], v142 offset:1024
	ds_read_b128 v[212:215], v142 offset:2048
	ds_read_b128 v[216:219], v142 offset:3072
	global_load_lds_dwordx4 v[220:221], off
	v_lshl_add_u64 v[220:221], v[222:223], 0, s[46:47]
	s_add_i32 m0, s9, 0x2000
	s_nop 0
	global_load_lds_dwordx4 v[220:221], off
	s_barrier
	s_waitcnt lgkmcnt(0)
	s_setprio 1
	s_waitcnt lgkmcnt(0)
	v_mfma_f32_16x16x32_bf16 v[110:113], v[204:207], v[172:175], v[110:113]
	v_mfma_f32_16x16x32_bf16 v[106:109], v[212:215], v[172:175], v[106:109]
	v_mfma_f32_16x16x32_bf16 v[94:97], v[204:207], v[180:183], v[94:97]
	v_mfma_f32_16x16x32_bf16 v[90:93], v[212:215], v[180:183], v[90:93]
	v_mfma_f32_16x16x32_bf16 v[78:81], v[204:207], v[188:191], v[78:81]
	v_mfma_f32_16x16x32_bf16 v[74:77], v[212:215], v[188:191], v[74:77]
	v_mfma_f32_16x16x32_bf16 v[70:73], v[204:207], v[196:199], v[70:73]
	v_mfma_f32_16x16x32_bf16 v[66:69], v[212:215], v[196:199], v[66:69]
	v_mfma_f32_16x16x32_bf16 v[110:113], v[208:211], v[176:179], v[110:113]
	v_mfma_f32_16x16x32_bf16 v[106:109], v[216:219], v[176:179], v[106:109]
	v_mfma_f32_16x16x32_bf16 v[94:97], v[208:211], v[184:187], v[94:97]
	v_mfma_f32_16x16x32_bf16 v[90:93], v[216:219], v[184:187], v[90:93]
	v_mfma_f32_16x16x32_bf16 v[78:81], v[208:211], v[192:195], v[78:81]
	v_mfma_f32_16x16x32_bf16 v[74:77], v[216:219], v[192:195], v[74:77]
	v_mfma_f32_16x16x32_bf16 v[70:73], v[208:211], v[200:203], v[70:73]
	v_mfma_f32_16x16x32_bf16 v[66:69], v[216:219], v[200:203], v[66:69]
	s_setprio 0
	s_mov_b32 m0, s69
	v_lshl_add_u64 v[220:221], v[224:225], 0, s[46:47]
	s_barrier
	ds_read_b128 v[172:175], v166 offset:49152
	ds_read_b128 v[176:179], v166 offset:50176
	ds_read_b128 v[180:183], v166 offset:51200
	ds_read_b128 v[184:187], v166 offset:52224
	ds_read_b128 v[188:191], v166 offset:53248
	ds_read_b128 v[192:195], v166 offset:54272
	ds_read_b128 v[196:199], v166 offset:55296
	ds_read_b128 v[200:203], v166 offset:56320
	global_load_lds_dwordx4 v[220:221], off
	v_lshl_add_u64 v[220:221], v[226:227], 0, s[46:47]
	s_mov_b32 m0, s70
	s_nop 0
	global_load_lds_dwordx4 v[220:221], off
	s_barrier
; __device__ __forceinline__ float sigmoidf_(float x) { return 1.0f / (1.0f + __expf(-x)); }
; __device__ __forceinline__ float siluf_(float x) { return x / (1.0f + __expf(-x)); }
; __device__ __forceinline__ float tanhf_(float x) { return 1.0f - 2.0f / (1.0f + __expf(2.0f * x)); }
; __device__ __forceinline__ float gelu_tanh(float x) { const float z = 1.5957691216057308f * (x + 0.044715f * x * x * x); return x / (1.0f + __expf(-z)); }
; #define PG8_MMA(ai, bj, At, Bt) do { __builtin_amdgcn_s_setprio(1); _Pragma("unroll") for (int m = 0; m < 4; ++m) _Pragma("unroll") for (int n = 0; n < 2; ++n) _Pragma("unroll") for (int k = 0; k < 2; ++k) \
;         acc[ai][bj][m][n] = __builtin_amdgcn_mfma_f32_16x16x32_bf16(Bt[n][k], At[m][k], acc[ai][bj][m][n], 0, 0, 0); __builtin_amdgcn_s_setprio(0); } while (0)
; #define PG8_WAIT_V(n) asm volatile("s_waitcnt vmcnt(" #n ")" ::: "memory")
; #define PG8_BAR __builtin_amdgcn_s_barrier()
; template <class Epi, class GT>
; __device__ __forceinline__ void gemm_phase(LAS unsigned char* lds, const GT g, const StaticOrder& S, const Epi& E) {
;     ...
;             PG8_WAIT_V(6); PG8_BAR; PG8_MMA(1, 1, At, B1); PG8_BAR;
;         }
;         E(acc, cur, wr, wc, fr, fq);
; template <int ACT> __device__ __forceinline__ float actf(float x) {
;     if (ACT == 1) return gelu_tanh(x); if (ACT == 2) return tanhf_(x); if (ACT == 3) return sigmoidf_(x); if (ACT == 4) return siluf_(x); return x; }
; template <int ACT> __device__ __forceinline__ void store_tile_bf16(AccRef acc, bf16_t* dst, int ld, int row0, int col0) {
; #pragma unroll
;     for (int ai = 0; ai < 2; ++ai)
; #pragma unroll
;         for (int m = 0; m < 4; ++m) { bf16_t* rowp = dst + (size_t)(row0 + ai * 128 + m * 16) * ld + col0;
; #pragma unroll
;             for (int bj = 0; bj < 2; ++bj) { const f32x4 v0 = acc[ai][bj][m][0], v1 = acc[ai][bj][m][1];
;                 u32x4 w; w.x = cvt_pk_bf16(actf<ACT>(v0[0]), actf<ACT>(v0[1])); w.y = cvt_pk_bf16(actf<ACT>(v0[2]), actf<ACT>(v0[3]));
;                 w.z = cvt_pk_bf16(actf<ACT>(v1[0]), actf<ACT>(v1[1])); w.w = cvt_pk_bf16(actf<ACT>(v1[2]), actf<ACT>(v1[3]));
;                 *(u32x4*)(rowp + bj * 128) = w; } }
	s_waitcnt lgkmcnt(0)
	s_setprio 1
	s_waitcnt lgkmcnt(0)
	v_mfma_f32_16x16x32_bf16 v[62:65], v[130:133], v[172:175], v[62:65]
	v_mfma_f32_16x16x32_bf16 v[58:61], v[158:161], v[172:175], v[58:61]
	v_mfma_f32_16x16x32_bf16 v[54:57], v[130:133], v[180:183], v[54:57]
	v_mfma_f32_16x16x32_bf16 v[50:53], v[158:161], v[180:183], v[50:53]
	v_mfma_f32_16x16x32_bf16 v[38:41], v[130:133], v[188:191], v[38:41]
	v_mfma_f32_16x16x32_bf16 v[34:37], v[158:161], v[188:191], v[34:37]
	v_mfma_f32_16x16x32_bf16 v[22:25], v[130:133], v[196:199], v[22:25]
	v_mfma_f32_16x16x32_bf16 v[18:21], v[158:161], v[196:199], v[18:21]
	v_mfma_f32_16x16x32_bf16 v[62:65], v[154:157], v[176:179], v[62:65]
	v_mfma_f32_16x16x32_bf16 v[58:61], v[168:171], v[176:179], v[58:61]
	v_mfma_f32_16x16x32_bf16 v[54:57], v[154:157], v[184:187], v[54:57]
	v_mfma_f32_16x16x32_bf16 v[50:53], v[168:171], v[184:187], v[50:53]
	v_mfma_f32_16x16x32_bf16 v[38:41], v[154:157], v[192:195], v[38:41]
	v_mfma_f32_16x16x32_bf16 v[34:37], v[168:171], v[192:195], v[34:37]
	v_mfma_f32_16x16x32_bf16 v[22:25], v[154:157], v[200:203], v[22:25]
	v_mfma_f32_16x16x32_bf16 v[18:21], v[168:171], v[200:203], v[18:21]
	s_setprio 0
	s_barrier
	s_add_u32 s10, s44, 0x80080
	s_addc_u32 s11, s45, 0
	s_add_i32 s9, s12, s61
	v_lshl_add_u64 v[130:131], s[10:11], 0, v[138:139]
	s_mov_b32 m0, s9
	s_nop 0
	global_load_lds_dwordx4 v[130:131], off
	v_lshl_add_u64 v[130:131], s[10:11], 0, v[134:135]
	s_add_i32 m0, s9, 0x2000
	s_nop 0
	global_load_lds_dwordx4 v[130:131], off
	s_waitcnt vmcnt(6)
	s_barrier
	s_setprio 1
	v_mfma_f32_16x16x32_bf16 v[46:49], v[204:207], v[172:175], v[46:49]
	v_mfma_f32_16x16x32_bf16 v[42:45], v[212:215], v[172:175], v[42:45]
	v_mfma_f32_16x16x32_bf16 v[30:33], v[204:207], v[180:183], v[30:33]
	v_mfma_f32_16x16x32_bf16 v[26:29], v[212:215], v[180:183], v[26:29]
	v_mfma_f32_16x16x32_bf16 v[14:17], v[204:207], v[188:191], v[14:17]
	v_mfma_f32_16x16x32_bf16 v[10:13], v[212:215], v[188:191], v[10:13]
	v_mfma_f32_16x16x32_bf16 v[6:9], v[204:207], v[196:199], v[6:9]
	v_mfma_f32_16x16x32_bf16 v[2:5], v[212:215], v[196:199], v[2:5]
	v_mfma_f32_16x16x32_bf16 v[46:49], v[208:211], v[176:179], v[46:49]
	v_mfma_f32_16x16x32_bf16 v[42:45], v[216:219], v[176:179], v[42:45]
	v_mfma_f32_16x16x32_bf16 v[30:33], v[208:211], v[184:187], v[30:33]
	v_mfma_f32_16x16x32_bf16 v[26:29], v[216:219], v[184:187], v[26:29]
	v_mfma_f32_16x16x32_bf16 v[14:17], v[208:211], v[192:195], v[14:17]
	v_mfma_f32_16x16x32_bf16 v[10:13], v[216:219], v[192:195], v[10:13]
	v_mfma_f32_16x16x32_bf16 v[6:9], v[208:211], v[200:203], v[6:9]
	v_mfma_f32_16x16x32_bf16 v[2:5], v[216:219], v[200:203], v[2:5]
	s_setprio 0
	s_add_i32 s8, s8, 2
	s_add_u32 s4, s4, 0x100
	s_addc_u32 s5, s5, 0
	s_cmp_gt_u32 s8, 29
	s_mov_b64 s[38:39], s[40:41]
	s_barrier
	s_cbranch_scc0 .LBB0_1608
	v_lshl_add_u32 v154, s3, 8, v162
	s_cmp_gt_i32 s71, 23
	s_mov_b64 s[0:1], -1
	s_cbranch_scc0 .LBB0_1619
	v_mad_i64_i32 v[156:157], s[0:1], v154, s74, 0
	s_cmp_lt_i32 s71, 25
	s_mov_b64 s[0:1], -1
	s_cbranch_scc1 .LBB0_1616
	s_cmp_lg_u32 s71, 25
	s_cbranch_scc0 .LBB0_1613
	v_mul_f32_e32 v130, 0xbfb8aa3b, v126
	v_exp_f32_e32 v130, v130
	v_lshl_add_u64 v[158:159], v[144:145], 0, v[156:157]
	v_add_f32_e32 v130, 1.0, v130
	v_rcp_f32_e32 v130, v130
	v_mul_f32_e32 v131, 0xbfb8aa3b, v127
	v_exp_f32_e32 v131, v131
	s_nop 0
	v_add_f32_e32 v131, 1.0, v131
	v_rcp_f32_e32 v131, v131
	s_nop 0
	v_cvt_pk_bf16_f32 v130, v130, v131
	v_mul_f32_e32 v131, 0xbfb8aa3b, v128
	v_exp_f32_e32 v131, v131
	s_nop 0
	v_add_f32_e32 v131, 1.0, v131
	v_rcp_f32_e32 v131, v131
	v_mul_f32_e32 v132, 0xbfb8aa3b, v129
	v_exp_f32_e32 v132, v132
	s_nop 0
	v_add_f32_e32 v132, 1.0, v132
	v_rcp_f32_e32 v132, v132
	s_nop 0
	v_cvt_pk_bf16_f32 v131, v131, v132
	v_mul_f32_e32 v132, 0xbfb8aa3b, v122
	v_exp_f32_e32 v132, v132
	s_nop 0
	v_add_f32_e32 v132, 1.0, v132
	v_rcp_f32_e32 v132, v132
	v_mul_f32_e32 v133, 0xbfb8aa3b, v123
	v_exp_f32_e32 v133, v133
	s_nop 0
	v_add_f32_e32 v133, 1.0, v133
	v_rcp_f32_e32 v133, v133
	s_nop 0
	v_cvt_pk_bf16_f32 v132, v132, v133
	v_mul_f32_e32 v133, 0xbfb8aa3b, v124
	v_exp_f32_e32 v133, v133
	s_nop 0
	v_add_f32_e32 v133, 1.0, v133
	v_rcp_f32_e32 v133, v133
	v_mul_f32_e32 v142, 0xbfb8aa3b, v125
	v_exp_f32_e32 v142, v142
	s_nop 0
	v_add_f32_e32 v142, 1.0, v142
	v_rcp_f32_e32 v142, v142
	s_nop 0
	v_cvt_pk_bf16_f32 v133, v133, v142
	global_store_dwordx4 v[158:159], v[130:133], off offset:1024
	s_nop 1
	v_mul_f32_e32 v130, 0xbfb8aa3b, v110
	v_exp_f32_e32 v130, v130
	s_nop 0
	v_add_f32_e32 v130, 1.0, v130
	v_rcp_f32_e32 v130, v130
	v_mul_f32_e32 v131, 0xbfb8aa3b, v111
	v_exp_f32_e32 v131, v131
	s_nop 0
	v_add_f32_e32 v131, 1.0, v131
	v_rcp_f32_e32 v131, v131
	s_nop 0
	v_cvt_pk_bf16_f32 v130, v130, v131
	v_mul_f32_e32 v131, 0xbfb8aa3b, v112
	v_exp_f32_e32 v131, v131
	s_nop 0
	v_add_f32_e32 v131, 1.0, v131
	v_rcp_f32_e32 v131, v131
	v_mul_f32_e32 v132, 0xbfb8aa3b, v113
	v_exp_f32_e32 v132, v132
	s_nop 0
	v_add_f32_e32 v132, 1.0, v132
	v_rcp_f32_e32 v132, v132
	s_nop 0
	v_cvt_pk_bf16_f32 v131, v131, v132
	v_mul_f32_e32 v132, 0xbfb8aa3b, v106
	v_exp_f32_e32 v132, v132
	s_nop 0
	v_add_f32_e32 v132, 1.0, v132
	v_rcp_f32_e32 v132, v132
	v_mul_f32_e32 v133, 0xbfb8aa3b, v107
	v_exp_f32_e32 v133, v133
	s_nop 0
	v_add_f32_e32 v133, 1.0, v133
	v_rcp_f32_e32 v133, v133
	s_nop 0
	v_cvt_pk_bf16_f32 v132, v132, v133
	v_mul_f32_e32 v133, 0xbfb8aa3b, v108
	v_exp_f32_e32 v133, v133
	s_nop 0
	v_add_f32_e32 v133, 1.0, v133
	v_rcp_f32_e32 v133, v133
	v_mul_f32_e32 v142, 0xbfb8aa3b, v109
	v_exp_f32_e32 v142, v142
	s_nop 0
	v_add_f32_e32 v142, 1.0, v142
	v_rcp_f32_e32 v142, v142
	s_nop 0
	v_cvt_pk_bf16_f32 v133, v133, v142
; __device__ __forceinline__ float sigmoidf_(float x) { return 1.0f / (1.0f + __expf(-x)); }
; template <int ACT> __device__ __forceinline__ void store_tile_bf16(AccRef acc, bf16_t* dst, int ld, int row0, int col0) {
; #pragma unroll
;     for (int ai = 0; ai < 2; ++ai)
; #pragma unroll
;         for (int m = 0; m < 4; ++m) { bf16_t* rowp = dst + (size_t)(row0 + ai * 128 + m * 16) * ld + col0;
; #pragma unroll
;             for (int bj = 0; bj < 2; ++bj) { const f32x4 v0 = acc[ai][bj][m][0], v1 = acc[ai][bj][m][1];
;                 u32x4 w; w.x = cvt_pk_bf16(actf<ACT>(v0[0]), actf<ACT>(v0[1])); w.y = cvt_pk_bf16(actf<ACT>(v0[2]), actf<ACT>(v0[3]));
;                 w.z = cvt_pk_bf16(actf<ACT>(v1[0]), actf<ACT>(v1[1])); w.w = cvt_pk_bf16(actf<ACT>(v1[2]), actf<ACT>(v1[3]));
;                 *(u32x4*)(rowp + bj * 128) = w; } }
; }
	global_store_dwordx4 v[158:159], v[130:133], off offset:1280
	s_nop 1
	v_or_b32_e32 v130, 16, v154
	v_mad_i64_i32 v[158:159], s[0:1], v130, s74, v[144:145]
	v_mul_f32_e32 v130, 0xbfb8aa3b, v118
	v_exp_f32_e32 v130, v130
	s_nop 0
	v_add_f32_e32 v130, 1.0, v130
	v_rcp_f32_e32 v130, v130
	v_mul_f32_e32 v131, 0xbfb8aa3b, v119
	v_exp_f32_e32 v131, v131
	s_nop 0
	v_add_f32_e32 v131, 1.0, v131
	v_rcp_f32_e32 v131, v131
	s_nop 0
	v_cvt_pk_bf16_f32 v130, v130, v131
	v_mul_f32_e32 v131, 0xbfb8aa3b, v120
	v_exp_f32_e32 v131, v131
	s_nop 0
	v_add_f32_e32 v131, 1.0, v131
	v_rcp_f32_e32 v131, v131
	v_mul_f32_e32 v132, 0xbfb8aa3b, v121
	v_exp_f32_e32 v132, v132
	s_nop 0
	v_add_f32_e32 v132, 1.0, v132
	v_rcp_f32_e32 v132, v132
	s_nop 0
	v_cvt_pk_bf16_f32 v131, v131, v132
	v_mul_f32_e32 v132, 0xbfb8aa3b, v114
	v_exp_f32_e32 v132, v132
	s_nop 0
	v_add_f32_e32 v132, 1.0, v132
	v_rcp_f32_e32 v132, v132
	v_mul_f32_e32 v133, 0xbfb8aa3b, v115
	v_exp_f32_e32 v133, v133
	s_nop 0
	v_add_f32_e32 v133, 1.0, v133
	v_rcp_f32_e32 v133, v133
	s_nop 0
	v_cvt_pk_bf16_f32 v132, v132, v133
	v_mul_f32_e32 v133, 0xbfb8aa3b, v116
	v_exp_f32_e32 v133, v133
	s_nop 0
	v_add_f32_e32 v133, 1.0, v133
	v_rcp_f32_e32 v133, v133
	v_mul_f32_e32 v142, 0xbfb8aa3b, v117
	v_exp_f32_e32 v142, v142
	s_nop 0
	v_add_f32_e32 v142, 1.0, v142
	v_rcp_f32_e32 v142, v142
	s_nop 0
	v_cvt_pk_bf16_f32 v133, v133, v142
	global_store_dwordx4 v[158:159], v[130:133], off offset:1024
	s_nop 1
	v_mul_f32_e32 v130, 0xbfb8aa3b, v94
	v_exp_f32_e32 v130, v130
	s_nop 0
	v_add_f32_e32 v130, 1.0, v130
	v_rcp_f32_e32 v130, v130
	v_mul_f32_e32 v131, 0xbfb8aa3b, v95
	v_exp_f32_e32 v131, v131
	s_nop 0
	v_add_f32_e32 v131, 1.0, v131
	v_rcp_f32_e32 v131, v131
	s_nop 0
	v_cvt_pk_bf16_f32 v130, v130, v131
	v_mul_f32_e32 v131, 0xbfb8aa3b, v96
	v_exp_f32_e32 v131, v131
	s_nop 0
	v_add_f32_e32 v131, 1.0, v131
	v_rcp_f32_e32 v131, v131
	v_mul_f32_e32 v132, 0xbfb8aa3b, v97
	v_exp_f32_e32 v132, v132
	s_nop 0
	v_add_f32_e32 v132, 1.0, v132
	v_rcp_f32_e32 v132, v132
	s_nop 0
	v_cvt_pk_bf16_f32 v131, v131, v132
	v_mul_f32_e32 v132, 0xbfb8aa3b, v90
	v_exp_f32_e32 v132, v132
	s_nop 0
	v_add_f32_e32 v132, 1.0, v132
	v_rcp_f32_e32 v132, v132
	v_mul_f32_e32 v133, 0xbfb8aa3b, v91
	v_exp_f32_e32 v133, v133
	s_nop 0
	v_add_f32_e32 v133, 1.0, v133
	v_rcp_f32_e32 v133, v133
	s_nop 0
	v_cvt_pk_bf16_f32 v132, v132, v133
	v_mul_f32_e32 v133, 0xbfb8aa3b, v92
	v_exp_f32_e32 v133, v133
	s_nop 0
	v_add_f32_e32 v133, 1.0, v133
	v_rcp_f32_e32 v133, v133
	v_mul_f32_e32 v142, 0xbfb8aa3b, v93
	v_exp_f32_e32 v142, v142
	s_nop 0
	v_add_f32_e32 v142, 1.0, v142
	v_rcp_f32_e32 v142, v142
	s_nop 0
	v_cvt_pk_bf16_f32 v133, v133, v142
	global_store_dwordx4 v[158:159], v[130:133], off offset:1280
	s_nop 1
	v_or_b32_e32 v130, 32, v154
	v_mad_i64_i32 v[158:159], s[0:1], v130, s74, v[144:145]
	v_mul_f32_e32 v130, 0xbfb8aa3b, v102
	v_exp_f32_e32 v130, v130
	s_nop 0
	v_add_f32_e32 v130, 1.0, v130
	v_rcp_f32_e32 v130, v130
	v_mul_f32_e32 v131, 0xbfb8aa3b, v103
	v_exp_f32_e32 v131, v131
	s_nop 0
	v_add_f32_e32 v131, 1.0, v131
	v_rcp_f32_e32 v131, v131
	s_nop 0
	v_cvt_pk_bf16_f32 v130, v130, v131
	v_mul_f32_e32 v131, 0xbfb8aa3b, v104
	v_exp_f32_e32 v131, v131
	s_nop 0
	v_add_f32_e32 v131, 1.0, v131
	v_rcp_f32_e32 v131, v131
	v_mul_f32_e32 v132, 0xbfb8aa3b, v105
	v_exp_f32_e32 v132, v132
	s_nop 0
	v_add_f32_e32 v132, 1.0, v132
	v_rcp_f32_e32 v132, v132
	s_nop 0
	v_cvt_pk_bf16_f32 v131, v131, v132
	v_mul_f32_e32 v132, 0xbfb8aa3b, v98
	v_exp_f32_e32 v132, v132
	s_nop 0
	v_add_f32_e32 v132, 1.0, v132
	v_rcp_f32_e32 v132, v132
	v_mul_f32_e32 v133, 0xbfb8aa3b, v99
	v_exp_f32_e32 v133, v133
	s_nop 0
	v_add_f32_e32 v133, 1.0, v133
	v_rcp_f32_e32 v133, v133
	s_nop 0
	v_cvt_pk_bf16_f32 v132, v132, v133
	v_mul_f32_e32 v133, 0xbfb8aa3b, v100
	v_exp_f32_e32 v133, v133
	s_nop 0
	v_add_f32_e32 v133, 1.0, v133
	v_rcp_f32_e32 v133, v133
	v_mul_f32_e32 v142, 0xbfb8aa3b, v101
	v_exp_f32_e32 v142, v142
	s_nop 0
	v_add_f32_e32 v142, 1.0, v142
	v_rcp_f32_e32 v142, v142
	s_nop 0
	v_cvt_pk_bf16_f32 v133, v133, v142
	global_store_dwordx4 v[158:159], v[130:133], off offset:1024
	s_nop 1
	v_mul_f32_e32 v130, 0xbfb8aa3b, v78
	v_exp_f32_e32 v130, v130
	s_nop 0
	v_add_f32_e32 v130, 1.0, v130
	v_rcp_f32_e32 v130, v130
	v_mul_f32_e32 v131, 0xbfb8aa3b, v79
	v_exp_f32_e32 v131, v131
	s_nop 0
	v_add_f32_e32 v131, 1.0, v131
	v_rcp_f32_e32 v131, v131
	s_nop 0
	v_cvt_pk_bf16_f32 v130, v130, v131
	v_mul_f32_e32 v131, 0xbfb8aa3b, v80
	v_exp_f32_e32 v131, v131
	s_nop 0
	v_add_f32_e32 v131, 1.0, v131
	v_rcp_f32_e32 v131, v131
	v_mul_f32_e32 v132, 0xbfb8aa3b, v81
	v_exp_f32_e32 v132, v132
	s_nop 0
	v_add_f32_e32 v132, 1.0, v132
	v_rcp_f32_e32 v132, v132
	s_nop 0
	v_cvt_pk_bf16_f32 v131, v131, v132
	v_mul_f32_e32 v132, 0xbfb8aa3b, v74
	v_exp_f32_e32 v132, v132
	s_nop 0
	v_add_f32_e32 v132, 1.0, v132
	v_rcp_f32_e32 v132, v132
	v_mul_f32_e32 v133, 0xbfb8aa3b, v75
	v_exp_f32_e32 v133, v133
	s_nop 0
	v_add_f32_e32 v133, 1.0, v133
	v_rcp_f32_e32 v133, v133
	s_nop 0
	v_cvt_pk_bf16_f32 v132, v132, v133
	v_mul_f32_e32 v133, 0xbfb8aa3b, v76
	v_exp_f32_e32 v133, v133
	s_nop 0
	v_add_f32_e32 v133, 1.0, v133
	v_rcp_f32_e32 v133, v133
	v_mul_f32_e32 v142, 0xbfb8aa3b, v77
	v_exp_f32_e32 v142, v142
	s_nop 0
	v_add_f32_e32 v142, 1.0, v142
	v_rcp_f32_e32 v142, v142
	s_nop 0
	v_cvt_pk_bf16_f32 v133, v133, v142
	global_store_dwordx4 v[158:159], v[130:133], off offset:1280
	s_nop 1
	v_or_b32_e32 v130, 48, v154
	v_mad_i64_i32 v[158:159], s[0:1], v130, s74, v[144:145]
	v_mul_f32_e32 v130, 0xbfb8aa3b, v86
	v_exp_f32_e32 v130, v130
	s_nop 0
	v_add_f32_e32 v130, 1.0, v130
	v_rcp_f32_e32 v130, v130
	v_mul_f32_e32 v131, 0xbfb8aa3b, v87
; __device__ __forceinline__ float sigmoidf_(float x) { return 1.0f / (1.0f + __expf(-x)); }
; template <int ACT> __device__ __forceinline__ void store_tile_bf16(AccRef acc, bf16_t* dst, int ld, int row0, int col0) {
; #pragma unroll
;     for (int ai = 0; ai < 2; ++ai)
; #pragma unroll
;         for (int m = 0; m < 4; ++m) { bf16_t* rowp = dst + (size_t)(row0 + ai * 128 + m * 16) * ld + col0;
; #pragma unroll
;             for (int bj = 0; bj < 2; ++bj) { const f32x4 v0 = acc[ai][bj][m][0], v1 = acc[ai][bj][m][1];
;                 u32x4 w; w.x = cvt_pk_bf16(actf<ACT>(v0[0]), actf<ACT>(v0[1])); w.y = cvt_pk_bf16(actf<ACT>(v0[2]), actf<ACT>(v0[3]));
;                 w.z = cvt_pk_bf16(actf<ACT>(v1[0]), actf<ACT>(v1[1])); w.w = cvt_pk_bf16(actf<ACT>(v1[2]), actf<ACT>(v1[3]));
;                 *(u32x4*)(rowp + bj * 128) = w; } }
; }
	v_exp_f32_e32 v131, v131
	s_nop 0
	v_add_f32_e32 v131, 1.0, v131
	v_rcp_f32_e32 v131, v131
	s_nop 0
	v_cvt_pk_bf16_f32 v130, v130, v131
	v_mul_f32_e32 v131, 0xbfb8aa3b, v88
	v_exp_f32_e32 v131, v131
	s_nop 0
	v_add_f32_e32 v131, 1.0, v131
	v_rcp_f32_e32 v131, v131
	v_mul_f32_e32 v132, 0xbfb8aa3b, v89
	v_exp_f32_e32 v132, v132
	s_nop 0
	v_add_f32_e32 v132, 1.0, v132
	v_rcp_f32_e32 v132, v132
	s_nop 0
	v_cvt_pk_bf16_f32 v131, v131, v132
	v_mul_f32_e32 v132, 0xbfb8aa3b, v82
	v_exp_f32_e32 v132, v132
	s_nop 0
	v_add_f32_e32 v132, 1.0, v132
	v_rcp_f32_e32 v132, v132
	v_mul_f32_e32 v133, 0xbfb8aa3b, v83
	v_exp_f32_e32 v133, v133
	s_nop 0
	v_add_f32_e32 v133, 1.0, v133
	v_rcp_f32_e32 v133, v133
	s_nop 0
	v_cvt_pk_bf16_f32 v132, v132, v133
	v_mul_f32_e32 v133, 0xbfb8aa3b, v84
	v_exp_f32_e32 v133, v133
	s_nop 0
	v_add_f32_e32 v133, 1.0, v133
	v_rcp_f32_e32 v133, v133
	v_mul_f32_e32 v142, 0xbfb8aa3b, v85
	v_exp_f32_e32 v142, v142
	s_nop 0
	v_add_f32_e32 v142, 1.0, v142
	v_rcp_f32_e32 v142, v142
	s_nop 0
	v_cvt_pk_bf16_f32 v133, v133, v142
	global_store_dwordx4 v[158:159], v[130:133], off offset:1024
	s_nop 1
	v_mul_f32_e32 v130, 0xbfb8aa3b, v70
	v_exp_f32_e32 v130, v130
	s_nop 0
	v_add_f32_e32 v130, 1.0, v130
	v_rcp_f32_e32 v130, v130
	v_mul_f32_e32 v131, 0xbfb8aa3b, v71
	v_exp_f32_e32 v131, v131
	s_nop 0
	v_add_f32_e32 v131, 1.0, v131
	v_rcp_f32_e32 v131, v131
	s_nop 0
	v_cvt_pk_bf16_f32 v130, v130, v131
	v_mul_f32_e32 v131, 0xbfb8aa3b, v72
	v_exp_f32_e32 v131, v131
	s_nop 0
	v_add_f32_e32 v131, 1.0, v131
	v_rcp_f32_e32 v131, v131
	v_mul_f32_e32 v132, 0xbfb8aa3b, v73
	v_exp_f32_e32 v132, v132
	s_nop 0
	v_add_f32_e32 v132, 1.0, v132
	v_rcp_f32_e32 v132, v132
	s_nop 0
	v_cvt_pk_bf16_f32 v131, v131, v132
	v_mul_f32_e32 v132, 0xbfb8aa3b, v66
	v_exp_f32_e32 v132, v132
	s_nop 0
	v_add_f32_e32 v132, 1.0, v132
	v_rcp_f32_e32 v132, v132
	v_mul_f32_e32 v133, 0xbfb8aa3b, v67
	v_exp_f32_e32 v133, v133
	s_nop 0
	v_add_f32_e32 v133, 1.0, v133
	v_rcp_f32_e32 v133, v133
	s_nop 0
	v_cvt_pk_bf16_f32 v132, v132, v133
	v_mul_f32_e32 v133, 0xbfb8aa3b, v68
	v_exp_f32_e32 v133, v133
	s_nop 0
	v_add_f32_e32 v133, 1.0, v133
	v_rcp_f32_e32 v133, v133
	v_mul_f32_e32 v142, 0xbfb8aa3b, v69
	v_exp_f32_e32 v142, v142
	s_nop 0
	v_add_f32_e32 v142, 1.0, v142
	v_rcp_f32_e32 v142, v142
	s_nop 0
	v_cvt_pk_bf16_f32 v133, v133, v142
	global_store_dwordx4 v[158:159], v[130:133], off offset:1280
	s_nop 1
	v_add_u32_e32 v130, 0x80, v154
	v_mad_i64_i32 v[158:159], s[0:1], v130, s74, v[144:145]
	v_mul_f32_e32 v130, 0xbfb8aa3b, v62
	v_exp_f32_e32 v130, v130
	s_nop 0
	v_add_f32_e32 v130, 1.0, v130
	v_rcp_f32_e32 v130, v130
	v_mul_f32_e32 v131, 0xbfb8aa3b, v63
	v_exp_f32_e32 v131, v131
	s_nop 0
	v_add_f32_e32 v131, 1.0, v131
	v_rcp_f32_e32 v131, v131
	s_nop 0
	v_cvt_pk_bf16_f32 v130, v130, v131
	v_mul_f32_e32 v131, 0xbfb8aa3b, v64
	v_exp_f32_e32 v131, v131
	s_nop 0
	v_add_f32_e32 v131, 1.0, v131
	v_rcp_f32_e32 v131, v131
	v_mul_f32_e32 v132, 0xbfb8aa3b, v65
	v_exp_f32_e32 v132, v132
	s_nop 0
	v_add_f32_e32 v132, 1.0, v132
	v_rcp_f32_e32 v132, v132
	s_nop 0
	v_cvt_pk_bf16_f32 v131, v131, v132
	v_mul_f32_e32 v132, 0xbfb8aa3b, v58
	v_exp_f32_e32 v132, v132
	s_nop 0
	v_add_f32_e32 v132, 1.0, v132
	v_rcp_f32_e32 v132, v132
	v_mul_f32_e32 v133, 0xbfb8aa3b, v59
	v_exp_f32_e32 v133, v133
	s_nop 0
	v_add_f32_e32 v133, 1.0, v133
	v_rcp_f32_e32 v133, v133
	s_nop 0
	v_cvt_pk_bf16_f32 v132, v132, v133
	v_mul_f32_e32 v133, 0xbfb8aa3b, v60
	v_exp_f32_e32 v133, v133
	s_nop 0
	v_add_f32_e32 v133, 1.0, v133
	v_rcp_f32_e32 v133, v133
	v_mul_f32_e32 v142, 0xbfb8aa3b, v61
	v_exp_f32_e32 v142, v142
	s_nop 0
	v_add_f32_e32 v142, 1.0, v142
	v_rcp_f32_e32 v142, v142
	s_nop 0
	v_cvt_pk_bf16_f32 v133, v133, v142
	global_store_dwordx4 v[158:159], v[130:133], off offset:1024
	s_nop 1
	v_mul_f32_e32 v130, 0xbfb8aa3b, v46
	v_exp_f32_e32 v130, v130
	s_nop 0
	v_add_f32_e32 v130, 1.0, v130
	v_rcp_f32_e32 v130, v130
	v_mul_f32_e32 v131, 0xbfb8aa3b, v47
	v_exp_f32_e32 v131, v131
	s_nop 0
	v_add_f32_e32 v131, 1.0, v131
	v_rcp_f32_e32 v131, v131
	s_nop 0
	v_cvt_pk_bf16_f32 v130, v130, v131
	v_mul_f32_e32 v131, 0xbfb8aa3b, v48
	v_exp_f32_e32 v131, v131
	s_nop 0
	v_add_f32_e32 v131, 1.0, v131
	v_rcp_f32_e32 v131, v131
	v_mul_f32_e32 v132, 0xbfb8aa3b, v49
	v_exp_f32_e32 v132, v132
	s_nop 0
	v_add_f32_e32 v132, 1.0, v132
	v_rcp_f32_e32 v132, v132
	s_nop 0
	v_cvt_pk_bf16_f32 v131, v131, v132
	v_mul_f32_e32 v132, 0xbfb8aa3b, v42
	v_exp_f32_e32 v132, v132
	s_nop 0
	v_add_f32_e32 v132, 1.0, v132
	v_rcp_f32_e32 v132, v132
	v_mul_f32_e32 v133, 0xbfb8aa3b, v43
	v_exp_f32_e32 v133, v133
	s_nop 0
	v_add_f32_e32 v133, 1.0, v133
	v_rcp_f32_e32 v133, v133
	s_nop 0
	v_cvt_pk_bf16_f32 v132, v132, v133
	v_mul_f32_e32 v133, 0xbfb8aa3b, v44
	v_exp_f32_e32 v133, v133
	s_nop 0
	v_add_f32_e32 v133, 1.0, v133
	v_rcp_f32_e32 v133, v133
	v_mul_f32_e32 v142, 0xbfb8aa3b, v45
	v_exp_f32_e32 v142, v142
	s_nop 0
	v_add_f32_e32 v142, 1.0, v142
	v_rcp_f32_e32 v142, v142
	s_nop 0
	v_cvt_pk_bf16_f32 v133, v133, v142
	global_store_dwordx4 v[158:159], v[130:133], off offset:1280
	s_nop 1
	v_add_u32_e32 v130, 0x90, v154
	v_mad_i64_i32 v[158:159], s[0:1], v130, s74, v[144:145]
	v_mul_f32_e32 v130, 0xbfb8aa3b, v54
	v_exp_f32_e32 v130, v130
	s_nop 0
	v_add_f32_e32 v130, 1.0, v130
	v_rcp_f32_e32 v130, v130
	v_mul_f32_e32 v131, 0xbfb8aa3b, v55
	v_exp_f32_e32 v131, v131
	s_nop 0
	v_add_f32_e32 v131, 1.0, v131
	v_rcp_f32_e32 v131, v131
	s_nop 0
	v_cvt_pk_bf16_f32 v130, v130, v131
	v_mul_f32_e32 v131, 0xbfb8aa3b, v56
	v_exp_f32_e32 v131, v131
	s_nop 0
	v_add_f32_e32 v131, 1.0, v131
	v_rcp_f32_e32 v131, v131
	v_mul_f32_e32 v132, 0xbfb8aa3b, v57
	v_exp_f32_e32 v132, v132
; __device__ __forceinline__ float sigmoidf_(float x) { return 1.0f / (1.0f + __expf(-x)); }
; template <int ACT> __device__ __forceinline__ void store_tile_bf16(AccRef acc, bf16_t* dst, int ld, int row0, int col0) {
; #pragma unroll
;     for (int ai = 0; ai < 2; ++ai)
; #pragma unroll
;         for (int m = 0; m < 4; ++m) { bf16_t* rowp = dst + (size_t)(row0 + ai * 128 + m * 16) * ld + col0;
; #pragma unroll
;             for (int bj = 0; bj < 2; ++bj) { const f32x4 v0 = acc[ai][bj][m][0], v1 = acc[ai][bj][m][1];
;                 u32x4 w; w.x = cvt_pk_bf16(actf<ACT>(v0[0]), actf<ACT>(v0[1])); w.y = cvt_pk_bf16(actf<ACT>(v0[2]), actf<ACT>(v0[3]));
;                 w.z = cvt_pk_bf16(actf<ACT>(v1[0]), actf<ACT>(v1[1])); w.w = cvt_pk_bf16(actf<ACT>(v1[2]), actf<ACT>(v1[3]));
;                 *(u32x4*)(rowp + bj * 128) = w; } }
; }
	s_nop 0
	v_add_f32_e32 v132, 1.0, v132
	v_rcp_f32_e32 v132, v132
	s_nop 0
	v_cvt_pk_bf16_f32 v131, v131, v132
	v_mul_f32_e32 v132, 0xbfb8aa3b, v50
	v_exp_f32_e32 v132, v132
	s_nop 0
	v_add_f32_e32 v132, 1.0, v132
	v_rcp_f32_e32 v132, v132
	v_mul_f32_e32 v133, 0xbfb8aa3b, v51
	v_exp_f32_e32 v133, v133
	s_nop 0
	v_add_f32_e32 v133, 1.0, v133
	v_rcp_f32_e32 v133, v133
	s_nop 0
	v_cvt_pk_bf16_f32 v132, v132, v133
	v_mul_f32_e32 v133, 0xbfb8aa3b, v52
	v_exp_f32_e32 v133, v133
	s_nop 0
	v_add_f32_e32 v133, 1.0, v133
	v_rcp_f32_e32 v133, v133
	v_mul_f32_e32 v142, 0xbfb8aa3b, v53
	v_exp_f32_e32 v142, v142
	s_nop 0
	v_add_f32_e32 v142, 1.0, v142
	v_rcp_f32_e32 v142, v142
	s_nop 0
	v_cvt_pk_bf16_f32 v133, v133, v142
	global_store_dwordx4 v[158:159], v[130:133], off offset:1024
	s_nop 1
	v_mul_f32_e32 v130, 0xbfb8aa3b, v30
	v_exp_f32_e32 v130, v130
	s_nop 0
	v_add_f32_e32 v130, 1.0, v130
	v_rcp_f32_e32 v130, v130
	v_mul_f32_e32 v131, 0xbfb8aa3b, v31
	v_exp_f32_e32 v131, v131
	s_nop 0
	v_add_f32_e32 v131, 1.0, v131
	v_rcp_f32_e32 v131, v131
	s_nop 0
	v_cvt_pk_bf16_f32 v130, v130, v131
	v_mul_f32_e32 v131, 0xbfb8aa3b, v32
	v_exp_f32_e32 v131, v131
	s_nop 0
	v_add_f32_e32 v131, 1.0, v131
	v_rcp_f32_e32 v131, v131
	v_mul_f32_e32 v132, 0xbfb8aa3b, v33
	v_exp_f32_e32 v132, v132
	s_nop 0
	v_add_f32_e32 v132, 1.0, v132
	v_rcp_f32_e32 v132, v132
	s_nop 0
	v_cvt_pk_bf16_f32 v131, v131, v132
	v_mul_f32_e32 v132, 0xbfb8aa3b, v26
	v_exp_f32_e32 v132, v132
	s_nop 0
	v_add_f32_e32 v132, 1.0, v132
	v_rcp_f32_e32 v132, v132
	v_mul_f32_e32 v133, 0xbfb8aa3b, v27
	v_exp_f32_e32 v133, v133
	s_nop 0
	v_add_f32_e32 v133, 1.0, v133
	v_rcp_f32_e32 v133, v133
	s_nop 0
	v_cvt_pk_bf16_f32 v132, v132, v133
	v_mul_f32_e32 v133, 0xbfb8aa3b, v28
	v_exp_f32_e32 v133, v133
	s_nop 0
	v_add_f32_e32 v133, 1.0, v133
	v_rcp_f32_e32 v133, v133
	v_mul_f32_e32 v142, 0xbfb8aa3b, v29
	v_exp_f32_e32 v142, v142
	s_nop 0
	v_add_f32_e32 v142, 1.0, v142
	v_rcp_f32_e32 v142, v142
	s_nop 0
	v_cvt_pk_bf16_f32 v133, v133, v142
	global_store_dwordx4 v[158:159], v[130:133], off offset:1280
	s_nop 1
	v_add_u32_e32 v130, 0xa0, v154
	v_mad_i64_i32 v[158:159], s[0:1], v130, s74, v[144:145]
	v_mul_f32_e32 v130, 0xbfb8aa3b, v38
	v_exp_f32_e32 v130, v130
	s_nop 0
	v_add_f32_e32 v130, 1.0, v130
	v_rcp_f32_e32 v130, v130
	v_mul_f32_e32 v131, 0xbfb8aa3b, v39
	v_exp_f32_e32 v131, v131
	s_nop 0
	v_add_f32_e32 v131, 1.0, v131
	v_rcp_f32_e32 v131, v131
	s_nop 0
	v_cvt_pk_bf16_f32 v130, v130, v131
	v_mul_f32_e32 v131, 0xbfb8aa3b, v40
	v_exp_f32_e32 v131, v131
	s_nop 0
	v_add_f32_e32 v131, 1.0, v131
	v_rcp_f32_e32 v131, v131
	v_mul_f32_e32 v132, 0xbfb8aa3b, v41
	v_exp_f32_e32 v132, v132
	s_nop 0
	v_add_f32_e32 v132, 1.0, v132
	v_rcp_f32_e32 v132, v132
	s_nop 0
	v_cvt_pk_bf16_f32 v131, v131, v132
	v_mul_f32_e32 v132, 0xbfb8aa3b, v34
	v_exp_f32_e32 v132, v132
	s_nop 0
	v_add_f32_e32 v132, 1.0, v132
	v_rcp_f32_e32 v132, v132
	v_mul_f32_e32 v133, 0xbfb8aa3b, v35
	v_exp_f32_e32 v133, v133
	s_nop 0
	v_add_f32_e32 v133, 1.0, v133
	v_rcp_f32_e32 v133, v133
	s_nop 0
	v_cvt_pk_bf16_f32 v132, v132, v133
	v_mul_f32_e32 v133, 0xbfb8aa3b, v36
	v_exp_f32_e32 v133, v133
	s_nop 0
	v_add_f32_e32 v133, 1.0, v133
	v_rcp_f32_e32 v133, v133
	v_mul_f32_e32 v142, 0xbfb8aa3b, v37
	v_exp_f32_e32 v142, v142
	s_nop 0
	v_add_f32_e32 v142, 1.0, v142
	v_rcp_f32_e32 v142, v142
	s_nop 0
	v_cvt_pk_bf16_f32 v133, v133, v142
	global_store_dwordx4 v[158:159], v[130:133], off offset:1024
	s_nop 1
	v_mul_f32_e32 v130, 0xbfb8aa3b, v14
	v_exp_f32_e32 v130, v130
	s_nop 0
	v_add_f32_e32 v130, 1.0, v130
	v_rcp_f32_e32 v130, v130
	v_mul_f32_e32 v131, 0xbfb8aa3b, v15
	v_exp_f32_e32 v131, v131
	s_nop 0
	v_add_f32_e32 v131, 1.0, v131
; __device__ __forceinline__ float sigmoidf_(float x) { return 1.0f / (1.0f + __expf(-x)); }
; template <int ACT> __device__ __forceinline__ void store_tile_bf16(AccRef acc, bf16_t* dst, int ld, int row0, int col0) {
; #pragma unroll
;     for (int ai = 0; ai < 2; ++ai)
; #pragma unroll
;         for (int m = 0; m < 4; ++m) { bf16_t* rowp = dst + (size_t)(row0 + ai * 128 + m * 16) * ld + col0;
; #pragma unroll
;             for (int bj = 0; bj < 2; ++bj) { const f32x4 v0 = acc[ai][bj][m][0], v1 = acc[ai][bj][m][1];
;                 u32x4 w; w.x = cvt_pk_bf16(actf<ACT>(v0[0]), actf<ACT>(v0[1])); w.y = cvt_pk_bf16(actf<ACT>(v0[2]), actf<ACT>(v0[3]));
;                 w.z = cvt_pk_bf16(actf<ACT>(v1[0]), actf<ACT>(v1[1])); w.w = cvt_pk_bf16(actf<ACT>(v1[2]), actf<ACT>(v1[3]));
;                 *(u32x4*)(rowp + bj * 128) = w; } }
; }
	v_rcp_f32_e32 v131, v131
	s_nop 0
	v_cvt_pk_bf16_f32 v130, v130, v131
	v_mul_f32_e32 v131, 0xbfb8aa3b, v16
	v_exp_f32_e32 v131, v131
	s_nop 0
	v_add_f32_e32 v131, 1.0, v131
	v_rcp_f32_e32 v131, v131
	v_mul_f32_e32 v132, 0xbfb8aa3b, v17
	v_exp_f32_e32 v132, v132
	s_nop 0
	v_add_f32_e32 v132, 1.0, v132
	v_rcp_f32_e32 v132, v132
	s_nop 0
	v_cvt_pk_bf16_f32 v131, v131, v132
	v_mul_f32_e32 v132, 0xbfb8aa3b, v10
	v_exp_f32_e32 v132, v132
	s_nop 0
	v_add_f32_e32 v132, 1.0, v132
	v_rcp_f32_e32 v132, v132
	v_mul_f32_e32 v133, 0xbfb8aa3b, v11
	v_exp_f32_e32 v133, v133
	s_nop 0
	v_add_f32_e32 v133, 1.0, v133
	v_rcp_f32_e32 v133, v133
	s_nop 0
	v_cvt_pk_bf16_f32 v132, v132, v133
	v_mul_f32_e32 v133, 0xbfb8aa3b, v12
	v_exp_f32_e32 v133, v133
	s_nop 0
	v_add_f32_e32 v133, 1.0, v133
	v_rcp_f32_e32 v133, v133
	v_mul_f32_e32 v142, 0xbfb8aa3b, v13
	v_exp_f32_e32 v142, v142
	s_nop 0
	v_add_f32_e32 v142, 1.0, v142
	v_rcp_f32_e32 v142, v142
	s_nop 0
	v_cvt_pk_bf16_f32 v133, v133, v142
	global_store_dwordx4 v[158:159], v[130:133], off offset:1280
	s_nop 1
	v_add_u32_e32 v130, 0xb0, v154
	v_mad_i64_i32 v[160:161], s[0:1], v130, s74, v[144:145]
	v_mul_f32_e32 v130, 0xbfb8aa3b, v22
	v_exp_f32_e32 v130, v130
	s_mov_b64 s[0:1], 0x400
	v_lshl_add_u64 v[158:159], v[160:161], 0, s[0:1]
	v_add_f32_e32 v130, 1.0, v130
	v_rcp_f32_e32 v130, v130
	v_mul_f32_e32 v131, 0xbfb8aa3b, v23
	v_exp_f32_e32 v131, v131
	s_nop 0
	v_add_f32_e32 v131, 1.0, v131
	v_rcp_f32_e32 v131, v131
	s_nop 0
	v_cvt_pk_bf16_f32 v130, v130, v131
	v_mul_f32_e32 v131, 0xbfb8aa3b, v24
	v_exp_f32_e32 v131, v131
	s_nop 0
	v_add_f32_e32 v131, 1.0, v131
	v_rcp_f32_e32 v131, v131
	v_mul_f32_e32 v132, 0xbfb8aa3b, v25
	v_exp_f32_e32 v132, v132
	s_nop 0
	v_add_f32_e32 v132, 1.0, v132
	v_rcp_f32_e32 v132, v132
	s_nop 0
	v_cvt_pk_bf16_f32 v131, v131, v132
	v_mul_f32_e32 v132, 0xbfb8aa3b, v18
	v_exp_f32_e32 v132, v132
	s_nop 0
	v_add_f32_e32 v132, 1.0, v132
	v_rcp_f32_e32 v132, v132
	v_mul_f32_e32 v133, 0xbfb8aa3b, v19
	v_exp_f32_e32 v133, v133
	s_nop 0
	v_add_f32_e32 v133, 1.0, v133
	v_rcp_f32_e32 v133, v133
	s_nop 0
	v_cvt_pk_bf16_f32 v132, v132, v133
	v_mul_f32_e32 v133, 0xbfb8aa3b, v20
	v_exp_f32_e32 v133, v133
	s_nop 0
	v_add_f32_e32 v133, 1.0, v133
	v_rcp_f32_e32 v133, v133
	v_mul_f32_e32 v142, 0xbfb8aa3b, v21
	v_exp_f32_e32 v142, v142
	s_nop 0
	v_add_f32_e32 v142, 1.0, v142
	v_rcp_f32_e32 v142, v142
	s_nop 0
	v_cvt_pk_bf16_f32 v133, v133, v142
	global_store_dwordx4 v[160:161], v[130:133], off offset:1024
	s_nop 1
	v_mul_f32_e32 v130, 0xbfb8aa3b, v6
	v_exp_f32_e32 v130, v130
	s_nop 0
	v_add_f32_e32 v130, 1.0, v130
	v_rcp_f32_e32 v130, v130
	v_mul_f32_e32 v131, 0xbfb8aa3b, v7
	v_exp_f32_e32 v131, v131
	s_nop 0
	v_add_f32_e32 v131, 1.0, v131
	v_rcp_f32_e32 v131, v131
	s_nop 0
	v_cvt_pk_bf16_f32 v130, v130, v131
	v_mul_f32_e32 v131, 0xbfb8aa3b, v8
	v_exp_f32_e32 v131, v131
	s_nop 0
	v_add_f32_e32 v131, 1.0, v131
	v_rcp_f32_e32 v131, v131
	v_mul_f32_e32 v132, 0xbfb8aa3b, v9
	v_exp_f32_e32 v132, v132
	s_nop 0
	v_add_f32_e32 v132, 1.0, v132
	v_rcp_f32_e32 v132, v132
	s_nop 0
	v_cvt_pk_bf16_f32 v131, v131, v132
	v_mul_f32_e32 v132, 0xbfb8aa3b, v2
	v_exp_f32_e32 v132, v132
	s_nop 0
	v_add_f32_e32 v132, 1.0, v132
	v_rcp_f32_e32 v132, v132
	v_mul_f32_e32 v133, 0xbfb8aa3b, v3
	v_exp_f32_e32 v133, v133
	s_nop 0
	v_add_f32_e32 v133, 1.0, v133
	v_rcp_f32_e32 v133, v133
	s_nop 0
	v_cvt_pk_bf16_f32 v132, v132, v133
	v_mul_f32_e32 v133, 0xbfb8aa3b, v4
	v_exp_f32_e32 v160, v133
	v_mul_f32_e32 v133, 0xbfb8aa3b, v5
	v_exp_f32_e32 v161, v133
	s_nop 0
	v_pk_add_f32 v[160:161], v[160:161], 1.0 op_sel_hi:[1,0]
	s_nop 0
	v_rcp_f32_e32 v160, v160
	s_mov_b64 s[0:1], 0
	v_rcp_f32_e32 v161, v161

; __device__ __forceinline__ float tanhf_(float x) { return 1.0f - 2.0f / (1.0f + __expf(2.0f * x)); }
; template <int ACT> __device__ __forceinline__ void store_tile_bf16(AccRef acc, bf16_t* dst, int ld, int row0, int col0) {
; #pragma unroll
;     for (int ai = 0; ai < 2; ++ai)
; #pragma unroll
;         for (int m = 0; m < 4; ++m) { bf16_t* rowp = dst + (size_t)(row0 + ai * 128 + m * 16) * ld + col0;
; #pragma unroll
;             for (int bj = 0; bj < 2; ++bj) { const f32x4 v0 = acc[ai][bj][m][0], v1 = acc[ai][bj][m][1];
;                 u32x4 w; w.x = cvt_pk_bf16(actf<ACT>(v0[0]), actf<ACT>(v0[1])); w.y = cvt_pk_bf16(actf<ACT>(v0[2]), actf<ACT>(v0[3]));
;                 w.z = cvt_pk_bf16(actf<ACT>(v1[0]), actf<ACT>(v1[1])); w.w = cvt_pk_bf16(actf<ACT>(v1[2]), actf<ACT>(v1[3]));
;                 *(u32x4*)(rowp + bj * 128) = w; } }
; }
.LBB0_1616:
	s_andn2_b64 vcc, exec, s[0:1]
	s_cbranch_vccnz .LBB0_1618
	v_add_f32_e32 v130, v126, v126
	v_add_f32_e32 v131, v127, v127
	v_mul_f32_e32 v130, 0x3fb8aa3b, v130
	v_mul_f32_e32 v131, 0x3fb8aa3b, v131
	v_exp_f32_e32 v130, v130
	v_exp_f32_e32 v131, v131
	v_lshl_add_u64 v[156:157], v[144:145], 0, v[156:157]
	v_pk_add_f32 v[130:131], v[130:131], 1.0 op_sel_hi:[1,0]
	s_nop 0
	v_rcp_f32_e32 v131, v131
	s_nop 0
	v_mul_f32_e32 v131, 2.0, v131
	v_rcp_f32_e32 v130, v130
	s_nop 0
	v_mul_f32_e32 v130, 2.0, v130
	v_pk_add_f32 v[130:131], v[130:131], 1.0 op_sel_hi:[1,0] neg_lo:[1,0] neg_hi:[1,0]
	s_nop 0
	v_cvt_pk_bf16_f32 v130, v130, v131
	v_add_f32_e32 v131, v128, v128
	v_mul_f32_e32 v131, 0x3fb8aa3b, v131
	v_exp_f32_e32 v132, v131
	v_add_f32_e32 v131, v129, v129
	v_mul_f32_e32 v131, 0x3fb8aa3b, v131
	v_exp_f32_e32 v133, v131
	s_nop 0
	v_pk_add_f32 v[132:133], v[132:133], 1.0 op_sel_hi:[1,0]
	s_nop 0
	v_rcp_f32_e32 v133, v133
	s_nop 0
	v_mul_f32_e32 v133, 2.0, v133
	v_rcp_f32_e32 v132, v132
	s_nop 0
	v_mul_f32_e32 v132, 2.0, v132
	v_pk_add_f32 v[132:133], v[132:133], 1.0 op_sel_hi:[1,0] neg_lo:[1,0] neg_hi:[1,0]
	s_nop 0
	v_cvt_pk_bf16_f32 v131, v132, v133
	v_add_f32_e32 v132, v122, v122
	v_add_f32_e32 v133, v123, v123
	v_mul_f32_e32 v132, 0x3fb8aa3b, v132
	v_mul_f32_e32 v133, 0x3fb8aa3b, v133
	v_exp_f32_e32 v132, v132
	v_exp_f32_e32 v133, v133
	s_nop 0
	v_pk_add_f32 v[132:133], v[132:133], 1.0 op_sel_hi:[1,0]
	s_nop 0
	v_rcp_f32_e32 v133, v133
	s_nop 0
	v_mul_f32_e32 v133, 2.0, v133
	v_rcp_f32_e32 v132, v132
	s_nop 0
	v_mul_f32_e32 v132, 2.0, v132
	v_pk_add_f32 v[132:133], v[132:133], 1.0 op_sel_hi:[1,0] neg_lo:[1,0] neg_hi:[1,0]
	s_nop 0
	v_cvt_pk_bf16_f32 v132, v132, v133
	v_add_f32_e32 v133, v124, v124
	v_mul_f32_e32 v133, 0x3fb8aa3b, v133
	v_exp_f32_e32 v158, v133
	v_add_f32_e32 v133, v125, v125
	v_mul_f32_e32 v133, 0x3fb8aa3b, v133
	v_exp_f32_e32 v159, v133
	s_nop 0
	v_pk_add_f32 v[158:159], v[158:159], 1.0 op_sel_hi:[1,0]
	s_nop 0
	v_rcp_f32_e32 v159, v159
	s_nop 0
	v_mul_f32_e32 v159, 2.0, v159
	v_rcp_f32_e32 v158, v158
	s_nop 0
	v_mul_f32_e32 v158, 2.0, v158
	v_pk_add_f32 v[158:159], v[158:159], 1.0 op_sel_hi:[1,0] neg_lo:[1,0] neg_hi:[1,0]
	s_nop 0
	v_cvt_pk_bf16_f32 v133, v158, v159
	global_store_dwordx4 v[156:157], v[130:133], off
	s_nop 1
	v_add_f32_e32 v130, v110, v110
	v_add_f32_e32 v131, v111, v111
	v_mul_f32_e32 v130, 0x3fb8aa3b, v130
	v_mul_f32_e32 v131, 0x3fb8aa3b, v131
	v_exp_f32_e32 v130, v130
	v_exp_f32_e32 v131, v131
	s_nop 0
	v_pk_add_f32 v[130:131], v[130:131], 1.0 op_sel_hi:[1,0]
	s_nop 0
	v_rcp_f32_e32 v131, v131
	s_nop 0
	v_mul_f32_e32 v131, 2.0, v131
	v_rcp_f32_e32 v130, v130
	s_nop 0
	v_mul_f32_e32 v130, 2.0, v130
	v_pk_add_f32 v[130:131], v[130:131], 1.0 op_sel_hi:[1,0] neg_lo:[1,0] neg_hi:[1,0]
	s_nop 0
	v_cvt_pk_bf16_f32 v130, v130, v131
	v_add_f32_e32 v131, v112, v112
	v_mul_f32_e32 v131, 0x3fb8aa3b, v131
	v_exp_f32_e32 v132, v131
	v_add_f32_e32 v131, v113, v113
	v_mul_f32_e32 v131, 0x3fb8aa3b, v131
	v_exp_f32_e32 v133, v131
	s_nop 0
	v_pk_add_f32 v[132:133], v[132:133], 1.0 op_sel_hi:[1,0]
	s_nop 0
	v_rcp_f32_e32 v133, v133
	s_nop 0
	v_mul_f32_e32 v133, 2.0, v133
	v_rcp_f32_e32 v132, v132
	s_nop 0
	v_mul_f32_e32 v132, 2.0, v132
	v_pk_add_f32 v[132:133], v[132:133], 1.0 op_sel_hi:[1,0] neg_lo:[1,0] neg_hi:[1,0]
	s_nop 0
	v_cvt_pk_bf16_f32 v131, v132, v133
	v_add_f32_e32 v132, v106, v106
	v_add_f32_e32 v133, v107, v107
	v_mul_f32_e32 v132, 0x3fb8aa3b, v132
	v_mul_f32_e32 v133, 0x3fb8aa3b, v133
	v_exp_f32_e32 v132, v132
	v_exp_f32_e32 v133, v133
	s_nop 0
	v_pk_add_f32 v[132:133], v[132:133], 1.0 op_sel_hi:[1,0]
	s_nop 0
	v_rcp_f32_e32 v133, v133
	s_nop 0
	v_mul_f32_e32 v133, 2.0, v133
	v_rcp_f32_e32 v132, v132
	s_nop 0
	v_mul_f32_e32 v132, 2.0, v132
	v_pk_add_f32 v[132:133], v[132:133], 1.0 op_sel_hi:[1,0] neg_lo:[1,0] neg_hi:[1,0]
	s_nop 0
	v_cvt_pk_bf16_f32 v132, v132, v133
	v_add_f32_e32 v133, v108, v108
	v_mul_f32_e32 v133, 0x3fb8aa3b, v133
	v_exp_f32_e32 v158, v133
	v_add_f32_e32 v133, v109, v109
	v_mul_f32_e32 v133, 0x3fb8aa3b, v133
	v_exp_f32_e32 v159, v133
	s_nop 0
	v_pk_add_f32 v[158:159], v[158:159], 1.0 op_sel_hi:[1,0]
	s_nop 0
	v_rcp_f32_e32 v159, v159
	s_nop 0
	v_mul_f32_e32 v159, 2.0, v159
	v_rcp_f32_e32 v158, v158
	s_nop 0
	v_mul_f32_e32 v158, 2.0, v158
	v_pk_add_f32 v[158:159], v[158:159], 1.0 op_sel_hi:[1,0] neg_lo:[1,0] neg_hi:[1,0]
	s_nop 0
	v_cvt_pk_bf16_f32 v133, v158, v159
	global_store_dwordx4 v[156:157], v[130:133], off offset:256
	s_nop 1
	v_or_b32_e32 v130, 16, v154
	v_mad_i64_i32 v[156:157], s[0:1], v130, s74, v[144:145]
	v_add_f32_e32 v130, v118, v118
	v_add_f32_e32 v131, v119, v119
	v_mul_f32_e32 v130, 0x3fb8aa3b, v130
	v_mul_f32_e32 v131, 0x3fb8aa3b, v131
	v_exp_f32_e32 v130, v130
	v_exp_f32_e32 v131, v131
	s_nop 0
	v_pk_add_f32 v[130:131], v[130:131], 1.0 op_sel_hi:[1,0]
	s_nop 0
	v_rcp_f32_e32 v131, v131
	s_nop 0
	v_mul_f32_e32 v131, 2.0, v131
	v_rcp_f32_e32 v130, v130
	s_nop 0
	v_mul_f32_e32 v130, 2.0, v130
	v_pk_add_f32 v[130:131], v[130:131], 1.0 op_sel_hi:[1,0] neg_lo:[1,0] neg_hi:[1,0]
	s_nop 0
	v_cvt_pk_bf16_f32 v130, v130, v131
	v_add_f32_e32 v131, v120, v120
	v_mul_f32_e32 v131, 0x3fb8aa3b, v131
	v_exp_f32_e32 v132, v131
	v_add_f32_e32 v131, v121, v121
	v_mul_f32_e32 v131, 0x3fb8aa3b, v131
	v_exp_f32_e32 v133, v131
	s_nop 0
	v_pk_add_f32 v[132:133], v[132:133], 1.0 op_sel_hi:[1,0]
	s_nop 0
	v_rcp_f32_e32 v133, v133
	s_nop 0
	v_mul_f32_e32 v133, 2.0, v133
	v_rcp_f32_e32 v132, v132
	s_nop 0
	v_mul_f32_e32 v132, 2.0, v132
	v_pk_add_f32 v[132:133], v[132:133], 1.0 op_sel_hi:[1,0] neg_lo:[1,0] neg_hi:[1,0]
	s_nop 0
	v_cvt_pk_bf16_f32 v131, v132, v133
	v_add_f32_e32 v132, v114, v114
; __device__ __forceinline__ float tanhf_(float x) { return 1.0f - 2.0f / (1.0f + __expf(2.0f * x)); }
; template <int ACT> __device__ __forceinline__ void store_tile_bf16(AccRef acc, bf16_t* dst, int ld, int row0, int col0) {
; #pragma unroll
;     for (int ai = 0; ai < 2; ++ai)
; #pragma unroll
;         for (int m = 0; m < 4; ++m) { bf16_t* rowp = dst + (size_t)(row0 + ai * 128 + m * 16) * ld + col0;
; #pragma unroll
;             for (int bj = 0; bj < 2; ++bj) { const f32x4 v0 = acc[ai][bj][m][0], v1 = acc[ai][bj][m][1];
;                 u32x4 w; w.x = cvt_pk_bf16(actf<ACT>(v0[0]), actf<ACT>(v0[1])); w.y = cvt_pk_bf16(actf<ACT>(v0[2]), actf<ACT>(v0[3]));
;                 w.z = cvt_pk_bf16(actf<ACT>(v1[0]), actf<ACT>(v1[1])); w.w = cvt_pk_bf16(actf<ACT>(v1[2]), actf<ACT>(v1[3]));
;                 *(u32x4*)(rowp + bj * 128) = w; } }
; }
	v_add_f32_e32 v133, v115, v115
	v_mul_f32_e32 v132, 0x3fb8aa3b, v132
	v_mul_f32_e32 v133, 0x3fb8aa3b, v133
	v_exp_f32_e32 v132, v132
	v_exp_f32_e32 v133, v133
	s_nop 0
	v_pk_add_f32 v[132:133], v[132:133], 1.0 op_sel_hi:[1,0]
	s_nop 0
	v_rcp_f32_e32 v133, v133
	s_nop 0
	v_mul_f32_e32 v133, 2.0, v133
	v_rcp_f32_e32 v132, v132
	s_nop 0
	v_mul_f32_e32 v132, 2.0, v132
	v_pk_add_f32 v[132:133], v[132:133], 1.0 op_sel_hi:[1,0] neg_lo:[1,0] neg_hi:[1,0]
	s_nop 0
	v_cvt_pk_bf16_f32 v132, v132, v133
	v_add_f32_e32 v133, v116, v116
	v_mul_f32_e32 v133, 0x3fb8aa3b, v133
	v_exp_f32_e32 v158, v133
	v_add_f32_e32 v133, v117, v117
	v_mul_f32_e32 v133, 0x3fb8aa3b, v133
	v_exp_f32_e32 v159, v133
	s_nop 0
	v_pk_add_f32 v[158:159], v[158:159], 1.0 op_sel_hi:[1,0]
	s_nop 0
	v_rcp_f32_e32 v159, v159
	s_nop 0
	v_mul_f32_e32 v159, 2.0, v159
	v_rcp_f32_e32 v158, v158
	s_nop 0
	v_mul_f32_e32 v158, 2.0, v158
	v_pk_add_f32 v[158:159], v[158:159], 1.0 op_sel_hi:[1,0] neg_lo:[1,0] neg_hi:[1,0]
	s_nop 0
	v_cvt_pk_bf16_f32 v133, v158, v159
	global_store_dwordx4 v[156:157], v[130:133], off
	s_nop 1
	v_add_f32_e32 v130, v94, v94
	v_add_f32_e32 v131, v95, v95
	v_mul_f32_e32 v130, 0x3fb8aa3b, v130
	v_mul_f32_e32 v131, 0x3fb8aa3b, v131
	v_exp_f32_e32 v130, v130
	v_exp_f32_e32 v131, v131
	s_nop 0
	v_pk_add_f32 v[130:131], v[130:131], 1.0 op_sel_hi:[1,0]
	s_nop 0
	v_rcp_f32_e32 v131, v131
	s_nop 0
	v_mul_f32_e32 v131, 2.0, v131
	v_rcp_f32_e32 v130, v130
	s_nop 0
	v_mul_f32_e32 v130, 2.0, v130
	v_pk_add_f32 v[130:131], v[130:131], 1.0 op_sel_hi:[1,0] neg_lo:[1,0] neg_hi:[1,0]
	s_nop 0
	v_cvt_pk_bf16_f32 v130, v130, v131
	v_add_f32_e32 v131, v96, v96
	v_mul_f32_e32 v131, 0x3fb8aa3b, v131
	v_exp_f32_e32 v132, v131
	v_add_f32_e32 v131, v97, v97
	v_mul_f32_e32 v131, 0x3fb8aa3b, v131
	v_exp_f32_e32 v133, v131
	s_nop 0
	v_pk_add_f32 v[132:133], v[132:133], 1.0 op_sel_hi:[1,0]
	s_nop 0
	v_rcp_f32_e32 v133, v133
	s_nop 0
	v_mul_f32_e32 v133, 2.0, v133
	v_rcp_f32_e32 v132, v132
	s_nop 0
	v_mul_f32_e32 v132, 2.0, v132
	v_pk_add_f32 v[132:133], v[132:133], 1.0 op_sel_hi:[1,0] neg_lo:[1,0] neg_hi:[1,0]
	s_nop 0
	v_cvt_pk_bf16_f32 v131, v132, v133
	v_add_f32_e32 v132, v90, v90
	v_add_f32_e32 v133, v91, v91
	v_mul_f32_e32 v132, 0x3fb8aa3b, v132
	v_mul_f32_e32 v133, 0x3fb8aa3b, v133
	v_exp_f32_e32 v132, v132
	v_exp_f32_e32 v133, v133
	s_nop 0
	v_pk_add_f32 v[132:133], v[132:133], 1.0 op_sel_hi:[1,0]
	s_nop 0
	v_rcp_f32_e32 v133, v133
	s_nop 0
	v_mul_f32_e32 v133, 2.0, v133
	v_rcp_f32_e32 v132, v132
	s_nop 0
	v_mul_f32_e32 v132, 2.0, v132
	v_pk_add_f32 v[132:133], v[132:133], 1.0 op_sel_hi:[1,0] neg_lo:[1,0] neg_hi:[1,0]
	s_nop 0
	v_cvt_pk_bf16_f32 v132, v132, v133
	v_add_f32_e32 v133, v92, v92
	v_mul_f32_e32 v133, 0x3fb8aa3b, v133
	v_exp_f32_e32 v158, v133
	v_add_f32_e32 v133, v93, v93
	v_mul_f32_e32 v133, 0x3fb8aa3b, v133
	v_exp_f32_e32 v159, v133
	s_nop 0
	v_pk_add_f32 v[158:159], v[158:159], 1.0 op_sel_hi:[1,0]
	s_nop 0
	v_rcp_f32_e32 v159, v159
	s_nop 0
	v_mul_f32_e32 v159, 2.0, v159
	v_rcp_f32_e32 v158, v158
	s_nop 0
	v_mul_f32_e32 v158, 2.0, v158
	v_pk_add_f32 v[158:159], v[158:159], 1.0 op_sel_hi:[1,0] neg_lo:[1,0] neg_hi:[1,0]
	s_nop 0
	v_cvt_pk_bf16_f32 v133, v158, v159
	global_store_dwordx4 v[156:157], v[130:133], off offset:256
	s_nop 1
	v_or_b32_e32 v130, 32, v154
	v_mad_i64_i32 v[156:157], s[0:1], v130, s74, v[144:145]
	v_add_f32_e32 v130, v102, v102
	v_add_f32_e32 v131, v103, v103
	v_mul_f32_e32 v130, 0x3fb8aa3b, v130
	v_mul_f32_e32 v131, 0x3fb8aa3b, v131
	v_exp_f32_e32 v130, v130
	v_exp_f32_e32 v131, v131
	s_nop 0
	v_pk_add_f32 v[130:131], v[130:131], 1.0 op_sel_hi:[1,0]
	s_nop 0
	v_rcp_f32_e32 v131, v131
	s_nop 0
	v_mul_f32_e32 v131, 2.0, v131
	v_rcp_f32_e32 v130, v130
	s_nop 0
	v_mul_f32_e32 v130, 2.0, v130
	v_pk_add_f32 v[130:131], v[130:131], 1.0 op_sel_hi:[1,0] neg_lo:[1,0] neg_hi:[1,0]
	s_nop 0
	v_cvt_pk_bf16_f32 v130, v130, v131
	v_add_f32_e32 v131, v104, v104
	v_mul_f32_e32 v131, 0x3fb8aa3b, v131
	v_exp_f32_e32 v132, v131
	v_add_f32_e32 v131, v105, v105
	v_mul_f32_e32 v131, 0x3fb8aa3b, v131
	v_exp_f32_e32 v133, v131
	s_nop 0
	v_pk_add_f32 v[132:133], v[132:133], 1.0 op_sel_hi:[1,0]
	s_nop 0
	v_rcp_f32_e32 v133, v133
	s_nop 0
	v_mul_f32_e32 v133, 2.0, v133
	v_rcp_f32_e32 v132, v132
	s_nop 0
	v_mul_f32_e32 v132, 2.0, v132
	v_pk_add_f32 v[132:133], v[132:133], 1.0 op_sel_hi:[1,0] neg_lo:[1,0] neg_hi:[1,0]
	s_nop 0
	v_cvt_pk_bf16_f32 v131, v132, v133
	v_add_f32_e32 v132, v98, v98
	v_add_f32_e32 v133, v99, v99
	v_mul_f32_e32 v132, 0x3fb8aa3b, v132
	v_mul_f32_e32 v133, 0x3fb8aa3b, v133
	v_exp_f32_e32 v132, v132
	v_exp_f32_e32 v133, v133
	s_nop 0
	v_pk_add_f32 v[132:133], v[132:133], 1.0 op_sel_hi:[1,0]
	s_nop 0
	v_rcp_f32_e32 v133, v133
	s_nop 0
	v_mul_f32_e32 v133, 2.0, v133
	v_rcp_f32_e32 v132, v132
	s_nop 0
	v_mul_f32_e32 v132, 2.0, v132
	v_pk_add_f32 v[132:133], v[132:133], 1.0 op_sel_hi:[1,0] neg_lo:[1,0] neg_hi:[1,0]
	s_nop 0
	v_cvt_pk_bf16_f32 v132, v132, v133
	v_add_f32_e32 v133, v100, v100
	v_mul_f32_e32 v133, 0x3fb8aa3b, v133
	v_exp_f32_e32 v158, v133
	v_add_f32_e32 v133, v101, v101
	v_mul_f32_e32 v133, 0x3fb8aa3b, v133
	v_exp_f32_e32 v159, v133
	s_nop 0
	v_pk_add_f32 v[158:159], v[158:159], 1.0 op_sel_hi:[1,0]
	s_nop 0
	v_rcp_f32_e32 v159, v159
	s_nop 0
	v_mul_f32_e32 v159, 2.0, v159
	v_rcp_f32_e32 v158, v158
	s_nop 0
	v_mul_f32_e32 v158, 2.0, v158
	v_pk_add_f32 v[158:159], v[158:159], 1.0 op_sel_hi:[1,0] neg_lo:[1,0] neg_hi:[1,0]
	s_nop 0
	v_cvt_pk_bf16_f32 v133, v158, v159
	global_store_dwordx4 v[156:157], v[130:133], off
	s_nop 1
	v_add_f32_e32 v130, v78, v78
	v_add_f32_e32 v131, v79, v79
	v_mul_f32_e32 v130, 0x3fb8aa3b, v130
	v_mul_f32_e32 v131, 0x3fb8aa3b, v131
; __device__ __forceinline__ float tanhf_(float x) { return 1.0f - 2.0f / (1.0f + __expf(2.0f * x)); }
; template <int ACT> __device__ __forceinline__ void store_tile_bf16(AccRef acc, bf16_t* dst, int ld, int row0, int col0) {
; #pragma unroll
;     for (int ai = 0; ai < 2; ++ai)
; #pragma unroll
;         for (int m = 0; m < 4; ++m) { bf16_t* rowp = dst + (size_t)(row0 + ai * 128 + m * 16) * ld + col0;
; #pragma unroll
;             for (int bj = 0; bj < 2; ++bj) { const f32x4 v0 = acc[ai][bj][m][0], v1 = acc[ai][bj][m][1];
;                 u32x4 w; w.x = cvt_pk_bf16(actf<ACT>(v0[0]), actf<ACT>(v0[1])); w.y = cvt_pk_bf16(actf<ACT>(v0[2]), actf<ACT>(v0[3]));
;                 w.z = cvt_pk_bf16(actf<ACT>(v1[0]), actf<ACT>(v1[1])); w.w = cvt_pk_bf16(actf<ACT>(v1[2]), actf<ACT>(v1[3]));
;                 *(u32x4*)(rowp + bj * 128) = w; } }
; }
	v_exp_f32_e32 v130, v130
	v_exp_f32_e32 v131, v131
	s_nop 0
	v_pk_add_f32 v[130:131], v[130:131], 1.0 op_sel_hi:[1,0]
	s_nop 0
	v_rcp_f32_e32 v131, v131
	s_nop 0
	v_mul_f32_e32 v131, 2.0, v131
	v_rcp_f32_e32 v130, v130
	s_nop 0
	v_mul_f32_e32 v130, 2.0, v130
	v_pk_add_f32 v[130:131], v[130:131], 1.0 op_sel_hi:[1,0] neg_lo:[1,0] neg_hi:[1,0]
	s_nop 0
	v_cvt_pk_bf16_f32 v130, v130, v131
	v_add_f32_e32 v131, v80, v80
	v_mul_f32_e32 v131, 0x3fb8aa3b, v131
	v_exp_f32_e32 v132, v131
	v_add_f32_e32 v131, v81, v81
	v_mul_f32_e32 v131, 0x3fb8aa3b, v131
	v_exp_f32_e32 v133, v131
	s_nop 0
	v_pk_add_f32 v[132:133], v[132:133], 1.0 op_sel_hi:[1,0]
	s_nop 0
	v_rcp_f32_e32 v133, v133
	s_nop 0
	v_mul_f32_e32 v133, 2.0, v133
	v_rcp_f32_e32 v132, v132
	s_nop 0
	v_mul_f32_e32 v132, 2.0, v132
	v_pk_add_f32 v[132:133], v[132:133], 1.0 op_sel_hi:[1,0] neg_lo:[1,0] neg_hi:[1,0]
	s_nop 0
	v_cvt_pk_bf16_f32 v131, v132, v133
	v_add_f32_e32 v132, v74, v74
	v_add_f32_e32 v133, v75, v75
	v_mul_f32_e32 v132, 0x3fb8aa3b, v132
	v_mul_f32_e32 v133, 0x3fb8aa3b, v133
	v_exp_f32_e32 v132, v132
	v_exp_f32_e32 v133, v133
	s_nop 0
	v_pk_add_f32 v[132:133], v[132:133], 1.0 op_sel_hi:[1,0]
	s_nop 0
	v_rcp_f32_e32 v133, v133
	s_nop 0
	v_mul_f32_e32 v133, 2.0, v133
	v_rcp_f32_e32 v132, v132
	s_nop 0
	v_mul_f32_e32 v132, 2.0, v132
	v_pk_add_f32 v[132:133], v[132:133], 1.0 op_sel_hi:[1,0] neg_lo:[1,0] neg_hi:[1,0]
	s_nop 0
	v_cvt_pk_bf16_f32 v132, v132, v133
	v_add_f32_e32 v133, v76, v76
	v_mul_f32_e32 v133, 0x3fb8aa3b, v133
	v_exp_f32_e32 v158, v133
	v_add_f32_e32 v133, v77, v77
	v_mul_f32_e32 v133, 0x3fb8aa3b, v133
	v_exp_f32_e32 v159, v133
	s_nop 0
	v_pk_add_f32 v[158:159], v[158:159], 1.0 op_sel_hi:[1,0]
	s_nop 0
	v_rcp_f32_e32 v159, v159
	s_nop 0
	v_mul_f32_e32 v159, 2.0, v159
	v_rcp_f32_e32 v158, v158
	s_nop 0
	v_mul_f32_e32 v158, 2.0, v158
	v_pk_add_f32 v[158:159], v[158:159], 1.0 op_sel_hi:[1,0] neg_lo:[1,0] neg_hi:[1,0]
	s_nop 0
	v_cvt_pk_bf16_f32 v133, v158, v159
	global_store_dwordx4 v[156:157], v[130:133], off offset:256
	s_nop 1
	v_or_b32_e32 v130, 48, v154
	v_mad_i64_i32 v[156:157], s[0:1], v130, s74, v[144:145]
	v_add_f32_e32 v130, v86, v86
	v_add_f32_e32 v131, v87, v87
	v_mul_f32_e32 v130, 0x3fb8aa3b, v130
	v_mul_f32_e32 v131, 0x3fb8aa3b, v131
	v_exp_f32_e32 v130, v130
	v_exp_f32_e32 v131, v131
	s_nop 0
	v_pk_add_f32 v[130:131], v[130:131], 1.0 op_sel_hi:[1,0]
	s_nop 0
	v_rcp_f32_e32 v131, v131
	s_nop 0
	v_mul_f32_e32 v131, 2.0, v131
	v_rcp_f32_e32 v130, v130
	s_nop 0
	v_mul_f32_e32 v130, 2.0, v130
	v_pk_add_f32 v[130:131], v[130:131], 1.0 op_sel_hi:[1,0] neg_lo:[1,0] neg_hi:[1,0]
	s_nop 0
	v_cvt_pk_bf16_f32 v130, v130, v131
	v_add_f32_e32 v131, v88, v88
	v_mul_f32_e32 v131, 0x3fb8aa3b, v131
	v_exp_f32_e32 v132, v131
	v_add_f32_e32 v131, v89, v89
	v_mul_f32_e32 v131, 0x3fb8aa3b, v131
	v_exp_f32_e32 v133, v131
	s_nop 0
	v_pk_add_f32 v[132:133], v[132:133], 1.0 op_sel_hi:[1,0]
	s_nop 0
	v_rcp_f32_e32 v133, v133
	s_nop 0
	v_mul_f32_e32 v133, 2.0, v133
	v_rcp_f32_e32 v132, v132
	s_nop 0
	v_mul_f32_e32 v132, 2.0, v132
	v_pk_add_f32 v[132:133], v[132:133], 1.0 op_sel_hi:[1,0] neg_lo:[1,0] neg_hi:[1,0]
	s_nop 0
	v_cvt_pk_bf16_f32 v131, v132, v133
	v_add_f32_e32 v132, v82, v82
	v_add_f32_e32 v133, v83, v83
	v_mul_f32_e32 v132, 0x3fb8aa3b, v132
	v_mul_f32_e32 v133, 0x3fb8aa3b, v133
	v_exp_f32_e32 v132, v132
	v_exp_f32_e32 v133, v133
	s_nop 0
	v_pk_add_f32 v[132:133], v[132:133], 1.0 op_sel_hi:[1,0]
	s_nop 0
	v_rcp_f32_e32 v133, v133
	s_nop 0
	v_mul_f32_e32 v133, 2.0, v133
	v_rcp_f32_e32 v132, v132
	s_nop 0
	v_mul_f32_e32 v132, 2.0, v132
	v_pk_add_f32 v[132:133], v[132:133], 1.0 op_sel_hi:[1,0] neg_lo:[1,0] neg_hi:[1,0]
	s_nop 0
	v_cvt_pk_bf16_f32 v132, v132, v133
	v_add_f32_e32 v133, v84, v84
	v_mul_f32_e32 v133, 0x3fb8aa3b, v133
	v_exp_f32_e32 v158, v133
	v_add_f32_e32 v133, v85, v85
	v_mul_f32_e32 v133, 0x3fb8aa3b, v133
	v_exp_f32_e32 v159, v133
	s_nop 0
	v_pk_add_f32 v[158:159], v[158:159], 1.0 op_sel_hi:[1,0]
	s_nop 0
	v_rcp_f32_e32 v159, v159
	s_nop 0
	v_mul_f32_e32 v159, 2.0, v159
	v_rcp_f32_e32 v158, v158
	s_nop 0
	v_mul_f32_e32 v158, 2.0, v158
	v_pk_add_f32 v[158:159], v[158:159], 1.0 op_sel_hi:[1,0] neg_lo:[1,0] neg_hi:[1,0]
	s_nop 0
	v_cvt_pk_bf16_f32 v133, v158, v159
	global_store_dwordx4 v[156:157], v[130:133], off
	s_nop 1
	v_add_f32_e32 v130, v70, v70
	v_add_f32_e32 v131, v71, v71
	v_mul_f32_e32 v130, 0x3fb8aa3b, v130
	v_mul_f32_e32 v131, 0x3fb8aa3b, v131
	v_exp_f32_e32 v130, v130
	v_exp_f32_e32 v131, v131
	s_nop 0
	v_pk_add_f32 v[130:131], v[130:131], 1.0 op_sel_hi:[1,0]
	s_nop 0
	v_rcp_f32_e32 v131, v131
	s_nop 0
	v_mul_f32_e32 v131, 2.0, v131
	v_rcp_f32_e32 v130, v130
	s_nop 0
	v_mul_f32_e32 v130, 2.0, v130
	v_pk_add_f32 v[130:131], v[130:131], 1.0 op_sel_hi:[1,0] neg_lo:[1,0] neg_hi:[1,0]
	s_nop 0
	v_cvt_pk_bf16_f32 v130, v130, v131
	v_add_f32_e32 v131, v72, v72
	v_mul_f32_e32 v131, 0x3fb8aa3b, v131
	v_exp_f32_e32 v132, v131
	v_add_f32_e32 v131, v73, v73
	v_mul_f32_e32 v131, 0x3fb8aa3b, v131
	v_exp_f32_e32 v133, v131
	s_nop 0
	v_pk_add_f32 v[132:133], v[132:133], 1.0 op_sel_hi:[1,0]
	s_nop 0
	v_rcp_f32_e32 v133, v133
	s_nop 0
	v_mul_f32_e32 v133, 2.0, v133
	v_rcp_f32_e32 v132, v132
	s_nop 0
	v_mul_f32_e32 v132, 2.0, v132
	v_pk_add_f32 v[132:133], v[132:133], 1.0 op_sel_hi:[1,0] neg_lo:[1,0] neg_hi:[1,0]
	s_nop 0
	v_cvt_pk_bf16_f32 v131, v132, v133
	v_add_f32_e32 v132, v66, v66
	v_add_f32_e32 v133, v67, v67
	v_mul_f32_e32 v132, 0x3fb8aa3b, v132
	v_mul_f32_e32 v133, 0x3fb8aa3b, v133
	v_exp_f32_e32 v132, v132
	v_exp_f32_e32 v133, v133
	s_nop 0
	v_pk_add_f32 v[132:133], v[132:133], 1.0 op_sel_hi:[1,0]
	s_nop 0
	v_rcp_f32_e32 v133, v133
	s_nop 0
; __device__ __forceinline__ float tanhf_(float x) { return 1.0f - 2.0f / (1.0f + __expf(2.0f * x)); }
; template <int ACT> __device__ __forceinline__ void store_tile_bf16(AccRef acc, bf16_t* dst, int ld, int row0, int col0) {
; #pragma unroll
;     for (int ai = 0; ai < 2; ++ai)
; #pragma unroll
;         for (int m = 0; m < 4; ++m) { bf16_t* rowp = dst + (size_t)(row0 + ai * 128 + m * 16) * ld + col0;
; #pragma unroll
;             for (int bj = 0; bj < 2; ++bj) { const f32x4 v0 = acc[ai][bj][m][0], v1 = acc[ai][bj][m][1];
;                 u32x4 w; w.x = cvt_pk_bf16(actf<ACT>(v0[0]), actf<ACT>(v0[1])); w.y = cvt_pk_bf16(actf<ACT>(v0[2]), actf<ACT>(v0[3]));
;                 w.z = cvt_pk_bf16(actf<ACT>(v1[0]), actf<ACT>(v1[1])); w.w = cvt_pk_bf16(actf<ACT>(v1[2]), actf<ACT>(v1[3]));
;                 *(u32x4*)(rowp + bj * 128) = w; } }
; }
	v_mul_f32_e32 v133, 2.0, v133
	v_rcp_f32_e32 v132, v132
	s_nop 0
	v_mul_f32_e32 v132, 2.0, v132
	v_pk_add_f32 v[132:133], v[132:133], 1.0 op_sel_hi:[1,0] neg_lo:[1,0] neg_hi:[1,0]
	s_nop 0
	v_cvt_pk_bf16_f32 v132, v132, v133
	v_add_f32_e32 v133, v68, v68
	v_mul_f32_e32 v133, 0x3fb8aa3b, v133
	v_exp_f32_e32 v158, v133
	v_add_f32_e32 v133, v69, v69
	v_mul_f32_e32 v133, 0x3fb8aa3b, v133
	v_exp_f32_e32 v159, v133
	s_nop 0
	v_pk_add_f32 v[158:159], v[158:159], 1.0 op_sel_hi:[1,0]
	s_nop 0
	v_rcp_f32_e32 v159, v159
	s_nop 0
	v_mul_f32_e32 v159, 2.0, v159
	v_rcp_f32_e32 v158, v158
	s_nop 0
	v_mul_f32_e32 v158, 2.0, v158
	v_pk_add_f32 v[158:159], v[158:159], 1.0 op_sel_hi:[1,0] neg_lo:[1,0] neg_hi:[1,0]
	s_nop 0
	v_cvt_pk_bf16_f32 v133, v158, v159
	global_store_dwordx4 v[156:157], v[130:133], off offset:256
	s_nop 1
	v_add_u32_e32 v130, 0x80, v154
	v_mad_i64_i32 v[156:157], s[0:1], v130, s74, v[144:145]
	v_add_f32_e32 v130, v62, v62
	v_add_f32_e32 v131, v63, v63
	v_mul_f32_e32 v130, 0x3fb8aa3b, v130
	v_mul_f32_e32 v131, 0x3fb8aa3b, v131
	v_exp_f32_e32 v130, v130
	v_exp_f32_e32 v131, v131
	s_nop 0
	v_pk_add_f32 v[130:131], v[130:131], 1.0 op_sel_hi:[1,0]
	s_nop 0
	v_rcp_f32_e32 v131, v131
	s_nop 0
	v_mul_f32_e32 v131, 2.0, v131
	v_rcp_f32_e32 v130, v130
	s_nop 0
	v_mul_f32_e32 v130, 2.0, v130
	v_pk_add_f32 v[130:131], v[130:131], 1.0 op_sel_hi:[1,0] neg_lo:[1,0] neg_hi:[1,0]
	s_nop 0
	v_cvt_pk_bf16_f32 v130, v130, v131
	v_add_f32_e32 v131, v64, v64
	v_mul_f32_e32 v131, 0x3fb8aa3b, v131
	v_exp_f32_e32 v132, v131
	v_add_f32_e32 v131, v65, v65
	v_mul_f32_e32 v131, 0x3fb8aa3b, v131
	v_exp_f32_e32 v133, v131
	s_nop 0
	v_pk_add_f32 v[132:133], v[132:133], 1.0 op_sel_hi:[1,0]
	s_nop 0
	v_rcp_f32_e32 v133, v133
	s_nop 0
	v_mul_f32_e32 v133, 2.0, v133
	v_rcp_f32_e32 v132, v132
	s_nop 0
	v_mul_f32_e32 v132, 2.0, v132
	v_pk_add_f32 v[132:133], v[132:133], 1.0 op_sel_hi:[1,0] neg_lo:[1,0] neg_hi:[1,0]
	s_nop 0
	v_cvt_pk_bf16_f32 v131, v132, v133
	v_add_f32_e32 v132, v58, v58
	v_add_f32_e32 v133, v59, v59
	v_mul_f32_e32 v132, 0x3fb8aa3b, v132
	v_mul_f32_e32 v133, 0x3fb8aa3b, v133
	v_exp_f32_e32 v132, v132
	v_exp_f32_e32 v133, v133
	s_nop 0
	v_pk_add_f32 v[132:133], v[132:133], 1.0 op_sel_hi:[1,0]
	s_nop 0
	v_rcp_f32_e32 v133, v133
	s_nop 0
	v_mul_f32_e32 v133, 2.0, v133
	v_rcp_f32_e32 v132, v132
	s_nop 0
	v_mul_f32_e32 v132, 2.0, v132
	v_pk_add_f32 v[132:133], v[132:133], 1.0 op_sel_hi:[1,0] neg_lo:[1,0] neg_hi:[1,0]
	s_nop 0
	v_cvt_pk_bf16_f32 v132, v132, v133
	v_add_f32_e32 v133, v60, v60
	v_mul_f32_e32 v133, 0x3fb8aa3b, v133
	v_exp_f32_e32 v158, v133
	v_add_f32_e32 v133, v61, v61
	v_mul_f32_e32 v133, 0x3fb8aa3b, v133
	v_exp_f32_e32 v159, v133
	s_nop 0
	v_pk_add_f32 v[158:159], v[158:159], 1.0 op_sel_hi:[1,0]
	s_nop 0
	v_rcp_f32_e32 v159, v159
	s_nop 0
	v_mul_f32_e32 v159, 2.0, v159
	v_rcp_f32_e32 v158, v158
	s_nop 0
	v_mul_f32_e32 v158, 2.0, v158
	v_pk_add_f32 v[158:159], v[158:159], 1.0 op_sel_hi:[1,0] neg_lo:[1,0] neg_hi:[1,0]
	s_nop 0
	v_cvt_pk_bf16_f32 v133, v158, v159
	global_store_dwordx4 v[156:157], v[130:133], off
	s_nop 1
	v_add_f32_e32 v130, v46, v46
	v_add_f32_e32 v131, v47, v47
	v_mul_f32_e32 v130, 0x3fb8aa3b, v130
	v_mul_f32_e32 v131, 0x3fb8aa3b, v131
	v_exp_f32_e32 v130, v130
	v_exp_f32_e32 v131, v131
	s_nop 0
	v_pk_add_f32 v[130:131], v[130:131], 1.0 op_sel_hi:[1,0]
	s_nop 0
	v_rcp_f32_e32 v131, v131
	s_nop 0
	v_mul_f32_e32 v131, 2.0, v131
	v_rcp_f32_e32 v130, v130
	s_nop 0
	v_mul_f32_e32 v130, 2.0, v130
	v_pk_add_f32 v[130:131], v[130:131], 1.0 op_sel_hi:[1,0] neg_lo:[1,0] neg_hi:[1,0]
	s_nop 0
	v_cvt_pk_bf16_f32 v130, v130, v131
	v_add_f32_e32 v131, v48, v48
	v_mul_f32_e32 v131, 0x3fb8aa3b, v131
	v_exp_f32_e32 v132, v131
	v_add_f32_e32 v131, v49, v49
	v_mul_f32_e32 v131, 0x3fb8aa3b, v131
	v_exp_f32_e32 v133, v131
	s_nop 0
	v_pk_add_f32 v[132:133], v[132:133], 1.0 op_sel_hi:[1,0]
	s_nop 0
	v_rcp_f32_e32 v133, v133
	s_nop 0
	v_mul_f32_e32 v133, 2.0, v133
	v_rcp_f32_e32 v132, v132
	s_nop 0
	v_mul_f32_e32 v132, 2.0, v132
	v_pk_add_f32 v[132:133], v[132:133], 1.0 op_sel_hi:[1,0] neg_lo:[1,0] neg_hi:[1,0]
	s_nop 0
	v_cvt_pk_bf16_f32 v131, v132, v133
	v_add_f32_e32 v132, v42, v42
	v_add_f32_e32 v133, v43, v43
	v_mul_f32_e32 v132, 0x3fb8aa3b, v132
	v_mul_f32_e32 v133, 0x3fb8aa3b, v133
	v_exp_f32_e32 v132, v132
	v_exp_f32_e32 v133, v133
	s_nop 0
	v_pk_add_f32 v[132:133], v[132:133], 1.0 op_sel_hi:[1,0]
	s_nop 0
	v_rcp_f32_e32 v133, v133
	s_nop 0
	v_mul_f32_e32 v133, 2.0, v133
	v_rcp_f32_e32 v132, v132
	s_nop 0
	v_mul_f32_e32 v132, 2.0, v132
	v_pk_add_f32 v[132:133], v[132:133], 1.0 op_sel_hi:[1,0] neg_lo:[1,0] neg_hi:[1,0]
	s_nop 0
	v_cvt_pk_bf16_f32 v132, v132, v133
	v_add_f32_e32 v133, v44, v44
	v_mul_f32_e32 v133, 0x3fb8aa3b, v133
	v_exp_f32_e32 v158, v133
	v_add_f32_e32 v133, v45, v45
	v_mul_f32_e32 v133, 0x3fb8aa3b, v133
	v_exp_f32_e32 v159, v133
	s_nop 0
	v_pk_add_f32 v[158:159], v[158:159], 1.0 op_sel_hi:[1,0]
	s_nop 0
	v_rcp_f32_e32 v159, v159
	s_nop 0
	v_mul_f32_e32 v159, 2.0, v159
	v_rcp_f32_e32 v158, v158
	s_nop 0
	v_mul_f32_e32 v158, 2.0, v158
	v_pk_add_f32 v[158:159], v[158:159], 1.0 op_sel_hi:[1,0] neg_lo:[1,0] neg_hi:[1,0]
	s_nop 0
	v_cvt_pk_bf16_f32 v133, v158, v159
	global_store_dwordx4 v[156:157], v[130:133], off offset:256
	s_nop 1
	v_add_u32_e32 v130, 0x90, v154
	v_mad_i64_i32 v[156:157], s[0:1], v130, s74, v[144:145]
	v_add_f32_e32 v130, v54, v54
	v_add_f32_e32 v131, v55, v55
	v_mul_f32_e32 v130, 0x3fb8aa3b, v130
	v_mul_f32_e32 v131, 0x3fb8aa3b, v131
	v_exp_f32_e32 v130, v130
	v_exp_f32_e32 v131, v131
	s_nop 0
	v_pk_add_f32 v[130:131], v[130:131], 1.0 op_sel_hi:[1,0]
	s_nop 0
	v_rcp_f32_e32 v131, v131
	s_nop 0
; __device__ __forceinline__ float tanhf_(float x) { return 1.0f - 2.0f / (1.0f + __expf(2.0f * x)); }
; template <int ACT> __device__ __forceinline__ void store_tile_bf16(AccRef acc, bf16_t* dst, int ld, int row0, int col0) {
; #pragma unroll
;     for (int ai = 0; ai < 2; ++ai)
; #pragma unroll
;         for (int m = 0; m < 4; ++m) { bf16_t* rowp = dst + (size_t)(row0 + ai * 128 + m * 16) * ld + col0;
; #pragma unroll
;             for (int bj = 0; bj < 2; ++bj) { const f32x4 v0 = acc[ai][bj][m][0], v1 = acc[ai][bj][m][1];
;                 u32x4 w; w.x = cvt_pk_bf16(actf<ACT>(v0[0]), actf<ACT>(v0[1])); w.y = cvt_pk_bf16(actf<ACT>(v0[2]), actf<ACT>(v0[3]));
;                 w.z = cvt_pk_bf16(actf<ACT>(v1[0]), actf<ACT>(v1[1])); w.w = cvt_pk_bf16(actf<ACT>(v1[2]), actf<ACT>(v1[3]));
;                 *(u32x4*)(rowp + bj * 128) = w; } }
	v_mul_f32_e32 v131, 2.0, v131
	v_rcp_f32_e32 v130, v130
	s_nop 0
	v_mul_f32_e32 v130, 2.0, v130
	v_pk_add_f32 v[130:131], v[130:131], 1.0 op_sel_hi:[1,0] neg_lo:[1,0] neg_hi:[1,0]
	s_nop 0
	v_cvt_pk_bf16_f32 v130, v130, v131
	v_add_f32_e32 v131, v56, v56
	v_mul_f32_e32 v131, 0x3fb8aa3b, v131
	v_exp_f32_e32 v132, v131
	v_add_f32_e32 v131, v57, v57
	v_mul_f32_e32 v131, 0x3fb8aa3b, v131
	v_exp_f32_e32 v133, v131
	s_nop 0
	v_pk_add_f32 v[132:133], v[132:133], 1.0 op_sel_hi:[1,0]
	s_nop 0
	v_rcp_f32_e32 v133, v133
	s_nop 0
	v_mul_f32_e32 v133, 2.0, v133
	v_rcp_f32_e32 v132, v132
	s_nop 0
	v_mul_f32_e32 v132, 2.0, v132
	v_pk_add_f32 v[132:133], v[132:133], 1.0 op_sel_hi:[1,0] neg_lo:[1,0] neg_hi:[1,0]
	s_nop 0
	v_cvt_pk_bf16_f32 v131, v132, v133
	v_add_f32_e32 v132, v50, v50
	v_add_f32_e32 v133, v51, v51
	v_mul_f32_e32 v132, 0x3fb8aa3b, v132
	v_mul_f32_e32 v133, 0x3fb8aa3b, v133
	v_exp_f32_e32 v132, v132
	v_exp_f32_e32 v133, v133
	s_nop 0
	v_pk_add_f32 v[132:133], v[132:133], 1.0 op_sel_hi:[1,0]
	s_nop 0
	v_rcp_f32_e32 v133, v133
	s_nop 0
	v_mul_f32_e32 v133, 2.0, v133
	v_rcp_f32_e32 v132, v132
	s_nop 0
	v_mul_f32_e32 v132, 2.0, v132
	v_pk_add_f32 v[132:133], v[132:133], 1.0 op_sel_hi:[1,0] neg_lo:[1,0] neg_hi:[1,0]
	s_nop 0
	v_cvt_pk_bf16_f32 v132, v132, v133
	v_add_f32_e32 v133, v52, v52
	v_mul_f32_e32 v133, 0x3fb8aa3b, v133
	v_exp_f32_e32 v158, v133
	v_add_f32_e32 v133, v53, v53
	v_mul_f32_e32 v133, 0x3fb8aa3b, v133
	v_exp_f32_e32 v159, v133
	s_nop 0
	v_pk_add_f32 v[158:159], v[158:159], 1.0 op_sel_hi:[1,0]
	s_nop 0
	v_rcp_f32_e32 v159, v159
	s_nop 0
	v_mul_f32_e32 v159, 2.0, v159
	v_rcp_f32_e32 v158, v158
	s_nop 0
	v_mul_f32_e32 v158, 2.0, v158
	v_pk_add_f32 v[158:159], v[158:159], 1.0 op_sel_hi:[1,0] neg_lo:[1,0] neg_hi:[1,0]
	s_nop 0
	v_cvt_pk_bf16_f32 v133, v158, v159
	global_store_dwordx4 v[156:157], v[130:133], off
	s_nop 1
	v_add_f32_e32 v130, v30, v30
	v_add_f32_e32 v131, v31, v31
	v_mul_f32_e32 v130, 0x3fb8aa3b, v130
	v_mul_f32_e32 v131, 0x3fb8aa3b, v131
	v_exp_f32_e32 v130, v130
	v_exp_f32_e32 v131, v131
	s_nop 0
	v_pk_add_f32 v[130:131], v[130:131], 1.0 op_sel_hi:[1,0]
	s_nop 0
	v_rcp_f32_e32 v131, v131
	s_nop 0
	v_mul_f32_e32 v131, 2.0, v131
	v_rcp_f32_e32 v130, v130
	s_nop 0
	v_mul_f32_e32 v130, 2.0, v130
	v_pk_add_f32 v[130:131], v[130:131], 1.0 op_sel_hi:[1,0] neg_lo:[1,0] neg_hi:[1,0]
	s_nop 0
	v_cvt_pk_bf16_f32 v130, v130, v131
	v_add_f32_e32 v131, v32, v32
	v_mul_f32_e32 v131, 0x3fb8aa3b, v131
	v_exp_f32_e32 v132, v131
	v_add_f32_e32 v131, v33, v33
	v_mul_f32_e32 v131, 0x3fb8aa3b, v131
	v_exp_f32_e32 v133, v131
	s_nop 0
	v_pk_add_f32 v[132:133], v[132:133], 1.0 op_sel_hi:[1,0]
	s_nop 0
	v_rcp_f32_e32 v133, v133
	s_nop 0
	v_mul_f32_e32 v133, 2.0, v133
	v_rcp_f32_e32 v132, v132
	s_nop 0
	v_mul_f32_e32 v132, 2.0, v132
	v_pk_add_f32 v[132:133], v[132:133], 1.0 op_sel_hi:[1,0] neg_lo:[1,0] neg_hi:[1,0]
	s_nop 0
	v_cvt_pk_bf16_f32 v131, v132, v133
	v_add_f32_e32 v132, v26, v26
	v_add_f32_e32 v133, v27, v27
	v_mul_f32_e32 v132, 0x3fb8aa3b, v132
	v_mul_f32_e32 v133, 0x3fb8aa3b, v133
	v_exp_f32_e32 v132, v132
	v_exp_f32_e32 v133, v133
	s_nop 0
	v_pk_add_f32 v[132:133], v[132:133], 1.0 op_sel_hi:[1,0]
	s_nop 0
	v_rcp_f32_e32 v133, v133
	s_nop 0
	v_mul_f32_e32 v133, 2.0, v133
	v_rcp_f32_e32 v132, v132
	s_nop 0
	v_mul_f32_e32 v132, 2.0, v132
	v_pk_add_f32 v[132:133], v[132:133], 1.0 op_sel_hi:[1,0] neg_lo:[1,0] neg_hi:[1,0]
	s_nop 0
	v_cvt_pk_bf16_f32 v132, v132, v133
	v_add_f32_e32 v133, v28, v28
	v_mul_f32_e32 v133, 0x3fb8aa3b, v133
	v_exp_f32_e32 v158, v133
	v_add_f32_e32 v133, v29, v29
	v_mul_f32_e32 v133, 0x3fb8aa3b, v133
	v_exp_f32_e32 v159, v133
	s_nop 0
	v_pk_add_f32 v[158:159], v[158:159], 1.0 op_sel_hi:[1,0]
	s_nop 0
	v_rcp_f32_e32 v159, v159
	s_nop 0
	v_mul_f32_e32 v159, 2.0, v159
	v_rcp_f32_e32 v158, v158
	s_nop 0
	v_mul_f32_e32 v158, 2.0, v158
	v_pk_add_f32 v[158:159], v[158:159], 1.0 op_sel_hi:[1,0] neg_lo:[1,0] neg_hi:[1,0]
	s_nop 0
	v_cvt_pk_bf16_f32 v133, v158, v159
	global_store_dwordx4 v[156:157], v[130:133], off offset:256
	s_nop 1
	v_add_u32_e32 v130, 0xa0, v154
	v_mad_i64_i32 v[156:157], s[0:1], v130, s74, v[144:145]
	v_add_f32_e32 v130, v38, v38
	v_add_f32_e32 v131, v39, v39
	v_mul_f32_e32 v130, 0x3fb8aa3b, v130
	v_mul_f32_e32 v131, 0x3fb8aa3b, v131
	v_exp_f32_e32 v130, v130
	v_exp_f32_e32 v131, v131
	s_nop 0
	v_pk_add_f32 v[130:131], v[130:131], 1.0 op_sel_hi:[1,0]
	s_nop 0
	v_rcp_f32_e32 v131, v131
	s_nop 0
	v_mul_f32_e32 v131, 2.0, v131
	v_rcp_f32_e32 v130, v130
	s_nop 0
	v_mul_f32_e32 v130, 2.0, v130
	v_pk_add_f32 v[130:131], v[130:131], 1.0 op_sel_hi:[1,0] neg_lo:[1,0] neg_hi:[1,0]
	s_nop 0
	v_cvt_pk_bf16_f32 v130, v130, v131
	v_add_f32_e32 v131, v40, v40
	v_mul_f32_e32 v131, 0x3fb8aa3b, v131
	v_exp_f32_e32 v132, v131
	v_add_f32_e32 v131, v41, v41
	v_mul_f32_e32 v131, 0x3fb8aa3b, v131
	v_exp_f32_e32 v133, v131
	s_nop 0
	v_pk_add_f32 v[132:133], v[132:133], 1.0 op_sel_hi:[1,0]
	s_nop 0
	v_rcp_f32_e32 v133, v133
	s_nop 0
	v_mul_f32_e32 v133, 2.0, v133
	v_rcp_f32_e32 v132, v132
	s_nop 0
	v_mul_f32_e32 v132, 2.0, v132
	v_pk_add_f32 v[132:133], v[132:133], 1.0 op_sel_hi:[1,0] neg_lo:[1,0] neg_hi:[1,0]
	s_nop 0
	v_cvt_pk_bf16_f32 v131, v132, v133
	v_add_f32_e32 v132, v34, v34
	v_add_f32_e32 v133, v35, v35
	v_mul_f32_e32 v132, 0x3fb8aa3b, v132
	v_mul_f32_e32 v133, 0x3fb8aa3b, v133
	v_exp_f32_e32 v132, v132
	v_exp_f32_e32 v133, v133
	s_nop 0
	v_pk_add_f32 v[132:133], v[132:133], 1.0 op_sel_hi:[1,0]
	s_nop 0
	v_rcp_f32_e32 v133, v133
	s_nop 0
	v_mul_f32_e32 v133, 2.0, v133
	v_rcp_f32_e32 v132, v132
	s_nop 0
	v_mul_f32_e32 v132, 2.0, v132
	v_pk_add_f32 v[132:133], v[132:133], 1.0 op_sel_hi:[1,0] neg_lo:[1,0] neg_hi:[1,0]
; __device__ __forceinline__ float tanhf_(float x) { return 1.0f - 2.0f / (1.0f + __expf(2.0f * x)); }
; template <int ACT> __device__ __forceinline__ void store_tile_bf16(AccRef acc, bf16_t* dst, int ld, int row0, int col0) {
; #pragma unroll
;     for (int ai = 0; ai < 2; ++ai)
; #pragma unroll
;         for (int m = 0; m < 4; ++m) { bf16_t* rowp = dst + (size_t)(row0 + ai * 128 + m * 16) * ld + col0;
; #pragma unroll
;             for (int bj = 0; bj < 2; ++bj) { const f32x4 v0 = acc[ai][bj][m][0], v1 = acc[ai][bj][m][1];
;                 u32x4 w; w.x = cvt_pk_bf16(actf<ACT>(v0[0]), actf<ACT>(v0[1])); w.y = cvt_pk_bf16(actf<ACT>(v0[2]), actf<ACT>(v0[3]));
;                 w.z = cvt_pk_bf16(actf<ACT>(v1[0]), actf<ACT>(v1[1])); w.w = cvt_pk_bf16(actf<ACT>(v1[2]), actf<ACT>(v1[3]));
;                 *(u32x4*)(rowp + bj * 128) = w; } }
	s_nop 0
	v_cvt_pk_bf16_f32 v132, v132, v133
	v_add_f32_e32 v133, v36, v36
	v_mul_f32_e32 v133, 0x3fb8aa3b, v133
	v_exp_f32_e32 v158, v133
	v_add_f32_e32 v133, v37, v37
	v_mul_f32_e32 v133, 0x3fb8aa3b, v133
	v_exp_f32_e32 v159, v133
	s_nop 0
	v_pk_add_f32 v[158:159], v[158:159], 1.0 op_sel_hi:[1,0]
	s_nop 0
	v_rcp_f32_e32 v159, v159
	s_nop 0
	v_mul_f32_e32 v159, 2.0, v159
	v_rcp_f32_e32 v158, v158
	s_nop 0
	v_mul_f32_e32 v158, 2.0, v158
	v_pk_add_f32 v[158:159], v[158:159], 1.0 op_sel_hi:[1,0] neg_lo:[1,0] neg_hi:[1,0]
	s_nop 0
	v_cvt_pk_bf16_f32 v133, v158, v159
	global_store_dwordx4 v[156:157], v[130:133], off
	s_nop 1
	v_add_f32_e32 v130, v14, v14
	v_add_f32_e32 v131, v15, v15
	v_mul_f32_e32 v130, 0x3fb8aa3b, v130
	v_mul_f32_e32 v131, 0x3fb8aa3b, v131
	v_exp_f32_e32 v130, v130
	v_exp_f32_e32 v131, v131
	s_nop 0
	v_pk_add_f32 v[130:131], v[130:131], 1.0 op_sel_hi:[1,0]
	s_nop 0
	v_rcp_f32_e32 v131, v131
	s_nop 0
	v_mul_f32_e32 v131, 2.0, v131
	v_rcp_f32_e32 v130, v130
	s_nop 0
	v_mul_f32_e32 v130, 2.0, v130
	v_pk_add_f32 v[130:131], v[130:131], 1.0 op_sel_hi:[1,0] neg_lo:[1,0] neg_hi:[1,0]
	s_nop 0
	v_cvt_pk_bf16_f32 v130, v130, v131
	v_add_f32_e32 v131, v16, v16
	v_mul_f32_e32 v131, 0x3fb8aa3b, v131
	v_exp_f32_e32 v132, v131
	v_add_f32_e32 v131, v17, v17
	v_mul_f32_e32 v131, 0x3fb8aa3b, v131
	v_exp_f32_e32 v133, v131
	s_nop 0
	v_pk_add_f32 v[132:133], v[132:133], 1.0 op_sel_hi:[1,0]
	s_nop 0
	v_rcp_f32_e32 v133, v133
	s_nop 0
	v_mul_f32_e32 v133, 2.0, v133
	v_rcp_f32_e32 v132, v132
	s_nop 0
	v_mul_f32_e32 v132, 2.0, v132
	v_pk_add_f32 v[132:133], v[132:133], 1.0 op_sel_hi:[1,0] neg_lo:[1,0] neg_hi:[1,0]
	s_nop 0
	v_cvt_pk_bf16_f32 v131, v132, v133
	v_add_f32_e32 v132, v10, v10
	v_add_f32_e32 v133, v11, v11
	v_mul_f32_e32 v132, 0x3fb8aa3b, v132
	v_mul_f32_e32 v133, 0x3fb8aa3b, v133
	v_exp_f32_e32 v132, v132
	v_exp_f32_e32 v133, v133
	s_nop 0
	v_pk_add_f32 v[132:133], v[132:133], 1.0 op_sel_hi:[1,0]
	s_nop 0
	v_rcp_f32_e32 v133, v133
	s_nop 0
	v_mul_f32_e32 v133, 2.0, v133
	v_rcp_f32_e32 v132, v132
	s_nop 0
	v_mul_f32_e32 v132, 2.0, v132
	v_pk_add_f32 v[132:133], v[132:133], 1.0 op_sel_hi:[1,0] neg_lo:[1,0] neg_hi:[1,0]
	s_nop 0
	v_cvt_pk_bf16_f32 v132, v132, v133
	v_add_f32_e32 v133, v12, v12
	v_mul_f32_e32 v133, 0x3fb8aa3b, v133
	v_exp_f32_e32 v158, v133
	v_add_f32_e32 v133, v13, v13
	v_mul_f32_e32 v133, 0x3fb8aa3b, v133
	v_exp_f32_e32 v159, v133
	s_nop 0
	v_pk_add_f32 v[158:159], v[158:159], 1.0 op_sel_hi:[1,0]
	s_nop 0
	v_rcp_f32_e32 v159, v159
	s_nop 0
	v_mul_f32_e32 v159, 2.0, v159
	v_rcp_f32_e32 v158, v158
	s_nop 0
	v_mul_f32_e32 v158, 2.0, v158
	v_pk_add_f32 v[158:159], v[158:159], 1.0 op_sel_hi:[1,0] neg_lo:[1,0] neg_hi:[1,0]
	s_nop 0
	v_cvt_pk_bf16_f32 v133, v158, v159
	global_store_dwordx4 v[156:157], v[130:133], off offset:256
	s_nop 1
	v_add_u32_e32 v130, 0xb0, v154
	v_mad_i64_i32 v[158:159], s[0:1], v130, s74, v[144:145]
	v_add_f32_e32 v130, v22, v22
	v_add_f32_e32 v131, v23, v23
	v_mul_f32_e32 v130, 0x3fb8aa3b, v130
	v_mul_f32_e32 v131, 0x3fb8aa3b, v131
	v_exp_f32_e32 v130, v130
	v_exp_f32_e32 v131, v131
	s_nop 0
	v_pk_add_f32 v[130:131], v[130:131], 1.0 op_sel_hi:[1,0]
	s_nop 0
	v_rcp_f32_e32 v131, v131
	s_nop 0
	v_mul_f32_e32 v131, 2.0, v131
	v_rcp_f32_e32 v130, v130
	s_nop 0
	v_mul_f32_e32 v130, 2.0, v130
	v_pk_add_f32 v[130:131], v[130:131], 1.0 op_sel_hi:[1,0] neg_lo:[1,0] neg_hi:[1,0]
	s_nop 0
	v_cvt_pk_bf16_f32 v130, v130, v131
	v_add_f32_e32 v131, v24, v24
	v_mul_f32_e32 v131, 0x3fb8aa3b, v131
	v_exp_f32_e32 v132, v131
	v_add_f32_e32 v131, v25, v25
; __device__ __forceinline__ float tanhf_(float x) { return 1.0f - 2.0f / (1.0f + __expf(2.0f * x)); }
; template <int ACT> __device__ __forceinline__ void store_tile_bf16(AccRef acc, bf16_t* dst, int ld, int row0, int col0) {
; #pragma unroll
;     for (int ai = 0; ai < 2; ++ai)
; #pragma unroll
;         for (int m = 0; m < 4; ++m) { bf16_t* rowp = dst + (size_t)(row0 + ai * 128 + m * 16) * ld + col0;
; #pragma unroll
;             for (int bj = 0; bj < 2; ++bj) { const f32x4 v0 = acc[ai][bj][m][0], v1 = acc[ai][bj][m][1];
;                 u32x4 w; w.x = cvt_pk_bf16(actf<ACT>(v0[0]), actf<ACT>(v0[1])); w.y = cvt_pk_bf16(actf<ACT>(v0[2]), actf<ACT>(v0[3]));
;                 w.z = cvt_pk_bf16(actf<ACT>(v1[0]), actf<ACT>(v1[1])); w.w = cvt_pk_bf16(actf<ACT>(v1[2]), actf<ACT>(v1[3]));
;                 *(u32x4*)(rowp + bj * 128) = w; } }
	v_mul_f32_e32 v131, 0x3fb8aa3b, v131
	v_exp_f32_e32 v133, v131
	s_nop 0
	v_pk_add_f32 v[132:133], v[132:133], 1.0 op_sel_hi:[1,0]
	s_nop 0
	v_rcp_f32_e32 v133, v133
	s_nop 0
	v_mul_f32_e32 v133, 2.0, v133
	v_rcp_f32_e32 v132, v132
	s_nop 0
	v_mul_f32_e32 v132, 2.0, v132
	v_pk_add_f32 v[132:133], v[132:133], 1.0 op_sel_hi:[1,0] neg_lo:[1,0] neg_hi:[1,0]
	s_nop 0
	v_cvt_pk_bf16_f32 v131, v132, v133
	v_add_f32_e32 v132, v18, v18
	v_add_f32_e32 v133, v19, v19
	v_mul_f32_e32 v132, 0x3fb8aa3b, v132
	v_mul_f32_e32 v133, 0x3fb8aa3b, v133
	v_exp_f32_e32 v132, v132
	v_exp_f32_e32 v133, v133
	s_nop 0
	v_pk_add_f32 v[132:133], v[132:133], 1.0 op_sel_hi:[1,0]
	s_nop 0
	v_rcp_f32_e32 v133, v133
	s_nop 0
	v_mul_f32_e32 v133, 2.0, v133
	v_rcp_f32_e32 v132, v132
	s_nop 0
	v_mul_f32_e32 v132, 2.0, v132
	v_pk_add_f32 v[132:133], v[132:133], 1.0 op_sel_hi:[1,0] neg_lo:[1,0] neg_hi:[1,0]
	s_nop 0
	v_cvt_pk_bf16_f32 v132, v132, v133
	v_add_f32_e32 v133, v20, v20
	v_mul_f32_e32 v133, 0x3fb8aa3b, v133
	v_exp_f32_e32 v156, v133
	v_add_f32_e32 v133, v21, v21
	v_mul_f32_e32 v133, 0x3fb8aa3b, v133
	v_exp_f32_e32 v157, v133
	s_nop 0
	v_pk_add_f32 v[156:157], v[156:157], 1.0 op_sel_hi:[1,0]
	s_nop 0
	v_rcp_f32_e32 v157, v157
	s_nop 0
	v_mul_f32_e32 v157, 2.0, v157
	v_rcp_f32_e32 v156, v156
	s_nop 0
	v_mul_f32_e32 v156, 2.0, v156
	v_pk_add_f32 v[156:157], v[156:157], 1.0 op_sel_hi:[1,0] neg_lo:[1,0] neg_hi:[1,0]
	s_nop 0
	v_cvt_pk_bf16_f32 v133, v156, v157
	global_store_dwordx4 v[158:159], v[130:133], off
	s_nop 1
	v_add_f32_e32 v130, v6, v6
	v_add_f32_e32 v131, v7, v7
	v_mul_f32_e32 v130, 0x3fb8aa3b, v130
	v_mul_f32_e32 v131, 0x3fb8aa3b, v131
	v_exp_f32_e32 v130, v130
	v_exp_f32_e32 v131, v131
	s_nop 0
	v_pk_add_f32 v[130:131], v[130:131], 1.0 op_sel_hi:[1,0]
	s_nop 0
	v_rcp_f32_e32 v131, v131
	s_nop 0
	v_mul_f32_e32 v131, 2.0, v131
	v_rcp_f32_e32 v130, v130
	s_nop 0
	v_mul_f32_e32 v130, 2.0, v130
	v_pk_add_f32 v[130:131], v[130:131], 1.0 op_sel_hi:[1,0] neg_lo:[1,0] neg_hi:[1,0]
	s_nop 0
	v_cvt_pk_bf16_f32 v130, v130, v131
	v_add_f32_e32 v131, v8, v8
	v_mul_f32_e32 v131, 0x3fb8aa3b, v131
	v_exp_f32_e32 v132, v131
	v_add_f32_e32 v131, v9, v9
	v_mul_f32_e32 v131, 0x3fb8aa3b, v131
	v_exp_f32_e32 v133, v131
	s_nop 0
	v_pk_add_f32 v[132:133], v[132:133], 1.0 op_sel_hi:[1,0]
	s_nop 0
	v_rcp_f32_e32 v133, v133
	s_nop 0
	v_mul_f32_e32 v133, 2.0, v133
	v_rcp_f32_e32 v132, v132
	s_nop 0
	v_mul_f32_e32 v132, 2.0, v132
	v_pk_add_f32 v[132:133], v[132:133], 1.0 op_sel_hi:[1,0] neg_lo:[1,0] neg_hi:[1,0]
	s_nop 0
	v_cvt_pk_bf16_f32 v131, v132, v133
	v_add_f32_e32 v132, v2, v2
	v_add_f32_e32 v133, v3, v3
	v_mul_f32_e32 v132, 0x3fb8aa3b, v132
	v_mul_f32_e32 v133, 0x3fb8aa3b, v133
	v_exp_f32_e32 v132, v132
	v_exp_f32_e32 v133, v133
	s_nop 0
	v_pk_add_f32 v[132:133], v[132:133], 1.0 op_sel_hi:[1,0]
	s_nop 0
	v_rcp_f32_e32 v133, v133
	s_nop 0
	v_mul_f32_e32 v133, 2.0, v133
	v_rcp_f32_e32 v132, v132
	s_nop 0
	v_mul_f32_e32 v132, 2.0, v132
	v_pk_add_f32 v[132:133], v[132:133], 1.0 op_sel_hi:[1,0] neg_lo:[1,0] neg_hi:[1,0]
	s_nop 0
	v_cvt_pk_bf16_f32 v132, v132, v133
	v_add_f32_e32 v133, v4, v4
	v_mul_f32_e32 v133, 0x3fb8aa3b, v133
	v_exp_f32_e32 v156, v133
	v_add_f32_e32 v133, v5, v5
	v_mul_f32_e32 v133, 0x3fb8aa3b, v133
	v_exp_f32_e32 v157, v133
	s_nop 0
	v_pk_add_f32 v[156:157], v[156:157], 1.0 op_sel_hi:[1,0]
	s_nop 0
	v_rcp_f32_e32 v157, v157
	s_nop 0
	v_mul_f32_e32 v157, 2.0, v157
	v_rcp_f32_e32 v156, v156
	s_nop 0
	v_mul_f32_e32 v156, 2.0, v156
	v_pk_add_f32 v[160:161], v[156:157], 1.0 op_sel_hi:[1,0] neg_lo:[1,0] neg_hi:[1,0]

; #define PG8_STAGE(bufoff, gbase, voff) do { _Pragma("unroll") for (int _i = 0; _i < 2; ++_i) \
;         __builtin_amdgcn_global_load_lds((const unsigned*)((const char*)(gbase) + (voff)[_i]), (LAS unsigned*)(lds + (bufoff) + ldsw + _i * 8192), 16, 0, 0); } while (0)
; #define PG8_LDA(dst, b, h) do { _Pragma("unroll") for (int m = 0; m < 4; ++m) _Pragma("unroll") for (int k = 0; k < 2; ++k) dst[m][k] = *(const LAS bf16x8*)(lds + PG8_SA(b, h) + aoff + m * 2048 + k * 1024); } while (0)
; #define PG8_LDB(dst, b, h) do { _Pragma("unroll") for (int n = 0; n < 2; ++n) _Pragma("unroll") for (int k = 0; k < 2; ++k) dst[n][k] = *(const LAS bf16x8*)(lds + PG8_SB(b, h) + boff + n * 2048 + k * 1024); } while (0)
; #define PG8_MMA(ai, bj, At, Bt) do { __builtin_amdgcn_s_setprio(1); _Pragma("unroll") for (int m = 0; m < 4; ++m) _Pragma("unroll") for (int n = 0; n < 2; ++n) _Pragma("unroll") for (int k = 0; k < 2; ++k) \
;         acc[ai][bj][m][n] = __builtin_amdgcn_mfma_f32_16x16x32_bf16(Bt[n][k], At[m][k], acc[ai][bj][m][n], 0, 0, 0); __builtin_amdgcn_s_setprio(0); } while (0)
; #define PG8_WAIT_L(n) asm volatile("s_waitcnt lgkmcnt(" #n ")" ::: "memory")
; #define PG8_BAR __builtin_amdgcn_s_barrier()
; #define PG8_SCHED __builtin_amdgcn_sched_barrier(0)
;     __device__ __forceinline__ const char* a_ptr(const Unit& u) const { return (const char*)(A + (size_t)u.pm * 256 * lda); }
; template <class Epi, class GT>
; __device__ __forceinline__ void gemm_phase(LAS unsigned char* lds, const GT g, const StaticOrder& S, const Epi& E) {
;     ...
;         const bool has_next = S.next(ui + 1, nxt);
;         const char* nA = has_next ? g.a_ptr(nxt) : cA; const char* nB = has_next ? g.b_ptr(nxt) : cB;
;         for (int t = 0; t < nt; t += 2) {
;             const bool last = (t == nt - 2);
;             const char* a1 = cA + (size_t)(t + 1) * kstep;
;             const char* a2 = last ? nA : cA + (size_t)(t + 2) * kstep; const char* b2 = last ? nB : cB + (size_t)(t + 2) * kstep;
;             const char* a3 = a2 + kstep; const char* b3 = b2 + kstep;
;             PG8_LDB(B0, 0, 0); PG8_SCHED; PG8_LDA(At, 0, 0); PG8_STAGE(PG8_SA(1, 1), a1 + hstepA, voffA);
;             PG8_WAIT_L(8); PG8_BAR; PG8_WAIT_L(0); PG8_MMA(0, 0, At, B0); PG8_BAR; PG8_SCHED;
;             PG8_LDB(B1, 0, 1); PG8_STAGE(PG8_SB(0, 0), b2, voffB);
;             PG8_BAR; PG8_WAIT_L(0); PG8_MMA(0, 1, At, B1); PG8_BAR;
.LBB0_1686:
	s_add_u32 s10, s40, s5
	s_addc_u32 s11, s41, 0
	s_add_u32 s12, s10, 0x100
	s_addc_u32 s13, s11, 0
	s_and_b64 s[8:9], s[62:63], exec
	s_cselect_b32 s69, s59, s13
	s_cselect_b32 s68, s58, s12
	s_add_u32 s5, s38, s5
	s_addc_u32 s8, s39, 0
	s_add_u32 s5, s5, 0x100
	s_addc_u32 s12, s8, 0
	s_and_b64 s[8:9], s[62:63], exec
	s_cselect_b32 s71, s0, s12
	s_cselect_b32 s70, s1, s5
	s_add_u32 s72, s10, 0x30080
	s_addc_u32 s73, s11, 0
	s_add_i32 s16, s89, s79
	s_add_i32 m0, s81, 0xc000
	s_add_i32 s17, s81, 0xe000
	s_add_i32 s15, s16, 0x2000
	s_add_u32 s66, s70, 0x10000
	s_addc_u32 s67, s71, 0
	s_add_i32 s14, s90, s79
	s_add_i32 s13, s14, 0x2000
	s_add_i32 s12, 0, 0x18000
	ds_read_b128 v[130:133], v173
	ds_read_b128 v[134:137], v173 offset:1024
	ds_read_b128 v[138:141], v173 offset:2048
	ds_read_b128 v[142:145], v173 offset:3072
	s_add_u32 s64, s68, 0x30000
	s_addc_u32 s65, s69, 0
	s_add_i32 s11, s12, s79
	s_add_i32 s10, 0, 0x1c000
	s_add_i32 s9, s11, 0x2000
	s_add_u32 s62, s70, 0x10080
	s_addc_u32 s63, s71, 0
	s_add_i32 s8, s10, s79
	s_add_i32 s5, s8, 0x2000
	v_lshl_add_u64 v[168:169], s[72:73], 0, v[152:153]
	ds_read_b128 v[160:163], v174
	ds_read_b128 v[164:167], v174 offset:1024
	ds_read_b128 v[176:179], v174 offset:2048
	ds_read_b128 v[180:183], v174 offset:3072
	ds_read_b128 v[184:187], v174 offset:4096
	ds_read_b128 v[188:191], v174 offset:5120
	ds_read_b128 v[192:195], v174 offset:6144
	ds_read_b128 v[196:199], v174 offset:7168
	global_load_lds_dwordx4 v[168:169], off
	v_lshl_add_u64 v[168:169], s[72:73], 0, v[148:149]
	s_mov_b32 m0, s17
	s_nop 0
	global_load_lds_dwordx4 v[168:169], off
	s_waitcnt lgkmcnt(8)
	s_barrier
	s_waitcnt lgkmcnt(0)
	s_setprio 1
	s_waitcnt lgkmcnt(0)
	v_mfma_f32_16x16x32_bf16 v[126:129], v[130:133], v[160:163], v[126:129]
	v_mfma_f32_16x16x32_bf16 v[122:125], v[138:141], v[160:163], v[122:125]
	v_mfma_f32_16x16x32_bf16 v[118:121], v[130:133], v[176:179], v[118:121]
	v_mfma_f32_16x16x32_bf16 v[114:117], v[138:141], v[176:179], v[114:117]
	v_mfma_f32_16x16x32_bf16 v[102:105], v[130:133], v[184:187], v[102:105]
	v_mfma_f32_16x16x32_bf16 v[98:101], v[138:141], v[184:187], v[98:101]
	v_mfma_f32_16x16x32_bf16 v[86:89], v[130:133], v[192:195], v[86:89]
	v_mfma_f32_16x16x32_bf16 v[82:85], v[138:141], v[192:195], v[82:85]
	v_mfma_f32_16x16x32_bf16 v[126:129], v[134:137], v[164:167], v[126:129]
	v_mfma_f32_16x16x32_bf16 v[122:125], v[142:145], v[164:167], v[122:125]
	v_mfma_f32_16x16x32_bf16 v[118:121], v[134:137], v[180:183], v[118:121]
	v_mfma_f32_16x16x32_bf16 v[114:117], v[142:145], v[180:183], v[114:117]
	v_mfma_f32_16x16x32_bf16 v[102:105], v[134:137], v[188:191], v[102:105]
	v_mfma_f32_16x16x32_bf16 v[98:101], v[142:145], v[188:191], v[98:101]
	v_mfma_f32_16x16x32_bf16 v[86:89], v[134:137], v[196:199], v[86:89]
	v_mfma_f32_16x16x32_bf16 v[82:85], v[142:145], v[196:199], v[82:85]
	s_setprio 0
	s_barrier
	s_mov_b32 m0, s16
	v_lshl_add_u64 v[168:169], s[70:71], 0, v[150:151]
	ds_read_b128 v[200:203], v175
	ds_read_b128 v[204:207], v175 offset:1024
	ds_read_b128 v[208:211], v175 offset:2048
	ds_read_b128 v[212:215], v175 offset:3072
	global_load_lds_dwordx4 v[168:169], off
	v_lshl_add_u64 v[216:217], s[70:71], 0, v[146:147]
	s_mov_b32 m0, s15
	s_nop 0
	global_load_lds_dwordx4 v[216:217], off
	s_barrier
	s_waitcnt lgkmcnt(0)
	s_setprio 1
	s_waitcnt lgkmcnt(0)
	v_mfma_f32_16x16x32_bf16 v[110:113], v[200:203], v[160:163], v[110:113]
	v_mfma_f32_16x16x32_bf16 v[106:109], v[208:211], v[160:163], v[106:109]
	v_mfma_f32_16x16x32_bf16 v[94:97], v[200:203], v[176:179], v[94:97]
	v_mfma_f32_16x16x32_bf16 v[90:93], v[208:211], v[176:179], v[90:93]
	v_mfma_f32_16x16x32_bf16 v[78:81], v[200:203], v[184:187], v[78:81]
	v_mfma_f32_16x16x32_bf16 v[74:77], v[208:211], v[184:187], v[74:77]
	v_mfma_f32_16x16x32_bf16 v[70:73], v[200:203], v[192:195], v[70:73]
	v_mfma_f32_16x16x32_bf16 v[66:69], v[208:211], v[192:195], v[66:69]
	v_mfma_f32_16x16x32_bf16 v[110:113], v[204:207], v[164:167], v[110:113]
	v_mfma_f32_16x16x32_bf16 v[106:109], v[212:215], v[164:167], v[106:109]
	v_mfma_f32_16x16x32_bf16 v[94:97], v[204:207], v[180:183], v[94:97]
	v_mfma_f32_16x16x32_bf16 v[90:93], v[212:215], v[180:183], v[90:93]
	v_mfma_f32_16x16x32_bf16 v[78:81], v[204:207], v[188:191], v[78:81]
	v_mfma_f32_16x16x32_bf16 v[74:77], v[212:215], v[188:191], v[74:77]
	v_mfma_f32_16x16x32_bf16 v[70:73], v[204:207], v[196:199], v[70:73]
	v_mfma_f32_16x16x32_bf16 v[66:69], v[212:215], v[196:199], v[66:69]
	s_setprio 0
	s_mov_b32 m0, s81
	v_lshl_add_u64 v[218:219], s[68:69], 0, v[152:153]
	s_barrier
	ds_read_b128 v[160:163], v174 offset:16384
	ds_read_b128 v[164:167], v174 offset:17408
	ds_read_b128 v[176:179], v174 offset:18432
	ds_read_b128 v[180:183], v174 offset:19456
	ds_read_b128 v[184:187], v174 offset:20480
	ds_read_b128 v[188:191], v174 offset:21504
	ds_read_b128 v[192:195], v174 offset:22528
	ds_read_b128 v[196:199], v174 offset:23552
	global_load_lds_dwordx4 v[218:219], off
	v_lshl_add_u64 v[220:221], s[68:69], 0, v[148:149]
	s_mov_b32 m0, s83
	s_nop 0
	global_load_lds_dwordx4 v[220:221], off
	s_barrier
; #define PG8_STAGE(bufoff, gbase, voff) do { _Pragma("unroll") for (int _i = 0; _i < 2; ++_i) \
;         __builtin_amdgcn_global_load_lds((const unsigned*)((const char*)(gbase) + (voff)[_i]), (LAS unsigned*)(lds + (bufoff) + ldsw + _i * 8192), 16, 0, 0); } while (0)
; #define PG8_LDA(dst, b, h) do { _Pragma("unroll") for (int m = 0; m < 4; ++m) _Pragma("unroll") for (int k = 0; k < 2; ++k) dst[m][k] = *(const LAS bf16x8*)(lds + PG8_SA(b, h) + aoff + m * 2048 + k * 1024); } while (0)
; #define PG8_LDB(dst, b, h) do { _Pragma("unroll") for (int n = 0; n < 2; ++n) _Pragma("unroll") for (int k = 0; k < 2; ++k) dst[n][k] = *(const LAS bf16x8*)(lds + PG8_SB(b, h) + boff + n * 2048 + k * 1024); } while (0)
; #define PG8_MMA(ai, bj, At, Bt) do { __builtin_amdgcn_s_setprio(1); _Pragma("unroll") for (int m = 0; m < 4; ++m) _Pragma("unroll") for (int n = 0; n < 2; ++n) _Pragma("unroll") for (int k = 0; k < 2; ++k) \
;         acc[ai][bj][m][n] = __builtin_amdgcn_mfma_f32_16x16x32_bf16(Bt[n][k], At[m][k], acc[ai][bj][m][n], 0, 0, 0); __builtin_amdgcn_s_setprio(0); } while (0)
; #define PG8_WAIT_V(n) asm volatile("s_waitcnt vmcnt(" #n ")" ::: "memory")
; #define PG8_WAIT_L(n) asm volatile("s_waitcnt lgkmcnt(" #n ")" ::: "memory")
; #define PG8_BAR __builtin_amdgcn_s_barrier()
; #define PG8_SCHED __builtin_amdgcn_sched_barrier(0)
; template <class Epi, class GT>
; __device__ __forceinline__ void gemm_phase(LAS unsigned char* lds, const GT g, const StaticOrder& S, const Epi& E) {
;     ...
;             PG8_BAR; PG8_WAIT_L(0); PG8_MMA(1, 0, At, B0); PG8_BAR; PG8_SCHED;
;             PG8_STAGE(PG8_SB(0, 1), b2 + hstepB, voffB);
;             PG8_WAIT_V(6); PG8_BAR; PG8_MMA(1, 1, At, B1); PG8_BAR;
;             PG8_LDB(B0, 1, 0); PG8_SCHED; PG8_LDA(At, 1, 0); PG8_STAGE(PG8_SA(0, 1), a2 + hstepA, voffA);
;             PG8_WAIT_L(8); PG8_BAR; PG8_WAIT_L(0); PG8_MMA(0, 0, At, B0); PG8_BAR; PG8_SCHED;
;             PG8_LDB(B1, 1, 1); PG8_STAGE(PG8_SB(1, 0), b3, voffB);
;             PG8_BAR; PG8_WAIT_L(0); PG8_MMA(0, 1, At, B1); PG8_BAR;
	s_waitcnt lgkmcnt(0)
	s_setprio 1
	s_waitcnt lgkmcnt(0)
	v_mfma_f32_16x16x32_bf16 v[62:65], v[130:133], v[160:163], v[62:65]
	v_mfma_f32_16x16x32_bf16 v[58:61], v[138:141], v[160:163], v[58:61]
	v_mfma_f32_16x16x32_bf16 v[54:57], v[130:133], v[176:179], v[54:57]
	v_mfma_f32_16x16x32_bf16 v[50:53], v[138:141], v[176:179], v[50:53]
	v_mfma_f32_16x16x32_bf16 v[38:41], v[130:133], v[184:187], v[38:41]
	v_mfma_f32_16x16x32_bf16 v[34:37], v[138:141], v[184:187], v[34:37]
	v_mfma_f32_16x16x32_bf16 v[22:25], v[130:133], v[192:195], v[22:25]
	v_mfma_f32_16x16x32_bf16 v[18:21], v[138:141], v[192:195], v[18:21]
	v_mfma_f32_16x16x32_bf16 v[62:65], v[134:137], v[164:167], v[62:65]
	v_mfma_f32_16x16x32_bf16 v[58:61], v[142:145], v[164:167], v[58:61]
	v_mfma_f32_16x16x32_bf16 v[54:57], v[134:137], v[180:183], v[54:57]
	v_mfma_f32_16x16x32_bf16 v[50:53], v[142:145], v[180:183], v[50:53]
	v_mfma_f32_16x16x32_bf16 v[38:41], v[134:137], v[188:191], v[38:41]
	v_mfma_f32_16x16x32_bf16 v[34:37], v[142:145], v[188:191], v[34:37]
	v_mfma_f32_16x16x32_bf16 v[22:25], v[134:137], v[196:199], v[22:25]
	v_mfma_f32_16x16x32_bf16 v[18:21], v[142:145], v[196:199], v[18:21]
	s_setprio 0
	s_barrier
	s_mov_b32 m0, s14
	v_lshl_add_u64 v[130:131], s[66:67], 0, v[150:151]
	global_load_lds_dwordx4 v[130:131], off
	v_lshl_add_u64 v[130:131], s[66:67], 0, v[146:147]
	s_mov_b32 m0, s13
	s_nop 0
	global_load_lds_dwordx4 v[130:131], off
	s_waitcnt vmcnt(6)
	s_barrier
	s_setprio 1
	v_mfma_f32_16x16x32_bf16 v[46:49], v[200:203], v[160:163], v[46:49]
	v_mfma_f32_16x16x32_bf16 v[42:45], v[208:211], v[160:163], v[42:45]
	v_mfma_f32_16x16x32_bf16 v[30:33], v[200:203], v[176:179], v[30:33]
	v_mfma_f32_16x16x32_bf16 v[26:29], v[208:211], v[176:179], v[26:29]
	v_mfma_f32_16x16x32_bf16 v[14:17], v[200:203], v[184:187], v[14:17]
	v_mfma_f32_16x16x32_bf16 v[10:13], v[208:211], v[184:187], v[10:13]
	v_mfma_f32_16x16x32_bf16 v[6:9], v[200:203], v[192:195], v[6:9]
	v_mfma_f32_16x16x32_bf16 v[2:5], v[208:211], v[192:195], v[2:5]
	v_mfma_f32_16x16x32_bf16 v[46:49], v[204:207], v[164:167], v[46:49]
	v_mfma_f32_16x16x32_bf16 v[42:45], v[212:215], v[164:167], v[42:45]
	v_mfma_f32_16x16x32_bf16 v[30:33], v[204:207], v[180:183], v[30:33]
	v_mfma_f32_16x16x32_bf16 v[26:29], v[212:215], v[180:183], v[26:29]
	v_mfma_f32_16x16x32_bf16 v[14:17], v[204:207], v[188:191], v[14:17]
	v_mfma_f32_16x16x32_bf16 v[10:13], v[212:215], v[188:191], v[10:13]
	v_mfma_f32_16x16x32_bf16 v[6:9], v[204:207], v[196:199], v[6:9]
	v_mfma_f32_16x16x32_bf16 v[2:5], v[212:215], v[196:199], v[2:5]
	s_setprio 0
	v_add_u32_e32 v142, s12, v171
	s_barrier
	ds_read_b128 v[130:133], v142
	ds_read_b128 v[134:137], v142 offset:1024
	ds_read_b128 v[138:141], v142 offset:2048
	ds_read_b128 v[142:145], v142 offset:3072
	s_mov_b32 m0, s84
	v_lshl_add_u64 v[200:201], s[64:65], 0, v[152:153]
	ds_read_b128 v[160:163], v174 offset:32768
	ds_read_b128 v[164:167], v174 offset:33792
	ds_read_b128 v[176:179], v174 offset:34816
	ds_read_b128 v[180:183], v174 offset:35840
	ds_read_b128 v[184:187], v174 offset:36864
	ds_read_b128 v[188:191], v174 offset:37888
	ds_read_b128 v[192:195], v174 offset:38912
	ds_read_b128 v[196:199], v174 offset:39936
	global_load_lds_dwordx4 v[200:201], off
	v_lshl_add_u64 v[200:201], s[64:65], 0, v[148:149]
	s_mov_b32 m0, s85
	s_nop 0
	global_load_lds_dwordx4 v[200:201], off
	s_waitcnt lgkmcnt(8)
	s_barrier
	s_waitcnt lgkmcnt(0)
	s_setprio 1
	s_waitcnt lgkmcnt(0)
	v_mfma_f32_16x16x32_bf16 v[126:129], v[130:133], v[160:163], v[126:129]
	v_mfma_f32_16x16x32_bf16 v[122:125], v[138:141], v[160:163], v[122:125]
	v_mfma_f32_16x16x32_bf16 v[118:121], v[130:133], v[176:179], v[118:121]
	v_mfma_f32_16x16x32_bf16 v[114:117], v[138:141], v[176:179], v[114:117]
	v_mfma_f32_16x16x32_bf16 v[102:105], v[130:133], v[184:187], v[102:105]
	v_mfma_f32_16x16x32_bf16 v[98:101], v[138:141], v[184:187], v[98:101]
	v_mfma_f32_16x16x32_bf16 v[86:89], v[130:133], v[192:195], v[86:89]
	v_mfma_f32_16x16x32_bf16 v[82:85], v[138:141], v[192:195], v[82:85]
	v_mfma_f32_16x16x32_bf16 v[126:129], v[134:137], v[164:167], v[126:129]
	v_mfma_f32_16x16x32_bf16 v[122:125], v[142:145], v[164:167], v[122:125]
	v_mfma_f32_16x16x32_bf16 v[118:121], v[134:137], v[180:183], v[118:121]
	v_mfma_f32_16x16x32_bf16 v[114:117], v[142:145], v[180:183], v[114:117]
	v_mfma_f32_16x16x32_bf16 v[102:105], v[134:137], v[188:191], v[102:105]
	v_mfma_f32_16x16x32_bf16 v[98:101], v[142:145], v[188:191], v[98:101]
	v_mfma_f32_16x16x32_bf16 v[86:89], v[134:137], v[196:199], v[86:89]
	v_mfma_f32_16x16x32_bf16 v[82:85], v[142:145], v[196:199], v[82:85]
	s_setprio 0
	s_barrier
	s_mov_b32 m0, s11
	v_add_u32_e32 v154, s10, v171
	v_lshl_add_u64 v[168:169], v[168:169], 0, s[54:55]
	ds_read_b128 v[200:203], v154
	ds_read_b128 v[204:207], v154 offset:1024
	ds_read_b128 v[208:211], v154 offset:2048
	ds_read_b128 v[212:215], v154 offset:3072
	global_load_lds_dwordx4 v[168:169], off
	v_lshl_add_u64 v[168:169], v[216:217], 0, s[54:55]
	s_mov_b32 m0, s9
	s_nop 0
	global_load_lds_dwordx4 v[168:169], off
	s_barrier
; #define PG8_STAGE(bufoff, gbase, voff) do { _Pragma("unroll") for (int _i = 0; _i < 2; ++_i) \
;         __builtin_amdgcn_global_load_lds((const unsigned*)((const char*)(gbase) + (voff)[_i]), (LAS unsigned*)(lds + (bufoff) + ldsw + _i * 8192), 16, 0, 0); } while (0)
; #define PG8_LDA(dst, b, h) do { _Pragma("unroll") for (int m = 0; m < 4; ++m) _Pragma("unroll") for (int k = 0; k < 2; ++k) dst[m][k] = *(const LAS bf16x8*)(lds + PG8_SA(b, h) + aoff + m * 2048 + k * 1024); } while (0)
; #define PG8_MMA(ai, bj, At, Bt) do { __builtin_amdgcn_s_setprio(1); _Pragma("unroll") for (int m = 0; m < 4; ++m) _Pragma("unroll") for (int n = 0; n < 2; ++n) _Pragma("unroll") for (int k = 0; k < 2; ++k) \
;         acc[ai][bj][m][n] = __builtin_amdgcn_mfma_f32_16x16x32_bf16(Bt[n][k], At[m][k], acc[ai][bj][m][n], 0, 0, 0); __builtin_amdgcn_s_setprio(0); } while (0)
; #define PG8_WAIT_V(n) asm volatile("s_waitcnt vmcnt(" #n ")" ::: "memory")
; #define PG8_WAIT_L(n) asm volatile("s_waitcnt lgkmcnt(" #n ")" ::: "memory")
; #define PG8_BAR __builtin_amdgcn_s_barrier()
; #define PG8_SCHED __builtin_amdgcn_sched_barrier(0)
; template <class Epi, class GT>
; __device__ __forceinline__ void gemm_phase(LAS unsigned char* lds, const GT g, const StaticOrder& S, const Epi& E) {
;     ...
;             PG8_BAR; PG8_WAIT_L(0); PG8_MMA(0, 1, At, B1); PG8_BAR;
;             PG8_LDA(At, 1, 1); PG8_STAGE(PG8_SA(1, 0), a3, voffA);
;             PG8_BAR; PG8_WAIT_L(0); PG8_MMA(1, 0, At, B0); PG8_BAR; PG8_SCHED;
;             PG8_STAGE(PG8_SB(1, 1), b3 + hstepB, voffB);
;             PG8_WAIT_V(6); PG8_BAR; PG8_MMA(1, 1, At, B1); PG8_BAR;
;         }
;         E(acc, cur, wr, wc, fr, fq);
	s_waitcnt lgkmcnt(0)
	s_setprio 1
	s_waitcnt lgkmcnt(0)
	v_mfma_f32_16x16x32_bf16 v[110:113], v[200:203], v[160:163], v[110:113]
	v_mfma_f32_16x16x32_bf16 v[106:109], v[208:211], v[160:163], v[106:109]
	v_mfma_f32_16x16x32_bf16 v[94:97], v[200:203], v[176:179], v[94:97]
	v_mfma_f32_16x16x32_bf16 v[90:93], v[208:211], v[176:179], v[90:93]
	v_mfma_f32_16x16x32_bf16 v[78:81], v[200:203], v[184:187], v[78:81]
	v_mfma_f32_16x16x32_bf16 v[74:77], v[208:211], v[184:187], v[74:77]
	v_mfma_f32_16x16x32_bf16 v[70:73], v[200:203], v[192:195], v[70:73]
	v_mfma_f32_16x16x32_bf16 v[66:69], v[208:211], v[192:195], v[66:69]
	v_mfma_f32_16x16x32_bf16 v[110:113], v[204:207], v[164:167], v[110:113]
	v_mfma_f32_16x16x32_bf16 v[106:109], v[212:215], v[164:167], v[106:109]
	v_mfma_f32_16x16x32_bf16 v[94:97], v[204:207], v[180:183], v[94:97]
	v_mfma_f32_16x16x32_bf16 v[90:93], v[212:215], v[180:183], v[90:93]
	v_mfma_f32_16x16x32_bf16 v[78:81], v[204:207], v[188:191], v[78:81]
	v_mfma_f32_16x16x32_bf16 v[74:77], v[212:215], v[188:191], v[74:77]
	v_mfma_f32_16x16x32_bf16 v[70:73], v[204:207], v[196:199], v[70:73]
	v_mfma_f32_16x16x32_bf16 v[66:69], v[212:215], v[196:199], v[66:69]
	s_setprio 0
	s_mov_b32 m0, s87
	v_lshl_add_u64 v[168:169], v[218:219], 0, s[54:55]
	s_barrier
	ds_read_b128 v[160:163], v174 offset:49152
	ds_read_b128 v[164:167], v174 offset:50176
	ds_read_b128 v[176:179], v174 offset:51200
	ds_read_b128 v[180:183], v174 offset:52224
	ds_read_b128 v[184:187], v174 offset:53248
	ds_read_b128 v[188:191], v174 offset:54272
	ds_read_b128 v[192:195], v174 offset:55296
	ds_read_b128 v[196:199], v174 offset:56320
	global_load_lds_dwordx4 v[168:169], off
	v_lshl_add_u64 v[168:169], v[220:221], 0, s[54:55]
	s_mov_b32 m0, s88
	s_nop 0
	global_load_lds_dwordx4 v[168:169], off
	s_barrier
	s_waitcnt lgkmcnt(0)
	s_setprio 1
	s_waitcnt lgkmcnt(0)
	v_mfma_f32_16x16x32_bf16 v[62:65], v[130:133], v[160:163], v[62:65]
	v_mfma_f32_16x16x32_bf16 v[58:61], v[138:141], v[160:163], v[58:61]
	v_mfma_f32_16x16x32_bf16 v[54:57], v[130:133], v[176:179], v[54:57]
	v_mfma_f32_16x16x32_bf16 v[50:53], v[138:141], v[176:179], v[50:53]
	v_mfma_f32_16x16x32_bf16 v[38:41], v[130:133], v[184:187], v[38:41]
	v_mfma_f32_16x16x32_bf16 v[34:37], v[138:141], v[184:187], v[34:37]
	v_mfma_f32_16x16x32_bf16 v[22:25], v[130:133], v[192:195], v[22:25]
	v_mfma_f32_16x16x32_bf16 v[18:21], v[138:141], v[192:195], v[18:21]
	v_mfma_f32_16x16x32_bf16 v[62:65], v[134:137], v[164:167], v[62:65]
	v_mfma_f32_16x16x32_bf16 v[58:61], v[142:145], v[164:167], v[58:61]
	v_mfma_f32_16x16x32_bf16 v[54:57], v[134:137], v[180:183], v[54:57]
	v_mfma_f32_16x16x32_bf16 v[50:53], v[142:145], v[180:183], v[50:53]
	v_mfma_f32_16x16x32_bf16 v[38:41], v[134:137], v[188:191], v[38:41]
	v_mfma_f32_16x16x32_bf16 v[34:37], v[142:145], v[188:191], v[34:37]
	v_mfma_f32_16x16x32_bf16 v[22:25], v[134:137], v[196:199], v[22:25]
	v_mfma_f32_16x16x32_bf16 v[18:21], v[142:145], v[196:199], v[18:21]
	s_setprio 0
	s_barrier
	s_mov_b32 m0, s8
	v_lshl_add_u64 v[130:131], s[62:63], 0, v[150:151]
	global_load_lds_dwordx4 v[130:131], off
	v_lshl_add_u64 v[130:131], s[62:63], 0, v[146:147]
	s_mov_b32 m0, s5
	s_nop 0
	global_load_lds_dwordx4 v[130:131], off
	s_waitcnt vmcnt(6)
	s_barrier
	s_setprio 1
	v_mfma_f32_16x16x32_bf16 v[46:49], v[200:203], v[160:163], v[46:49]
	v_mfma_f32_16x16x32_bf16 v[42:45], v[208:211], v[160:163], v[42:45]
	v_mfma_f32_16x16x32_bf16 v[30:33], v[200:203], v[176:179], v[30:33]
	v_mfma_f32_16x16x32_bf16 v[26:29], v[208:211], v[176:179], v[26:29]
	v_mfma_f32_16x16x32_bf16 v[14:17], v[200:203], v[184:187], v[14:17]
	v_mfma_f32_16x16x32_bf16 v[10:13], v[208:211], v[184:187], v[10:13]
	v_mfma_f32_16x16x32_bf16 v[6:9], v[200:203], v[192:195], v[6:9]
	v_mfma_f32_16x16x32_bf16 v[2:5], v[208:211], v[192:195], v[2:5]
	v_mfma_f32_16x16x32_bf16 v[46:49], v[204:207], v[164:167], v[46:49]
	v_mfma_f32_16x16x32_bf16 v[42:45], v[212:215], v[164:167], v[42:45]
	v_mfma_f32_16x16x32_bf16 v[30:33], v[204:207], v[180:183], v[30:33]
	v_mfma_f32_16x16x32_bf16 v[26:29], v[212:215], v[180:183], v[26:29]
	v_mfma_f32_16x16x32_bf16 v[14:17], v[204:207], v[188:191], v[14:17]
	v_mfma_f32_16x16x32_bf16 v[10:13], v[212:215], v[188:191], v[10:13]
	v_mfma_f32_16x16x32_bf16 v[6:9], v[204:207], v[196:199], v[6:9]
	v_mfma_f32_16x16x32_bf16 v[2:5], v[212:215], v[196:199], v[2:5]
	s_setprio 0
	s_movk_i32 s5, 0x100
	s_andn2_b64 vcc, exec, s[44:45]
	s_mov_b64 s[62:63], -1
	s_mov_b64 s[44:45], 0
	s_barrier
	s_cbranch_vccz .LBB0_1686
	v_lshl_add_u32 v160, s4, 8, v170
	s_lshl_b32 s4, s3, 8
	s_and_b32 s0, s4, 0x700
	v_or_b32_e32 v134, s0, v172
	v_or_b32_e32 v162, 16, v160
	s_mov_b64 s[0:1], -1
	s_cmp_lt_i32 s3, 32
	v_lshlrev_b32_e32 v154, 1, v134
	v_ashrrev_i32_e32 v161, 31, v160
	v_ashrrev_i32_e32 v163, 31, v162
	s_cbranch_scc0 .LBB0_1689
; __device__ __forceinline__ float sigmoidf_(float x) { return 1.0f / (1.0f + __expf(-x)); }
	s_and_b32 s4, s4, 0x800
	s_lshl_b32 s5, s4, 2
	s_cmp_gt_i32 s3, 15
	s_cselect_b64 s[44:45], -1, 0
	s_and_b64 s[0:1], s[44:45], exec
	s_cselect_b32 s0, s48, s50
	s_mov_b32 s3, 0x56400000
	s_cselect_b32 s1, s49, s51
	s_cselect_b32 s3, s3, 0x4dc00000
	s_add_u32 s0, s0, s5
	v_lshlrev_b32_e32 v134, 2, v134
	s_addc_u32 s1, s1, 0
	global_load_dwordx4 v[138:141], v134, s[0:1] offset:16
	global_load_dwordx4 v[142:145], v134, s[0:1]
	global_load_dwordx4 v[130:133], v134, s[0:1] offset:528
	global_load_dwordx4 v[134:137], v134, s[0:1] offset:512
	s_add_u32 s3, s46, s3
	s_addc_u32 s5, s47, 0
	s_lshl_b32 s0, s4, 1
	s_add_u32 s0, s3, s0
	s_addc_u32 s1, s5, 0
	v_lshl_add_u64 v[166:167], s[0:1], 0, v[154:155]
	v_lshlrev_b64 v[164:165], 13, v[160:161]
	v_lshl_add_u64 v[164:165], v[166:167], 0, v[164:165]
	s_waitcnt vmcnt(0)
	v_add_f32_e32 v168, v126, v142
	v_mul_f32_e32 v168, 0xbfb8aa3b, v168
	v_exp_f32_e32 v168, v168
	s_nop 0
	v_add_f32_e32 v168, 1.0, v168
	v_rcp_f32_e32 v168, v168
	s_nop 0
	v_mul_f32_e32 v169, 0xbf1b4598, v168
	v_mul_f32_e32 v169, 0x3fb8aa3b, v169
	v_exp_f32_e32 v169, v169
	s_nop 0
	v_cndmask_b32_e64 v168, v169, v168, s[44:45]
	v_add_f32_e32 v169, v127, v143
	v_mul_f32_e32 v169, 0xbfb8aa3b, v169
	v_exp_f32_e32 v169, v169
	s_nop 0
	v_add_f32_e32 v169, 1.0, v169
	v_rcp_f32_e32 v169, v169
	s_nop 0
	v_mul_f32_e32 v176, 0xbf1b4598, v169
	v_mul_f32_e32 v176, 0x3fb8aa3b, v176
	v_exp_f32_e32 v176, v176
	s_nop 0
	v_cndmask_b32_e64 v169, v176, v169, s[44:45]
	v_add_f32_e32 v176, v128, v144
	v_mul_f32_e32 v176, 0xbfb8aa3b, v176
	v_exp_f32_e32 v176, v176
	s_nop 0
	v_add_f32_e32 v176, 1.0, v176
	v_rcp_f32_e32 v176, v176
	s_nop 0
	v_mul_f32_e32 v177, 0xbf1b4598, v176
	v_mul_f32_e32 v177, 0x3fb8aa3b, v177
	v_exp_f32_e32 v177, v177
	s_nop 0
	v_cndmask_b32_e64 v176, v177, v176, s[44:45]
	v_add_f32_e32 v177, v129, v145
	v_mul_f32_e32 v177, 0xbfb8aa3b, v177
	v_exp_f32_e32 v177, v177
	s_nop 0
	v_add_f32_e32 v177, 1.0, v177
	v_rcp_f32_e32 v177, v177
	s_nop 0
	v_mul_f32_e32 v178, 0xbf1b4598, v177
	v_mul_f32_e32 v178, 0x3fb8aa3b, v178
	v_exp_f32_e32 v178, v178
	s_nop 0
	v_cndmask_b32_e64 v177, v178, v177, s[44:45]
	v_add_f32_e32 v178, v122, v138
	v_mul_f32_e32 v178, 0xbfb8aa3b, v178
	v_exp_f32_e32 v178, v178
	s_nop 0
	v_add_f32_e32 v178, 1.0, v178
	v_rcp_f32_e32 v178, v178
	s_nop 0
	v_mul_f32_e32 v179, 0xbf1b4598, v178
	v_mul_f32_e32 v179, 0x3fb8aa3b, v179
	v_exp_f32_e32 v179, v179
	s_nop 0
	v_cndmask_b32_e64 v180, v179, v178, s[44:45]
	v_add_f32_e32 v178, v123, v139
	v_mul_f32_e32 v178, 0xbfb8aa3b, v178
	v_exp_f32_e32 v178, v178
	s_nop 0
	v_add_f32_e32 v178, 1.0, v178
	v_rcp_f32_e32 v178, v178
	s_nop 0
	v_mul_f32_e32 v179, 0xbf1b4598, v178
	v_mul_f32_e32 v179, 0x3fb8aa3b, v179
	v_exp_f32_e32 v179, v179
	s_nop 0
	v_cndmask_b32_e64 v181, v179, v178, s[44:45]
	v_add_f32_e32 v178, v124, v140
	v_mul_f32_e32 v178, 0xbfb8aa3b, v178
	v_exp_f32_e32 v178, v178
	v_cvt_pk_bf16_f32 v180, v180, v181
	v_add_f32_e32 v178, 1.0, v178
	v_rcp_f32_e32 v178, v178
	s_nop 0
	v_mul_f32_e32 v179, 0xbf1b4598, v178
	v_mul_f32_e32 v179, 0x3fb8aa3b, v179
	v_exp_f32_e32 v179, v179
	s_nop 0
	v_cndmask_b32_e64 v182, v179, v178, s[44:45]
	v_add_f32_e32 v178, v125, v141
	v_mul_f32_e32 v178, 0xbfb8aa3b, v178
	v_exp_f32_e32 v178, v178
	s_nop 0
	v_add_f32_e32 v178, 1.0, v178
	v_rcp_f32_e32 v178, v178
	s_nop 0
	v_mul_f32_e32 v179, 0xbf1b4598, v178
	v_mul_f32_e32 v179, 0x3fb8aa3b, v179
	v_exp_f32_e32 v179, v179
	s_nop 0
	v_cndmask_b32_e64 v183, v179, v178, s[44:45]
	v_cvt_pk_bf16_f32 v178, v168, v169
	v_add_f32_e32 v168, v110, v134
	v_mul_f32_e32 v168, 0xbfb8aa3b, v168
	v_exp_f32_e32 v168, v168
	v_cvt_pk_bf16_f32 v179, v176, v177
	v_cvt_pk_bf16_f32 v181, v182, v183
	global_store_dwordx4 v[164:165], v[178:181], off
	v_add_f32_e32 v168, 1.0, v168
	v_rcp_f32_e32 v168, v168
	s_nop 0
	v_mul_f32_e32 v169, 0xbf1b4598, v168
	v_mul_f32_e32 v169, 0x3fb8aa3b, v169
	v_exp_f32_e32 v169, v169
	s_nop 0
	v_cndmask_b32_e64 v168, v169, v168, s[44:45]
	v_add_f32_e32 v169, v111, v135
	v_mul_f32_e32 v169, 0xbfb8aa3b, v169
	v_exp_f32_e32 v169, v169
	s_nop 0
	v_add_f32_e32 v169, 1.0, v169
	v_rcp_f32_e32 v169, v169
	s_nop 0
	v_mul_f32_e32 v176, 0xbf1b4598, v169
	v_mul_f32_e32 v176, 0x3fb8aa3b, v176
	v_exp_f32_e32 v176, v176
	s_nop 0
	v_cndmask_b32_e64 v169, v176, v169, s[44:45]
	v_add_f32_e32 v176, v112, v136
	v_mul_f32_e32 v176, 0xbfb8aa3b, v176
	v_exp_f32_e32 v176, v176
	s_nop 0
	v_add_f32_e32 v176, 1.0, v176
	v_rcp_f32_e32 v176, v176
	s_nop 0
	v_mul_f32_e32 v177, 0xbf1b4598, v176
	v_mul_f32_e32 v177, 0x3fb8aa3b, v177
	v_exp_f32_e32 v177, v177
	s_nop 0
	v_cndmask_b32_e64 v177, v177, v176, s[44:45]
	v_add_f32_e32 v176, v113, v137
	v_mul_f32_e32 v176, 0xbfb8aa3b, v176
	v_exp_f32_e32 v176, v176
	s_nop 0
	v_add_f32_e32 v176, 1.0, v176
	v_rcp_f32_e32 v176, v176
	s_nop 0
	v_mul_f32_e32 v178, 0xbf1b4598, v176
	v_mul_f32_e32 v178, 0x3fb8aa3b, v178
	v_exp_f32_e32 v178, v178
	s_nop 0
	v_cndmask_b32_e64 v178, v178, v176, s[44:45]
	v_add_f32_e32 v176, v106, v130
	v_mul_f32_e32 v176, 0xbfb8aa3b, v176
	v_exp_f32_e32 v176, v176
	v_cvt_pk_bf16_f32 v177, v177, v178
	v_add_f32_e32 v176, 1.0, v176
	v_rcp_f32_e32 v176, v176
	s_nop 0
	v_mul_f32_e32 v179, 0xbf1b4598, v176
	v_mul_f32_e32 v179, 0x3fb8aa3b, v179
	v_exp_f32_e32 v179, v179
	s_nop 0
	v_cndmask_b32_e64 v179, v179, v176, s[44:45]
	v_add_f32_e32 v176, v107, v131
	v_mul_f32_e32 v176, 0xbfb8aa3b, v176
	v_exp_f32_e32 v176, v176
	s_nop 0
	v_add_f32_e32 v176, 1.0, v176
	v_rcp_f32_e32 v176, v176
	s_nop 0
	v_mul_f32_e32 v180, 0xbf1b4598, v176
	v_mul_f32_e32 v180, 0x3fb8aa3b, v180
	v_exp_f32_e32 v180, v180
	s_nop 0
	v_cndmask_b32_e64 v180, v180, v176, s[44:45]
	v_add_f32_e32 v176, v108, v132
; __device__ __forceinline__ float sigmoidf_(float x) { return 1.0f / (1.0f + __expf(-x)); }
	v_mul_f32_e32 v176, 0xbfb8aa3b, v176
	v_exp_f32_e32 v176, v176
	v_cvt_pk_bf16_f32 v178, v179, v180
	v_add_f32_e32 v176, 1.0, v176
	v_rcp_f32_e32 v176, v176
	s_nop 0
	v_mul_f32_e32 v181, 0xbf1b4598, v176
	v_mul_f32_e32 v181, 0x3fb8aa3b, v181
	v_exp_f32_e32 v181, v181
	s_nop 0
	v_cndmask_b32_e64 v181, v181, v176, s[44:45]
	v_add_f32_e32 v176, v109, v133
	v_mul_f32_e32 v176, 0xbfb8aa3b, v176
	v_exp_f32_e32 v176, v176
	s_nop 0
	v_add_f32_e32 v176, 1.0, v176
	v_rcp_f32_e32 v176, v176
	s_nop 0
	v_mul_f32_e32 v182, 0xbf1b4598, v176
	v_mul_f32_e32 v182, 0x3fb8aa3b, v182
	v_exp_f32_e32 v182, v182
	s_nop 0
	v_cndmask_b32_e64 v182, v182, v176, s[44:45]
	v_cvt_pk_bf16_f32 v176, v168, v169
	v_cvt_pk_bf16_f32 v179, v181, v182
	global_store_dwordx4 v[164:165], v[176:179], off offset:256
	v_lshlrev_b64 v[168:169], 13, v[162:163]
	v_lshl_add_u64 v[168:169], v[166:167], 0, v[168:169]
	v_add_f32_e32 v176, v118, v142
	v_mul_f32_e32 v176, 0xbfb8aa3b, v176
	v_exp_f32_e32 v176, v176
	s_nop 0
	v_add_f32_e32 v176, 1.0, v176
	v_rcp_f32_e32 v176, v176
	s_nop 0
	v_mul_f32_e32 v177, 0xbf1b4598, v176
	v_mul_f32_e32 v177, 0x3fb8aa3b, v177
	v_exp_f32_e32 v177, v177
	s_nop 0
	v_cndmask_b32_e64 v176, v177, v176, s[44:45]
	v_add_f32_e32 v177, v119, v143
	v_mul_f32_e32 v177, 0xbfb8aa3b, v177
	v_exp_f32_e32 v177, v177
	s_nop 0
	v_add_f32_e32 v177, 1.0, v177
	v_rcp_f32_e32 v177, v177
	s_nop 0
	v_mul_f32_e32 v178, 0xbf1b4598, v177
	v_mul_f32_e32 v178, 0x3fb8aa3b, v178
	v_exp_f32_e32 v178, v178
	s_nop 0
	v_cndmask_b32_e64 v177, v178, v177, s[44:45]
	v_add_f32_e32 v178, v120, v144
	v_mul_f32_e32 v178, 0xbfb8aa3b, v178
	v_exp_f32_e32 v178, v178
	v_cvt_pk_bf16_f32 v176, v176, v177
	v_add_f32_e32 v178, 1.0, v178
	v_rcp_f32_e32 v178, v178
	s_nop 0
	v_mul_f32_e32 v179, 0xbf1b4598, v178
	v_mul_f32_e32 v179, 0x3fb8aa3b, v179
	v_exp_f32_e32 v179, v179
	s_nop 0
	v_cndmask_b32_e64 v178, v179, v178, s[44:45]
	v_add_f32_e32 v179, v121, v145
	v_mul_f32_e32 v179, 0xbfb8aa3b, v179
	v_exp_f32_e32 v179, v179
	s_nop 0
	v_add_f32_e32 v179, 1.0, v179
	v_rcp_f32_e32 v179, v179
	s_nop 0
	v_mul_f32_e32 v180, 0xbf1b4598, v179
	v_mul_f32_e32 v180, 0x3fb8aa3b, v180
	v_exp_f32_e32 v180, v180
	s_nop 0
	v_cndmask_b32_e64 v179, v180, v179, s[44:45]
	v_add_f32_e32 v180, v114, v138
	v_mul_f32_e32 v180, 0xbfb8aa3b, v180
	v_exp_f32_e32 v180, v180
	v_cvt_pk_bf16_f32 v177, v178, v179
	v_add_f32_e32 v180, 1.0, v180
	v_rcp_f32_e32 v180, v180
	s_nop 0
	v_mul_f32_e32 v181, 0xbf1b4598, v180
	v_mul_f32_e32 v181, 0x3fb8aa3b, v181
	v_exp_f32_e32 v181, v181
	s_nop 0
	v_cndmask_b32_e64 v180, v181, v180, s[44:45]
	v_add_f32_e32 v181, v115, v139
	v_mul_f32_e32 v181, 0xbfb8aa3b, v181
	v_exp_f32_e32 v181, v181
	s_nop 0
	v_add_f32_e32 v181, 1.0, v181
	v_rcp_f32_e32 v181, v181
	s_nop 0
	v_mul_f32_e32 v182, 0xbf1b4598, v181
	v_mul_f32_e32 v182, 0x3fb8aa3b, v182
	v_exp_f32_e32 v182, v182
	s_nop 0
	v_cndmask_b32_e64 v181, v182, v181, s[44:45]
	v_add_f32_e32 v182, v116, v140
	v_mul_f32_e32 v182, 0xbfb8aa3b, v182
	v_exp_f32_e32 v182, v182
	v_cvt_pk_bf16_f32 v178, v180, v181
	v_add_f32_e32 v182, 1.0, v182
	v_rcp_f32_e32 v182, v182
	s_nop 0
	v_mul_f32_e32 v183, 0xbf1b4598, v182
	v_mul_f32_e32 v183, 0x3fb8aa3b, v183
	v_exp_f32_e32 v183, v183
	s_nop 0
	v_cndmask_b32_e64 v182, v183, v182, s[44:45]
	v_add_f32_e32 v183, v117, v141
	v_mul_f32_e32 v183, 0xbfb8aa3b, v183
	v_exp_f32_e32 v183, v183
	s_nop 0
	v_add_f32_e32 v183, 1.0, v183
	v_rcp_f32_e32 v183, v183
	s_nop 0
	v_mul_f32_e32 v184, 0xbf1b4598, v183
	v_mul_f32_e32 v184, 0x3fb8aa3b, v184
	v_exp_f32_e32 v184, v184
	s_nop 0
	v_cndmask_b32_e64 v183, v184, v183, s[44:45]
	v_cvt_pk_bf16_f32 v179, v182, v183
	global_store_dwordx4 v[168:169], v[176:179], off
	s_nop 1
	v_add_f32_e32 v176, v94, v134
	v_mul_f32_e32 v176, 0xbfb8aa3b, v176
	v_exp_f32_e32 v176, v176
	s_nop 0
	v_add_f32_e32 v176, 1.0, v176
	v_rcp_f32_e32 v176, v176
	s_nop 0
	v_mul_f32_e32 v177, 0xbf1b4598, v176
	v_mul_f32_e32 v177, 0x3fb8aa3b, v177
	v_exp_f32_e32 v177, v177
	s_nop 0
	v_cndmask_b32_e64 v176, v177, v176, s[44:45]
	v_add_f32_e32 v177, v95, v135
	v_mul_f32_e32 v177, 0xbfb8aa3b, v177
	v_exp_f32_e32 v177, v177
	s_nop 0
	v_add_f32_e32 v177, 1.0, v177
	v_rcp_f32_e32 v177, v177
	s_nop 0
	v_mul_f32_e32 v178, 0xbf1b4598, v177
	v_mul_f32_e32 v178, 0x3fb8aa3b, v178
	v_exp_f32_e32 v178, v178
	s_nop 0
	v_cndmask_b32_e64 v177, v178, v177, s[44:45]
	v_add_f32_e32 v178, v96, v136
	v_mul_f32_e32 v178, 0xbfb8aa3b, v178
	v_exp_f32_e32 v178, v178
	v_cvt_pk_bf16_f32 v176, v176, v177
	v_add_f32_e32 v178, 1.0, v178
	v_rcp_f32_e32 v178, v178
	s_nop 0
	v_mul_f32_e32 v179, 0xbf1b4598, v178
	v_mul_f32_e32 v179, 0x3fb8aa3b, v179
	v_exp_f32_e32 v179, v179
	s_nop 0
	v_cndmask_b32_e64 v178, v179, v178, s[44:45]
	v_add_f32_e32 v179, v97, v137
	v_mul_f32_e32 v179, 0xbfb8aa3b, v179
	v_exp_f32_e32 v179, v179
	s_nop 0
	v_add_f32_e32 v179, 1.0, v179
	v_rcp_f32_e32 v179, v179
	s_nop 0
	v_mul_f32_e32 v180, 0xbf1b4598, v179
	v_mul_f32_e32 v180, 0x3fb8aa3b, v180
	v_exp_f32_e32 v180, v180
	s_nop 0
	v_cndmask_b32_e64 v179, v180, v179, s[44:45]
	v_add_f32_e32 v180, v90, v130
	v_mul_f32_e32 v180, 0xbfb8aa3b, v180
	v_exp_f32_e32 v180, v180
	v_cvt_pk_bf16_f32 v177, v178, v179
	v_add_f32_e32 v180, 1.0, v180
	v_rcp_f32_e32 v180, v180
	s_nop 0
	v_mul_f32_e32 v181, 0xbf1b4598, v180
	v_mul_f32_e32 v181, 0x3fb8aa3b, v181
	v_exp_f32_e32 v181, v181
	s_nop 0
	v_cndmask_b32_e64 v180, v181, v180, s[44:45]
	v_add_f32_e32 v181, v91, v131
	v_mul_f32_e32 v181, 0xbfb8aa3b, v181
	v_exp_f32_e32 v181, v181
	s_nop 0
	v_add_f32_e32 v181, 1.0, v181
	v_rcp_f32_e32 v181, v181
	s_nop 0
	v_mul_f32_e32 v182, 0xbf1b4598, v181
	v_mul_f32_e32 v182, 0x3fb8aa3b, v182
	v_exp_f32_e32 v182, v182
; __device__ __forceinline__ float sigmoidf_(float x) { return 1.0f / (1.0f + __expf(-x)); }
	s_nop 0
	v_cndmask_b32_e64 v181, v182, v181, s[44:45]
	v_add_f32_e32 v182, v92, v132
	v_mul_f32_e32 v182, 0xbfb8aa3b, v182
	v_exp_f32_e32 v182, v182
	v_cvt_pk_bf16_f32 v178, v180, v181
	v_add_f32_e32 v182, 1.0, v182
	v_rcp_f32_e32 v182, v182
	s_nop 0
	v_mul_f32_e32 v183, 0xbf1b4598, v182
	v_mul_f32_e32 v183, 0x3fb8aa3b, v183
	v_exp_f32_e32 v183, v183
	s_nop 0
	v_cndmask_b32_e64 v182, v183, v182, s[44:45]
	v_add_f32_e32 v183, v93, v133
	v_mul_f32_e32 v183, 0xbfb8aa3b, v183
	v_exp_f32_e32 v183, v183
	s_nop 0
	v_add_f32_e32 v183, 1.0, v183
	v_rcp_f32_e32 v183, v183
	s_nop 0
	v_mul_f32_e32 v184, 0xbf1b4598, v183
	v_mul_f32_e32 v184, 0x3fb8aa3b, v184
	v_exp_f32_e32 v184, v184
	s_nop 0
	v_cndmask_b32_e64 v183, v184, v183, s[44:45]
	v_cvt_pk_bf16_f32 v179, v182, v183
	global_store_dwordx4 v[168:169], v[176:179], off offset:256
	v_or_b32_e32 v168, 32, v160
	v_ashrrev_i32_e32 v169, 31, v168
	v_add_f32_e32 v176, v102, v142
	v_mul_f32_e32 v176, 0xbfb8aa3b, v176
	v_exp_f32_e32 v176, v176
	v_lshlrev_b64 v[168:169], 13, v[168:169]
	v_lshl_add_u64 v[168:169], v[166:167], 0, v[168:169]
	v_add_f32_e32 v176, 1.0, v176
	v_rcp_f32_e32 v176, v176
	s_nop 0
	v_mul_f32_e32 v177, 0xbf1b4598, v176
	v_mul_f32_e32 v177, 0x3fb8aa3b, v177
	v_exp_f32_e32 v177, v177
	s_nop 0
	v_cndmask_b32_e64 v176, v177, v176, s[44:45]
	v_add_f32_e32 v177, v103, v143
	v_mul_f32_e32 v177, 0xbfb8aa3b, v177
	v_exp_f32_e32 v177, v177
	s_nop 0
	v_add_f32_e32 v177, 1.0, v177
	v_rcp_f32_e32 v177, v177
	s_nop 0
	v_mul_f32_e32 v178, 0xbf1b4598, v177
	v_mul_f32_e32 v178, 0x3fb8aa3b, v178
	v_exp_f32_e32 v178, v178
	s_nop 0
	v_cndmask_b32_e64 v177, v178, v177, s[44:45]
	v_add_f32_e32 v178, v104, v144
	v_mul_f32_e32 v178, 0xbfb8aa3b, v178
	v_exp_f32_e32 v178, v178
	v_cvt_pk_bf16_f32 v176, v176, v177
	v_add_f32_e32 v178, 1.0, v178
	v_rcp_f32_e32 v178, v178
	s_nop 0
	v_mul_f32_e32 v179, 0xbf1b4598, v178
	v_mul_f32_e32 v179, 0x3fb8aa3b, v179
	v_exp_f32_e32 v179, v179
	s_nop 0
	v_cndmask_b32_e64 v178, v179, v178, s[44:45]
	v_add_f32_e32 v179, v105, v145
	v_mul_f32_e32 v179, 0xbfb8aa3b, v179
	v_exp_f32_e32 v179, v179
	s_nop 0
	v_add_f32_e32 v179, 1.0, v179
	v_rcp_f32_e32 v179, v179
	s_nop 0
	v_mul_f32_e32 v180, 0xbf1b4598, v179
	v_mul_f32_e32 v180, 0x3fb8aa3b, v180
	v_exp_f32_e32 v180, v180
	s_nop 0
	v_cndmask_b32_e64 v179, v180, v179, s[44:45]
	v_add_f32_e32 v180, v98, v138
	v_mul_f32_e32 v180, 0xbfb8aa3b, v180
	v_exp_f32_e32 v180, v180
	v_cvt_pk_bf16_f32 v177, v178, v179
	v_add_f32_e32 v180, 1.0, v180
	v_rcp_f32_e32 v180, v180
	s_nop 0
	v_mul_f32_e32 v181, 0xbf1b4598, v180
	v_mul_f32_e32 v181, 0x3fb8aa3b, v181
	v_exp_f32_e32 v181, v181
	s_nop 0
	v_cndmask_b32_e64 v180, v181, v180, s[44:45]
	v_add_f32_e32 v181, v99, v139
	v_mul_f32_e32 v181, 0xbfb8aa3b, v181
	v_exp_f32_e32 v181, v181
	s_nop 0
	v_add_f32_e32 v181, 1.0, v181
	v_rcp_f32_e32 v181, v181
	s_nop 0
	v_mul_f32_e32 v182, 0xbf1b4598, v181
	v_mul_f32_e32 v182, 0x3fb8aa3b, v182
	v_exp_f32_e32 v182, v182
	s_nop 0
	v_cndmask_b32_e64 v181, v182, v181, s[44:45]
	v_add_f32_e32 v182, v100, v140
	v_mul_f32_e32 v182, 0xbfb8aa3b, v182
	v_exp_f32_e32 v182, v182
	v_cvt_pk_bf16_f32 v178, v180, v181
	v_add_f32_e32 v182, 1.0, v182
	v_rcp_f32_e32 v182, v182
	s_nop 0
	v_mul_f32_e32 v183, 0xbf1b4598, v182
	v_mul_f32_e32 v183, 0x3fb8aa3b, v183
	v_exp_f32_e32 v183, v183
	s_nop 0
	v_cndmask_b32_e64 v182, v183, v182, s[44:45]
	v_add_f32_e32 v183, v101, v141
	v_mul_f32_e32 v183, 0xbfb8aa3b, v183
	v_exp_f32_e32 v183, v183
	s_nop 0
	v_add_f32_e32 v183, 1.0, v183
	v_rcp_f32_e32 v183, v183
	s_nop 0
	v_mul_f32_e32 v184, 0xbf1b4598, v183
	v_mul_f32_e32 v184, 0x3fb8aa3b, v184
	v_exp_f32_e32 v184, v184
	s_nop 0
	v_cndmask_b32_e64 v183, v184, v183, s[44:45]
	v_cvt_pk_bf16_f32 v179, v182, v183
	global_store_dwordx4 v[168:169], v[176:179], off
	s_nop 1
	v_add_f32_e32 v176, v78, v134
	v_mul_f32_e32 v176, 0xbfb8aa3b, v176
	v_exp_f32_e32 v176, v176
	s_nop 0
	v_add_f32_e32 v176, 1.0, v176
	v_rcp_f32_e32 v176, v176
	s_nop 0
	v_mul_f32_e32 v177, 0xbf1b4598, v176
	v_mul_f32_e32 v177, 0x3fb8aa3b, v177
	v_exp_f32_e32 v177, v177
	s_nop 0
	v_cndmask_b32_e64 v176, v177, v176, s[44:45]
	v_add_f32_e32 v177, v79, v135
	v_mul_f32_e32 v177, 0xbfb8aa3b, v177
	v_exp_f32_e32 v177, v177
	s_nop 0
	v_add_f32_e32 v177, 1.0, v177
	v_rcp_f32_e32 v177, v177
	s_nop 0
	v_mul_f32_e32 v178, 0xbf1b4598, v177
	v_mul_f32_e32 v178, 0x3fb8aa3b, v178
	v_exp_f32_e32 v178, v178
	s_nop 0
	v_cndmask_b32_e64 v177, v178, v177, s[44:45]
	v_add_f32_e32 v178, v80, v136
	v_mul_f32_e32 v178, 0xbfb8aa3b, v178
	v_exp_f32_e32 v178, v178
	v_cvt_pk_bf16_f32 v176, v176, v177
	v_add_f32_e32 v178, 1.0, v178
	v_rcp_f32_e32 v178, v178
	s_nop 0
	v_mul_f32_e32 v179, 0xbf1b4598, v178
	v_mul_f32_e32 v179, 0x3fb8aa3b, v179
	v_exp_f32_e32 v179, v179
	s_nop 0
	v_cndmask_b32_e64 v178, v179, v178, s[44:45]
	v_add_f32_e32 v179, v81, v137
	v_mul_f32_e32 v179, 0xbfb8aa3b, v179
	v_exp_f32_e32 v179, v179
	s_nop 0
	v_add_f32_e32 v179, 1.0, v179
	v_rcp_f32_e32 v179, v179
	s_nop 0
	v_mul_f32_e32 v180, 0xbf1b4598, v179
	v_mul_f32_e32 v180, 0x3fb8aa3b, v180
	v_exp_f32_e32 v180, v180
	s_nop 0
	v_cndmask_b32_e64 v179, v180, v179, s[44:45]
	v_add_f32_e32 v180, v74, v130
	v_mul_f32_e32 v180, 0xbfb8aa3b, v180
	v_exp_f32_e32 v180, v180
	v_cvt_pk_bf16_f32 v177, v178, v179
	v_add_f32_e32 v180, 1.0, v180
	v_rcp_f32_e32 v180, v180
	s_nop 0
	v_mul_f32_e32 v181, 0xbf1b4598, v180
	v_mul_f32_e32 v181, 0x3fb8aa3b, v181
	v_exp_f32_e32 v181, v181
	s_nop 0
	v_cndmask_b32_e64 v180, v181, v180, s[44:45]
	v_add_f32_e32 v181, v75, v131
	v_mul_f32_e32 v181, 0xbfb8aa3b, v181
	v_exp_f32_e32 v181, v181
	s_nop 0
	v_add_f32_e32 v181, 1.0, v181
	v_rcp_f32_e32 v181, v181
	s_nop 0
; __device__ __forceinline__ float sigmoidf_(float x) { return 1.0f / (1.0f + __expf(-x)); }
	v_mul_f32_e32 v182, 0xbf1b4598, v181
	v_mul_f32_e32 v182, 0x3fb8aa3b, v182
	v_exp_f32_e32 v182, v182
	s_nop 0
	v_cndmask_b32_e64 v181, v182, v181, s[44:45]
	v_add_f32_e32 v182, v76, v132
	v_mul_f32_e32 v182, 0xbfb8aa3b, v182
	v_exp_f32_e32 v182, v182
	v_cvt_pk_bf16_f32 v178, v180, v181
	v_add_f32_e32 v182, 1.0, v182
	v_rcp_f32_e32 v182, v182
	s_nop 0
	v_mul_f32_e32 v183, 0xbf1b4598, v182
	v_mul_f32_e32 v183, 0x3fb8aa3b, v183
	v_exp_f32_e32 v183, v183
	s_nop 0
	v_cndmask_b32_e64 v182, v183, v182, s[44:45]
	v_add_f32_e32 v183, v77, v133
	v_mul_f32_e32 v183, 0xbfb8aa3b, v183
	v_exp_f32_e32 v183, v183
	s_nop 0
	v_add_f32_e32 v183, 1.0, v183
	v_rcp_f32_e32 v183, v183
	s_nop 0
	v_mul_f32_e32 v184, 0xbf1b4598, v183
	v_mul_f32_e32 v184, 0x3fb8aa3b, v184
	v_exp_f32_e32 v184, v184
	s_nop 0
	v_cndmask_b32_e64 v183, v184, v183, s[44:45]
	v_cvt_pk_bf16_f32 v179, v182, v183
	global_store_dwordx4 v[168:169], v[176:179], off offset:256
	v_or_b32_e32 v168, 48, v160
	v_ashrrev_i32_e32 v169, 31, v168
	v_lshlrev_b64 v[168:169], 13, v[168:169]
	v_lshl_add_u64 v[166:167], v[166:167], 0, v[168:169]
	v_add_f32_e32 v168, v86, v142
	v_mul_f32_e32 v168, 0xbfb8aa3b, v168
	v_exp_f32_e32 v168, v168
	s_nop 0
	v_add_f32_e32 v168, 1.0, v168
	v_rcp_f32_e32 v168, v168
	s_nop 0
	v_mul_f32_e32 v169, 0xbf1b4598, v168
	v_mul_f32_e32 v169, 0x3fb8aa3b, v169
	v_exp_f32_e32 v169, v169
	s_nop 0
	v_cndmask_b32_e64 v168, v169, v168, s[44:45]
	v_add_f32_e32 v169, v87, v143
	v_mul_f32_e32 v169, 0xbfb8aa3b, v169
	v_exp_f32_e32 v169, v169
	s_nop 0
	v_add_f32_e32 v169, 1.0, v169
	v_rcp_f32_e32 v169, v169
	s_nop 0
	v_mul_f32_e32 v176, 0xbf1b4598, v169
	v_mul_f32_e32 v176, 0x3fb8aa3b, v176
	v_exp_f32_e32 v176, v176
	s_nop 0
	v_cndmask_b32_e64 v169, v176, v169, s[44:45]
	v_add_f32_e32 v176, v88, v144
	v_mul_f32_e32 v176, 0xbfb8aa3b, v176
	v_exp_f32_e32 v176, v176
	s_nop 0
	v_add_f32_e32 v176, 1.0, v176
	v_rcp_f32_e32 v176, v176
	s_nop 0
	v_mul_f32_e32 v177, 0xbf1b4598, v176
	v_mul_f32_e32 v177, 0x3fb8aa3b, v177
	v_exp_f32_e32 v177, v177
	s_nop 0
	v_cndmask_b32_e64 v177, v177, v176, s[44:45]
	v_add_f32_e32 v176, v89, v145
	v_mul_f32_e32 v176, 0xbfb8aa3b, v176
	v_exp_f32_e32 v176, v176
	s_nop 0
	v_add_f32_e32 v176, 1.0, v176
	v_rcp_f32_e32 v176, v176
	s_nop 0
	v_mul_f32_e32 v178, 0xbf1b4598, v176
	v_mul_f32_e32 v178, 0x3fb8aa3b, v178
	v_exp_f32_e32 v178, v178
	s_nop 0
	v_cndmask_b32_e64 v178, v178, v176, s[44:45]
	v_add_f32_e32 v176, v82, v138
	v_mul_f32_e32 v176, 0xbfb8aa3b, v176
	v_exp_f32_e32 v176, v176
	v_cvt_pk_bf16_f32 v177, v177, v178
	v_add_f32_e32 v176, 1.0, v176
	v_rcp_f32_e32 v176, v176
	s_nop 0
	v_mul_f32_e32 v179, 0xbf1b4598, v176
	v_mul_f32_e32 v179, 0x3fb8aa3b, v179
	v_exp_f32_e32 v179, v179
	s_nop 0
	v_cndmask_b32_e64 v179, v179, v176, s[44:45]
	v_add_f32_e32 v176, v83, v139
	v_mul_f32_e32 v176, 0xbfb8aa3b, v176
	v_exp_f32_e32 v176, v176
	s_nop 0
	v_add_f32_e32 v176, 1.0, v176
	v_rcp_f32_e32 v176, v176
	s_nop 0
	v_mul_f32_e32 v180, 0xbf1b4598, v176
	v_mul_f32_e32 v180, 0x3fb8aa3b, v180
	v_exp_f32_e32 v180, v180
	s_nop 0
	v_cndmask_b32_e64 v180, v180, v176, s[44:45]
	v_add_f32_e32 v176, v84, v140
	v_mul_f32_e32 v176, 0xbfb8aa3b, v176
	v_exp_f32_e32 v176, v176
	v_cvt_pk_bf16_f32 v178, v179, v180
	v_add_f32_e32 v176, 1.0, v176
	v_rcp_f32_e32 v176, v176
	s_nop 0
	v_mul_f32_e32 v181, 0xbf1b4598, v176
	v_mul_f32_e32 v181, 0x3fb8aa3b, v181
	v_exp_f32_e32 v181, v181
	s_nop 0
	v_cndmask_b32_e64 v181, v181, v176, s[44:45]
	v_add_f32_e32 v176, v85, v141
	v_mul_f32_e32 v176, 0xbfb8aa3b, v176
	v_exp_f32_e32 v176, v176
	s_nop 0
	v_add_f32_e32 v176, 1.0, v176
	v_rcp_f32_e32 v176, v176
	s_nop 0
	v_mul_f32_e32 v182, 0xbf1b4598, v176
	v_mul_f32_e32 v182, 0x3fb8aa3b, v182
	v_exp_f32_e32 v182, v182
	s_nop 0
	v_cndmask_b32_e64 v182, v182, v176, s[44:45]
	v_cvt_pk_bf16_f32 v176, v168, v169
	v_add_f32_e32 v168, v70, v134
	v_mul_f32_e32 v168, 0xbfb8aa3b, v168
	v_exp_f32_e32 v168, v168
	v_cvt_pk_bf16_f32 v179, v181, v182
	global_store_dwordx4 v[166:167], v[176:179], off
	v_add_f32_e32 v168, 1.0, v168
	v_rcp_f32_e32 v168, v168
	s_nop 0
	v_mul_f32_e32 v169, 0xbf1b4598, v168
	v_mul_f32_e32 v169, 0x3fb8aa3b, v169
	v_exp_f32_e32 v169, v169
	s_nop 0
	v_cndmask_b32_e64 v168, v169, v168, s[44:45]
	v_add_f32_e32 v169, v71, v135
	v_mul_f32_e32 v169, 0xbfb8aa3b, v169
	v_exp_f32_e32 v169, v169
	s_nop 0
	v_add_f32_e32 v169, 1.0, v169
	v_rcp_f32_e32 v169, v169
	s_nop 0
	v_mul_f32_e32 v176, 0xbf1b4598, v169
	v_mul_f32_e32 v176, 0x3fb8aa3b, v176
	v_exp_f32_e32 v176, v176
	s_nop 0
	v_cndmask_b32_e64 v169, v176, v169, s[44:45]
	v_add_f32_e32 v176, v72, v136
	v_mul_f32_e32 v176, 0xbfb8aa3b, v176
	v_exp_f32_e32 v176, v176
	s_nop 0
	v_add_f32_e32 v176, 1.0, v176
	v_rcp_f32_e32 v176, v176
	s_nop 0
	v_mul_f32_e32 v177, 0xbf1b4598, v176
	v_mul_f32_e32 v177, 0x3fb8aa3b, v177
	v_exp_f32_e32 v177, v177
	s_nop 0
	v_cndmask_b32_e64 v177, v177, v176, s[44:45]
	v_add_f32_e32 v176, v73, v137
	v_mul_f32_e32 v176, 0xbfb8aa3b, v176
	v_exp_f32_e32 v176, v176
	s_nop 0
	v_add_f32_e32 v176, 1.0, v176
	v_rcp_f32_e32 v176, v176
	s_nop 0
	v_mul_f32_e32 v178, 0xbf1b4598, v176
	v_mul_f32_e32 v178, 0x3fb8aa3b, v178
	v_exp_f32_e32 v178, v178
	s_nop 0
	v_cndmask_b32_e64 v178, v178, v176, s[44:45]
	v_add_f32_e32 v176, v66, v130
	v_mul_f32_e32 v176, 0xbfb8aa3b, v176
	v_exp_f32_e32 v176, v176
	v_cvt_pk_bf16_f32 v177, v177, v178
	v_add_f32_e32 v176, 1.0, v176
	v_rcp_f32_e32 v176, v176
	s_nop 0
	v_mul_f32_e32 v179, 0xbf1b4598, v176
	v_mul_f32_e32 v179, 0x3fb8aa3b, v179
	v_exp_f32_e32 v179, v179
	s_nop 0
	v_cndmask_b32_e64 v179, v179, v176, s[44:45]
	v_add_f32_e32 v176, v67, v131
	v_mul_f32_e32 v176, 0xbfb8aa3b, v176
	v_exp_f32_e32 v176, v176
	s_nop 0
; __device__ __forceinline__ float sigmoidf_(float x) { return 1.0f / (1.0f + __expf(-x)); }
	v_add_f32_e32 v176, 1.0, v176
	v_rcp_f32_e32 v176, v176
	s_nop 0
	v_mul_f32_e32 v180, 0xbf1b4598, v176
	v_mul_f32_e32 v180, 0x3fb8aa3b, v180
	v_exp_f32_e32 v180, v180
	s_nop 0
	v_cndmask_b32_e64 v180, v180, v176, s[44:45]
	v_add_f32_e32 v176, v68, v132
	v_mul_f32_e32 v176, 0xbfb8aa3b, v176
	v_exp_f32_e32 v176, v176
	v_cvt_pk_bf16_f32 v178, v179, v180
	v_add_f32_e32 v176, 1.0, v176
	v_rcp_f32_e32 v176, v176
	s_nop 0
	v_mul_f32_e32 v181, 0xbf1b4598, v176
	v_mul_f32_e32 v181, 0x3fb8aa3b, v181
	v_exp_f32_e32 v181, v181
	s_nop 0
	v_cndmask_b32_e64 v181, v181, v176, s[44:45]
	v_add_f32_e32 v176, v69, v133
	v_mul_f32_e32 v176, 0xbfb8aa3b, v176
	v_exp_f32_e32 v176, v176
	s_nop 0
	v_add_f32_e32 v176, 1.0, v176
	s_mov_b64 s[0:1], 0x100000
	v_rcp_f32_e32 v176, v176
	s_nop 0
	v_mul_f32_e32 v182, 0xbf1b4598, v176
	v_mul_f32_e32 v182, 0x3fb8aa3b, v182
	v_exp_f32_e32 v182, v182
	s_nop 0
	v_cndmask_b32_e64 v182, v182, v176, s[44:45]
	v_cvt_pk_bf16_f32 v176, v168, v169
	v_add_f32_e32 v168, v62, v142
	v_mul_f32_e32 v168, 0xbfb8aa3b, v168
	v_exp_f32_e32 v168, v168
	v_cvt_pk_bf16_f32 v179, v181, v182
	global_store_dwordx4 v[166:167], v[176:179], off offset:256
	v_lshl_add_u64 v[166:167], v[164:165], 0, s[0:1]
	v_add_f32_e32 v168, 1.0, v168
	v_rcp_f32_e32 v168, v168
	s_nop 0
	v_mul_f32_e32 v169, 0xbf1b4598, v168
	v_mul_f32_e32 v169, 0x3fb8aa3b, v169
	v_exp_f32_e32 v169, v169
	s_nop 0
	v_cndmask_b32_e64 v168, v169, v168, s[44:45]
	v_add_f32_e32 v169, v63, v143
	v_mul_f32_e32 v169, 0xbfb8aa3b, v169
	v_exp_f32_e32 v169, v169
	s_nop 0
	v_add_f32_e32 v169, 1.0, v169
	v_rcp_f32_e32 v169, v169
	s_nop 0
	v_mul_f32_e32 v176, 0xbf1b4598, v169
	v_mul_f32_e32 v176, 0x3fb8aa3b, v176
	v_exp_f32_e32 v176, v176
	s_nop 0
	v_cndmask_b32_e64 v169, v176, v169, s[44:45]
	v_add_f32_e32 v176, v64, v144
	v_mul_f32_e32 v176, 0xbfb8aa3b, v176
	v_exp_f32_e32 v176, v176
	s_nop 0
	v_add_f32_e32 v176, 1.0, v176
	v_rcp_f32_e32 v176, v176
	s_nop 0
	v_mul_f32_e32 v177, 0xbf1b4598, v176
	v_mul_f32_e32 v177, 0x3fb8aa3b, v177
	v_exp_f32_e32 v177, v177
	s_nop 0
	v_cndmask_b32_e64 v177, v177, v176, s[44:45]
	v_add_f32_e32 v176, v65, v145
	v_mul_f32_e32 v176, 0xbfb8aa3b, v176
	v_exp_f32_e32 v176, v176
	s_nop 0
	v_add_f32_e32 v176, 1.0, v176
	v_rcp_f32_e32 v176, v176
	s_nop 0
	v_mul_f32_e32 v178, 0xbf1b4598, v176
	v_mul_f32_e32 v178, 0x3fb8aa3b, v178
	v_exp_f32_e32 v178, v178
	s_nop 0
	v_cndmask_b32_e64 v178, v178, v176, s[44:45]
	v_add_f32_e32 v176, v58, v138
	v_mul_f32_e32 v176, 0xbfb8aa3b, v176
	v_exp_f32_e32 v176, v176
	v_cvt_pk_bf16_f32 v177, v177, v178
	v_add_f32_e32 v176, 1.0, v176
	v_rcp_f32_e32 v176, v176
	s_nop 0
	v_mul_f32_e32 v179, 0xbf1b4598, v176
	v_mul_f32_e32 v179, 0x3fb8aa3b, v179
	v_exp_f32_e32 v179, v179
	s_nop 0
	v_cndmask_b32_e64 v179, v179, v176, s[44:45]
	v_add_f32_e32 v176, v59, v139
	v_mul_f32_e32 v176, 0xbfb8aa3b, v176
	v_exp_f32_e32 v176, v176
	s_nop 0
	v_add_f32_e32 v176, 1.0, v176
	v_rcp_f32_e32 v176, v176
	s_nop 0
	v_mul_f32_e32 v180, 0xbf1b4598, v176
	v_mul_f32_e32 v180, 0x3fb8aa3b, v180
	v_exp_f32_e32 v180, v180
	s_nop 0
	v_cndmask_b32_e64 v180, v180, v176, s[44:45]
	v_add_f32_e32 v176, v60, v140
	v_mul_f32_e32 v176, 0xbfb8aa3b, v176
	v_exp_f32_e32 v176, v176
	v_cvt_pk_bf16_f32 v178, v179, v180
	v_add_f32_e32 v176, 1.0, v176
	v_rcp_f32_e32 v176, v176
	s_nop 0
	v_mul_f32_e32 v181, 0xbf1b4598, v176
	v_mul_f32_e32 v181, 0x3fb8aa3b, v181
	v_exp_f32_e32 v181, v181
	s_nop 0
	v_cndmask_b32_e64 v181, v181, v176, s[44:45]
	v_add_f32_e32 v176, v61, v141
	v_mul_f32_e32 v176, 0xbfb8aa3b, v176
	v_exp_f32_e32 v176, v176
	s_nop 0
	v_add_f32_e32 v176, 1.0, v176
	s_mov_b32 s0, 0x100000
	v_rcp_f32_e32 v176, v176
	s_nop 0
	v_mul_f32_e32 v182, 0xbf1b4598, v176
	v_mul_f32_e32 v182, 0x3fb8aa3b, v182
	v_exp_f32_e32 v182, v182
	s_nop 0
	v_cndmask_b32_e64 v182, v182, v176, s[44:45]
	v_cvt_pk_bf16_f32 v176, v168, v169
	v_add_co_u32_e32 v168, vcc, s0, v164
	v_cvt_pk_bf16_f32 v179, v181, v182
	s_nop 0
	v_addc_co_u32_e32 v169, vcc, 0, v165, vcc
	global_store_dwordx4 v[168:169], v[176:179], off
	v_add_f32_e32 v168, v46, v134
	v_mul_f32_e32 v168, 0xbfb8aa3b, v168
	v_exp_f32_e32 v168, v168
	s_nop 0
	v_add_f32_e32 v168, 1.0, v168
	v_rcp_f32_e32 v168, v168
	s_nop 0
	v_mul_f32_e32 v169, 0xbf1b4598, v168
	v_mul_f32_e32 v169, 0x3fb8aa3b, v169
	v_exp_f32_e32 v169, v169
	s_nop 0
	v_cndmask_b32_e64 v168, v169, v168, s[44:45]
	v_add_f32_e32 v169, v47, v135
	v_mul_f32_e32 v169, 0xbfb8aa3b, v169
	v_exp_f32_e32 v169, v169
	s_nop 0
	v_add_f32_e32 v169, 1.0, v169
	v_rcp_f32_e32 v169, v169
	s_nop 0
	v_mul_f32_e32 v176, 0xbf1b4598, v169
	v_mul_f32_e32 v176, 0x3fb8aa3b, v176
	v_exp_f32_e32 v176, v176
	s_nop 0
	v_cndmask_b32_e64 v169, v176, v169, s[44:45]
	v_add_f32_e32 v176, v48, v136
	v_mul_f32_e32 v176, 0xbfb8aa3b, v176
	v_exp_f32_e32 v176, v176
	s_nop 0
	v_add_f32_e32 v176, 1.0, v176
	v_rcp_f32_e32 v176, v176
	s_nop 0
	v_mul_f32_e32 v177, 0xbf1b4598, v176
	v_mul_f32_e32 v177, 0x3fb8aa3b, v177
	v_exp_f32_e32 v177, v177
	s_nop 0
	v_cndmask_b32_e64 v177, v177, v176, s[44:45]
	v_add_f32_e32 v176, v49, v137
	v_mul_f32_e32 v176, 0xbfb8aa3b, v176
	v_exp_f32_e32 v176, v176
	s_nop 0
	v_add_f32_e32 v176, 1.0, v176
	v_rcp_f32_e32 v176, v176
	s_nop 0
	v_mul_f32_e32 v178, 0xbf1b4598, v176
	v_mul_f32_e32 v178, 0x3fb8aa3b, v178
	v_exp_f32_e32 v178, v178
	s_nop 0
	v_cndmask_b32_e64 v178, v178, v176, s[44:45]
	v_add_f32_e32 v176, v42, v130
	v_mul_f32_e32 v176, 0xbfb8aa3b, v176
	v_exp_f32_e32 v176, v176
	v_cvt_pk_bf16_f32 v177, v177, v178
	v_add_f32_e32 v176, 1.0, v176
	v_rcp_f32_e32 v176, v176
	s_nop 0
	v_mul_f32_e32 v179, 0xbf1b4598, v176
	v_mul_f32_e32 v179, 0x3fb8aa3b, v179
	v_exp_f32_e32 v179, v179
	s_nop 0
; __device__ __forceinline__ float sigmoidf_(float x) { return 1.0f / (1.0f + __expf(-x)); }
	v_cndmask_b32_e64 v179, v179, v176, s[44:45]
	v_add_f32_e32 v176, v43, v131
	v_mul_f32_e32 v176, 0xbfb8aa3b, v176
	v_exp_f32_e32 v176, v176
	s_nop 0
	v_add_f32_e32 v176, 1.0, v176
	v_rcp_f32_e32 v176, v176
	s_nop 0
	v_mul_f32_e32 v180, 0xbf1b4598, v176
	v_mul_f32_e32 v180, 0x3fb8aa3b, v180
	v_exp_f32_e32 v180, v180
	s_nop 0
	v_cndmask_b32_e64 v180, v180, v176, s[44:45]
	v_add_f32_e32 v176, v44, v132
	v_mul_f32_e32 v176, 0xbfb8aa3b, v176
	v_exp_f32_e32 v176, v176
	v_cvt_pk_bf16_f32 v178, v179, v180
	v_add_f32_e32 v176, 1.0, v176
	v_rcp_f32_e32 v176, v176
	s_nop 0
	v_mul_f32_e32 v181, 0xbf1b4598, v176
	v_mul_f32_e32 v181, 0x3fb8aa3b, v181
	v_exp_f32_e32 v181, v181
	s_nop 0
	v_cndmask_b32_e64 v181, v181, v176, s[44:45]
	v_add_f32_e32 v176, v45, v133
	v_mul_f32_e32 v176, 0xbfb8aa3b, v176
	v_exp_f32_e32 v176, v176
	s_nop 0
	v_add_f32_e32 v176, 1.0, v176
	s_mov_b64 s[0:1], 0x120000
	v_rcp_f32_e32 v176, v176
	s_nop 0
	v_mul_f32_e32 v182, 0xbf1b4598, v176
	v_mul_f32_e32 v182, 0x3fb8aa3b, v182
	v_exp_f32_e32 v182, v182
	s_nop 0
	v_cndmask_b32_e64 v182, v182, v176, s[44:45]
	v_cvt_pk_bf16_f32 v176, v168, v169
	v_add_f32_e32 v168, v54, v142
	v_mul_f32_e32 v168, 0xbfb8aa3b, v168
	v_exp_f32_e32 v168, v168
	v_cvt_pk_bf16_f32 v179, v181, v182
	global_store_dwordx4 v[166:167], v[176:179], off offset:256
	v_lshl_add_u64 v[166:167], v[164:165], 0, s[0:1]
	v_add_f32_e32 v168, 1.0, v168
	v_rcp_f32_e32 v168, v168
	s_nop 0
	v_mul_f32_e32 v169, 0xbf1b4598, v168
	v_mul_f32_e32 v169, 0x3fb8aa3b, v169
	v_exp_f32_e32 v169, v169
	s_nop 0
	v_cndmask_b32_e64 v168, v169, v168, s[44:45]
	v_add_f32_e32 v169, v55, v143
	v_mul_f32_e32 v169, 0xbfb8aa3b, v169
	v_exp_f32_e32 v169, v169
	s_nop 0
	v_add_f32_e32 v169, 1.0, v169
	v_rcp_f32_e32 v169, v169
	s_nop 0
	v_mul_f32_e32 v176, 0xbf1b4598, v169
	v_mul_f32_e32 v176, 0x3fb8aa3b, v176
	v_exp_f32_e32 v176, v176
	s_nop 0
	v_cndmask_b32_e64 v169, v176, v169, s[44:45]
	v_add_f32_e32 v176, v56, v144
	v_mul_f32_e32 v176, 0xbfb8aa3b, v176
	v_exp_f32_e32 v176, v176
	s_nop 0
	v_add_f32_e32 v176, 1.0, v176
	v_rcp_f32_e32 v176, v176
	s_nop 0
	v_mul_f32_e32 v177, 0xbf1b4598, v176
	v_mul_f32_e32 v177, 0x3fb8aa3b, v177
	v_exp_f32_e32 v177, v177
	s_nop 0
	v_cndmask_b32_e64 v177, v177, v176, s[44:45]
	v_add_f32_e32 v176, v57, v145
	v_mul_f32_e32 v176, 0xbfb8aa3b, v176
	v_exp_f32_e32 v176, v176
	s_nop 0
	v_add_f32_e32 v176, 1.0, v176
	v_rcp_f32_e32 v176, v176
	s_nop 0
	v_mul_f32_e32 v178, 0xbf1b4598, v176
	v_mul_f32_e32 v178, 0x3fb8aa3b, v178
	v_exp_f32_e32 v178, v178
	s_nop 0
	v_cndmask_b32_e64 v178, v178, v176, s[44:45]
	v_add_f32_e32 v176, v50, v138
	v_mul_f32_e32 v176, 0xbfb8aa3b, v176
	v_exp_f32_e32 v176, v176
	v_cvt_pk_bf16_f32 v177, v177, v178
	v_add_f32_e32 v176, 1.0, v176
	v_rcp_f32_e32 v176, v176
	s_nop 0
	v_mul_f32_e32 v179, 0xbf1b4598, v176
	v_mul_f32_e32 v179, 0x3fb8aa3b, v179
	v_exp_f32_e32 v179, v179
	s_nop 0
	v_cndmask_b32_e64 v179, v179, v176, s[44:45]
	v_add_f32_e32 v176, v51, v139
	v_mul_f32_e32 v176, 0xbfb8aa3b, v176
	v_exp_f32_e32 v176, v176
	s_nop 0
	v_add_f32_e32 v176, 1.0, v176
	v_rcp_f32_e32 v176, v176
	s_nop 0
	v_mul_f32_e32 v180, 0xbf1b4598, v176
	v_mul_f32_e32 v180, 0x3fb8aa3b, v180
	v_exp_f32_e32 v180, v180
	s_nop 0
	v_cndmask_b32_e64 v180, v180, v176, s[44:45]
	v_add_f32_e32 v176, v52, v140
	v_mul_f32_e32 v176, 0xbfb8aa3b, v176
	v_exp_f32_e32 v176, v176
	v_cvt_pk_bf16_f32 v178, v179, v180
	v_add_f32_e32 v176, 1.0, v176
	v_rcp_f32_e32 v176, v176
	s_nop 0
	v_mul_f32_e32 v181, 0xbf1b4598, v176
	v_mul_f32_e32 v181, 0x3fb8aa3b, v181
	v_exp_f32_e32 v181, v181
	s_nop 0
	v_cndmask_b32_e64 v181, v181, v176, s[44:45]
	v_add_f32_e32 v176, v53, v141
	v_mul_f32_e32 v176, 0xbfb8aa3b, v176
	v_exp_f32_e32 v176, v176
	s_nop 0
	v_add_f32_e32 v176, 1.0, v176
	s_mov_b32 s0, 0x120000
	v_rcp_f32_e32 v176, v176
	s_nop 0
	v_mul_f32_e32 v182, 0xbf1b4598, v176
	v_mul_f32_e32 v182, 0x3fb8aa3b, v182
	v_exp_f32_e32 v182, v182
	s_nop 0
	v_cndmask_b32_e64 v182, v182, v176, s[44:45]
	v_cvt_pk_bf16_f32 v176, v168, v169
	v_add_co_u32_e32 v168, vcc, s0, v164
	v_cvt_pk_bf16_f32 v179, v181, v182
	s_nop 0
	v_addc_co_u32_e32 v169, vcc, 0, v165, vcc
	global_store_dwordx4 v[168:169], v[176:179], off
	v_add_f32_e32 v168, v30, v134
	v_mul_f32_e32 v168, 0xbfb8aa3b, v168
	v_exp_f32_e32 v168, v168
	s_nop 0
	v_add_f32_e32 v168, 1.0, v168
	v_rcp_f32_e32 v168, v168
	s_nop 0
	v_mul_f32_e32 v169, 0xbf1b4598, v168
	v_mul_f32_e32 v169, 0x3fb8aa3b, v169
	v_exp_f32_e32 v169, v169
	s_nop 0
	v_cndmask_b32_e64 v168, v169, v168, s[44:45]
	v_add_f32_e32 v169, v31, v135
	v_mul_f32_e32 v169, 0xbfb8aa3b, v169
	v_exp_f32_e32 v169, v169
	s_nop 0
	v_add_f32_e32 v169, 1.0, v169
	v_rcp_f32_e32 v169, v169
	s_nop 0
	v_mul_f32_e32 v176, 0xbf1b4598, v169
	v_mul_f32_e32 v176, 0x3fb8aa3b, v176
	v_exp_f32_e32 v176, v176
	s_nop 0
	v_cndmask_b32_e64 v169, v176, v169, s[44:45]
	v_add_f32_e32 v176, v32, v136
	v_mul_f32_e32 v176, 0xbfb8aa3b, v176
	v_exp_f32_e32 v176, v176
	s_nop 0
	v_add_f32_e32 v176, 1.0, v176
	v_rcp_f32_e32 v176, v176
	s_nop 0
	v_mul_f32_e32 v177, 0xbf1b4598, v176
	v_mul_f32_e32 v177, 0x3fb8aa3b, v177
	v_exp_f32_e32 v177, v177
	s_nop 0
	v_cndmask_b32_e64 v177, v177, v176, s[44:45]
	v_add_f32_e32 v176, v33, v137
	v_mul_f32_e32 v176, 0xbfb8aa3b, v176
	v_exp_f32_e32 v176, v176
	s_nop 0
	v_add_f32_e32 v176, 1.0, v176
	v_rcp_f32_e32 v176, v176
	s_nop 0
	v_mul_f32_e32 v178, 0xbf1b4598, v176
	v_mul_f32_e32 v178, 0x3fb8aa3b, v178
	v_exp_f32_e32 v178, v178
	s_nop 0
	v_cndmask_b32_e64 v178, v178, v176, s[44:45]
	v_add_f32_e32 v176, v26, v130
	v_mul_f32_e32 v176, 0xbfb8aa3b, v176
	v_exp_f32_e32 v176, v176
	v_cvt_pk_bf16_f32 v177, v177, v178
	v_add_f32_e32 v176, 1.0, v176
; __device__ __forceinline__ float sigmoidf_(float x) { return 1.0f / (1.0f + __expf(-x)); }
	v_rcp_f32_e32 v176, v176
	s_nop 0
	v_mul_f32_e32 v179, 0xbf1b4598, v176
	v_mul_f32_e32 v179, 0x3fb8aa3b, v179
	v_exp_f32_e32 v179, v179
	s_nop 0
	v_cndmask_b32_e64 v179, v179, v176, s[44:45]
	v_add_f32_e32 v176, v27, v131
	v_mul_f32_e32 v176, 0xbfb8aa3b, v176
	v_exp_f32_e32 v176, v176
	s_nop 0
	v_add_f32_e32 v176, 1.0, v176
	v_rcp_f32_e32 v176, v176
	s_nop 0
	v_mul_f32_e32 v180, 0xbf1b4598, v176
	v_mul_f32_e32 v180, 0x3fb8aa3b, v180
	v_exp_f32_e32 v180, v180
	s_nop 0
	v_cndmask_b32_e64 v180, v180, v176, s[44:45]
	v_add_f32_e32 v176, v28, v132
	v_mul_f32_e32 v176, 0xbfb8aa3b, v176
	v_exp_f32_e32 v176, v176
	v_cvt_pk_bf16_f32 v178, v179, v180
	v_add_f32_e32 v176, 1.0, v176
	v_rcp_f32_e32 v176, v176
	s_nop 0
	v_mul_f32_e32 v181, 0xbf1b4598, v176
	v_mul_f32_e32 v181, 0x3fb8aa3b, v181
	v_exp_f32_e32 v181, v181
	s_nop 0
	v_cndmask_b32_e64 v181, v181, v176, s[44:45]
	v_add_f32_e32 v176, v29, v133
	v_mul_f32_e32 v176, 0xbfb8aa3b, v176
	v_exp_f32_e32 v176, v176
	s_nop 0
	v_add_f32_e32 v176, 1.0, v176
	s_mov_b64 s[0:1], 0x140000
	v_rcp_f32_e32 v176, v176
	s_nop 0
	v_mul_f32_e32 v182, 0xbf1b4598, v176
	v_mul_f32_e32 v182, 0x3fb8aa3b, v182
	v_exp_f32_e32 v182, v182
	s_nop 0
	v_cndmask_b32_e64 v182, v182, v176, s[44:45]
	v_cvt_pk_bf16_f32 v176, v168, v169
	v_add_f32_e32 v168, v38, v142
	v_mul_f32_e32 v168, 0xbfb8aa3b, v168
	v_exp_f32_e32 v168, v168
	v_cvt_pk_bf16_f32 v179, v181, v182
	global_store_dwordx4 v[166:167], v[176:179], off offset:256
	v_lshl_add_u64 v[166:167], v[164:165], 0, s[0:1]
	v_add_f32_e32 v168, 1.0, v168
	v_add_f32_e32 v142, v22, v142
	v_mul_f32_e32 v142, 0xbfb8aa3b, v142
	v_exp_f32_e32 v142, v142
	v_rcp_f32_e32 v168, v168
	s_nop 0
	v_mul_f32_e32 v169, 0xbf1b4598, v168
	v_mul_f32_e32 v169, 0x3fb8aa3b, v169
	v_exp_f32_e32 v169, v169
	v_add_f32_e32 v142, 1.0, v142
	v_cndmask_b32_e64 v168, v169, v168, s[44:45]
	v_add_f32_e32 v169, v39, v143
	v_mul_f32_e32 v169, 0xbfb8aa3b, v169
	v_exp_f32_e32 v169, v169
	v_add_f32_e32 v143, v23, v143
	v_mul_f32_e32 v143, 0xbfb8aa3b, v143
	v_exp_f32_e32 v143, v143
	v_add_f32_e32 v169, 1.0, v169
	v_add_f32_e32 v143, 1.0, v143
	v_rcp_f32_e32 v169, v169
	s_nop 0
	v_mul_f32_e32 v176, 0xbf1b4598, v169
	v_mul_f32_e32 v176, 0x3fb8aa3b, v176
	v_exp_f32_e32 v176, v176
	s_nop 0
	v_cndmask_b32_e64 v169, v176, v169, s[44:45]
	v_add_f32_e32 v176, v40, v144
	v_mul_f32_e32 v176, 0xbfb8aa3b, v176
	v_exp_f32_e32 v176, v176
	v_add_f32_e32 v144, v24, v144
	v_mul_f32_e32 v144, 0xbfb8aa3b, v144
	v_exp_f32_e32 v144, v144
	v_add_f32_e32 v176, 1.0, v176
	v_add_f32_e32 v144, 1.0, v144
	v_rcp_f32_e32 v176, v176
	s_nop 0
	v_mul_f32_e32 v177, 0xbf1b4598, v176
	v_mul_f32_e32 v177, 0x3fb8aa3b, v177
	v_exp_f32_e32 v177, v177
	s_nop 0
	v_cndmask_b32_e64 v177, v177, v176, s[44:45]
	v_add_f32_e32 v176, v41, v145
	v_mul_f32_e32 v176, 0xbfb8aa3b, v176
	v_exp_f32_e32 v176, v176
	v_add_f32_e32 v145, v25, v145
	v_mul_f32_e32 v145, 0xbfb8aa3b, v145
	v_exp_f32_e32 v145, v145
	v_add_f32_e32 v176, 1.0, v176
	v_add_f32_e32 v145, 1.0, v145
	v_rcp_f32_e32 v176, v176
	s_nop 0
	v_mul_f32_e32 v178, 0xbf1b4598, v176
	v_mul_f32_e32 v178, 0x3fb8aa3b, v178
	v_exp_f32_e32 v178, v178
	s_nop 0
	v_cndmask_b32_e64 v178, v178, v176, s[44:45]
	v_add_f32_e32 v176, v34, v138
	v_mul_f32_e32 v176, 0xbfb8aa3b, v176
	v_exp_f32_e32 v176, v176
	v_cvt_pk_bf16_f32 v177, v177, v178
	v_add_f32_e32 v138, v18, v138
	v_mul_f32_e32 v138, 0xbfb8aa3b, v138
	v_add_f32_e32 v176, 1.0, v176
	v_exp_f32_e32 v138, v138
	v_rcp_f32_e32 v176, v176
	s_nop 0
	v_mul_f32_e32 v179, 0xbf1b4598, v176
	v_mul_f32_e32 v179, 0x3fb8aa3b, v179
	v_exp_f32_e32 v179, v179
	v_add_f32_e32 v138, 1.0, v138
	v_cndmask_b32_e64 v179, v179, v176, s[44:45]
	v_add_f32_e32 v176, v35, v139
	v_mul_f32_e32 v176, 0xbfb8aa3b, v176
	v_exp_f32_e32 v176, v176
	s_nop 0
	v_add_f32_e32 v176, 1.0, v176
	v_rcp_f32_e32 v176, v176
	s_nop 0
	v_mul_f32_e32 v180, 0xbf1b4598, v176
	v_mul_f32_e32 v180, 0x3fb8aa3b, v180
	v_exp_f32_e32 v180, v180
	s_nop 0
	v_cndmask_b32_e64 v180, v180, v176, s[44:45]
	v_add_f32_e32 v176, v36, v140
	v_mul_f32_e32 v176, 0xbfb8aa3b, v176
	v_exp_f32_e32 v176, v176
	v_cvt_pk_bf16_f32 v178, v179, v180
	v_add_f32_e32 v176, 1.0, v176
	v_rcp_f32_e32 v176, v176
	s_nop 0
	v_mul_f32_e32 v181, 0xbf1b4598, v176
	v_mul_f32_e32 v181, 0x3fb8aa3b, v181
	v_exp_f32_e32 v181, v181
	s_nop 0
	v_cndmask_b32_e64 v181, v181, v176, s[44:45]
	v_add_f32_e32 v176, v37, v141
	v_mul_f32_e32 v176, 0xbfb8aa3b, v176
	v_exp_f32_e32 v176, v176
	s_nop 0
	v_add_f32_e32 v176, 1.0, v176
	s_mov_b32 s0, 0x140000
	v_rcp_f32_e32 v176, v176
	s_nop 0
	v_mul_f32_e32 v182, 0xbf1b4598, v176
	v_mul_f32_e32 v182, 0x3fb8aa3b, v182
	v_exp_f32_e32 v182, v182
	s_nop 0
	v_cndmask_b32_e64 v182, v182, v176, s[44:45]
	v_cvt_pk_bf16_f32 v176, v168, v169
	v_add_co_u32_e32 v168, vcc, s0, v164
	v_cvt_pk_bf16_f32 v179, v181, v182
	s_nop 0
	v_addc_co_u32_e32 v169, vcc, 0, v165, vcc
	global_store_dwordx4 v[168:169], v[176:179], off
	v_add_f32_e32 v168, v14, v134
	v_mul_f32_e32 v168, 0xbfb8aa3b, v168
	v_exp_f32_e32 v168, v168
	v_add_f32_e32 v134, v6, v134
	v_mul_f32_e32 v134, 0xbfb8aa3b, v134
	v_exp_f32_e32 v134, v134
	v_add_f32_e32 v168, 1.0, v168
	v_add_f32_e32 v134, 1.0, v134
	v_rcp_f32_e32 v168, v168
	s_nop 0
	v_mul_f32_e32 v169, 0xbf1b4598, v168
	v_mul_f32_e32 v169, 0x3fb8aa3b, v169
	v_exp_f32_e32 v169, v169
	s_nop 0
	v_cndmask_b32_e64 v168, v169, v168, s[44:45]
	v_add_f32_e32 v169, v15, v135
	v_mul_f32_e32 v169, 0xbfb8aa3b, v169
	v_exp_f32_e32 v169, v169
	v_add_f32_e32 v135, v7, v135
	v_mul_f32_e32 v135, 0xbfb8aa3b, v135
	v_exp_f32_e32 v135, v135
	v_add_f32_e32 v169, 1.0, v169
	v_add_f32_e32 v135, 1.0, v135
	v_rcp_f32_e32 v169, v169
	s_nop 0
; __device__ __forceinline__ float sigmoidf_(float x) { return 1.0f / (1.0f + __expf(-x)); }
	v_mul_f32_e32 v176, 0xbf1b4598, v169
	v_mul_f32_e32 v176, 0x3fb8aa3b, v176
	v_exp_f32_e32 v176, v176
	s_nop 0
	v_cndmask_b32_e64 v169, v176, v169, s[44:45]
	v_add_f32_e32 v176, v16, v136
	v_mul_f32_e32 v176, 0xbfb8aa3b, v176
	v_exp_f32_e32 v176, v176
	s_nop 0
	v_add_f32_e32 v176, 1.0, v176
	v_rcp_f32_e32 v176, v176
	s_nop 0
	v_mul_f32_e32 v177, 0xbf1b4598, v176
	v_mul_f32_e32 v177, 0x3fb8aa3b, v177
	v_exp_f32_e32 v177, v177
	s_nop 0
	v_cndmask_b32_e64 v177, v177, v176, s[44:45]
	v_add_f32_e32 v176, v17, v137
	v_mul_f32_e32 v176, 0xbfb8aa3b, v176
	v_exp_f32_e32 v176, v176
	s_nop 0
	v_add_f32_e32 v176, 1.0, v176
	v_rcp_f32_e32 v176, v176
	s_nop 0
	v_mul_f32_e32 v178, 0xbf1b4598, v176
	v_mul_f32_e32 v178, 0x3fb8aa3b, v178
	v_exp_f32_e32 v178, v178
	s_nop 0
	v_cndmask_b32_e64 v178, v178, v176, s[44:45]
	v_add_f32_e32 v176, v10, v130
	v_mul_f32_e32 v176, 0xbfb8aa3b, v176
	v_exp_f32_e32 v176, v176
	v_cvt_pk_bf16_f32 v177, v177, v178
	v_add_f32_e32 v130, v2, v130
	v_mul_f32_e32 v130, 0xbfb8aa3b, v130
	v_add_f32_e32 v176, 1.0, v176
	v_exp_f32_e32 v130, v130
	v_rcp_f32_e32 v176, v176
	s_nop 0
	v_mul_f32_e32 v179, 0xbf1b4598, v176
	v_mul_f32_e32 v179, 0x3fb8aa3b, v179
	v_exp_f32_e32 v179, v179
	v_add_f32_e32 v130, 1.0, v130
	v_cndmask_b32_e64 v179, v179, v176, s[44:45]
	v_add_f32_e32 v176, v11, v131
	v_mul_f32_e32 v176, 0xbfb8aa3b, v176
	v_exp_f32_e32 v176, v176
	s_nop 0
	v_add_f32_e32 v176, 1.0, v176
	v_rcp_f32_e32 v176, v176
	s_nop 0
	v_mul_f32_e32 v180, 0xbf1b4598, v176
	v_mul_f32_e32 v180, 0x3fb8aa3b, v180
	v_exp_f32_e32 v180, v180
	s_nop 0
	v_cndmask_b32_e64 v180, v180, v176, s[44:45]
	v_add_f32_e32 v176, v12, v132
	v_mul_f32_e32 v176, 0xbfb8aa3b, v176
	v_exp_f32_e32 v176, v176
	v_cvt_pk_bf16_f32 v178, v179, v180
	v_add_f32_e32 v176, 1.0, v176
	v_rcp_f32_e32 v176, v176
	s_nop 0
	v_mul_f32_e32 v181, 0xbf1b4598, v176
	v_mul_f32_e32 v181, 0x3fb8aa3b, v181
	v_exp_f32_e32 v181, v181
	s_nop 0
	v_cndmask_b32_e64 v181, v181, v176, s[44:45]
	v_add_f32_e32 v176, v13, v133
	v_mul_f32_e32 v176, 0xbfb8aa3b, v176
	v_exp_f32_e32 v176, v176
	s_nop 0
	v_add_f32_e32 v176, 1.0, v176
	s_mov_b64 s[0:1], 0x160000
	v_rcp_f32_e32 v176, v176
	s_nop 0
	v_mul_f32_e32 v182, 0xbf1b4598, v176
	v_mul_f32_e32 v182, 0x3fb8aa3b, v182
	v_exp_f32_e32 v182, v182
	s_nop 0
	v_cndmask_b32_e64 v182, v182, v176, s[44:45]
	v_cvt_pk_bf16_f32 v176, v168, v169
	v_cvt_pk_bf16_f32 v179, v181, v182
	global_store_dwordx4 v[166:167], v[176:179], off offset:256
	v_lshl_add_u64 v[166:167], v[164:165], 0, s[0:1]
	v_rcp_f32_e32 v142, v142
	s_nop 0
	v_mul_f32_e32 v168, 0xbf1b4598, v142
	v_mul_f32_e32 v168, 0x3fb8aa3b, v168
	v_exp_f32_e32 v168, v168
	s_nop 0
	v_cndmask_b32_e64 v142, v168, v142, s[44:45]
	v_rcp_f32_e32 v143, v143
	s_nop 0
	v_mul_f32_e32 v168, 0xbf1b4598, v143
	v_mul_f32_e32 v168, 0x3fb8aa3b, v168
	v_exp_f32_e32 v168, v168
	s_nop 0
	v_cndmask_b32_e64 v143, v168, v143, s[44:45]
	v_rcp_f32_e32 v144, v144
	s_nop 0
	v_mul_f32_e32 v168, 0xbf1b4598, v144
	v_mul_f32_e32 v168, 0x3fb8aa3b, v168
	v_exp_f32_e32 v168, v168
	s_nop 0
	v_cndmask_b32_e64 v144, v168, v144, s[44:45]
	v_rcp_f32_e32 v145, v145
	s_nop 0
	v_mul_f32_e32 v168, 0xbf1b4598, v145
	v_mul_f32_e32 v168, 0x3fb8aa3b, v168
	v_exp_f32_e32 v168, v168
	s_nop 0
	v_cndmask_b32_e64 v145, v168, v145, s[44:45]
	v_rcp_f32_e32 v138, v138
	s_nop 0
	v_mul_f32_e32 v168, 0xbf1b4598, v138
	v_mul_f32_e32 v168, 0x3fb8aa3b, v168
	v_exp_f32_e32 v168, v168
	s_nop 0
	v_cndmask_b32_e64 v168, v168, v138, s[44:45]
	v_add_f32_e32 v138, v19, v139
	v_mul_f32_e32 v138, 0xbfb8aa3b, v138
; __device__ __forceinline__ float sigmoidf_(float x) { return 1.0f / (1.0f + __expf(-x)); }
	v_exp_f32_e32 v138, v138
	s_nop 0
	v_add_f32_e32 v138, 1.0, v138
	v_rcp_f32_e32 v138, v138
	s_nop 0
	v_mul_f32_e32 v139, 0xbf1b4598, v138
	v_mul_f32_e32 v139, 0x3fb8aa3b, v139
	v_exp_f32_e32 v139, v139
	s_nop 0
	v_cndmask_b32_e64 v169, v139, v138, s[44:45]
	v_add_f32_e32 v138, v20, v140
	v_mul_f32_e32 v138, 0xbfb8aa3b, v138
	v_exp_f32_e32 v138, v138
	s_nop 0
	v_add_f32_e32 v138, 1.0, v138
	v_rcp_f32_e32 v138, v138
	s_nop 0
	v_mul_f32_e32 v139, 0xbf1b4598, v138
	v_mul_f32_e32 v139, 0x3fb8aa3b, v139
	v_exp_f32_e32 v139, v139
	s_nop 0
	v_cndmask_b32_e64 v176, v139, v138, s[44:45]
	v_add_f32_e32 v138, v21, v141
	v_mul_f32_e32 v138, 0xbfb8aa3b, v138
	v_exp_f32_e32 v138, v138
	s_nop 0
	v_add_f32_e32 v138, 1.0, v138
	s_mov_b32 s0, 0x160000
	v_rcp_f32_e32 v138, v138
	s_nop 0
	v_mul_f32_e32 v139, 0xbf1b4598, v138
	v_mul_f32_e32 v139, 0x3fb8aa3b, v139
	v_exp_f32_e32 v139, v139
	v_cvt_pk_bf16_f32 v140, v168, v169
	v_cndmask_b32_e64 v141, v139, v138, s[44:45]
	v_cvt_pk_bf16_f32 v138, v142, v143
	v_add_co_u32_e32 v142, vcc, s0, v164
	v_cvt_pk_bf16_f32 v139, v144, v145
	v_cvt_pk_bf16_f32 v141, v176, v141
	v_addc_co_u32_e32 v143, vcc, 0, v165, vcc
	global_store_dwordx4 v[142:143], v[138:141], off
	v_rcp_f32_e32 v134, v134
	s_nop 0
	v_mul_f32_e32 v138, 0xbf1b4598, v134
	v_mul_f32_e32 v138, 0x3fb8aa3b, v138
	v_exp_f32_e32 v138, v138
	s_nop 0
	v_cndmask_b32_e64 v134, v138, v134, s[44:45]
	v_rcp_f32_e32 v135, v135
	s_nop 0
	v_mul_f32_e32 v138, 0xbf1b4598, v135
	v_mul_f32_e32 v138, 0x3fb8aa3b, v138
	v_exp_f32_e32 v138, v138
	s_nop 0
	v_cndmask_b32_e64 v138, v138, v135, s[44:45]
	v_add_f32_e32 v135, v8, v136
	v_mul_f32_e32 v135, 0xbfb8aa3b, v135
	v_exp_f32_e32 v135, v135
	s_nop 0
	v_add_f32_e32 v135, 1.0, v135
	v_rcp_f32_e32 v135, v135
	s_nop 0
	v_mul_f32_e32 v136, 0xbf1b4598, v135
	v_mul_f32_e32 v136, 0x3fb8aa3b, v136
	v_exp_f32_e32 v136, v136
	s_nop 0
	v_cndmask_b32_e64 v139, v136, v135, s[44:45]
	v_add_f32_e32 v135, v9, v137
	v_mul_f32_e32 v135, 0xbfb8aa3b, v135
	v_exp_f32_e32 v135, v135
	s_nop 0
	v_add_f32_e32 v135, 1.0, v135
	v_rcp_f32_e32 v135, v135
	s_nop 0
	v_mul_f32_e32 v136, 0xbf1b4598, v135
	v_mul_f32_e32 v136, 0x3fb8aa3b, v136
	v_exp_f32_e32 v136, v136
	s_nop 0
	v_cndmask_b32_e64 v137, v136, v135, s[44:45]
	v_rcp_f32_e32 v130, v130
	s_nop 0
	v_mul_f32_e32 v135, 0xbf1b4598, v130
	v_mul_f32_e32 v135, 0x3fb8aa3b, v135
	v_exp_f32_e32 v135, v135
	s_nop 0
	v_cndmask_b32_e64 v140, v135, v130, s[44:45]
	v_add_f32_e32 v130, v3, v131
	v_mul_f32_e32 v130, 0xbfb8aa3b, v130
	v_exp_f32_e32 v130, v130
	s_nop 0
	v_add_f32_e32 v130, 1.0, v130
	v_rcp_f32_e32 v130, v130
	s_nop 0
	v_mul_f32_e32 v131, 0xbf1b4598, v130
	v_mul_f32_e32 v131, 0x3fb8aa3b, v131
	v_exp_f32_e32 v131, v131
	s_nop 0
	v_cndmask_b32_e64 v141, v131, v130, s[44:45]
	v_add_f32_e32 v130, v4, v132
	v_mul_f32_e32 v130, 0xbfb8aa3b, v130
	v_exp_f32_e32 v130, v130
	s_nop 0
	v_add_f32_e32 v130, 1.0, v130
	v_rcp_f32_e32 v130, v130
	s_nop 0
	v_mul_f32_e32 v131, 0xbf1b4598, v130
	v_mul_f32_e32 v131, 0x3fb8aa3b, v131
	v_exp_f32_e32 v131, v131
	s_nop 0
	v_cndmask_b32_e64 v135, v131, v130, s[44:45]
	v_add_f32_e32 v130, v5, v133
	v_mul_f32_e32 v130, 0xbfb8aa3b, v130
	v_exp_f32_e32 v130, v130
	s_nop 0
	v_add_f32_e32 v130, 1.0, v130
	s_mov_b64 s[0:1], 0
	v_rcp_f32_e32 v130, v130
	s_nop 0
	v_mul_f32_e32 v131, 0xbf1b4598, v130
	v_mul_f32_e32 v131, 0x3fb8aa3b, v131
	v_exp_f32_e32 v131, v131
	v_cvt_pk_bf16_f32 v132, v140, v141
	v_cndmask_b32_e64 v136, v131, v130, s[44:45]
	v_cvt_pk_bf16_f32 v130, v134, v138
	v_cvt_pk_bf16_f32 v131, v139, v137

; template <int ACT> __device__ __forceinline__ void store_tile_bf16(AccRef acc, bf16_t* dst, int ld, int row0, int col0) {
; #pragma unroll
;     for (int ai = 0; ai < 2; ++ai)
; #pragma unroll
;         for (int m = 0; m < 4; ++m) { bf16_t* rowp = dst + (size_t)(row0 + ai * 128 + m * 16) * ld + col0;
; #pragma unroll
;             for (int bj = 0; bj < 2; ++bj) { const f32x4 v0 = acc[ai][bj][m][0], v1 = acc[ai][bj][m][1];
;                 u32x4 w; w.x = cvt_pk_bf16(actf<ACT>(v0[0]), actf<ACT>(v0[1])); w.y = cvt_pk_bf16(actf<ACT>(v0[2]), actf<ACT>(v0[3]));
;                 w.z = cvt_pk_bf16(actf<ACT>(v1[0]), actf<ACT>(v1[1])); w.w = cvt_pk_bf16(actf<ACT>(v1[2]), actf<ACT>(v1[3]));
;                 *(u32x4*)(rowp + bj * 128) = w; } }
.LBB0_2489:
	s_andn2_b64 vcc, exec, s[0:1]
	s_cbranch_vccnz .LBB0_2491
	v_lshl_add_u32 v206, s88, 8, v231
	v_ashrrev_i32_e32 v219, 31, v218
	v_lshl_add_u64 v[136:137], v[206:207], 1, s[50:51]
	v_lshlrev_b64 v[130:131], 13, v[218:219]
	v_lshl_add_u64 v[134:135], v[136:137], 0, v[130:131]
	v_mul_f32_e32 v130, 0xbfb8aa3b, v126
	v_exp_f32_e32 v130, v130
	s_nop 0
	v_add_f32_e32 v130, 1.0, v130
	v_rcp_f32_e32 v130, v130
	s_nop 0
	v_mul_f32_e32 v130, v126, v130
	v_mul_f32_e32 v131, 0xbfb8aa3b, v127
	v_exp_f32_e32 v131, v131
	s_nop 0
	v_add_f32_e32 v131, 1.0, v131
	v_rcp_f32_e32 v131, v131
	s_nop 0
	v_mul_f32_e32 v131, v127, v131
	v_cvt_pk_bf16_f32 v130, v130, v131
	v_mul_f32_e32 v131, 0xbfb8aa3b, v128
	v_exp_f32_e32 v131, v131
	s_nop 0
	v_add_f32_e32 v131, 1.0, v131
	v_rcp_f32_e32 v131, v131
	s_nop 0
	v_mul_f32_e32 v131, v128, v131
	v_mul_f32_e32 v132, 0xbfb8aa3b, v129
	v_exp_f32_e32 v132, v132
	s_nop 0
	v_add_f32_e32 v132, 1.0, v132
	v_rcp_f32_e32 v132, v132
	s_nop 0
	v_mul_f32_e32 v132, v129, v132
	v_cvt_pk_bf16_f32 v131, v131, v132
	v_mul_f32_e32 v132, 0xbfb8aa3b, v122
	v_exp_f32_e32 v132, v132
	s_nop 0
	v_add_f32_e32 v132, 1.0, v132
	v_rcp_f32_e32 v132, v132
	s_nop 0
	v_mul_f32_e32 v132, v122, v132
	v_mul_f32_e32 v133, 0xbfb8aa3b, v123
	v_exp_f32_e32 v133, v133
	s_nop 0
	v_add_f32_e32 v133, 1.0, v133
	v_rcp_f32_e32 v133, v133
	s_nop 0
	v_mul_f32_e32 v133, v123, v133
	v_cvt_pk_bf16_f32 v132, v132, v133
	v_mul_f32_e32 v133, 0xbfb8aa3b, v124
	v_exp_f32_e32 v133, v133
	s_nop 0
	v_add_f32_e32 v133, 1.0, v133
	v_rcp_f32_e32 v133, v133
	s_nop 0
	v_mul_f32_e32 v133, v124, v133
	v_mul_f32_e32 v138, 0xbfb8aa3b, v125
	v_exp_f32_e32 v138, v138
	s_nop 0
	v_add_f32_e32 v138, 1.0, v138
	v_rcp_f32_e32 v138, v138
	s_nop 0
	v_mul_f32_e32 v138, v125, v138
	v_cvt_pk_bf16_f32 v133, v133, v138
	global_store_dwordx4 v[134:135], v[130:133], off
	s_nop 1
	v_mul_f32_e32 v130, 0xbfb8aa3b, v118
	v_exp_f32_e32 v130, v130
	s_nop 0
	v_add_f32_e32 v130, 1.0, v130
	v_rcp_f32_e32 v130, v130
	s_nop 0
	v_mul_f32_e32 v130, v118, v130
	v_mul_f32_e32 v131, 0xbfb8aa3b, v119
	v_exp_f32_e32 v131, v131
	s_nop 0
	v_add_f32_e32 v131, 1.0, v131
	v_rcp_f32_e32 v131, v131
	s_nop 0
	v_mul_f32_e32 v131, v119, v131
	v_cvt_pk_bf16_f32 v130, v130, v131
	v_mul_f32_e32 v131, 0xbfb8aa3b, v120
	v_exp_f32_e32 v131, v131
	s_nop 0
	v_add_f32_e32 v131, 1.0, v131
	v_rcp_f32_e32 v131, v131
	s_nop 0
	v_mul_f32_e32 v131, v120, v131
	v_mul_f32_e32 v132, 0xbfb8aa3b, v121
	v_exp_f32_e32 v132, v132
	s_nop 0
	v_add_f32_e32 v132, 1.0, v132
	v_rcp_f32_e32 v132, v132
	s_nop 0
	v_mul_f32_e32 v132, v121, v132
	v_cvt_pk_bf16_f32 v131, v131, v132
	v_mul_f32_e32 v132, 0xbfb8aa3b, v114
	v_exp_f32_e32 v132, v132
	s_nop 0
	v_add_f32_e32 v132, 1.0, v132
	v_rcp_f32_e32 v132, v132
	s_nop 0
	v_mul_f32_e32 v132, v114, v132
	v_mul_f32_e32 v133, 0xbfb8aa3b, v115
	v_exp_f32_e32 v133, v133
	s_nop 0
	v_add_f32_e32 v133, 1.0, v133
	v_rcp_f32_e32 v133, v133
	s_nop 0
	v_mul_f32_e32 v133, v115, v133
	v_cvt_pk_bf16_f32 v132, v132, v133
	v_mul_f32_e32 v133, 0xbfb8aa3b, v116
	v_exp_f32_e32 v133, v133
	s_nop 0
	v_add_f32_e32 v133, 1.0, v133
	v_rcp_f32_e32 v133, v133
	s_nop 0
	v_mul_f32_e32 v133, v116, v133
	v_mul_f32_e32 v138, 0xbfb8aa3b, v117
	v_exp_f32_e32 v138, v138
	s_nop 0
	v_add_f32_e32 v138, 1.0, v138
	v_rcp_f32_e32 v138, v138
	s_nop 0
	v_mul_f32_e32 v138, v117, v138
	v_cvt_pk_bf16_f32 v133, v133, v138
	global_store_dwordx4 v[134:135], v[130:133], off offset:256
	s_nop 1
	v_or_b32_e32 v130, 16, v218
	v_ashrrev_i32_e32 v131, 31, v130
	v_lshlrev_b64 v[130:131], 13, v[130:131]
	v_lshl_add_u64 v[138:139], v[136:137], 0, v[130:131]
	v_mul_f32_e32 v130, 0xbfb8aa3b, v110
	v_exp_f32_e32 v130, v130
	s_nop 0
	v_add_f32_e32 v130, 1.0, v130
	v_rcp_f32_e32 v130, v130
	s_nop 0
	v_mul_f32_e32 v130, v110, v130
	v_mul_f32_e32 v131, 0xbfb8aa3b, v111
	v_exp_f32_e32 v131, v131
	s_nop 0
	v_add_f32_e32 v131, 1.0, v131
	v_rcp_f32_e32 v131, v131
	s_nop 0
	v_mul_f32_e32 v131, v111, v131
	v_cvt_pk_bf16_f32 v130, v130, v131
	v_mul_f32_e32 v131, 0xbfb8aa3b, v112
	v_exp_f32_e32 v131, v131
	s_nop 0
	v_add_f32_e32 v131, 1.0, v131
	v_rcp_f32_e32 v131, v131
	s_nop 0
	v_mul_f32_e32 v131, v112, v131
	v_mul_f32_e32 v132, 0xbfb8aa3b, v113
	v_exp_f32_e32 v132, v132
	s_nop 0
	v_add_f32_e32 v132, 1.0, v132
	v_rcp_f32_e32 v132, v132
	s_nop 0
	v_mul_f32_e32 v132, v113, v132
	v_cvt_pk_bf16_f32 v131, v131, v132
	v_mul_f32_e32 v132, 0xbfb8aa3b, v106
	v_exp_f32_e32 v132, v132
	s_nop 0
	v_add_f32_e32 v132, 1.0, v132
	v_rcp_f32_e32 v132, v132
	s_nop 0
	v_mul_f32_e32 v132, v106, v132
	v_mul_f32_e32 v133, 0xbfb8aa3b, v107
	v_exp_f32_e32 v133, v133
	s_nop 0
	v_add_f32_e32 v133, 1.0, v133
	v_rcp_f32_e32 v133, v133
	s_nop 0
	v_mul_f32_e32 v133, v107, v133
	v_cvt_pk_bf16_f32 v132, v132, v133
	v_mul_f32_e32 v133, 0xbfb8aa3b, v108
	v_exp_f32_e32 v133, v133
	s_nop 0
	v_add_f32_e32 v133, 1.0, v133
	v_rcp_f32_e32 v133, v133
	s_nop 0
	v_mul_f32_e32 v133, v108, v133
	v_mul_f32_e32 v140, 0xbfb8aa3b, v109
	v_exp_f32_e32 v140, v140
	s_nop 0
	v_add_f32_e32 v140, 1.0, v140
	v_rcp_f32_e32 v140, v140
	s_nop 0
	v_mul_f32_e32 v140, v109, v140
	v_cvt_pk_bf16_f32 v133, v133, v140
	global_store_dwordx4 v[138:139], v[130:133], off
	s_nop 1
	v_mul_f32_e32 v130, 0xbfb8aa3b, v102
	v_exp_f32_e32 v130, v130
	s_nop 0
	v_add_f32_e32 v130, 1.0, v130
	v_rcp_f32_e32 v130, v130
	s_nop 0
	v_mul_f32_e32 v130, v102, v130
	v_mul_f32_e32 v131, 0xbfb8aa3b, v103
	v_exp_f32_e32 v131, v131
	s_nop 0
	v_add_f32_e32 v131, 1.0, v131
	v_rcp_f32_e32 v131, v131
	s_nop 0
	v_mul_f32_e32 v131, v103, v131
	v_cvt_pk_bf16_f32 v130, v130, v131
	v_mul_f32_e32 v131, 0xbfb8aa3b, v104
	v_exp_f32_e32 v131, v131
	s_nop 0
	v_add_f32_e32 v131, 1.0, v131
; __device__ __forceinline__ float siluf_(float x) { return x / (1.0f + __expf(-x)); }
; template <int ACT> __device__ __forceinline__ void store_tile_bf16(AccRef acc, bf16_t* dst, int ld, int row0, int col0) {
; #pragma unroll
;     for (int ai = 0; ai < 2; ++ai)
; #pragma unroll
;         for (int m = 0; m < 4; ++m) { bf16_t* rowp = dst + (size_t)(row0 + ai * 128 + m * 16) * ld + col0;
; #pragma unroll
;             for (int bj = 0; bj < 2; ++bj) { const f32x4 v0 = acc[ai][bj][m][0], v1 = acc[ai][bj][m][1];
;                 u32x4 w; w.x = cvt_pk_bf16(actf<ACT>(v0[0]), actf<ACT>(v0[1])); w.y = cvt_pk_bf16(actf<ACT>(v0[2]), actf<ACT>(v0[3]));
;                 w.z = cvt_pk_bf16(actf<ACT>(v1[0]), actf<ACT>(v1[1])); w.w = cvt_pk_bf16(actf<ACT>(v1[2]), actf<ACT>(v1[3]));
;                 *(u32x4*)(rowp + bj * 128) = w; } }
	v_rcp_f32_e32 v131, v131
	s_nop 0
	v_mul_f32_e32 v131, v104, v131
	v_mul_f32_e32 v132, 0xbfb8aa3b, v105
	v_exp_f32_e32 v132, v132
	s_nop 0
	v_add_f32_e32 v132, 1.0, v132
	v_rcp_f32_e32 v132, v132
	s_nop 0
	v_mul_f32_e32 v132, v105, v132
	v_cvt_pk_bf16_f32 v131, v131, v132
	v_mul_f32_e32 v132, 0xbfb8aa3b, v98
	v_exp_f32_e32 v132, v132
	s_nop 0
	v_add_f32_e32 v132, 1.0, v132
	v_rcp_f32_e32 v132, v132
	s_nop 0
	v_mul_f32_e32 v132, v98, v132
	v_mul_f32_e32 v133, 0xbfb8aa3b, v99
	v_exp_f32_e32 v133, v133
	s_nop 0
	v_add_f32_e32 v133, 1.0, v133
	v_rcp_f32_e32 v133, v133
	s_nop 0
	v_mul_f32_e32 v133, v99, v133
	v_cvt_pk_bf16_f32 v132, v132, v133
	v_mul_f32_e32 v133, 0xbfb8aa3b, v100
	v_exp_f32_e32 v133, v133
	s_nop 0
	v_add_f32_e32 v133, 1.0, v133
	v_rcp_f32_e32 v133, v133
	s_nop 0
	v_mul_f32_e32 v133, v100, v133
	v_mul_f32_e32 v140, 0xbfb8aa3b, v101
	v_exp_f32_e32 v140, v140
	s_nop 0
	v_add_f32_e32 v140, 1.0, v140
	v_rcp_f32_e32 v140, v140
	s_nop 0
	v_mul_f32_e32 v140, v101, v140
	v_cvt_pk_bf16_f32 v133, v133, v140
	global_store_dwordx4 v[138:139], v[130:133], off offset:256
	s_nop 1
	v_or_b32_e32 v130, 32, v218
	v_ashrrev_i32_e32 v131, 31, v130
	v_lshlrev_b64 v[130:131], 13, v[130:131]
	v_lshl_add_u64 v[138:139], v[136:137], 0, v[130:131]
	v_mul_f32_e32 v130, 0xbfb8aa3b, v94
	v_exp_f32_e32 v130, v130
	s_nop 0
	v_add_f32_e32 v130, 1.0, v130
	v_rcp_f32_e32 v130, v130
	s_nop 0
	v_mul_f32_e32 v130, v94, v130
	v_mul_f32_e32 v131, 0xbfb8aa3b, v95
	v_exp_f32_e32 v131, v131
	s_nop 0
	v_add_f32_e32 v131, 1.0, v131
	v_rcp_f32_e32 v131, v131
	s_nop 0
	v_mul_f32_e32 v131, v95, v131
	v_cvt_pk_bf16_f32 v130, v130, v131
	v_mul_f32_e32 v131, 0xbfb8aa3b, v96
	v_exp_f32_e32 v131, v131
	s_nop 0
	v_add_f32_e32 v131, 1.0, v131
	v_rcp_f32_e32 v131, v131
	s_nop 0
	v_mul_f32_e32 v131, v96, v131
	v_mul_f32_e32 v132, 0xbfb8aa3b, v97
	v_exp_f32_e32 v132, v132
	s_nop 0
	v_add_f32_e32 v132, 1.0, v132
	v_rcp_f32_e32 v132, v132
	s_nop 0
	v_mul_f32_e32 v132, v97, v132
	v_cvt_pk_bf16_f32 v131, v131, v132
	v_mul_f32_e32 v132, 0xbfb8aa3b, v90
	v_exp_f32_e32 v132, v132
	s_nop 0
	v_add_f32_e32 v132, 1.0, v132
	v_rcp_f32_e32 v132, v132
	s_nop 0
	v_mul_f32_e32 v132, v90, v132
	v_mul_f32_e32 v133, 0xbfb8aa3b, v91
	v_exp_f32_e32 v133, v133
	s_nop 0
	v_add_f32_e32 v133, 1.0, v133
	v_rcp_f32_e32 v133, v133
	s_nop 0
	v_mul_f32_e32 v133, v91, v133
	v_cvt_pk_bf16_f32 v132, v132, v133
	v_mul_f32_e32 v133, 0xbfb8aa3b, v92
	v_exp_f32_e32 v133, v133
	s_nop 0
	v_add_f32_e32 v133, 1.0, v133
	v_rcp_f32_e32 v133, v133
	s_nop 0
	v_mul_f32_e32 v133, v92, v133
	v_mul_f32_e32 v140, 0xbfb8aa3b, v93
	v_exp_f32_e32 v140, v140
	s_nop 0
	v_add_f32_e32 v140, 1.0, v140
	v_rcp_f32_e32 v140, v140
	s_nop 0
	v_mul_f32_e32 v140, v93, v140
	v_cvt_pk_bf16_f32 v133, v133, v140
	global_store_dwordx4 v[138:139], v[130:133], off
	s_nop 1
	v_mul_f32_e32 v130, 0xbfb8aa3b, v86
	v_exp_f32_e32 v130, v130
	s_nop 0
	v_add_f32_e32 v130, 1.0, v130
	v_rcp_f32_e32 v130, v130
	s_nop 0
	v_mul_f32_e32 v130, v86, v130
	v_mul_f32_e32 v131, 0xbfb8aa3b, v87
	v_exp_f32_e32 v131, v131
	s_nop 0
	v_add_f32_e32 v131, 1.0, v131
	v_rcp_f32_e32 v131, v131
	s_nop 0
	v_mul_f32_e32 v131, v87, v131
	v_cvt_pk_bf16_f32 v130, v130, v131
	v_mul_f32_e32 v131, 0xbfb8aa3b, v88
	v_exp_f32_e32 v131, v131
	s_nop 0
	v_add_f32_e32 v131, 1.0, v131
	v_rcp_f32_e32 v131, v131
	s_nop 0
	v_mul_f32_e32 v131, v88, v131
	v_mul_f32_e32 v132, 0xbfb8aa3b, v89
	v_exp_f32_e32 v132, v132
	s_nop 0
	v_add_f32_e32 v132, 1.0, v132
	v_rcp_f32_e32 v132, v132
	s_nop 0
	v_mul_f32_e32 v132, v89, v132
	v_cvt_pk_bf16_f32 v131, v131, v132
	v_mul_f32_e32 v132, 0xbfb8aa3b, v82
	v_exp_f32_e32 v132, v132
	s_nop 0
	v_add_f32_e32 v132, 1.0, v132
	v_rcp_f32_e32 v132, v132
	s_nop 0
	v_mul_f32_e32 v132, v82, v132
	v_mul_f32_e32 v133, 0xbfb8aa3b, v83
	v_exp_f32_e32 v133, v133
	s_nop 0
	v_add_f32_e32 v133, 1.0, v133
	v_rcp_f32_e32 v133, v133
	s_nop 0
	v_mul_f32_e32 v133, v83, v133
	v_cvt_pk_bf16_f32 v132, v132, v133
	v_mul_f32_e32 v133, 0xbfb8aa3b, v84
	v_exp_f32_e32 v133, v133
	s_nop 0
	v_add_f32_e32 v133, 1.0, v133
	v_rcp_f32_e32 v133, v133
	s_nop 0
	v_mul_f32_e32 v133, v84, v133
	v_mul_f32_e32 v140, 0xbfb8aa3b, v85
	v_exp_f32_e32 v140, v140
	s_nop 0
	v_add_f32_e32 v140, 1.0, v140
	v_rcp_f32_e32 v140, v140
	s_nop 0
	v_mul_f32_e32 v140, v85, v140
	v_cvt_pk_bf16_f32 v133, v133, v140
	global_store_dwordx4 v[138:139], v[130:133], off offset:256
	s_nop 1
	v_or_b32_e32 v130, 48, v218
	v_ashrrev_i32_e32 v131, 31, v130
	v_lshlrev_b64 v[130:131], 13, v[130:131]
	v_lshl_add_u64 v[136:137], v[136:137], 0, v[130:131]
	v_mul_f32_e32 v130, 0xbfb8aa3b, v78
	v_exp_f32_e32 v130, v130
	s_nop 0
	v_add_f32_e32 v130, 1.0, v130
	v_rcp_f32_e32 v130, v130
	s_nop 0
	v_mul_f32_e32 v130, v78, v130
	v_mul_f32_e32 v131, 0xbfb8aa3b, v79
	v_exp_f32_e32 v131, v131
	s_nop 0
	v_add_f32_e32 v131, 1.0, v131
	v_rcp_f32_e32 v131, v131
	s_nop 0
	v_mul_f32_e32 v131, v79, v131
	v_cvt_pk_bf16_f32 v130, v130, v131
	v_mul_f32_e32 v131, 0xbfb8aa3b, v80
	v_exp_f32_e32 v131, v131
	s_nop 0
	v_add_f32_e32 v131, 1.0, v131
	v_rcp_f32_e32 v131, v131
	s_nop 0
	v_mul_f32_e32 v131, v80, v131
	v_mul_f32_e32 v132, 0xbfb8aa3b, v81
	v_exp_f32_e32 v132, v132
	s_nop 0
	v_add_f32_e32 v132, 1.0, v132
	v_rcp_f32_e32 v132, v132
	s_nop 0
	v_mul_f32_e32 v132, v81, v132
	v_cvt_pk_bf16_f32 v131, v131, v132
	v_mul_f32_e32 v132, 0xbfb8aa3b, v74
	v_exp_f32_e32 v132, v132
	s_nop 0
	v_add_f32_e32 v132, 1.0, v132
	v_rcp_f32_e32 v132, v132
	s_nop 0
	v_mul_f32_e32 v132, v74, v132
	v_mul_f32_e32 v133, 0xbfb8aa3b, v75
	v_exp_f32_e32 v133, v133
	s_nop 0
	v_add_f32_e32 v133, 1.0, v133
	v_rcp_f32_e32 v133, v133
	s_nop 0
	v_mul_f32_e32 v133, v75, v133
	v_cvt_pk_bf16_f32 v132, v132, v133
; __device__ __forceinline__ float siluf_(float x) { return x / (1.0f + __expf(-x)); }
; template <int ACT> __device__ __forceinline__ void store_tile_bf16(AccRef acc, bf16_t* dst, int ld, int row0, int col0) {
; #pragma unroll
;     for (int ai = 0; ai < 2; ++ai)
; #pragma unroll
;         for (int m = 0; m < 4; ++m) { bf16_t* rowp = dst + (size_t)(row0 + ai * 128 + m * 16) * ld + col0;
; #pragma unroll
;             for (int bj = 0; bj < 2; ++bj) { const f32x4 v0 = acc[ai][bj][m][0], v1 = acc[ai][bj][m][1];
;                 u32x4 w; w.x = cvt_pk_bf16(actf<ACT>(v0[0]), actf<ACT>(v0[1])); w.y = cvt_pk_bf16(actf<ACT>(v0[2]), actf<ACT>(v0[3]));
;                 w.z = cvt_pk_bf16(actf<ACT>(v1[0]), actf<ACT>(v1[1])); w.w = cvt_pk_bf16(actf<ACT>(v1[2]), actf<ACT>(v1[3]));
;                 *(u32x4*)(rowp + bj * 128) = w; } }
	v_mul_f32_e32 v133, 0xbfb8aa3b, v76
	v_exp_f32_e32 v133, v133
	s_nop 0
	v_add_f32_e32 v133, 1.0, v133
	v_rcp_f32_e32 v133, v133
	s_nop 0
	v_mul_f32_e32 v133, v76, v133
	v_mul_f32_e32 v138, 0xbfb8aa3b, v77
	v_exp_f32_e32 v138, v138
	s_nop 0
	v_add_f32_e32 v138, 1.0, v138
	v_rcp_f32_e32 v138, v138
	s_nop 0
	v_mul_f32_e32 v138, v77, v138
	v_cvt_pk_bf16_f32 v133, v133, v138
	global_store_dwordx4 v[136:137], v[130:133], off
	s_nop 1
	v_mul_f32_e32 v130, 0xbfb8aa3b, v70
	v_exp_f32_e32 v130, v130
	s_nop 0
	v_add_f32_e32 v130, 1.0, v130
	v_rcp_f32_e32 v130, v130
	s_nop 0
	v_mul_f32_e32 v130, v70, v130
	v_mul_f32_e32 v131, 0xbfb8aa3b, v71
	v_exp_f32_e32 v131, v131
	s_nop 0
	v_add_f32_e32 v131, 1.0, v131
	v_rcp_f32_e32 v131, v131
	s_nop 0
	v_mul_f32_e32 v131, v71, v131
	v_cvt_pk_bf16_f32 v130, v130, v131
	v_mul_f32_e32 v131, 0xbfb8aa3b, v72
	v_exp_f32_e32 v131, v131
	s_nop 0
	v_add_f32_e32 v131, 1.0, v131
	v_rcp_f32_e32 v131, v131
	s_nop 0
	v_mul_f32_e32 v131, v72, v131
	v_mul_f32_e32 v132, 0xbfb8aa3b, v73
	v_exp_f32_e32 v132, v132
	s_nop 0
	v_add_f32_e32 v132, 1.0, v132
	v_rcp_f32_e32 v132, v132
	s_nop 0
	v_mul_f32_e32 v132, v73, v132
	v_cvt_pk_bf16_f32 v131, v131, v132
	v_mul_f32_e32 v132, 0xbfb8aa3b, v66
	v_exp_f32_e32 v132, v132
	s_nop 0
	v_add_f32_e32 v132, 1.0, v132
	v_rcp_f32_e32 v132, v132
	s_nop 0
	v_mul_f32_e32 v132, v66, v132
	v_mul_f32_e32 v133, 0xbfb8aa3b, v67
	v_exp_f32_e32 v133, v133
	s_nop 0
	v_add_f32_e32 v133, 1.0, v133
	v_rcp_f32_e32 v133, v133
	s_nop 0
	v_mul_f32_e32 v133, v67, v133
	v_cvt_pk_bf16_f32 v132, v132, v133
	v_mul_f32_e32 v133, 0xbfb8aa3b, v68
	v_exp_f32_e32 v133, v133
	s_nop 0
	v_add_f32_e32 v133, 1.0, v133
	v_rcp_f32_e32 v133, v133
	s_nop 0
	v_mul_f32_e32 v133, v68, v133
	v_mul_f32_e32 v138, 0xbfb8aa3b, v69
	v_exp_f32_e32 v138, v138
	s_nop 0
	v_add_f32_e32 v138, 1.0, v138
	v_rcp_f32_e32 v138, v138
	s_nop 0
	v_mul_f32_e32 v138, v69, v138
	v_cvt_pk_bf16_f32 v133, v133, v138
	global_store_dwordx4 v[136:137], v[130:133], off offset:256
	v_lshl_add_u64 v[136:137], v[134:135], 0, s[58:59]
	s_nop 0
	v_mul_f32_e32 v130, 0xbfb8aa3b, v62
	v_exp_f32_e32 v130, v130
	s_nop 0
	v_add_f32_e32 v130, 1.0, v130
	v_rcp_f32_e32 v130, v130
	s_nop 0
	v_mul_f32_e32 v130, v62, v130
	v_mul_f32_e32 v131, 0xbfb8aa3b, v63
	v_exp_f32_e32 v131, v131
	s_nop 0
	v_add_f32_e32 v131, 1.0, v131
	v_rcp_f32_e32 v131, v131
	s_nop 0
	v_mul_f32_e32 v131, v63, v131
	v_cvt_pk_bf16_f32 v130, v130, v131
	v_mul_f32_e32 v131, 0xbfb8aa3b, v64
	v_exp_f32_e32 v131, v131
	s_nop 0
	v_add_f32_e32 v131, 1.0, v131
	v_rcp_f32_e32 v131, v131
	s_nop 0
	v_mul_f32_e32 v131, v64, v131
	v_mul_f32_e32 v132, 0xbfb8aa3b, v65
	v_exp_f32_e32 v132, v132
	s_nop 0
	v_add_f32_e32 v132, 1.0, v132
	v_rcp_f32_e32 v132, v132
	s_nop 0
	v_mul_f32_e32 v132, v65, v132
	v_cvt_pk_bf16_f32 v131, v131, v132
	v_mul_f32_e32 v132, 0xbfb8aa3b, v58
	v_exp_f32_e32 v132, v132
	s_nop 0
	v_add_f32_e32 v132, 1.0, v132
	v_rcp_f32_e32 v132, v132
	s_nop 0
	v_mul_f32_e32 v132, v58, v132
	v_mul_f32_e32 v133, 0xbfb8aa3b, v59
	v_exp_f32_e32 v133, v133
	s_nop 0
	v_add_f32_e32 v133, 1.0, v133
	v_rcp_f32_e32 v133, v133
	s_nop 0
	v_mul_f32_e32 v133, v59, v133
	v_cvt_pk_bf16_f32 v132, v132, v133
	v_mul_f32_e32 v133, 0xbfb8aa3b, v60
	v_exp_f32_e32 v133, v133
	s_nop 0
	v_add_f32_e32 v133, 1.0, v133
	v_rcp_f32_e32 v133, v133
	s_nop 0
	v_mul_f32_e32 v133, v60, v133
	v_mul_f32_e32 v138, 0xbfb8aa3b, v61
	v_exp_f32_e32 v138, v138
	s_nop 0
	v_add_f32_e32 v138, 1.0, v138
	v_rcp_f32_e32 v138, v138
	s_nop 0
	v_mul_f32_e32 v138, v61, v138
	v_cvt_pk_bf16_f32 v133, v133, v138
	v_add_co_u32_e32 v138, vcc, s97, v134
	s_nop 1
	v_addc_co_u32_e32 v139, vcc, 0, v135, vcc
	global_store_dwordx4 v[138:139], v[130:133], off
	s_nop 1
	v_mul_f32_e32 v130, 0xbfb8aa3b, v54
	v_exp_f32_e32 v130, v130
	s_nop 0
	v_add_f32_e32 v130, 1.0, v130
	v_rcp_f32_e32 v130, v130
	s_nop 0
	v_mul_f32_e32 v130, v54, v130
	v_mul_f32_e32 v131, 0xbfb8aa3b, v55
	v_exp_f32_e32 v131, v131
	s_nop 0
	v_add_f32_e32 v131, 1.0, v131
	v_rcp_f32_e32 v131, v131
	s_nop 0
	v_mul_f32_e32 v131, v55, v131
	v_cvt_pk_bf16_f32 v130, v130, v131
	v_mul_f32_e32 v131, 0xbfb8aa3b, v56
	v_exp_f32_e32 v131, v131
	s_nop 0
	v_add_f32_e32 v131, 1.0, v131
	v_rcp_f32_e32 v131, v131
	s_nop 0
	v_mul_f32_e32 v131, v56, v131
	v_mul_f32_e32 v132, 0xbfb8aa3b, v57
	v_exp_f32_e32 v132, v132
	s_nop 0
	v_add_f32_e32 v132, 1.0, v132
	v_rcp_f32_e32 v132, v132
	s_nop 0
	v_mul_f32_e32 v132, v57, v132
	v_cvt_pk_bf16_f32 v131, v131, v132
	v_mul_f32_e32 v132, 0xbfb8aa3b, v50
	v_exp_f32_e32 v132, v132
	s_nop 0
	v_add_f32_e32 v132, 1.0, v132
	v_rcp_f32_e32 v132, v132
	s_nop 0
	v_mul_f32_e32 v132, v50, v132
	v_mul_f32_e32 v133, 0xbfb8aa3b, v51
	v_exp_f32_e32 v133, v133
	s_nop 0
	v_add_f32_e32 v133, 1.0, v133
	v_rcp_f32_e32 v133, v133
	s_nop 0
	v_mul_f32_e32 v133, v51, v133
	v_cvt_pk_bf16_f32 v132, v132, v133
	v_mul_f32_e32 v133, 0xbfb8aa3b, v52
	v_exp_f32_e32 v133, v133
	s_nop 0
	v_add_f32_e32 v133, 1.0, v133
	v_rcp_f32_e32 v133, v133
	s_nop 0
	v_mul_f32_e32 v133, v52, v133
	v_mul_f32_e32 v138, 0xbfb8aa3b, v53
	v_exp_f32_e32 v138, v138
	s_nop 0
	v_add_f32_e32 v138, 1.0, v138
	v_rcp_f32_e32 v138, v138
	s_nop 0
	v_mul_f32_e32 v138, v53, v138
	v_cvt_pk_bf16_f32 v133, v133, v138
	global_store_dwordx4 v[136:137], v[130:133], off offset:256
	v_lshl_add_u64 v[136:137], v[134:135], 0, s[60:61]
	s_nop 0
	v_mul_f32_e32 v130, 0xbfb8aa3b, v46
	v_exp_f32_e32 v130, v130
	s_nop 0
	v_add_f32_e32 v130, 1.0, v130
	v_rcp_f32_e32 v130, v130
	s_nop 0
	v_mul_f32_e32 v130, v46, v130
	v_mul_f32_e32 v131, 0xbfb8aa3b, v47
	v_exp_f32_e32 v131, v131
	s_nop 0
	v_add_f32_e32 v131, 1.0, v131
	v_rcp_f32_e32 v131, v131
	s_nop 0
	v_mul_f32_e32 v131, v47, v131
; __device__ __forceinline__ float siluf_(float x) { return x / (1.0f + __expf(-x)); }
; template <int ACT> __device__ __forceinline__ void store_tile_bf16(AccRef acc, bf16_t* dst, int ld, int row0, int col0) {
; #pragma unroll
;     for (int ai = 0; ai < 2; ++ai)
; #pragma unroll
;         for (int m = 0; m < 4; ++m) { bf16_t* rowp = dst + (size_t)(row0 + ai * 128 + m * 16) * ld + col0;
; #pragma unroll
;             for (int bj = 0; bj < 2; ++bj) { const f32x4 v0 = acc[ai][bj][m][0], v1 = acc[ai][bj][m][1];
;                 u32x4 w; w.x = cvt_pk_bf16(actf<ACT>(v0[0]), actf<ACT>(v0[1])); w.y = cvt_pk_bf16(actf<ACT>(v0[2]), actf<ACT>(v0[3]));
;                 w.z = cvt_pk_bf16(actf<ACT>(v1[0]), actf<ACT>(v1[1])); w.w = cvt_pk_bf16(actf<ACT>(v1[2]), actf<ACT>(v1[3]));
;                 *(u32x4*)(rowp + bj * 128) = w; } }
	v_cvt_pk_bf16_f32 v130, v130, v131
	v_mul_f32_e32 v131, 0xbfb8aa3b, v48
	v_exp_f32_e32 v131, v131
	s_nop 0
	v_add_f32_e32 v131, 1.0, v131
	v_rcp_f32_e32 v131, v131
	s_nop 0
	v_mul_f32_e32 v131, v48, v131
	v_mul_f32_e32 v132, 0xbfb8aa3b, v49
	v_exp_f32_e32 v132, v132
	s_nop 0
	v_add_f32_e32 v132, 1.0, v132
	v_rcp_f32_e32 v132, v132
	s_nop 0
	v_mul_f32_e32 v132, v49, v132
	v_cvt_pk_bf16_f32 v131, v131, v132
	v_mul_f32_e32 v132, 0xbfb8aa3b, v42
	v_exp_f32_e32 v132, v132
	s_nop 0
	v_add_f32_e32 v132, 1.0, v132
	v_rcp_f32_e32 v132, v132
	s_nop 0
	v_mul_f32_e32 v132, v42, v132
	v_mul_f32_e32 v133, 0xbfb8aa3b, v43
	v_exp_f32_e32 v133, v133
	s_nop 0
	v_add_f32_e32 v133, 1.0, v133
	v_rcp_f32_e32 v133, v133
	s_nop 0
	v_mul_f32_e32 v133, v43, v133
	v_cvt_pk_bf16_f32 v132, v132, v133
	v_mul_f32_e32 v133, 0xbfb8aa3b, v44
	v_exp_f32_e32 v133, v133
	s_nop 0
	v_add_f32_e32 v133, 1.0, v133
	v_rcp_f32_e32 v133, v133
	s_nop 0
	v_mul_f32_e32 v133, v44, v133
	v_mul_f32_e32 v138, 0xbfb8aa3b, v45
	v_exp_f32_e32 v138, v138
	s_nop 0
	v_add_f32_e32 v138, 1.0, v138
	v_rcp_f32_e32 v138, v138
	s_nop 0
	v_mul_f32_e32 v138, v45, v138
	v_cvt_pk_bf16_f32 v133, v133, v138
	v_add_co_u32_e32 v138, vcc, s76, v134
	s_nop 1
	v_addc_co_u32_e32 v139, vcc, 0, v135, vcc
	global_store_dwordx4 v[138:139], v[130:133], off
	s_nop 1
	v_mul_f32_e32 v130, 0xbfb8aa3b, v38
	v_exp_f32_e32 v130, v130
	s_nop 0
	v_add_f32_e32 v130, 1.0, v130
	v_rcp_f32_e32 v130, v130
	s_nop 0
	v_mul_f32_e32 v130, v38, v130
	v_mul_f32_e32 v131, 0xbfb8aa3b, v39
	v_exp_f32_e32 v131, v131
	s_nop 0
	v_add_f32_e32 v131, 1.0, v131
	v_rcp_f32_e32 v131, v131
	s_nop 0
	v_mul_f32_e32 v131, v39, v131
	v_cvt_pk_bf16_f32 v130, v130, v131
	v_mul_f32_e32 v131, 0xbfb8aa3b, v40
	v_exp_f32_e32 v131, v131
	s_nop 0
	v_add_f32_e32 v131, 1.0, v131
	v_rcp_f32_e32 v131, v131
	s_nop 0
	v_mul_f32_e32 v131, v40, v131
	v_mul_f32_e32 v132, 0xbfb8aa3b, v41
	v_exp_f32_e32 v132, v132
	s_nop 0
	v_add_f32_e32 v132, 1.0, v132
	v_rcp_f32_e32 v132, v132
	s_nop 0
	v_mul_f32_e32 v132, v41, v132
	v_cvt_pk_bf16_f32 v131, v131, v132
	v_mul_f32_e32 v132, 0xbfb8aa3b, v34
	v_exp_f32_e32 v132, v132
	s_nop 0
	v_add_f32_e32 v132, 1.0, v132
	v_rcp_f32_e32 v132, v132
	s_nop 0
	v_mul_f32_e32 v132, v34, v132
	v_mul_f32_e32 v133, 0xbfb8aa3b, v35
	v_exp_f32_e32 v133, v133
	s_nop 0
	v_add_f32_e32 v133, 1.0, v133
	v_rcp_f32_e32 v133, v133
	s_nop 0
	v_mul_f32_e32 v133, v35, v133
	v_cvt_pk_bf16_f32 v132, v132, v133
	v_mul_f32_e32 v133, 0xbfb8aa3b, v36
	v_exp_f32_e32 v133, v133
	s_nop 0
	v_add_f32_e32 v133, 1.0, v133
	v_rcp_f32_e32 v133, v133
	s_nop 0
	v_mul_f32_e32 v133, v36, v133
	v_mul_f32_e32 v138, 0xbfb8aa3b, v37
	v_exp_f32_e32 v138, v138
	s_nop 0
	v_add_f32_e32 v138, 1.0, v138
	v_rcp_f32_e32 v138, v138
	s_nop 0
	v_mul_f32_e32 v138, v37, v138
	v_cvt_pk_bf16_f32 v133, v133, v138
	global_store_dwordx4 v[136:137], v[130:133], off offset:256
	v_lshl_add_u64 v[136:137], v[134:135], 0, s[62:63]
	s_nop 0
	v_mul_f32_e32 v130, 0xbfb8aa3b, v30
	v_exp_f32_e32 v130, v130
	s_nop 0
	v_add_f32_e32 v130, 1.0, v130
	v_rcp_f32_e32 v130, v130
	s_nop 0
	v_mul_f32_e32 v130, v30, v130
	v_mul_f32_e32 v131, 0xbfb8aa3b, v31
	v_exp_f32_e32 v131, v131
	s_nop 0
	v_add_f32_e32 v131, 1.0, v131
	v_rcp_f32_e32 v131, v131
	s_nop 0
	v_mul_f32_e32 v131, v31, v131
	v_cvt_pk_bf16_f32 v130, v130, v131
	v_mul_f32_e32 v131, 0xbfb8aa3b, v32
	v_exp_f32_e32 v131, v131
	s_nop 0
	v_add_f32_e32 v131, 1.0, v131
	v_rcp_f32_e32 v131, v131
	s_nop 0
	v_mul_f32_e32 v131, v32, v131
	v_mul_f32_e32 v132, 0xbfb8aa3b, v33
	v_exp_f32_e32 v132, v132
	s_nop 0
	v_add_f32_e32 v132, 1.0, v132
	v_rcp_f32_e32 v132, v132
	s_nop 0
	v_mul_f32_e32 v132, v33, v132
	v_cvt_pk_bf16_f32 v131, v131, v132
	v_mul_f32_e32 v132, 0xbfb8aa3b, v26
	v_exp_f32_e32 v132, v132
	s_nop 0
	v_add_f32_e32 v132, 1.0, v132
	v_rcp_f32_e32 v132, v132
	s_nop 0
	v_mul_f32_e32 v132, v26, v132
	v_mul_f32_e32 v133, 0xbfb8aa3b, v27
	v_exp_f32_e32 v133, v133
	s_nop 0
	v_add_f32_e32 v133, 1.0, v133
	v_rcp_f32_e32 v133, v133
	s_nop 0
	v_mul_f32_e32 v133, v27, v133
	v_cvt_pk_bf16_f32 v132, v132, v133
	v_mul_f32_e32 v133, 0xbfb8aa3b, v28
	v_exp_f32_e32 v133, v133
	s_nop 0
	v_add_f32_e32 v133, 1.0, v133
	v_rcp_f32_e32 v133, v133
	s_nop 0
	v_mul_f32_e32 v133, v28, v133
	v_mul_f32_e32 v138, 0xbfb8aa3b, v29
	v_exp_f32_e32 v138, v138
	s_nop 0
	v_add_f32_e32 v138, 1.0, v138
	v_rcp_f32_e32 v138, v138
	s_nop 0
	v_mul_f32_e32 v138, v29, v138
	v_cvt_pk_bf16_f32 v133, v133, v138
	v_add_co_u32_e32 v138, vcc, s48, v134
	s_nop 1
	v_addc_co_u32_e32 v139, vcc, 0, v135, vcc
	global_store_dwordx4 v[138:139], v[130:133], off
	s_nop 1
	v_mul_f32_e32 v130, 0xbfb8aa3b, v22
	v_exp_f32_e32 v130, v130
	s_nop 0
	v_add_f32_e32 v130, 1.0, v130
; __device__ __forceinline__ float siluf_(float x) { return x / (1.0f + __expf(-x)); }
; template <int ACT> __device__ __forceinline__ void store_tile_bf16(AccRef acc, bf16_t* dst, int ld, int row0, int col0) {
; #pragma unroll
;     for (int ai = 0; ai < 2; ++ai)
; #pragma unroll
;         for (int m = 0; m < 4; ++m) { bf16_t* rowp = dst + (size_t)(row0 + ai * 128 + m * 16) * ld + col0;
; #pragma unroll
;             for (int bj = 0; bj < 2; ++bj) { const f32x4 v0 = acc[ai][bj][m][0], v1 = acc[ai][bj][m][1];
;                 u32x4 w; w.x = cvt_pk_bf16(actf<ACT>(v0[0]), actf<ACT>(v0[1])); w.y = cvt_pk_bf16(actf<ACT>(v0[2]), actf<ACT>(v0[3]));
;                 w.z = cvt_pk_bf16(actf<ACT>(v1[0]), actf<ACT>(v1[1])); w.w = cvt_pk_bf16(actf<ACT>(v1[2]), actf<ACT>(v1[3]));
;                 *(u32x4*)(rowp + bj * 128) = w; } }
	v_rcp_f32_e32 v130, v130
	s_nop 0
	v_mul_f32_e32 v130, v22, v130
	v_mul_f32_e32 v131, 0xbfb8aa3b, v23
	v_exp_f32_e32 v131, v131
	s_nop 0
	v_add_f32_e32 v131, 1.0, v131
	v_rcp_f32_e32 v131, v131
	s_nop 0
	v_mul_f32_e32 v131, v23, v131
	v_cvt_pk_bf16_f32 v130, v130, v131
	v_mul_f32_e32 v131, 0xbfb8aa3b, v24
	v_exp_f32_e32 v131, v131
	s_nop 0
	v_add_f32_e32 v131, 1.0, v131
	v_rcp_f32_e32 v131, v131
	s_nop 0
	v_mul_f32_e32 v131, v24, v131
	v_mul_f32_e32 v132, 0xbfb8aa3b, v25
	v_exp_f32_e32 v132, v132
	s_nop 0
	v_add_f32_e32 v132, 1.0, v132
	v_rcp_f32_e32 v132, v132
	s_nop 0
	v_mul_f32_e32 v132, v25, v132
	v_cvt_pk_bf16_f32 v131, v131, v132
	v_mul_f32_e32 v132, 0xbfb8aa3b, v18
	v_exp_f32_e32 v132, v132
	s_nop 0
	v_add_f32_e32 v132, 1.0, v132
	v_rcp_f32_e32 v132, v132
	s_nop 0
	v_mul_f32_e32 v132, v18, v132
	v_mul_f32_e32 v133, 0xbfb8aa3b, v19
	v_exp_f32_e32 v133, v133
	s_nop 0
	v_add_f32_e32 v133, 1.0, v133
	v_rcp_f32_e32 v133, v133
	s_nop 0
	v_mul_f32_e32 v133, v19, v133
	v_cvt_pk_bf16_f32 v132, v132, v133
	v_mul_f32_e32 v133, 0xbfb8aa3b, v20
	v_exp_f32_e32 v133, v133
	s_nop 0
	v_add_f32_e32 v133, 1.0, v133
	v_rcp_f32_e32 v133, v133
	s_nop 0
	v_mul_f32_e32 v133, v20, v133
	v_mul_f32_e32 v138, 0xbfb8aa3b, v21
	v_exp_f32_e32 v138, v138
	s_nop 0
	v_add_f32_e32 v138, 1.0, v138
	v_rcp_f32_e32 v138, v138
	s_nop 0
	v_mul_f32_e32 v138, v21, v138
	v_cvt_pk_bf16_f32 v133, v133, v138
	global_store_dwordx4 v[136:137], v[130:133], off offset:256
	v_lshl_add_u64 v[136:137], v[134:135], 0, s[64:65]
	s_nop 0
	v_mul_f32_e32 v130, 0xbfb8aa3b, v14
	v_exp_f32_e32 v130, v130
	s_nop 0
	v_add_f32_e32 v130, 1.0, v130
	v_rcp_f32_e32 v130, v130
	s_nop 0
	v_mul_f32_e32 v130, v14, v130
	v_mul_f32_e32 v131, 0xbfb8aa3b, v15
	v_exp_f32_e32 v131, v131
	s_nop 0
	v_add_f32_e32 v131, 1.0, v131
	v_rcp_f32_e32 v131, v131
	s_nop 0
	v_mul_f32_e32 v131, v15, v131
	v_cvt_pk_bf16_f32 v130, v130, v131
	v_mul_f32_e32 v131, 0xbfb8aa3b, v16
	v_exp_f32_e32 v131, v131
	s_nop 0
	v_add_f32_e32 v131, 1.0, v131
	v_rcp_f32_e32 v131, v131
	s_nop 0
	v_mul_f32_e32 v131, v16, v131
	v_mul_f32_e32 v132, 0xbfb8aa3b, v17
	v_exp_f32_e32 v132, v132
	s_nop 0
	v_add_f32_e32 v132, 1.0, v132
	v_rcp_f32_e32 v132, v132
	s_nop 0
	v_mul_f32_e32 v132, v17, v132
	v_cvt_pk_bf16_f32 v131, v131, v132
	v_mul_f32_e32 v132, 0xbfb8aa3b, v10
	v_exp_f32_e32 v132, v132
	s_nop 0
	v_add_f32_e32 v132, 1.0, v132
	v_rcp_f32_e32 v132, v132
	s_nop 0
	v_mul_f32_e32 v132, v10, v132
	v_mul_f32_e32 v133, 0xbfb8aa3b, v11
	v_exp_f32_e32 v133, v133
	s_nop 0
	v_add_f32_e32 v133, 1.0, v133
	v_rcp_f32_e32 v133, v133
	s_nop 0
	v_mul_f32_e32 v133, v11, v133
	v_cvt_pk_bf16_f32 v132, v132, v133
	v_mul_f32_e32 v133, 0xbfb8aa3b, v12
	v_exp_f32_e32 v133, v133
	s_nop 0
	v_add_f32_e32 v133, 1.0, v133
	v_rcp_f32_e32 v133, v133
	s_nop 0
	v_mul_f32_e32 v133, v12, v133
	v_mul_f32_e32 v138, 0xbfb8aa3b, v13
	v_exp_f32_e32 v138, v138
	s_nop 0
	v_add_f32_e32 v138, 1.0, v138
	v_rcp_f32_e32 v138, v138
	s_nop 0
	v_mul_f32_e32 v138, v13, v138
	v_add_co_u32_e32 v134, vcc, s49, v134
	v_cvt_pk_bf16_f32 v133, v133, v138
	s_nop 0
	v_addc_co_u32_e32 v135, vcc, 0, v135, vcc
	global_store_dwordx4 v[134:135], v[130:133], off
	s_nop 1
	v_mul_f32_e32 v130, 0xbfb8aa3b, v6
	v_exp_f32_e32 v130, v130
	s_nop 0
	v_add_f32_e32 v130, 1.0, v130
	v_rcp_f32_e32 v130, v130
	s_nop 0
	v_mul_f32_e32 v130, v6, v130
	v_mul_f32_e32 v131, 0xbfb8aa3b, v7
	v_exp_f32_e32 v131, v131
	s_nop 0
	v_add_f32_e32 v131, 1.0, v131
	v_rcp_f32_e32 v131, v131
	s_nop 0
	v_mul_f32_e32 v131, v7, v131
	v_cvt_pk_bf16_f32 v130, v130, v131
	v_mul_f32_e32 v131, 0xbfb8aa3b, v8
	v_exp_f32_e32 v131, v131
	s_nop 0
	v_add_f32_e32 v131, 1.0, v131
	v_rcp_f32_e32 v131, v131
	s_nop 0
	v_mul_f32_e32 v131, v8, v131
	v_mul_f32_e32 v132, 0xbfb8aa3b, v9
	v_exp_f32_e32 v132, v132
	s_nop 0
	v_add_f32_e32 v132, 1.0, v132
	v_rcp_f32_e32 v132, v132
	s_nop 0
	v_mul_f32_e32 v132, v9, v132
	v_cvt_pk_bf16_f32 v131, v131, v132
	v_mul_f32_e32 v132, 0xbfb8aa3b, v2
	v_exp_f32_e32 v132, v132
	s_nop 0
	v_add_f32_e32 v132, 1.0, v132
	v_rcp_f32_e32 v132, v132
	s_nop 0
	v_mul_f32_e32 v132, v2, v132
	v_mul_f32_e32 v133, 0xbfb8aa3b, v3
	v_exp_f32_e32 v133, v133
	s_nop 0
	v_add_f32_e32 v133, 1.0, v133
	v_rcp_f32_e32 v133, v133
	s_nop 0
	v_mul_f32_e32 v133, v3, v133
	v_cvt_pk_bf16_f32 v132, v132, v133
	v_mul_f32_e32 v133, 0xbfb8aa3b, v4
	v_exp_f32_e32 v133, v133
	s_nop 0
	v_add_f32_e32 v133, 1.0, v133
	v_rcp_f32_e32 v133, v133
	s_nop 0
	v_mul_f32_e32 v133, v4, v133
	v_mul_f32_e32 v134, 0xbfb8aa3b, v5
	v_exp_f32_e32 v134, v134
	s_nop 0
	v_add_f32_e32 v134, 1.0, v134
	v_rcp_f32_e32 v134, v134
	s_nop 0
	v_mul_f32_e32 v134, v5, v134
	v_cvt_pk_bf16_f32 v133, v133, v134
	global_store_dwordx4 v[136:137], v[130:133], off offset:256

; template <int ACT> __device__ __forceinline__ void store_tile_bf16(AccRef acc, bf16_t* dst, int ld, int row0, int col0) {
; #pragma unroll
;     for (int ai = 0; ai < 2; ++ai)
; #pragma unroll
;         for (int m = 0; m < 4; ++m) { bf16_t* rowp = dst + (size_t)(row0 + ai * 128 + m * 16) * ld + col0;
; #pragma unroll
;             for (int bj = 0; bj < 2; ++bj) { const f32x4 v0 = acc[ai][bj][m][0], v1 = acc[ai][bj][m][1];
;                 u32x4 w; w.x = cvt_pk_bf16(actf<ACT>(v0[0]), actf<ACT>(v0[1])); w.y = cvt_pk_bf16(actf<ACT>(v0[2]), actf<ACT>(v0[3]));
;                 w.z = cvt_pk_bf16(actf<ACT>(v1[0]), actf<ACT>(v1[1])); w.w = cvt_pk_bf16(actf<ACT>(v1[2]), actf<ACT>(v1[3]));
;                 *(u32x4*)(rowp + bj * 128) = w; } }
.LBB0_2492:
	s_andn2_b64 vcc, exec, s[0:1]
	s_cbranch_vccnz .LBB0_2477
	v_mul_f32_e32 v134, 0xbfb8aa3b, v126
	v_exp_f32_e32 v134, v134
	v_lshl_add_u32 v206, s88, 8, v232
	v_ashrrev_i32_e32 v219, 31, v218
	v_lshl_add_u64 v[132:133], v[206:207], 1, s[52:53]
	v_add_f32_e32 v134, 1.0, v134
	v_lshlrev_b64 v[130:131], 13, v[218:219]
	v_lshl_add_u64 v[130:131], v[132:133], 0, v[130:131]
	v_rcp_f32_e32 v135, v134
	s_nop 0
	v_mul_f32_e32 v126, v126, v135
	v_mul_f32_e32 v134, 0xbfb8aa3b, v127
	v_exp_f32_e32 v134, v134
	s_nop 0
	v_add_f32_e32 v134, 1.0, v134
	v_rcp_f32_e32 v135, v134
	s_nop 0
	v_mul_f32_e32 v127, v127, v135
	v_cvt_pk_bf16_f32 v126, v126, v127
	v_mul_f32_e32 v127, 0xbfb8aa3b, v128
	v_exp_f32_e32 v127, v127
	s_nop 0
	v_add_f32_e32 v127, 1.0, v127
	v_rcp_f32_e32 v127, v127
	s_nop 0
	v_mul_f32_e32 v127, v128, v127
	v_mul_f32_e32 v128, 0xbfb8aa3b, v129
	v_exp_f32_e32 v128, v128
	s_nop 0
	v_add_f32_e32 v128, 1.0, v128
	v_rcp_f32_e32 v128, v128
	s_nop 0
	v_mul_f32_e32 v128, v129, v128
	v_cvt_pk_bf16_f32 v127, v127, v128
	v_mul_f32_e32 v128, 0xbfb8aa3b, v122
	v_exp_f32_e32 v128, v128
	s_nop 0
	v_add_f32_e32 v128, 1.0, v128
	v_rcp_f32_e32 v129, v128
	s_nop 0
	v_mul_f32_e32 v122, v122, v129
	v_mul_f32_e32 v128, 0xbfb8aa3b, v123
	v_exp_f32_e32 v128, v128
	s_nop 0
	v_add_f32_e32 v128, 1.0, v128
	v_rcp_f32_e32 v129, v128
	s_nop 0
	v_mul_f32_e32 v123, v123, v129
	v_cvt_pk_bf16_f32 v128, v122, v123
	v_mul_f32_e32 v122, 0xbfb8aa3b, v124
	v_exp_f32_e32 v122, v122
	s_nop 0
	v_add_f32_e32 v122, 1.0, v122
	v_rcp_f32_e32 v122, v122
	s_nop 0
	v_mul_f32_e32 v122, v124, v122
	v_mul_f32_e32 v123, 0xbfb8aa3b, v125
	v_exp_f32_e32 v123, v123
	s_nop 0
	v_add_f32_e32 v123, 1.0, v123
	v_rcp_f32_e32 v123, v123
	s_nop 0
	v_mul_f32_e32 v123, v125, v123
	v_cvt_pk_bf16_f32 v129, v122, v123
	v_mul_f32_e32 v122, 0xbfb8aa3b, v118
	v_exp_f32_e32 v122, v122
	global_store_dwordx4 v[130:131], v[126:129], off
	v_add_f32_e32 v122, 1.0, v122
	v_rcp_f32_e32 v123, v122
	s_nop 0
	v_mul_f32_e32 v118, v118, v123
	v_mul_f32_e32 v122, 0xbfb8aa3b, v119
	v_exp_f32_e32 v122, v122
	s_nop 0
	v_add_f32_e32 v122, 1.0, v122
	v_rcp_f32_e32 v123, v122
	s_nop 0
	v_mul_f32_e32 v119, v119, v123
	v_cvt_pk_bf16_f32 v118, v118, v119
	v_mul_f32_e32 v119, 0xbfb8aa3b, v120
	v_exp_f32_e32 v119, v119
	s_nop 0
	v_add_f32_e32 v119, 1.0, v119
	v_rcp_f32_e32 v119, v119
	s_nop 0
	v_mul_f32_e32 v119, v120, v119
	v_mul_f32_e32 v120, 0xbfb8aa3b, v121
	v_exp_f32_e32 v120, v120
	s_nop 0
	v_add_f32_e32 v120, 1.0, v120
	v_rcp_f32_e32 v120, v120
	s_nop 0
	v_mul_f32_e32 v120, v121, v120
	v_cvt_pk_bf16_f32 v119, v119, v120
	v_mul_f32_e32 v120, 0xbfb8aa3b, v114
	v_exp_f32_e32 v120, v120
	s_nop 0
	v_add_f32_e32 v120, 1.0, v120
	v_rcp_f32_e32 v121, v120
	s_nop 0
	v_mul_f32_e32 v114, v114, v121
	v_mul_f32_e32 v120, 0xbfb8aa3b, v115
	v_exp_f32_e32 v120, v120
	s_nop 0
	v_add_f32_e32 v120, 1.0, v120
	v_rcp_f32_e32 v121, v120
	s_nop 0
	v_mul_f32_e32 v115, v115, v121
	v_cvt_pk_bf16_f32 v120, v114, v115
	v_mul_f32_e32 v114, 0xbfb8aa3b, v116
	v_exp_f32_e32 v114, v114
	s_nop 0
	v_add_f32_e32 v114, 1.0, v114
	v_rcp_f32_e32 v114, v114
	s_nop 0
	v_mul_f32_e32 v114, v116, v114
	v_mul_f32_e32 v115, 0xbfb8aa3b, v117
	v_exp_f32_e32 v115, v115
	s_nop 0
	v_add_f32_e32 v115, 1.0, v115
	v_rcp_f32_e32 v115, v115
	s_nop 0
	v_mul_f32_e32 v115, v117, v115
	v_mul_f32_e32 v116, 0xbfb8aa3b, v110
	v_exp_f32_e32 v116, v116
	v_cvt_pk_bf16_f32 v121, v114, v115
	global_store_dwordx4 v[130:131], v[118:121], off offset:256
	v_or_b32_e32 v114, 16, v218
	v_add_f32_e32 v116, 1.0, v116
	v_ashrrev_i32_e32 v115, 31, v114
	v_lshlrev_b64 v[114:115], 13, v[114:115]
	v_lshl_add_u64 v[114:115], v[132:133], 0, v[114:115]
	v_rcp_f32_e32 v117, v116
	s_nop 0
	v_mul_f32_e32 v110, v110, v117
	v_mul_f32_e32 v116, 0xbfb8aa3b, v111
	v_exp_f32_e32 v116, v116
	s_nop 0
	v_add_f32_e32 v116, 1.0, v116
	v_rcp_f32_e32 v117, v116
	s_nop 0
	v_mul_f32_e32 v111, v111, v117
	v_cvt_pk_bf16_f32 v110, v110, v111
	v_mul_f32_e32 v111, 0xbfb8aa3b, v112
	v_exp_f32_e32 v111, v111
	s_nop 0
	v_add_f32_e32 v111, 1.0, v111
	v_rcp_f32_e32 v111, v111
	s_nop 0
	v_mul_f32_e32 v111, v112, v111
	v_mul_f32_e32 v112, 0xbfb8aa3b, v113
	v_exp_f32_e32 v112, v112
	s_nop 0
	v_add_f32_e32 v112, 1.0, v112
	v_rcp_f32_e32 v112, v112
	s_nop 0
	v_mul_f32_e32 v112, v113, v112
	v_cvt_pk_bf16_f32 v111, v111, v112
	v_mul_f32_e32 v112, 0xbfb8aa3b, v106
	v_exp_f32_e32 v112, v112
	s_nop 0
	v_add_f32_e32 v112, 1.0, v112
	v_rcp_f32_e32 v113, v112
	s_nop 0
	v_mul_f32_e32 v106, v106, v113
	v_mul_f32_e32 v112, 0xbfb8aa3b, v107
	v_exp_f32_e32 v112, v112
	s_nop 0
	v_add_f32_e32 v112, 1.0, v112
	v_rcp_f32_e32 v113, v112
	s_nop 0
	v_mul_f32_e32 v107, v107, v113
	v_cvt_pk_bf16_f32 v112, v106, v107
	v_mul_f32_e32 v106, 0xbfb8aa3b, v108
	v_exp_f32_e32 v106, v106
	s_nop 0
	v_add_f32_e32 v106, 1.0, v106
	v_rcp_f32_e32 v106, v106
	s_nop 0
	v_mul_f32_e32 v106, v108, v106
	v_mul_f32_e32 v107, 0xbfb8aa3b, v109
	v_exp_f32_e32 v107, v107
	s_nop 0
	v_add_f32_e32 v107, 1.0, v107
	v_rcp_f32_e32 v107, v107
	s_nop 0
	v_mul_f32_e32 v107, v109, v107
	v_cvt_pk_bf16_f32 v113, v106, v107
	v_mul_f32_e32 v106, 0xbfb8aa3b, v102
	v_exp_f32_e32 v106, v106
	global_store_dwordx4 v[114:115], v[110:113], off
	v_add_f32_e32 v106, 1.0, v106
	v_rcp_f32_e32 v107, v106
	s_nop 0
	v_mul_f32_e32 v102, v102, v107
	v_mul_f32_e32 v106, 0xbfb8aa3b, v103
	v_exp_f32_e32 v106, v106
	s_nop 0
	v_add_f32_e32 v106, 1.0, v106
	v_rcp_f32_e32 v107, v106
	s_nop 0
	v_mul_f32_e32 v103, v103, v107
	v_cvt_pk_bf16_f32 v102, v102, v103
	v_mul_f32_e32 v103, 0xbfb8aa3b, v104
	v_exp_f32_e32 v103, v103
	s_nop 0
	v_add_f32_e32 v103, 1.0, v103
	v_rcp_f32_e32 v103, v103
	s_nop 0
; __device__ __forceinline__ float siluf_(float x) { return x / (1.0f + __expf(-x)); }
; template <int ACT> __device__ __forceinline__ void store_tile_bf16(AccRef acc, bf16_t* dst, int ld, int row0, int col0) {
; #pragma unroll
;     for (int ai = 0; ai < 2; ++ai)
; #pragma unroll
;         for (int m = 0; m < 4; ++m) { bf16_t* rowp = dst + (size_t)(row0 + ai * 128 + m * 16) * ld + col0;
; #pragma unroll
;             for (int bj = 0; bj < 2; ++bj) { const f32x4 v0 = acc[ai][bj][m][0], v1 = acc[ai][bj][m][1];
;                 u32x4 w; w.x = cvt_pk_bf16(actf<ACT>(v0[0]), actf<ACT>(v0[1])); w.y = cvt_pk_bf16(actf<ACT>(v0[2]), actf<ACT>(v0[3]));
;                 w.z = cvt_pk_bf16(actf<ACT>(v1[0]), actf<ACT>(v1[1])); w.w = cvt_pk_bf16(actf<ACT>(v1[2]), actf<ACT>(v1[3]));
;                 *(u32x4*)(rowp + bj * 128) = w; } }
; }
	v_mul_f32_e32 v103, v104, v103
	v_mul_f32_e32 v104, 0xbfb8aa3b, v105
	v_exp_f32_e32 v104, v104
	s_nop 0
	v_add_f32_e32 v104, 1.0, v104
	v_rcp_f32_e32 v104, v104
	s_nop 0
	v_mul_f32_e32 v104, v105, v104
	v_cvt_pk_bf16_f32 v103, v103, v104
	v_mul_f32_e32 v104, 0xbfb8aa3b, v98
	v_exp_f32_e32 v104, v104
	s_nop 0
	v_add_f32_e32 v104, 1.0, v104
	v_rcp_f32_e32 v105, v104
	s_nop 0
	v_mul_f32_e32 v98, v98, v105
	v_mul_f32_e32 v104, 0xbfb8aa3b, v99
	v_exp_f32_e32 v104, v104
	s_nop 0
	v_add_f32_e32 v104, 1.0, v104
	v_rcp_f32_e32 v105, v104
	s_nop 0
	v_mul_f32_e32 v99, v99, v105
	v_cvt_pk_bf16_f32 v104, v98, v99
	v_mul_f32_e32 v98, 0xbfb8aa3b, v100
	v_exp_f32_e32 v98, v98
	s_nop 0
	v_add_f32_e32 v98, 1.0, v98
	v_rcp_f32_e32 v98, v98
	s_nop 0
	v_mul_f32_e32 v98, v100, v98
	v_mul_f32_e32 v99, 0xbfb8aa3b, v101
	v_exp_f32_e32 v99, v99
	s_nop 0
	v_add_f32_e32 v99, 1.0, v99
	v_rcp_f32_e32 v99, v99
	s_nop 0
	v_mul_f32_e32 v99, v101, v99
	v_mul_f32_e32 v100, 0xbfb8aa3b, v94
	v_exp_f32_e32 v100, v100
	v_cvt_pk_bf16_f32 v105, v98, v99
	global_store_dwordx4 v[114:115], v[102:105], off offset:256
	v_or_b32_e32 v98, 32, v218
	v_add_f32_e32 v100, 1.0, v100
	v_ashrrev_i32_e32 v99, 31, v98
	v_lshlrev_b64 v[98:99], 13, v[98:99]
	v_lshl_add_u64 v[98:99], v[132:133], 0, v[98:99]
	v_rcp_f32_e32 v101, v100
	s_nop 0
	v_mul_f32_e32 v94, v94, v101
	v_mul_f32_e32 v100, 0xbfb8aa3b, v95
	v_exp_f32_e32 v100, v100
	s_nop 0
	v_add_f32_e32 v100, 1.0, v100
	v_rcp_f32_e32 v101, v100
	s_nop 0
	v_mul_f32_e32 v95, v95, v101
	v_cvt_pk_bf16_f32 v94, v94, v95
	v_mul_f32_e32 v95, 0xbfb8aa3b, v96
	v_exp_f32_e32 v95, v95
	s_nop 0
	v_add_f32_e32 v95, 1.0, v95
	v_rcp_f32_e32 v95, v95
	s_nop 0
	v_mul_f32_e32 v95, v96, v95
	v_mul_f32_e32 v96, 0xbfb8aa3b, v97
	v_exp_f32_e32 v96, v96
	s_nop 0
	v_add_f32_e32 v96, 1.0, v96
	v_rcp_f32_e32 v96, v96
	s_nop 0
	v_mul_f32_e32 v96, v97, v96
	v_cvt_pk_bf16_f32 v95, v95, v96
	v_mul_f32_e32 v96, 0xbfb8aa3b, v90
	v_exp_f32_e32 v96, v96
	s_nop 0
	v_add_f32_e32 v96, 1.0, v96
	v_rcp_f32_e32 v97, v96
	s_nop 0
	v_mul_f32_e32 v90, v90, v97
	v_mul_f32_e32 v96, 0xbfb8aa3b, v91
	v_exp_f32_e32 v96, v96
	s_nop 0
	v_add_f32_e32 v96, 1.0, v96
	v_rcp_f32_e32 v97, v96
	s_nop 0
	v_mul_f32_e32 v91, v91, v97
	v_cvt_pk_bf16_f32 v96, v90, v91
	v_mul_f32_e32 v90, 0xbfb8aa3b, v92
	v_exp_f32_e32 v90, v90
	s_nop 0
	v_add_f32_e32 v90, 1.0, v90
	v_rcp_f32_e32 v90, v90
	s_nop 0
	v_mul_f32_e32 v90, v92, v90
	v_mul_f32_e32 v91, 0xbfb8aa3b, v93
	v_exp_f32_e32 v91, v91
	s_nop 0
	v_add_f32_e32 v91, 1.0, v91
	v_rcp_f32_e32 v91, v91
	s_nop 0
	v_mul_f32_e32 v91, v93, v91
	v_cvt_pk_bf16_f32 v97, v90, v91
	v_mul_f32_e32 v90, 0xbfb8aa3b, v86
	v_exp_f32_e32 v90, v90
	global_store_dwordx4 v[98:99], v[94:97], off
	v_add_f32_e32 v90, 1.0, v90
	v_rcp_f32_e32 v91, v90
	s_nop 0
	v_mul_f32_e32 v86, v86, v91
	v_mul_f32_e32 v90, 0xbfb8aa3b, v87
	v_exp_f32_e32 v90, v90
	s_nop 0
	v_add_f32_e32 v90, 1.0, v90
	v_rcp_f32_e32 v91, v90
	s_nop 0
	v_mul_f32_e32 v87, v87, v91
	v_cvt_pk_bf16_f32 v86, v86, v87
	v_mul_f32_e32 v87, 0xbfb8aa3b, v88
	v_exp_f32_e32 v87, v87
	s_nop 0
	v_add_f32_e32 v87, 1.0, v87
	v_rcp_f32_e32 v87, v87
	s_nop 0
	v_mul_f32_e32 v87, v88, v87
	v_mul_f32_e32 v88, 0xbfb8aa3b, v89
	v_exp_f32_e32 v88, v88
	s_nop 0
	v_add_f32_e32 v88, 1.0, v88
	v_rcp_f32_e32 v88, v88
	s_nop 0
	v_mul_f32_e32 v88, v89, v88
	v_cvt_pk_bf16_f32 v87, v87, v88
	v_mul_f32_e32 v88, 0xbfb8aa3b, v82
	v_exp_f32_e32 v88, v88
	s_nop 0
	v_add_f32_e32 v88, 1.0, v88
	v_rcp_f32_e32 v89, v88
	s_nop 0
	v_mul_f32_e32 v82, v82, v89
	v_mul_f32_e32 v88, 0xbfb8aa3b, v83
	v_exp_f32_e32 v88, v88
	s_nop 0
	v_add_f32_e32 v88, 1.0, v88
	v_rcp_f32_e32 v89, v88
	s_nop 0
	v_mul_f32_e32 v83, v83, v89
	v_cvt_pk_bf16_f32 v88, v82, v83
	v_mul_f32_e32 v82, 0xbfb8aa3b, v84
	v_exp_f32_e32 v82, v82
	s_nop 0
	v_add_f32_e32 v82, 1.0, v82
	v_rcp_f32_e32 v82, v82
	s_nop 0
	v_mul_f32_e32 v82, v84, v82
	v_mul_f32_e32 v83, 0xbfb8aa3b, v85
	v_exp_f32_e32 v83, v83
	s_nop 0
	v_add_f32_e32 v83, 1.0, v83
	v_rcp_f32_e32 v83, v83
	s_nop 0
	v_mul_f32_e32 v83, v85, v83
	v_mul_f32_e32 v84, 0xbfb8aa3b, v78
	v_exp_f32_e32 v84, v84
	v_cvt_pk_bf16_f32 v89, v82, v83
	global_store_dwordx4 v[98:99], v[86:89], off offset:256
	v_or_b32_e32 v82, 48, v218
	v_add_f32_e32 v84, 1.0, v84
	v_ashrrev_i32_e32 v83, 31, v82
	v_lshlrev_b64 v[82:83], 13, v[82:83]
	v_lshl_add_u64 v[82:83], v[132:133], 0, v[82:83]
	v_rcp_f32_e32 v85, v84
	s_nop 0
	v_mul_f32_e32 v78, v78, v85
	v_mul_f32_e32 v84, 0xbfb8aa3b, v79
	v_exp_f32_e32 v84, v84
	s_nop 0
	v_add_f32_e32 v84, 1.0, v84
	v_rcp_f32_e32 v85, v84
	s_nop 0
	v_mul_f32_e32 v79, v79, v85
	v_cvt_pk_bf16_f32 v78, v78, v79
	v_mul_f32_e32 v79, 0xbfb8aa3b, v80
	v_exp_f32_e32 v79, v79
	s_nop 0
	v_add_f32_e32 v79, 1.0, v79
	v_rcp_f32_e32 v79, v79
	s_nop 0
	v_mul_f32_e32 v79, v80, v79
	v_mul_f32_e32 v80, 0xbfb8aa3b, v81
	v_exp_f32_e32 v80, v80
	s_nop 0
	v_add_f32_e32 v80, 1.0, v80
	v_rcp_f32_e32 v80, v80
	s_nop 0
	v_mul_f32_e32 v80, v81, v80
	v_cvt_pk_bf16_f32 v79, v79, v80
	v_mul_f32_e32 v80, 0xbfb8aa3b, v74
	v_exp_f32_e32 v80, v80
	s_nop 0
	v_add_f32_e32 v80, 1.0, v80
	v_rcp_f32_e32 v81, v80
	s_nop 0
	v_mul_f32_e32 v74, v74, v81
	v_mul_f32_e32 v80, 0xbfb8aa3b, v75
	v_exp_f32_e32 v80, v80
	s_nop 0
	v_add_f32_e32 v80, 1.0, v80
	v_rcp_f32_e32 v81, v80
	s_nop 0
	v_mul_f32_e32 v75, v75, v81
	v_cvt_pk_bf16_f32 v80, v74, v75
	v_mul_f32_e32 v74, 0xbfb8aa3b, v76
	v_exp_f32_e32 v74, v74
	s_nop 0
	v_add_f32_e32 v74, 1.0, v74
	v_rcp_f32_e32 v74, v74
	s_nop 0
	v_mul_f32_e32 v74, v76, v74
	v_mul_f32_e32 v75, 0xbfb8aa3b, v77
	v_exp_f32_e32 v75, v75
	s_nop 0
	v_add_f32_e32 v75, 1.0, v75
	v_rcp_f32_e32 v75, v75
	s_nop 0
	v_mul_f32_e32 v75, v77, v75
	v_cvt_pk_bf16_f32 v81, v74, v75
; __device__ __forceinline__ float siluf_(float x) { return x / (1.0f + __expf(-x)); }
; template <int ACT> __device__ __forceinline__ void store_tile_bf16(AccRef acc, bf16_t* dst, int ld, int row0, int col0) {
; #pragma unroll
;     for (int ai = 0; ai < 2; ++ai)
; #pragma unroll
;         for (int m = 0; m < 4; ++m) { bf16_t* rowp = dst + (size_t)(row0 + ai * 128 + m * 16) * ld + col0;
; #pragma unroll
;             for (int bj = 0; bj < 2; ++bj) { const f32x4 v0 = acc[ai][bj][m][0], v1 = acc[ai][bj][m][1];
;                 u32x4 w; w.x = cvt_pk_bf16(actf<ACT>(v0[0]), actf<ACT>(v0[1])); w.y = cvt_pk_bf16(actf<ACT>(v0[2]), actf<ACT>(v0[3]));
;                 w.z = cvt_pk_bf16(actf<ACT>(v1[0]), actf<ACT>(v1[1])); w.w = cvt_pk_bf16(actf<ACT>(v1[2]), actf<ACT>(v1[3]));
;                 *(u32x4*)(rowp + bj * 128) = w; } }
; }
	v_mul_f32_e32 v74, 0xbfb8aa3b, v70
	v_exp_f32_e32 v74, v74
	global_store_dwordx4 v[82:83], v[78:81], off
	v_add_f32_e32 v74, 1.0, v74
	v_rcp_f32_e32 v75, v74
	s_nop 0
	v_mul_f32_e32 v70, v70, v75
	v_mul_f32_e32 v74, 0xbfb8aa3b, v71
	v_exp_f32_e32 v74, v74
	s_nop 0
	v_add_f32_e32 v74, 1.0, v74
	v_rcp_f32_e32 v75, v74
	s_nop 0
	v_mul_f32_e32 v71, v71, v75
	v_cvt_pk_bf16_f32 v70, v70, v71
	v_mul_f32_e32 v71, 0xbfb8aa3b, v72
	v_exp_f32_e32 v71, v71
	s_nop 0
	v_add_f32_e32 v71, 1.0, v71
	v_rcp_f32_e32 v71, v71
	s_nop 0
	v_mul_f32_e32 v71, v72, v71
	v_mul_f32_e32 v72, 0xbfb8aa3b, v73
	v_exp_f32_e32 v72, v72
	s_nop 0
	v_add_f32_e32 v72, 1.0, v72
	v_rcp_f32_e32 v72, v72
	s_nop 0
	v_mul_f32_e32 v72, v73, v72
	v_cvt_pk_bf16_f32 v71, v71, v72
	v_mul_f32_e32 v72, 0xbfb8aa3b, v66
	v_exp_f32_e32 v72, v72
	s_nop 0
	v_add_f32_e32 v72, 1.0, v72
	v_rcp_f32_e32 v73, v72
	s_nop 0
	v_mul_f32_e32 v66, v66, v73
	v_mul_f32_e32 v72, 0xbfb8aa3b, v67
	v_exp_f32_e32 v72, v72
	s_nop 0
	v_add_f32_e32 v72, 1.0, v72
	v_rcp_f32_e32 v73, v72
	s_nop 0
	v_mul_f32_e32 v67, v67, v73
	v_cvt_pk_bf16_f32 v72, v66, v67
	v_mul_f32_e32 v66, 0xbfb8aa3b, v68
	v_exp_f32_e32 v66, v66
	s_nop 0
	v_add_f32_e32 v66, 1.0, v66
	v_rcp_f32_e32 v66, v66
	s_nop 0
	v_mul_f32_e32 v66, v68, v66
	v_mul_f32_e32 v67, 0xbfb8aa3b, v69
	v_exp_f32_e32 v67, v67
	s_nop 0
	v_add_f32_e32 v67, 1.0, v67
	v_rcp_f32_e32 v67, v67
	s_nop 0
	v_mul_f32_e32 v67, v69, v67
	v_mul_f32_e32 v68, 0xbfb8aa3b, v62
	v_exp_f32_e32 v68, v68
	v_cvt_pk_bf16_f32 v73, v66, v67
	global_store_dwordx4 v[82:83], v[70:73], off offset:256
	v_lshl_add_u64 v[66:67], v[130:131], 0, s[58:59]
	v_add_f32_e32 v68, 1.0, v68
	v_rcp_f32_e32 v69, v68
	s_nop 0
	v_mul_f32_e32 v62, v62, v69
	v_mul_f32_e32 v68, 0xbfb8aa3b, v63
	v_exp_f32_e32 v68, v68
	s_nop 0
	v_add_f32_e32 v68, 1.0, v68
	v_rcp_f32_e32 v69, v68
	s_nop 0
	v_mul_f32_e32 v63, v63, v69
	v_cvt_pk_bf16_f32 v62, v62, v63
	v_mul_f32_e32 v63, 0xbfb8aa3b, v64
	v_exp_f32_e32 v63, v63
	s_nop 0
	v_add_f32_e32 v63, 1.0, v63
	v_rcp_f32_e32 v63, v63
	s_nop 0
	v_mul_f32_e32 v63, v64, v63
	v_mul_f32_e32 v64, 0xbfb8aa3b, v65
	v_exp_f32_e32 v64, v64
	s_nop 0
	v_add_f32_e32 v64, 1.0, v64
	v_rcp_f32_e32 v64, v64
	s_nop 0
	v_mul_f32_e32 v64, v65, v64
	v_cvt_pk_bf16_f32 v63, v63, v64
	v_mul_f32_e32 v64, 0xbfb8aa3b, v58
	v_exp_f32_e32 v64, v64
	s_nop 0
	v_add_f32_e32 v64, 1.0, v64
	v_rcp_f32_e32 v65, v64
	s_nop 0
	v_mul_f32_e32 v58, v58, v65
	v_mul_f32_e32 v64, 0xbfb8aa3b, v59
	v_exp_f32_e32 v64, v64
	s_nop 0
	v_add_f32_e32 v64, 1.0, v64
	v_rcp_f32_e32 v65, v64
	s_nop 0
	v_mul_f32_e32 v59, v59, v65
	v_cvt_pk_bf16_f32 v64, v58, v59
	v_mul_f32_e32 v58, 0xbfb8aa3b, v60
	v_exp_f32_e32 v58, v58
	s_nop 0
	v_add_f32_e32 v58, 1.0, v58
	v_rcp_f32_e32 v58, v58
	s_nop 0
	v_mul_f32_e32 v58, v60, v58
	v_mul_f32_e32 v59, 0xbfb8aa3b, v61
	v_exp_f32_e32 v59, v59
	s_nop 0
	v_add_f32_e32 v59, 1.0, v59
	v_rcp_f32_e32 v59, v59
	s_nop 0
	v_mul_f32_e32 v59, v61, v59
	v_cvt_pk_bf16_f32 v65, v58, v59
	v_add_co_u32_e32 v58, vcc, s97, v130
	s_nop 1
	v_addc_co_u32_e32 v59, vcc, 0, v131, vcc
	global_store_dwordx4 v[58:59], v[62:65], off
	v_mul_f32_e32 v58, 0xbfb8aa3b, v54
	v_exp_f32_e32 v58, v58
	s_nop 0
	v_add_f32_e32 v58, 1.0, v58
	v_rcp_f32_e32 v59, v58
	s_nop 0
	v_mul_f32_e32 v54, v54, v59
	v_mul_f32_e32 v58, 0xbfb8aa3b, v55
	v_exp_f32_e32 v58, v58
	s_nop 0
	v_add_f32_e32 v58, 1.0, v58
	v_rcp_f32_e32 v59, v58
	s_nop 0
	v_mul_f32_e32 v55, v55, v59
	v_cvt_pk_bf16_f32 v54, v54, v55
	v_mul_f32_e32 v55, 0xbfb8aa3b, v56
	v_exp_f32_e32 v55, v55
	s_nop 0
	v_add_f32_e32 v55, 1.0, v55
	v_rcp_f32_e32 v55, v55
	s_nop 0
	v_mul_f32_e32 v55, v56, v55
	v_mul_f32_e32 v56, 0xbfb8aa3b, v57
	v_exp_f32_e32 v56, v56
	s_nop 0
	v_add_f32_e32 v56, 1.0, v56
	v_rcp_f32_e32 v56, v56
	s_nop 0
	v_mul_f32_e32 v56, v57, v56
	v_cvt_pk_bf16_f32 v55, v55, v56
	v_mul_f32_e32 v56, 0xbfb8aa3b, v50
	v_exp_f32_e32 v56, v56
	s_nop 0
	v_add_f32_e32 v56, 1.0, v56
	v_rcp_f32_e32 v57, v56
	s_nop 0
	v_mul_f32_e32 v50, v50, v57
	v_mul_f32_e32 v56, 0xbfb8aa3b, v51
	v_exp_f32_e32 v56, v56
	s_nop 0
	v_add_f32_e32 v56, 1.0, v56
	v_rcp_f32_e32 v57, v56
	s_nop 0
	v_mul_f32_e32 v51, v51, v57
	v_cvt_pk_bf16_f32 v56, v50, v51
	v_mul_f32_e32 v50, 0xbfb8aa3b, v52
	v_exp_f32_e32 v50, v50
	s_nop 0
	v_add_f32_e32 v50, 1.0, v50
	v_rcp_f32_e32 v50, v50
	s_nop 0
	v_mul_f32_e32 v50, v52, v50
	v_mul_f32_e32 v51, 0xbfb8aa3b, v53
	v_exp_f32_e32 v51, v51
	s_nop 0
	v_add_f32_e32 v51, 1.0, v51
	v_rcp_f32_e32 v51, v51
	s_nop 0
	v_mul_f32_e32 v51, v53, v51
	v_mul_f32_e32 v52, 0xbfb8aa3b, v46
	v_exp_f32_e32 v52, v52
	v_cvt_pk_bf16_f32 v57, v50, v51
	global_store_dwordx4 v[66:67], v[54:57], off offset:256
	v_lshl_add_u64 v[50:51], v[130:131], 0, s[60:61]
	v_add_f32_e32 v52, 1.0, v52
	v_rcp_f32_e32 v53, v52
	s_nop 0
	v_mul_f32_e32 v46, v46, v53
	v_mul_f32_e32 v52, 0xbfb8aa3b, v47
	v_exp_f32_e32 v52, v52
	s_nop 0
	v_add_f32_e32 v52, 1.0, v52
	v_rcp_f32_e32 v53, v52
	s_nop 0
	v_mul_f32_e32 v47, v47, v53
	v_cvt_pk_bf16_f32 v46, v46, v47
	v_mul_f32_e32 v47, 0xbfb8aa3b, v48
	v_exp_f32_e32 v47, v47
	s_nop 0
	v_add_f32_e32 v47, 1.0, v47
	v_rcp_f32_e32 v47, v47
	s_nop 0
	v_mul_f32_e32 v47, v48, v47
	v_mul_f32_e32 v48, 0xbfb8aa3b, v49
	v_exp_f32_e32 v48, v48
	s_nop 0
	v_add_f32_e32 v48, 1.0, v48
	v_rcp_f32_e32 v48, v48
	s_nop 0
	v_mul_f32_e32 v48, v49, v48
	v_cvt_pk_bf16_f32 v47, v47, v48
	v_mul_f32_e32 v48, 0xbfb8aa3b, v42
	v_exp_f32_e32 v48, v48
	s_nop 0
	v_add_f32_e32 v48, 1.0, v48
	v_rcp_f32_e32 v49, v48
	s_nop 0
	v_mul_f32_e32 v42, v42, v49
	v_mul_f32_e32 v48, 0xbfb8aa3b, v43
	v_exp_f32_e32 v48, v48
	s_nop 0
	v_add_f32_e32 v48, 1.0, v48
	v_rcp_f32_e32 v49, v48
	s_nop 0
	v_mul_f32_e32 v43, v43, v49
; __device__ __forceinline__ float siluf_(float x) { return x / (1.0f + __expf(-x)); }
; template <int ACT> __device__ __forceinline__ void store_tile_bf16(AccRef acc, bf16_t* dst, int ld, int row0, int col0) {
; #pragma unroll
;     for (int ai = 0; ai < 2; ++ai)
; #pragma unroll
;         for (int m = 0; m < 4; ++m) { bf16_t* rowp = dst + (size_t)(row0 + ai * 128 + m * 16) * ld + col0;
; #pragma unroll
;             for (int bj = 0; bj < 2; ++bj) { const f32x4 v0 = acc[ai][bj][m][0], v1 = acc[ai][bj][m][1];
;                 u32x4 w; w.x = cvt_pk_bf16(actf<ACT>(v0[0]), actf<ACT>(v0[1])); w.y = cvt_pk_bf16(actf<ACT>(v0[2]), actf<ACT>(v0[3]));
;                 w.z = cvt_pk_bf16(actf<ACT>(v1[0]), actf<ACT>(v1[1])); w.w = cvt_pk_bf16(actf<ACT>(v1[2]), actf<ACT>(v1[3]));
;                 *(u32x4*)(rowp + bj * 128) = w; } }
; }
	v_cvt_pk_bf16_f32 v48, v42, v43
	v_mul_f32_e32 v42, 0xbfb8aa3b, v44
	v_exp_f32_e32 v42, v42
	s_nop 0
	v_add_f32_e32 v42, 1.0, v42
	v_rcp_f32_e32 v42, v42
	s_nop 0
	v_mul_f32_e32 v42, v44, v42
	v_mul_f32_e32 v43, 0xbfb8aa3b, v45
	v_exp_f32_e32 v43, v43
	s_nop 0
	v_add_f32_e32 v43, 1.0, v43
	v_rcp_f32_e32 v43, v43
	s_nop 0
	v_mul_f32_e32 v43, v45, v43
	v_cvt_pk_bf16_f32 v49, v42, v43
	v_add_co_u32_e32 v42, vcc, s76, v130
	s_nop 1
	v_addc_co_u32_e32 v43, vcc, 0, v131, vcc
	global_store_dwordx4 v[42:43], v[46:49], off
	v_mul_f32_e32 v42, 0xbfb8aa3b, v38
	v_exp_f32_e32 v42, v42
	s_nop 0
	v_add_f32_e32 v42, 1.0, v42
	v_rcp_f32_e32 v43, v42
	s_nop 0
	v_mul_f32_e32 v38, v38, v43
	v_mul_f32_e32 v42, 0xbfb8aa3b, v39
	v_exp_f32_e32 v42, v42
	s_nop 0
	v_add_f32_e32 v42, 1.0, v42
	v_rcp_f32_e32 v43, v42
	s_nop 0
	v_mul_f32_e32 v39, v39, v43
	v_cvt_pk_bf16_f32 v38, v38, v39
	v_mul_f32_e32 v39, 0xbfb8aa3b, v40
	v_exp_f32_e32 v39, v39
	s_nop 0
	v_add_f32_e32 v39, 1.0, v39
	v_rcp_f32_e32 v39, v39
	s_nop 0
	v_mul_f32_e32 v39, v40, v39
	v_mul_f32_e32 v40, 0xbfb8aa3b, v41
	v_exp_f32_e32 v40, v40
	s_nop 0
	v_add_f32_e32 v40, 1.0, v40
	v_rcp_f32_e32 v40, v40
	s_nop 0
	v_mul_f32_e32 v40, v41, v40
	v_cvt_pk_bf16_f32 v39, v39, v40
	v_mul_f32_e32 v40, 0xbfb8aa3b, v34
	v_exp_f32_e32 v40, v40
	s_nop 0
	v_add_f32_e32 v40, 1.0, v40
	v_rcp_f32_e32 v41, v40
	s_nop 0
	v_mul_f32_e32 v34, v34, v41
	v_mul_f32_e32 v40, 0xbfb8aa3b, v35
	v_exp_f32_e32 v40, v40
	s_nop 0
	v_add_f32_e32 v40, 1.0, v40
	v_rcp_f32_e32 v41, v40
	s_nop 0
	v_mul_f32_e32 v35, v35, v41
	v_cvt_pk_bf16_f32 v40, v34, v35
	v_mul_f32_e32 v34, 0xbfb8aa3b, v36
	v_exp_f32_e32 v34, v34
	s_nop 0
	v_add_f32_e32 v34, 1.0, v34
	v_rcp_f32_e32 v34, v34
	s_nop 0
	v_mul_f32_e32 v34, v36, v34
	v_mul_f32_e32 v35, 0xbfb8aa3b, v37
	v_exp_f32_e32 v35, v35
	s_nop 0
	v_add_f32_e32 v35, 1.0, v35
	v_rcp_f32_e32 v35, v35
	s_nop 0
	v_mul_f32_e32 v35, v37, v35
	v_mul_f32_e32 v36, 0xbfb8aa3b, v30
	v_exp_f32_e32 v36, v36
	v_cvt_pk_bf16_f32 v41, v34, v35
	global_store_dwordx4 v[50:51], v[38:41], off offset:256
	v_lshl_add_u64 v[34:35], v[130:131], 0, s[62:63]
	v_add_f32_e32 v36, 1.0, v36
	v_rcp_f32_e32 v37, v36
	s_nop 0
	v_mul_f32_e32 v30, v30, v37
	v_mul_f32_e32 v36, 0xbfb8aa3b, v31
	v_exp_f32_e32 v36, v36
	s_nop 0
	v_add_f32_e32 v36, 1.0, v36
	v_rcp_f32_e32 v37, v36
	s_nop 0
	v_mul_f32_e32 v31, v31, v37
	v_cvt_pk_bf16_f32 v30, v30, v31
	v_mul_f32_e32 v31, 0xbfb8aa3b, v32
	v_exp_f32_e32 v31, v31
	s_nop 0
	v_add_f32_e32 v31, 1.0, v31
	v_rcp_f32_e32 v31, v31
	s_nop 0
	v_mul_f32_e32 v31, v32, v31
	v_mul_f32_e32 v32, 0xbfb8aa3b, v33
	v_exp_f32_e32 v32, v32
	s_nop 0
	v_add_f32_e32 v32, 1.0, v32
	v_rcp_f32_e32 v32, v32
	s_nop 0
	v_mul_f32_e32 v32, v33, v32
	v_cvt_pk_bf16_f32 v31, v31, v32
	v_mul_f32_e32 v32, 0xbfb8aa3b, v26
	v_exp_f32_e32 v32, v32
	s_nop 0
	v_add_f32_e32 v32, 1.0, v32
	v_rcp_f32_e32 v33, v32
	s_nop 0
	v_mul_f32_e32 v26, v26, v33
	v_mul_f32_e32 v32, 0xbfb8aa3b, v27
	v_exp_f32_e32 v32, v32
	s_nop 0
	v_add_f32_e32 v32, 1.0, v32
	v_rcp_f32_e32 v33, v32
	s_nop 0
	v_mul_f32_e32 v27, v27, v33
	v_cvt_pk_bf16_f32 v32, v26, v27
	v_mul_f32_e32 v26, 0xbfb8aa3b, v28
	v_exp_f32_e32 v26, v26
	s_nop 0
	v_add_f32_e32 v26, 1.0, v26
	v_rcp_f32_e32 v26, v26
	s_nop 0
	v_mul_f32_e32 v26, v28, v26
	v_mul_f32_e32 v27, 0xbfb8aa3b, v29
	v_exp_f32_e32 v27, v27
	s_nop 0
	v_add_f32_e32 v27, 1.0, v27
	v_rcp_f32_e32 v27, v27
	s_nop 0
	v_mul_f32_e32 v27, v29, v27
	v_cvt_pk_bf16_f32 v33, v26, v27
	v_add_co_u32_e32 v26, vcc, s48, v130
	s_nop 1
	v_addc_co_u32_e32 v27, vcc, 0, v131, vcc
	global_store_dwordx4 v[26:27], v[30:33], off
	v_mul_f32_e32 v26, 0xbfb8aa3b, v22
	v_exp_f32_e32 v26, v26
	s_nop 0
	v_add_f32_e32 v26, 1.0, v26
	v_rcp_f32_e32 v27, v26
	s_nop 0
	v_mul_f32_e32 v22, v22, v27
	v_mul_f32_e32 v26, 0xbfb8aa3b, v23
	v_exp_f32_e32 v26, v26
	s_nop 0
	v_add_f32_e32 v26, 1.0, v26
	v_rcp_f32_e32 v27, v26
	s_nop 0
	v_mul_f32_e32 v23, v23, v27
	v_cvt_pk_bf16_f32 v22, v22, v23
	v_mul_f32_e32 v23, 0xbfb8aa3b, v24
	v_exp_f32_e32 v23, v23
	s_nop 0
	v_add_f32_e32 v23, 1.0, v23
; __device__ __forceinline__ float siluf_(float x) { return x / (1.0f + __expf(-x)); }
; template <int ACT> __device__ __forceinline__ void store_tile_bf16(AccRef acc, bf16_t* dst, int ld, int row0, int col0) {
; #pragma unroll
;     for (int ai = 0; ai < 2; ++ai)
; #pragma unroll
;         for (int m = 0; m < 4; ++m) { bf16_t* rowp = dst + (size_t)(row0 + ai * 128 + m * 16) * ld + col0;
; #pragma unroll
;             for (int bj = 0; bj < 2; ++bj) { const f32x4 v0 = acc[ai][bj][m][0], v1 = acc[ai][bj][m][1];
;                 u32x4 w; w.x = cvt_pk_bf16(actf<ACT>(v0[0]), actf<ACT>(v0[1])); w.y = cvt_pk_bf16(actf<ACT>(v0[2]), actf<ACT>(v0[3]));
;                 w.z = cvt_pk_bf16(actf<ACT>(v1[0]), actf<ACT>(v1[1])); w.w = cvt_pk_bf16(actf<ACT>(v1[2]), actf<ACT>(v1[3]));
;                 *(u32x4*)(rowp + bj * 128) = w; } }
; }
	v_rcp_f32_e32 v23, v23
	s_nop 0
	v_mul_f32_e32 v23, v24, v23
	v_mul_f32_e32 v24, 0xbfb8aa3b, v25
	v_exp_f32_e32 v24, v24
	s_nop 0
	v_add_f32_e32 v24, 1.0, v24
	v_rcp_f32_e32 v24, v24
	s_nop 0
	v_mul_f32_e32 v24, v25, v24
	v_cvt_pk_bf16_f32 v23, v23, v24
	v_mul_f32_e32 v24, 0xbfb8aa3b, v18
	v_exp_f32_e32 v24, v24
	s_nop 0
	v_add_f32_e32 v24, 1.0, v24
	v_rcp_f32_e32 v25, v24
	s_nop 0
	v_mul_f32_e32 v18, v18, v25
	v_mul_f32_e32 v24, 0xbfb8aa3b, v19
	v_exp_f32_e32 v24, v24
	s_nop 0
	v_add_f32_e32 v24, 1.0, v24
	v_rcp_f32_e32 v25, v24
	s_nop 0
	v_mul_f32_e32 v19, v19, v25
	v_cvt_pk_bf16_f32 v24, v18, v19
	v_mul_f32_e32 v18, 0xbfb8aa3b, v20
	v_exp_f32_e32 v18, v18
	s_nop 0
	v_add_f32_e32 v18, 1.0, v18
	v_rcp_f32_e32 v18, v18
	s_nop 0
	v_mul_f32_e32 v18, v20, v18
	v_mul_f32_e32 v19, 0xbfb8aa3b, v21
	v_exp_f32_e32 v19, v19
	s_nop 0
	v_add_f32_e32 v19, 1.0, v19
	v_rcp_f32_e32 v19, v19
	s_nop 0
	v_mul_f32_e32 v19, v21, v19
	v_mul_f32_e32 v20, 0xbfb8aa3b, v14
	v_exp_f32_e32 v20, v20
	v_cvt_pk_bf16_f32 v25, v18, v19
	global_store_dwordx4 v[34:35], v[22:25], off offset:256
	v_lshl_add_u64 v[18:19], v[130:131], 0, s[64:65]
	v_add_f32_e32 v20, 1.0, v20
	v_rcp_f32_e32 v21, v20
	s_nop 0
	v_mul_f32_e32 v14, v14, v21
	v_mul_f32_e32 v20, 0xbfb8aa3b, v15
	v_exp_f32_e32 v20, v20
	s_nop 0
	v_add_f32_e32 v20, 1.0, v20
	v_rcp_f32_e32 v21, v20
	s_nop 0
	v_mul_f32_e32 v15, v15, v21
	v_cvt_pk_bf16_f32 v14, v14, v15
	v_mul_f32_e32 v15, 0xbfb8aa3b, v16
	v_exp_f32_e32 v15, v15
	s_nop 0
	v_add_f32_e32 v15, 1.0, v15
	v_rcp_f32_e32 v15, v15
	s_nop 0
	v_mul_f32_e32 v15, v16, v15
	v_mul_f32_e32 v16, 0xbfb8aa3b, v17
	v_exp_f32_e32 v16, v16
	s_nop 0
	v_add_f32_e32 v16, 1.0, v16
	v_rcp_f32_e32 v16, v16
	s_nop 0
	v_mul_f32_e32 v16, v17, v16
	v_cvt_pk_bf16_f32 v15, v15, v16
	v_mul_f32_e32 v16, 0xbfb8aa3b, v10
	v_exp_f32_e32 v16, v16
	s_nop 0
	v_add_f32_e32 v16, 1.0, v16
	v_rcp_f32_e32 v17, v16
	s_nop 0
	v_mul_f32_e32 v10, v10, v17
	v_mul_f32_e32 v16, 0xbfb8aa3b, v11
	v_exp_f32_e32 v16, v16
	s_nop 0
	v_add_f32_e32 v16, 1.0, v16
	v_rcp_f32_e32 v17, v16
	s_nop 0
	v_mul_f32_e32 v11, v11, v17
	v_cvt_pk_bf16_f32 v16, v10, v11
	v_mul_f32_e32 v10, 0xbfb8aa3b, v12
	v_exp_f32_e32 v10, v10
	s_nop 0
	v_add_f32_e32 v10, 1.0, v10
	v_rcp_f32_e32 v10, v10
	s_nop 0
	v_mul_f32_e32 v10, v12, v10
	v_mul_f32_e32 v11, 0xbfb8aa3b, v13
	v_exp_f32_e32 v11, v11
	s_nop 0
	v_add_f32_e32 v11, 1.0, v11
	v_rcp_f32_e32 v11, v11
	s_nop 0
	v_mul_f32_e32 v11, v13, v11
	v_cvt_pk_bf16_f32 v17, v10, v11
	v_add_co_u32_e32 v10, vcc, s49, v130
	s_nop 1
	v_addc_co_u32_e32 v11, vcc, 0, v131, vcc
	global_store_dwordx4 v[10:11], v[14:17], off
	v_mul_f32_e32 v10, 0xbfb8aa3b, v6
	v_exp_f32_e32 v10, v10
	s_nop 0
	v_add_f32_e32 v10, 1.0, v10
	v_rcp_f32_e32 v11, v10
	s_nop 0
	v_mul_f32_e32 v6, v6, v11
	v_mul_f32_e32 v10, 0xbfb8aa3b, v7
	v_exp_f32_e32 v10, v10
	s_nop 0
	v_add_f32_e32 v10, 1.0, v10
	v_rcp_f32_e32 v11, v10
	s_nop 0
	v_mul_f32_e32 v7, v7, v11
	v_cvt_pk_bf16_f32 v6, v6, v7
	v_mul_f32_e32 v7, 0xbfb8aa3b, v8
	v_exp_f32_e32 v7, v7
	s_nop 0
	v_add_f32_e32 v7, 1.0, v7
	v_rcp_f32_e32 v7, v7
	s_nop 0
	v_mul_f32_e32 v7, v8, v7
	v_mul_f32_e32 v8, 0xbfb8aa3b, v9
	v_exp_f32_e32 v8, v8
	s_nop 0
	v_add_f32_e32 v8, 1.0, v8
	v_rcp_f32_e32 v8, v8
	s_nop 0
	v_mul_f32_e32 v8, v9, v8
	v_cvt_pk_bf16_f32 v7, v7, v8
	v_mul_f32_e32 v8, 0xbfb8aa3b, v2
	v_exp_f32_e32 v8, v8
	s_nop 0
	v_add_f32_e32 v8, 1.0, v8
	v_rcp_f32_e32 v9, v8
	s_nop 0
	v_mul_f32_e32 v2, v2, v9
	v_mul_f32_e32 v8, 0xbfb8aa3b, v3
	v_exp_f32_e32 v8, v8
	s_nop 0
	v_add_f32_e32 v8, 1.0, v8
	v_rcp_f32_e32 v9, v8
	s_nop 0
	v_mul_f32_e32 v3, v3, v9
	v_cvt_pk_bf16_f32 v8, v2, v3
	v_mul_f32_e32 v2, 0xbfb8aa3b, v4
	v_exp_f32_e32 v2, v2
	s_nop 0
	v_add_f32_e32 v2, 1.0, v2
	v_rcp_f32_e32 v2, v2
	s_nop 0
	v_mul_f32_e32 v2, v4, v2
	v_mul_f32_e32 v3, 0xbfb8aa3b, v5
	v_exp_f32_e32 v3, v3
	s_nop 0
	v_add_f32_e32 v3, 1.0, v3
	v_rcp_f32_e32 v3, v3
	s_nop 0
	v_mul_f32_e32 v3, v5, v3
	v_cvt_pk_bf16_f32 v9, v2, v3
	global_store_dwordx4 v[18:19], v[6:9], off offset:256
	s_branch .LBB0_2477

; template <int ACT> __device__ __forceinline__ void store_tile_bf16(AccRef acc, bf16_t* dst, int ld, int row0, int col0) {
; #pragma unroll
;     for (int ai = 0; ai < 2; ++ai)
; #pragma unroll
;         for (int m = 0; m < 4; ++m) { bf16_t* rowp = dst + (size_t)(row0 + ai * 128 + m * 16) * ld + col0;
; #pragma unroll
;             for (int bj = 0; bj < 2; ++bj) { const f32x4 v0 = acc[ai][bj][m][0], v1 = acc[ai][bj][m][1];
;                 u32x4 w; w.x = cvt_pk_bf16(actf<ACT>(v0[0]), actf<ACT>(v0[1])); w.y = cvt_pk_bf16(actf<ACT>(v0[2]), actf<ACT>(v0[3]));
;                 w.z = cvt_pk_bf16(actf<ACT>(v1[0]), actf<ACT>(v1[1])); w.w = cvt_pk_bf16(actf<ACT>(v1[2]), actf<ACT>(v1[3]));
;                 *(u32x4*)(rowp + bj * 128) = w; } }
; }
.LBB0_3290:
	s_andn2_b64 vcc, exec, s[0:1]
	s_cbranch_vccnz .LBB0_3283
	v_lshl_add_u64 v[130:131], s[42:43], 0, v[142:143]
	v_mul_f32_e32 v142, 0x3d372713, v126
	v_mul_f32_e32 v142, v126, v142
	v_fma_f32 v142, v126, v142, v126
	v_mul_f32_e32 v142, 0xbfcc422a, v142
	v_mul_f32_e32 v142, 0x3fb8aa3b, v142
	v_exp_f32_e32 v142, v142
	v_lshl_add_u64 v[132:133], v[130:131], 0, v[162:163]
	v_add_f32_e32 v142, 1.0, v142
	v_rcp_f32_e32 v160, v142
	s_nop 0
	v_mul_f32_e32 v126, v126, v160
	v_mul_f32_e32 v142, 0x3d372713, v127
	v_mul_f32_e32 v142, v127, v142
	v_fma_f32 v142, v127, v142, v127
	v_mul_f32_e32 v142, 0xbfcc422a, v142
	v_mul_f32_e32 v142, 0x3fb8aa3b, v142
	v_exp_f32_e32 v142, v142
	s_nop 0
	v_add_f32_e32 v142, 1.0, v142
	v_rcp_f32_e32 v160, v142
	s_nop 0
	v_mul_f32_e32 v127, v127, v160
	v_cvt_pk_bf16_f32 v126, v126, v127
	v_mul_f32_e32 v127, 0x3d372713, v128
	v_mul_f32_e32 v127, v128, v127
	v_fma_f32 v127, v128, v127, v128
	v_mul_f32_e32 v127, 0xbfcc422a, v127
	v_mul_f32_e32 v127, 0x3fb8aa3b, v127
	v_exp_f32_e32 v127, v127
	s_nop 0
	v_add_f32_e32 v127, 1.0, v127
	v_rcp_f32_e32 v127, v127
	s_nop 0
	v_mul_f32_e32 v127, v128, v127
	v_mul_f32_e32 v128, 0x3d372713, v129
	v_mul_f32_e32 v128, v129, v128
	v_fma_f32 v128, v129, v128, v129
	v_mul_f32_e32 v128, 0xbfcc422a, v128
	v_mul_f32_e32 v128, 0x3fb8aa3b, v128
	v_exp_f32_e32 v128, v128
	s_nop 0
	v_add_f32_e32 v128, 1.0, v128
	v_rcp_f32_e32 v128, v128
	s_nop 0
	v_mul_f32_e32 v128, v129, v128
	v_cvt_pk_bf16_f32 v127, v127, v128
	v_mul_f32_e32 v128, 0x3d372713, v122
	v_mul_f32_e32 v128, v122, v128
	v_fma_f32 v128, v122, v128, v122
	v_mul_f32_e32 v128, 0xbfcc422a, v128
	v_mul_f32_e32 v128, 0x3fb8aa3b, v128
	v_exp_f32_e32 v128, v128
	s_nop 0
	v_add_f32_e32 v128, 1.0, v128
	v_rcp_f32_e32 v129, v128
	s_nop 0
	v_mul_f32_e32 v122, v122, v129
	v_mul_f32_e32 v128, 0x3d372713, v123
	v_mul_f32_e32 v128, v123, v128
	v_fma_f32 v128, v123, v128, v123
	v_mul_f32_e32 v128, 0xbfcc422a, v128
	v_mul_f32_e32 v128, 0x3fb8aa3b, v128
	v_exp_f32_e32 v128, v128
	s_nop 0
	v_add_f32_e32 v128, 1.0, v128
	v_rcp_f32_e32 v129, v128
	s_nop 0
	v_mul_f32_e32 v123, v123, v129
	v_cvt_pk_bf16_f32 v128, v122, v123
	v_mul_f32_e32 v122, 0x3d372713, v124
	v_mul_f32_e32 v122, v124, v122
	v_fma_f32 v122, v124, v122, v124
	v_mul_f32_e32 v122, 0xbfcc422a, v122
	v_mul_f32_e32 v122, 0x3fb8aa3b, v122
	v_exp_f32_e32 v122, v122
	s_nop 0
	v_add_f32_e32 v122, 1.0, v122
	v_rcp_f32_e32 v122, v122
	s_nop 0
	v_mul_f32_e32 v122, v124, v122
	v_mul_f32_e32 v123, 0x3d372713, v125
	v_mul_f32_e32 v123, v125, v123
	v_fma_f32 v123, v125, v123, v125
	v_mul_f32_e32 v123, 0xbfcc422a, v123
	v_mul_f32_e32 v123, 0x3fb8aa3b, v123
	v_exp_f32_e32 v123, v123
	s_nop 0
	v_add_f32_e32 v123, 1.0, v123
	v_rcp_f32_e32 v123, v123
	s_nop 0
	v_mul_f32_e32 v123, v125, v123
	v_cvt_pk_bf16_f32 v129, v122, v123
	v_mul_f32_e32 v122, 0x3d372713, v118
	v_mul_f32_e32 v122, v118, v122
	v_fma_f32 v122, v118, v122, v118
	v_mul_f32_e32 v122, 0xbfcc422a, v122
	v_mul_f32_e32 v122, 0x3fb8aa3b, v122
	v_exp_f32_e32 v122, v122
	global_store_dwordx4 v[132:133], v[126:129], off
	v_add_f32_e32 v122, 1.0, v122
	v_rcp_f32_e32 v123, v122
	s_nop 0
	v_mul_f32_e32 v118, v118, v123
	v_mul_f32_e32 v122, 0x3d372713, v119
	v_mul_f32_e32 v122, v119, v122
	v_fma_f32 v122, v119, v122, v119
	v_mul_f32_e32 v122, 0xbfcc422a, v122
	v_mul_f32_e32 v122, 0x3fb8aa3b, v122
	v_exp_f32_e32 v122, v122
	s_nop 0
	v_add_f32_e32 v122, 1.0, v122
	v_rcp_f32_e32 v123, v122
	s_nop 0
	v_mul_f32_e32 v119, v119, v123
	v_cvt_pk_bf16_f32 v118, v118, v119
	v_mul_f32_e32 v119, 0x3d372713, v120
	v_mul_f32_e32 v119, v120, v119
	v_fma_f32 v119, v120, v119, v120
	v_mul_f32_e32 v119, 0xbfcc422a, v119
	v_mul_f32_e32 v119, 0x3fb8aa3b, v119
	v_exp_f32_e32 v119, v119
	s_nop 0
	v_add_f32_e32 v119, 1.0, v119
	v_rcp_f32_e32 v119, v119
	s_nop 0
	v_mul_f32_e32 v119, v120, v119
	v_mul_f32_e32 v120, 0x3d372713, v121
	v_mul_f32_e32 v120, v121, v120
	v_fma_f32 v120, v121, v120, v121
	v_mul_f32_e32 v120, 0xbfcc422a, v120
	v_mul_f32_e32 v120, 0x3fb8aa3b, v120
	v_exp_f32_e32 v120, v120
	s_nop 0
	v_add_f32_e32 v120, 1.0, v120
	v_rcp_f32_e32 v120, v120
	s_nop 0
	v_mul_f32_e32 v120, v121, v120
	v_cvt_pk_bf16_f32 v119, v119, v120
	v_mul_f32_e32 v120, 0x3d372713, v114
	v_mul_f32_e32 v120, v114, v120
	v_fma_f32 v120, v114, v120, v114
	v_mul_f32_e32 v120, 0xbfcc422a, v120
	v_mul_f32_e32 v120, 0x3fb8aa3b, v120
	v_exp_f32_e32 v120, v120
	s_nop 0
	v_add_f32_e32 v120, 1.0, v120
	v_rcp_f32_e32 v121, v120
	s_nop 0
	v_mul_f32_e32 v114, v114, v121
	v_mul_f32_e32 v120, 0x3d372713, v115
	v_mul_f32_e32 v120, v115, v120
	v_fma_f32 v120, v115, v120, v115
	v_mul_f32_e32 v120, 0xbfcc422a, v120
	v_mul_f32_e32 v120, 0x3fb8aa3b, v120
	v_exp_f32_e32 v120, v120
	s_nop 0
	v_add_f32_e32 v120, 1.0, v120
	v_rcp_f32_e32 v121, v120
	s_nop 0
	v_mul_f32_e32 v115, v115, v121
	v_cvt_pk_bf16_f32 v120, v114, v115
	v_mul_f32_e32 v114, 0x3d372713, v116
	v_mul_f32_e32 v114, v116, v114
	v_fma_f32 v114, v116, v114, v116
	v_mul_f32_e32 v114, 0xbfcc422a, v114
	v_mul_f32_e32 v114, 0x3fb8aa3b, v114
	v_exp_f32_e32 v114, v114
	s_nop 0
	v_add_f32_e32 v114, 1.0, v114
	v_rcp_f32_e32 v114, v114
	s_nop 0
	v_mul_f32_e32 v114, v116, v114
	v_mul_f32_e32 v115, 0x3d372713, v117
	v_mul_f32_e32 v115, v117, v115
	v_fma_f32 v115, v117, v115, v117
	v_mul_f32_e32 v115, 0xbfcc422a, v115
	v_mul_f32_e32 v115, 0x3fb8aa3b, v115
	v_exp_f32_e32 v115, v115
	s_nop 0
	v_add_f32_e32 v115, 1.0, v115
	v_rcp_f32_e32 v115, v115
	s_nop 0
	v_mul_f32_e32 v115, v117, v115
	v_mul_f32_e32 v116, 0x3d372713, v110
	v_mul_f32_e32 v116, v110, v116
	v_fma_f32 v116, v110, v116, v110
	v_mul_f32_e32 v116, 0xbfcc422a, v116
	v_mul_f32_e32 v116, 0x3fb8aa3b, v116
; template <int ACT> __device__ __forceinline__ void store_tile_bf16(AccRef acc, bf16_t* dst, int ld, int row0, int col0) {
; #pragma unroll
;     for (int ai = 0; ai < 2; ++ai)
; #pragma unroll
;         for (int m = 0; m < 4; ++m) { bf16_t* rowp = dst + (size_t)(row0 + ai * 128 + m * 16) * ld + col0;
; #pragma unroll
;             for (int bj = 0; bj < 2; ++bj) { const f32x4 v0 = acc[ai][bj][m][0], v1 = acc[ai][bj][m][1];
;                 u32x4 w; w.x = cvt_pk_bf16(actf<ACT>(v0[0]), actf<ACT>(v0[1])); w.y = cvt_pk_bf16(actf<ACT>(v0[2]), actf<ACT>(v0[3]));
;                 w.z = cvt_pk_bf16(actf<ACT>(v1[0]), actf<ACT>(v1[1])); w.w = cvt_pk_bf16(actf<ACT>(v1[2]), actf<ACT>(v1[3]));
;                 *(u32x4*)(rowp + bj * 128) = w; } }
; }
	v_exp_f32_e32 v116, v116
	v_cvt_pk_bf16_f32 v121, v114, v115
	global_store_dwordx4 v[132:133], v[118:121], off offset:256
	v_lshlrev_b64 v[114:115], 12, v[158:159]
	v_add_f32_e32 v116, 1.0, v116
	v_lshl_add_u64 v[114:115], v[130:131], 0, v[114:115]
	v_rcp_f32_e32 v117, v116
	s_nop 0
	v_mul_f32_e32 v110, v110, v117
	v_mul_f32_e32 v116, 0x3d372713, v111
	v_mul_f32_e32 v116, v111, v116
	v_fma_f32 v116, v111, v116, v111
	v_mul_f32_e32 v116, 0xbfcc422a, v116
	v_mul_f32_e32 v116, 0x3fb8aa3b, v116
	v_exp_f32_e32 v116, v116
	s_nop 0
	v_add_f32_e32 v116, 1.0, v116
	v_rcp_f32_e32 v117, v116
	s_nop 0
	v_mul_f32_e32 v111, v111, v117
	v_cvt_pk_bf16_f32 v110, v110, v111
	v_mul_f32_e32 v111, 0x3d372713, v112
	v_mul_f32_e32 v111, v112, v111
	v_fma_f32 v111, v112, v111, v112
	v_mul_f32_e32 v111, 0xbfcc422a, v111
	v_mul_f32_e32 v111, 0x3fb8aa3b, v111
	v_exp_f32_e32 v111, v111
	s_nop 0
	v_add_f32_e32 v111, 1.0, v111
	v_rcp_f32_e32 v111, v111
	s_nop 0
	v_mul_f32_e32 v111, v112, v111
	v_mul_f32_e32 v112, 0x3d372713, v113
	v_mul_f32_e32 v112, v113, v112
	v_fma_f32 v112, v113, v112, v113
	v_mul_f32_e32 v112, 0xbfcc422a, v112
	v_mul_f32_e32 v112, 0x3fb8aa3b, v112
	v_exp_f32_e32 v112, v112
	s_nop 0
	v_add_f32_e32 v112, 1.0, v112
	v_rcp_f32_e32 v112, v112
	s_nop 0
	v_mul_f32_e32 v112, v113, v112
	v_cvt_pk_bf16_f32 v111, v111, v112
	v_mul_f32_e32 v112, 0x3d372713, v106
	v_mul_f32_e32 v112, v106, v112
	v_fma_f32 v112, v106, v112, v106
	v_mul_f32_e32 v112, 0xbfcc422a, v112
	v_mul_f32_e32 v112, 0x3fb8aa3b, v112
	v_exp_f32_e32 v112, v112
	s_nop 0
	v_add_f32_e32 v112, 1.0, v112
	v_rcp_f32_e32 v113, v112
	s_nop 0
	v_mul_f32_e32 v106, v106, v113
	v_mul_f32_e32 v112, 0x3d372713, v107
	v_mul_f32_e32 v112, v107, v112
	v_fma_f32 v112, v107, v112, v107
	v_mul_f32_e32 v112, 0xbfcc422a, v112
	v_mul_f32_e32 v112, 0x3fb8aa3b, v112
	v_exp_f32_e32 v112, v112
	s_nop 0
	v_add_f32_e32 v112, 1.0, v112
	v_rcp_f32_e32 v113, v112
	s_nop 0
	v_mul_f32_e32 v107, v107, v113
	v_cvt_pk_bf16_f32 v112, v106, v107
	v_mul_f32_e32 v106, 0x3d372713, v108
	v_mul_f32_e32 v106, v108, v106
	v_fma_f32 v106, v108, v106, v108
	v_mul_f32_e32 v106, 0xbfcc422a, v106
	v_mul_f32_e32 v106, 0x3fb8aa3b, v106
	v_exp_f32_e32 v106, v106
	s_nop 0
	v_add_f32_e32 v106, 1.0, v106
	v_rcp_f32_e32 v106, v106
	s_nop 0
	v_mul_f32_e32 v106, v108, v106
	v_mul_f32_e32 v107, 0x3d372713, v109
	v_mul_f32_e32 v107, v109, v107
	v_fma_f32 v107, v109, v107, v109
	v_mul_f32_e32 v107, 0xbfcc422a, v107
	v_mul_f32_e32 v107, 0x3fb8aa3b, v107
	v_exp_f32_e32 v107, v107
	s_nop 0
	v_add_f32_e32 v107, 1.0, v107
	v_rcp_f32_e32 v107, v107
	s_nop 0
	v_mul_f32_e32 v107, v109, v107
	v_cvt_pk_bf16_f32 v113, v106, v107
	v_mul_f32_e32 v106, 0x3d372713, v102
	v_mul_f32_e32 v106, v102, v106
	v_fma_f32 v106, v102, v106, v102
	v_mul_f32_e32 v106, 0xbfcc422a, v106
	v_mul_f32_e32 v106, 0x3fb8aa3b, v106
	v_exp_f32_e32 v106, v106
	global_store_dwordx4 v[114:115], v[110:113], off
	v_add_f32_e32 v106, 1.0, v106
	v_rcp_f32_e32 v107, v106
	s_nop 0
	v_mul_f32_e32 v102, v102, v107
	v_mul_f32_e32 v106, 0x3d372713, v103
	v_mul_f32_e32 v106, v103, v106
	v_fma_f32 v106, v103, v106, v103
	v_mul_f32_e32 v106, 0xbfcc422a, v106
	v_mul_f32_e32 v106, 0x3fb8aa3b, v106
	v_exp_f32_e32 v106, v106
	s_nop 0
	v_add_f32_e32 v106, 1.0, v106
	v_rcp_f32_e32 v107, v106
	s_nop 0
	v_mul_f32_e32 v103, v103, v107
	v_cvt_pk_bf16_f32 v102, v102, v103
	v_mul_f32_e32 v103, 0x3d372713, v104
	v_mul_f32_e32 v103, v104, v103
	v_fma_f32 v103, v104, v103, v104
	v_mul_f32_e32 v103, 0xbfcc422a, v103
	v_mul_f32_e32 v103, 0x3fb8aa3b, v103
	v_exp_f32_e32 v103, v103
	s_nop 0
	v_add_f32_e32 v103, 1.0, v103
	v_rcp_f32_e32 v103, v103
	s_nop 0
	v_mul_f32_e32 v103, v104, v103
	v_mul_f32_e32 v104, 0x3d372713, v105
	v_mul_f32_e32 v104, v105, v104
	v_fma_f32 v104, v105, v104, v105
	v_mul_f32_e32 v104, 0xbfcc422a, v104
	v_mul_f32_e32 v104, 0x3fb8aa3b, v104
	v_exp_f32_e32 v104, v104
	s_nop 0
	v_add_f32_e32 v104, 1.0, v104
	v_rcp_f32_e32 v104, v104
	s_nop 0
	v_mul_f32_e32 v104, v105, v104
	v_cvt_pk_bf16_f32 v103, v103, v104
	v_mul_f32_e32 v104, 0x3d372713, v98
	v_mul_f32_e32 v104, v98, v104
	v_fma_f32 v104, v98, v104, v98
	v_mul_f32_e32 v104, 0xbfcc422a, v104
	v_mul_f32_e32 v104, 0x3fb8aa3b, v104
	v_exp_f32_e32 v104, v104
	s_nop 0
	v_add_f32_e32 v104, 1.0, v104
	v_rcp_f32_e32 v105, v104
	s_nop 0
	v_mul_f32_e32 v98, v98, v105
	v_mul_f32_e32 v104, 0x3d372713, v99
	v_mul_f32_e32 v104, v99, v104
	v_fma_f32 v104, v99, v104, v99
	v_mul_f32_e32 v104, 0xbfcc422a, v104
	v_mul_f32_e32 v104, 0x3fb8aa3b, v104
	v_exp_f32_e32 v104, v104
	s_nop 0
	v_add_f32_e32 v104, 1.0, v104
	v_rcp_f32_e32 v105, v104
	s_nop 0
	v_mul_f32_e32 v99, v99, v105
	v_cvt_pk_bf16_f32 v104, v98, v99
	v_mul_f32_e32 v98, 0x3d372713, v100
	v_mul_f32_e32 v98, v100, v98
	v_fma_f32 v98, v100, v98, v100
	v_mul_f32_e32 v98, 0xbfcc422a, v98
	v_mul_f32_e32 v98, 0x3fb8aa3b, v98
	v_exp_f32_e32 v98, v98
	s_nop 0
	v_add_f32_e32 v98, 1.0, v98
	v_rcp_f32_e32 v98, v98
	s_nop 0
	v_mul_f32_e32 v98, v100, v98
	v_mul_f32_e32 v99, 0x3d372713, v101
	v_mul_f32_e32 v99, v101, v99
	v_fma_f32 v99, v101, v99, v101
	v_mul_f32_e32 v99, 0xbfcc422a, v99
	v_mul_f32_e32 v99, 0x3fb8aa3b, v99
	v_exp_f32_e32 v99, v99
	s_nop 0
	v_add_f32_e32 v99, 1.0, v99
	v_rcp_f32_e32 v99, v99
	s_nop 0
	v_mul_f32_e32 v99, v101, v99
	v_mul_f32_e32 v100, 0x3d372713, v94
	v_mul_f32_e32 v100, v94, v100
	v_fma_f32 v100, v94, v100, v94
	v_mul_f32_e32 v100, 0xbfcc422a, v100
	v_mul_f32_e32 v100, 0x3fb8aa3b, v100
	v_exp_f32_e32 v100, v100
	v_cvt_pk_bf16_f32 v105, v98, v99
	global_store_dwordx4 v[114:115], v[102:105], off offset:256
	v_lshlrev_b64 v[98:99], 12, v[156:157]
	v_add_f32_e32 v100, 1.0, v100
; template <int ACT> __device__ __forceinline__ void store_tile_bf16(AccRef acc, bf16_t* dst, int ld, int row0, int col0) {
; #pragma unroll
;     for (int ai = 0; ai < 2; ++ai)
; #pragma unroll
;         for (int m = 0; m < 4; ++m) { bf16_t* rowp = dst + (size_t)(row0 + ai * 128 + m * 16) * ld + col0;
; #pragma unroll
;             for (int bj = 0; bj < 2; ++bj) { const f32x4 v0 = acc[ai][bj][m][0], v1 = acc[ai][bj][m][1];
;                 u32x4 w; w.x = cvt_pk_bf16(actf<ACT>(v0[0]), actf<ACT>(v0[1])); w.y = cvt_pk_bf16(actf<ACT>(v0[2]), actf<ACT>(v0[3]));
;                 w.z = cvt_pk_bf16(actf<ACT>(v1[0]), actf<ACT>(v1[1])); w.w = cvt_pk_bf16(actf<ACT>(v1[2]), actf<ACT>(v1[3]));
;                 *(u32x4*)(rowp + bj * 128) = w; } }
; }
	v_lshl_add_u64 v[98:99], v[130:131], 0, v[98:99]
	v_rcp_f32_e32 v101, v100
	s_nop 0
	v_mul_f32_e32 v94, v94, v101
	v_mul_f32_e32 v100, 0x3d372713, v95
	v_mul_f32_e32 v100, v95, v100
	v_fma_f32 v100, v95, v100, v95
	v_mul_f32_e32 v100, 0xbfcc422a, v100
	v_mul_f32_e32 v100, 0x3fb8aa3b, v100
	v_exp_f32_e32 v100, v100
	s_nop 0
	v_add_f32_e32 v100, 1.0, v100
	v_rcp_f32_e32 v101, v100
	s_nop 0
	v_mul_f32_e32 v95, v95, v101
	v_cvt_pk_bf16_f32 v94, v94, v95
	v_mul_f32_e32 v95, 0x3d372713, v96
	v_mul_f32_e32 v95, v96, v95
	v_fma_f32 v95, v96, v95, v96
	v_mul_f32_e32 v95, 0xbfcc422a, v95
	v_mul_f32_e32 v95, 0x3fb8aa3b, v95
	v_exp_f32_e32 v95, v95
	s_nop 0
	v_add_f32_e32 v95, 1.0, v95
	v_rcp_f32_e32 v95, v95
	s_nop 0
	v_mul_f32_e32 v95, v96, v95
	v_mul_f32_e32 v96, 0x3d372713, v97
	v_mul_f32_e32 v96, v97, v96
	v_fma_f32 v96, v97, v96, v97
	v_mul_f32_e32 v96, 0xbfcc422a, v96
	v_mul_f32_e32 v96, 0x3fb8aa3b, v96
	v_exp_f32_e32 v96, v96
	s_nop 0
	v_add_f32_e32 v96, 1.0, v96
	v_rcp_f32_e32 v96, v96
	s_nop 0
	v_mul_f32_e32 v96, v97, v96
	v_cvt_pk_bf16_f32 v95, v95, v96
	v_mul_f32_e32 v96, 0x3d372713, v90
	v_mul_f32_e32 v96, v90, v96
	v_fma_f32 v96, v90, v96, v90
	v_mul_f32_e32 v96, 0xbfcc422a, v96
	v_mul_f32_e32 v96, 0x3fb8aa3b, v96
	v_exp_f32_e32 v96, v96
	s_nop 0
	v_add_f32_e32 v96, 1.0, v96
	v_rcp_f32_e32 v97, v96
	s_nop 0
	v_mul_f32_e32 v90, v90, v97
	v_mul_f32_e32 v96, 0x3d372713, v91
	v_mul_f32_e32 v96, v91, v96
	v_fma_f32 v96, v91, v96, v91
	v_mul_f32_e32 v96, 0xbfcc422a, v96
	v_mul_f32_e32 v96, 0x3fb8aa3b, v96
	v_exp_f32_e32 v96, v96
	s_nop 0
	v_add_f32_e32 v96, 1.0, v96
	v_rcp_f32_e32 v97, v96
	s_nop 0
	v_mul_f32_e32 v91, v91, v97
	v_cvt_pk_bf16_f32 v96, v90, v91
	v_mul_f32_e32 v90, 0x3d372713, v92
	v_mul_f32_e32 v90, v92, v90
	v_fma_f32 v90, v92, v90, v92
	v_mul_f32_e32 v90, 0xbfcc422a, v90
	v_mul_f32_e32 v90, 0x3fb8aa3b, v90
	v_exp_f32_e32 v90, v90
	s_nop 0
	v_add_f32_e32 v90, 1.0, v90
	v_rcp_f32_e32 v90, v90
	s_nop 0
	v_mul_f32_e32 v90, v92, v90
	v_mul_f32_e32 v91, 0x3d372713, v93
	v_mul_f32_e32 v91, v93, v91
	v_fma_f32 v91, v93, v91, v93
	v_mul_f32_e32 v91, 0xbfcc422a, v91
	v_mul_f32_e32 v91, 0x3fb8aa3b, v91
	v_exp_f32_e32 v91, v91
	s_nop 0
	v_add_f32_e32 v91, 1.0, v91
	v_rcp_f32_e32 v91, v91
	s_nop 0
	v_mul_f32_e32 v91, v93, v91
	v_cvt_pk_bf16_f32 v97, v90, v91
	v_mul_f32_e32 v90, 0x3d372713, v86
	v_mul_f32_e32 v90, v86, v90
	v_fma_f32 v90, v86, v90, v86
	v_mul_f32_e32 v90, 0xbfcc422a, v90
	v_mul_f32_e32 v90, 0x3fb8aa3b, v90
	v_exp_f32_e32 v90, v90
	global_store_dwordx4 v[98:99], v[94:97], off
	v_add_f32_e32 v90, 1.0, v90
	v_rcp_f32_e32 v91, v90
	s_nop 0
	v_mul_f32_e32 v86, v86, v91
	v_mul_f32_e32 v90, 0x3d372713, v87
	v_mul_f32_e32 v90, v87, v90
	v_fma_f32 v90, v87, v90, v87
	v_mul_f32_e32 v90, 0xbfcc422a, v90
	v_mul_f32_e32 v90, 0x3fb8aa3b, v90
	v_exp_f32_e32 v90, v90
	s_nop 0
	v_add_f32_e32 v90, 1.0, v90
	v_rcp_f32_e32 v91, v90
	s_nop 0
	v_mul_f32_e32 v87, v87, v91
	v_cvt_pk_bf16_f32 v86, v86, v87
	v_mul_f32_e32 v87, 0x3d372713, v88
	v_mul_f32_e32 v87, v88, v87
	v_fma_f32 v87, v88, v87, v88
	v_mul_f32_e32 v87, 0xbfcc422a, v87
	v_mul_f32_e32 v87, 0x3fb8aa3b, v87
	v_exp_f32_e32 v87, v87
	s_nop 0
	v_add_f32_e32 v87, 1.0, v87
	v_rcp_f32_e32 v87, v87
	s_nop 0
	v_mul_f32_e32 v87, v88, v87
	v_mul_f32_e32 v88, 0x3d372713, v89
	v_mul_f32_e32 v88, v89, v88
	v_fma_f32 v88, v89, v88, v89
	v_mul_f32_e32 v88, 0xbfcc422a, v88
	v_mul_f32_e32 v88, 0x3fb8aa3b, v88
	v_exp_f32_e32 v88, v88
	s_nop 0
	v_add_f32_e32 v88, 1.0, v88
	v_rcp_f32_e32 v88, v88
	s_nop 0
	v_mul_f32_e32 v88, v89, v88
	v_cvt_pk_bf16_f32 v87, v87, v88
	v_mul_f32_e32 v88, 0x3d372713, v82
	v_mul_f32_e32 v88, v82, v88
	v_fma_f32 v88, v82, v88, v82
	v_mul_f32_e32 v88, 0xbfcc422a, v88
	v_mul_f32_e32 v88, 0x3fb8aa3b, v88
	v_exp_f32_e32 v88, v88
	s_nop 0
	v_add_f32_e32 v88, 1.0, v88
	v_rcp_f32_e32 v89, v88
	s_nop 0
	v_mul_f32_e32 v82, v82, v89
	v_mul_f32_e32 v88, 0x3d372713, v83
	v_mul_f32_e32 v88, v83, v88
	v_fma_f32 v88, v83, v88, v83
	v_mul_f32_e32 v88, 0xbfcc422a, v88
	v_mul_f32_e32 v88, 0x3fb8aa3b, v88
	v_exp_f32_e32 v88, v88
	s_nop 0
	v_add_f32_e32 v88, 1.0, v88
	v_rcp_f32_e32 v89, v88
	s_nop 0
	v_mul_f32_e32 v83, v83, v89
	v_cvt_pk_bf16_f32 v88, v82, v83
	v_mul_f32_e32 v82, 0x3d372713, v84
	v_mul_f32_e32 v82, v84, v82
	v_fma_f32 v82, v84, v82, v84
	v_mul_f32_e32 v82, 0xbfcc422a, v82
	v_mul_f32_e32 v82, 0x3fb8aa3b, v82
	v_exp_f32_e32 v82, v82
	s_nop 0
	v_add_f32_e32 v82, 1.0, v82
	v_rcp_f32_e32 v82, v82
	s_nop 0
	v_mul_f32_e32 v82, v84, v82
	v_mul_f32_e32 v83, 0x3d372713, v85
	v_mul_f32_e32 v83, v85, v83
	v_fma_f32 v83, v85, v83, v85
	v_mul_f32_e32 v83, 0xbfcc422a, v83
	v_mul_f32_e32 v83, 0x3fb8aa3b, v83
	v_exp_f32_e32 v83, v83
	s_nop 0
	v_add_f32_e32 v83, 1.0, v83
	v_rcp_f32_e32 v83, v83
	s_nop 0
	v_mul_f32_e32 v83, v85, v83
	v_mul_f32_e32 v84, 0x3d372713, v78
	v_mul_f32_e32 v84, v78, v84
	v_fma_f32 v84, v78, v84, v78
	v_mul_f32_e32 v84, 0xbfcc422a, v84
	v_mul_f32_e32 v84, 0x3fb8aa3b, v84
	v_exp_f32_e32 v84, v84
	v_cvt_pk_bf16_f32 v89, v82, v83
	global_store_dwordx4 v[98:99], v[86:89], off offset:256
	v_lshlrev_b64 v[82:83], 12, v[154:155]
	v_add_f32_e32 v84, 1.0, v84
	v_lshl_add_u64 v[82:83], v[130:131], 0, v[82:83]
	v_rcp_f32_e32 v85, v84
	s_nop 0
	v_mul_f32_e32 v78, v78, v85
	v_mul_f32_e32 v84, 0x3d372713, v79
	v_mul_f32_e32 v84, v79, v84
	v_fma_f32 v84, v79, v84, v79
	v_mul_f32_e32 v84, 0xbfcc422a, v84
	v_mul_f32_e32 v84, 0x3fb8aa3b, v84
	v_exp_f32_e32 v84, v84
	s_nop 0
	v_add_f32_e32 v84, 1.0, v84
	v_rcp_f32_e32 v85, v84
	s_nop 0
	v_mul_f32_e32 v79, v79, v85
	v_cvt_pk_bf16_f32 v78, v78, v79
	v_mul_f32_e32 v79, 0x3d372713, v80
	v_mul_f32_e32 v79, v80, v79
	v_fma_f32 v79, v80, v79, v80
; template <int ACT> __device__ __forceinline__ void store_tile_bf16(AccRef acc, bf16_t* dst, int ld, int row0, int col0) {
; #pragma unroll
;     for (int ai = 0; ai < 2; ++ai)
; #pragma unroll
;         for (int m = 0; m < 4; ++m) { bf16_t* rowp = dst + (size_t)(row0 + ai * 128 + m * 16) * ld + col0;
; #pragma unroll
;             for (int bj = 0; bj < 2; ++bj) { const f32x4 v0 = acc[ai][bj][m][0], v1 = acc[ai][bj][m][1];
;                 u32x4 w; w.x = cvt_pk_bf16(actf<ACT>(v0[0]), actf<ACT>(v0[1])); w.y = cvt_pk_bf16(actf<ACT>(v0[2]), actf<ACT>(v0[3]));
;                 w.z = cvt_pk_bf16(actf<ACT>(v1[0]), actf<ACT>(v1[1])); w.w = cvt_pk_bf16(actf<ACT>(v1[2]), actf<ACT>(v1[3]));
;                 *(u32x4*)(rowp + bj * 128) = w; } }
; }
	v_mul_f32_e32 v79, 0xbfcc422a, v79
	v_mul_f32_e32 v79, 0x3fb8aa3b, v79
	v_exp_f32_e32 v79, v79
	s_nop 0
	v_add_f32_e32 v79, 1.0, v79
	v_rcp_f32_e32 v79, v79
	s_nop 0
	v_mul_f32_e32 v79, v80, v79
	v_mul_f32_e32 v80, 0x3d372713, v81
	v_mul_f32_e32 v80, v81, v80
	v_fma_f32 v80, v81, v80, v81
	v_mul_f32_e32 v80, 0xbfcc422a, v80
	v_mul_f32_e32 v80, 0x3fb8aa3b, v80
	v_exp_f32_e32 v80, v80
	s_nop 0
	v_add_f32_e32 v80, 1.0, v80
	v_rcp_f32_e32 v80, v80
	s_nop 0
	v_mul_f32_e32 v80, v81, v80
	v_cvt_pk_bf16_f32 v79, v79, v80
	v_mul_f32_e32 v80, 0x3d372713, v74
	v_mul_f32_e32 v80, v74, v80
	v_fma_f32 v80, v74, v80, v74
	v_mul_f32_e32 v80, 0xbfcc422a, v80
	v_mul_f32_e32 v80, 0x3fb8aa3b, v80
	v_exp_f32_e32 v80, v80
	s_nop 0
	v_add_f32_e32 v80, 1.0, v80
	v_rcp_f32_e32 v81, v80
	s_nop 0
	v_mul_f32_e32 v74, v74, v81
	v_mul_f32_e32 v80, 0x3d372713, v75
	v_mul_f32_e32 v80, v75, v80
	v_fma_f32 v80, v75, v80, v75
	v_mul_f32_e32 v80, 0xbfcc422a, v80
	v_mul_f32_e32 v80, 0x3fb8aa3b, v80
	v_exp_f32_e32 v80, v80
	s_nop 0
	v_add_f32_e32 v80, 1.0, v80
	v_rcp_f32_e32 v81, v80
	s_nop 0
	v_mul_f32_e32 v75, v75, v81
	v_cvt_pk_bf16_f32 v80, v74, v75
	v_mul_f32_e32 v74, 0x3d372713, v76
	v_mul_f32_e32 v74, v76, v74
	v_fma_f32 v74, v76, v74, v76
	v_mul_f32_e32 v74, 0xbfcc422a, v74
	v_mul_f32_e32 v74, 0x3fb8aa3b, v74
	v_exp_f32_e32 v74, v74
	s_nop 0
	v_add_f32_e32 v74, 1.0, v74
	v_rcp_f32_e32 v74, v74
	s_nop 0
	v_mul_f32_e32 v74, v76, v74
	v_mul_f32_e32 v75, 0x3d372713, v77
	v_mul_f32_e32 v75, v77, v75
	v_fma_f32 v75, v77, v75, v77
	v_mul_f32_e32 v75, 0xbfcc422a, v75
	v_mul_f32_e32 v75, 0x3fb8aa3b, v75
	v_exp_f32_e32 v75, v75
	s_nop 0
	v_add_f32_e32 v75, 1.0, v75
	v_rcp_f32_e32 v75, v75
	s_nop 0
	v_mul_f32_e32 v75, v77, v75
	v_cvt_pk_bf16_f32 v81, v74, v75
	v_mul_f32_e32 v74, 0x3d372713, v70
	v_mul_f32_e32 v74, v70, v74
	v_fma_f32 v74, v70, v74, v70
	v_mul_f32_e32 v74, 0xbfcc422a, v74
	v_mul_f32_e32 v74, 0x3fb8aa3b, v74
	v_exp_f32_e32 v74, v74
	global_store_dwordx4 v[82:83], v[78:81], off
	v_add_f32_e32 v74, 1.0, v74
	v_rcp_f32_e32 v75, v74
	s_nop 0
	v_mul_f32_e32 v70, v70, v75
	v_mul_f32_e32 v74, 0x3d372713, v71
	v_mul_f32_e32 v74, v71, v74
	v_fma_f32 v74, v71, v74, v71
	v_mul_f32_e32 v74, 0xbfcc422a, v74
	v_mul_f32_e32 v74, 0x3fb8aa3b, v74
	v_exp_f32_e32 v74, v74
	s_nop 0
	v_add_f32_e32 v74, 1.0, v74
	v_rcp_f32_e32 v75, v74
	s_nop 0
	v_mul_f32_e32 v71, v71, v75
	v_cvt_pk_bf16_f32 v70, v70, v71
	v_mul_f32_e32 v71, 0x3d372713, v72
	v_mul_f32_e32 v71, v72, v71
	v_fma_f32 v71, v72, v71, v72
	v_mul_f32_e32 v71, 0xbfcc422a, v71
	v_mul_f32_e32 v71, 0x3fb8aa3b, v71
	v_exp_f32_e32 v71, v71
	s_nop 0
	v_add_f32_e32 v71, 1.0, v71
	v_rcp_f32_e32 v71, v71
	s_nop 0
	v_mul_f32_e32 v71, v72, v71
	v_mul_f32_e32 v72, 0x3d372713, v73
	v_mul_f32_e32 v72, v73, v72
	v_fma_f32 v72, v73, v72, v73
	v_mul_f32_e32 v72, 0xbfcc422a, v72
	v_mul_f32_e32 v72, 0x3fb8aa3b, v72
	v_exp_f32_e32 v72, v72
	s_nop 0
	v_add_f32_e32 v72, 1.0, v72
	v_rcp_f32_e32 v72, v72
	s_nop 0
	v_mul_f32_e32 v72, v73, v72
	v_cvt_pk_bf16_f32 v71, v71, v72
	v_mul_f32_e32 v72, 0x3d372713, v66
	v_mul_f32_e32 v72, v66, v72
	v_fma_f32 v72, v66, v72, v66
	v_mul_f32_e32 v72, 0xbfcc422a, v72
	v_mul_f32_e32 v72, 0x3fb8aa3b, v72
	v_exp_f32_e32 v72, v72
	s_nop 0
	v_add_f32_e32 v72, 1.0, v72
	v_rcp_f32_e32 v73, v72
	s_nop 0
	v_mul_f32_e32 v66, v66, v73
	v_mul_f32_e32 v72, 0x3d372713, v67
	v_mul_f32_e32 v72, v67, v72
	v_fma_f32 v72, v67, v72, v67
	v_mul_f32_e32 v72, 0xbfcc422a, v72
	v_mul_f32_e32 v72, 0x3fb8aa3b, v72
	v_exp_f32_e32 v72, v72
	s_nop 0
	v_add_f32_e32 v72, 1.0, v72
	v_rcp_f32_e32 v73, v72
	s_nop 0
	v_mul_f32_e32 v67, v67, v73
	v_cvt_pk_bf16_f32 v72, v66, v67
	v_mul_f32_e32 v66, 0x3d372713, v68
	v_mul_f32_e32 v66, v68, v66
	v_fma_f32 v66, v68, v66, v68
	v_mul_f32_e32 v66, 0xbfcc422a, v66
	v_mul_f32_e32 v66, 0x3fb8aa3b, v66
	v_exp_f32_e32 v66, v66
	s_nop 0
	v_add_f32_e32 v66, 1.0, v66
	v_rcp_f32_e32 v66, v66
	s_nop 0
	v_mul_f32_e32 v66, v68, v66
	v_mul_f32_e32 v67, 0x3d372713, v69
	v_mul_f32_e32 v67, v69, v67
	v_fma_f32 v67, v69, v67, v69
	v_mul_f32_e32 v67, 0xbfcc422a, v67
	v_mul_f32_e32 v67, 0x3fb8aa3b, v67
	v_exp_f32_e32 v67, v67
	s_nop 0
	v_add_f32_e32 v67, 1.0, v67
	v_rcp_f32_e32 v67, v67
	s_nop 0
	v_mul_f32_e32 v67, v69, v67
	v_cvt_pk_bf16_f32 v73, v66, v67
	global_store_dwordx4 v[82:83], v[70:73], off offset:256
	v_lshlrev_b64 v[66:67], 12, v[152:153]
	v_lshl_add_u64 v[66:67], v[130:131], 0, v[66:67]
	v_mul_f32_e32 v70, 0x3d372713, v62
	v_mul_f32_e32 v70, v62, v70
	v_fma_f32 v70, v62, v70, v62
	v_mul_f32_e32 v70, 0xbfcc422a, v70
	v_mul_f32_e32 v70, 0x3fb8aa3b, v70
	v_exp_f32_e32 v70, v70
	v_lshl_add_u64 v[68:69], v[66:67], 0, s[40:41]
	v_lshl_add_u64 v[160:161], v[66:67], 0, s[52:53]
	v_add_f32_e32 v70, 1.0, v70
	v_rcp_f32_e32 v71, v70
	s_nop 0
	v_mul_f32_e32 v62, v62, v71
	v_mul_f32_e32 v70, 0x3d372713, v63
	v_mul_f32_e32 v70, v63, v70
	v_fma_f32 v70, v63, v70, v63
	v_mul_f32_e32 v70, 0xbfcc422a, v70
	v_mul_f32_e32 v70, 0x3fb8aa3b, v70
	v_exp_f32_e32 v70, v70
	s_nop 0
	v_add_f32_e32 v70, 1.0, v70
	v_rcp_f32_e32 v71, v70
	s_nop 0
	v_mul_f32_e32 v63, v63, v71
	v_cvt_pk_bf16_f32 v62, v62, v63
	v_mul_f32_e32 v63, 0x3d372713, v64
	v_mul_f32_e32 v63, v64, v63
	v_fma_f32 v63, v64, v63, v64
	v_mul_f32_e32 v63, 0xbfcc422a, v63
	v_mul_f32_e32 v63, 0x3fb8aa3b, v63
	v_exp_f32_e32 v63, v63
	s_nop 0
	v_add_f32_e32 v63, 1.0, v63
	v_rcp_f32_e32 v63, v63
	s_nop 0
	v_mul_f32_e32 v63, v64, v63
	v_mul_f32_e32 v64, 0x3d372713, v65
	v_mul_f32_e32 v64, v65, v64
	v_fma_f32 v64, v65, v64, v65
	v_mul_f32_e32 v64, 0xbfcc422a, v64
	v_mul_f32_e32 v64, 0x3fb8aa3b, v64
	v_exp_f32_e32 v64, v64
	s_nop 0
	v_add_f32_e32 v64, 1.0, v64
	v_rcp_f32_e32 v64, v64
; template <int ACT> __device__ __forceinline__ void store_tile_bf16(AccRef acc, bf16_t* dst, int ld, int row0, int col0) {
; #pragma unroll
;     for (int ai = 0; ai < 2; ++ai)
; #pragma unroll
;         for (int m = 0; m < 4; ++m) { bf16_t* rowp = dst + (size_t)(row0 + ai * 128 + m * 16) * ld + col0;
; #pragma unroll
;             for (int bj = 0; bj < 2; ++bj) { const f32x4 v0 = acc[ai][bj][m][0], v1 = acc[ai][bj][m][1];
;                 u32x4 w; w.x = cvt_pk_bf16(actf<ACT>(v0[0]), actf<ACT>(v0[1])); w.y = cvt_pk_bf16(actf<ACT>(v0[2]), actf<ACT>(v0[3]));
;                 w.z = cvt_pk_bf16(actf<ACT>(v1[0]), actf<ACT>(v1[1])); w.w = cvt_pk_bf16(actf<ACT>(v1[2]), actf<ACT>(v1[3]));
;                 *(u32x4*)(rowp + bj * 128) = w; } }
; }
	s_nop 0
	v_mul_f32_e32 v64, v65, v64
	v_cvt_pk_bf16_f32 v63, v63, v64
	v_mul_f32_e32 v64, 0x3d372713, v58
	v_mul_f32_e32 v64, v58, v64
	v_fma_f32 v64, v58, v64, v58
	v_mul_f32_e32 v64, 0xbfcc422a, v64
	v_mul_f32_e32 v64, 0x3fb8aa3b, v64
	v_exp_f32_e32 v64, v64
	s_nop 0
	v_add_f32_e32 v64, 1.0, v64
	v_rcp_f32_e32 v65, v64
	s_nop 0
	v_mul_f32_e32 v58, v58, v65
	v_mul_f32_e32 v64, 0x3d372713, v59
	v_mul_f32_e32 v64, v59, v64
	v_fma_f32 v64, v59, v64, v59
	v_mul_f32_e32 v64, 0xbfcc422a, v64
	v_mul_f32_e32 v64, 0x3fb8aa3b, v64
	v_exp_f32_e32 v64, v64
	s_nop 0
	v_add_f32_e32 v64, 1.0, v64
	v_rcp_f32_e32 v65, v64
	s_nop 0
	v_mul_f32_e32 v59, v59, v65
	v_cvt_pk_bf16_f32 v64, v58, v59
	v_mul_f32_e32 v58, 0x3d372713, v60
	v_mul_f32_e32 v58, v60, v58
	v_fma_f32 v58, v60, v58, v60
	v_mul_f32_e32 v58, 0xbfcc422a, v58
	v_mul_f32_e32 v58, 0x3fb8aa3b, v58
	v_exp_f32_e32 v58, v58
	s_nop 0
	v_add_f32_e32 v58, 1.0, v58
	v_rcp_f32_e32 v58, v58
	s_nop 0
	v_mul_f32_e32 v58, v60, v58
	v_mul_f32_e32 v59, 0x3d372713, v61
	v_mul_f32_e32 v59, v61, v59
	v_fma_f32 v59, v61, v59, v61
	v_mul_f32_e32 v59, 0xbfcc422a, v59
	v_mul_f32_e32 v59, 0x3fb8aa3b, v59
	v_exp_f32_e32 v59, v59
	s_nop 0
	v_add_f32_e32 v59, 1.0, v59
	v_rcp_f32_e32 v59, v59
	s_nop 0
	v_mul_f32_e32 v59, v61, v59
	v_cvt_pk_bf16_f32 v65, v58, v59
	v_add_co_u32_e32 v58, vcc, s85, v66
	s_nop 1
	v_addc_co_u32_e32 v59, vcc, 0, v67, vcc
	global_store_dwordx4 v[58:59], v[62:65], off
	v_mul_f32_e32 v58, 0x3d372713, v54
	v_mul_f32_e32 v58, v54, v58
	v_fma_f32 v58, v54, v58, v54
	v_mul_f32_e32 v58, 0xbfcc422a, v58
	v_mul_f32_e32 v58, 0x3fb8aa3b, v58
	v_exp_f32_e32 v58, v58
	s_nop 0
	v_add_f32_e32 v58, 1.0, v58
	v_rcp_f32_e32 v59, v58
	s_nop 0
	v_mul_f32_e32 v54, v54, v59
	v_mul_f32_e32 v58, 0x3d372713, v55
	v_mul_f32_e32 v58, v55, v58
	v_fma_f32 v58, v55, v58, v55
	v_mul_f32_e32 v58, 0xbfcc422a, v58
	v_mul_f32_e32 v58, 0x3fb8aa3b, v58
	v_exp_f32_e32 v58, v58
	s_nop 0
	v_add_f32_e32 v58, 1.0, v58
	v_rcp_f32_e32 v59, v58
	s_nop 0
	v_mul_f32_e32 v55, v55, v59
	v_cvt_pk_bf16_f32 v54, v54, v55
	v_mul_f32_e32 v55, 0x3d372713, v56
	v_mul_f32_e32 v55, v56, v55
	v_fma_f32 v55, v56, v55, v56
	v_mul_f32_e32 v55, 0xbfcc422a, v55
	v_mul_f32_e32 v55, 0x3fb8aa3b, v55
	v_exp_f32_e32 v55, v55
	s_nop 0
	v_add_f32_e32 v55, 1.0, v55
	v_rcp_f32_e32 v55, v55
	s_nop 0
	v_mul_f32_e32 v55, v56, v55
	v_mul_f32_e32 v56, 0x3d372713, v57
	v_mul_f32_e32 v56, v57, v56
	v_fma_f32 v56, v57, v56, v57
	v_mul_f32_e32 v56, 0xbfcc422a, v56
	v_mul_f32_e32 v56, 0x3fb8aa3b, v56
	v_exp_f32_e32 v56, v56
	s_nop 0
	v_add_f32_e32 v56, 1.0, v56
	v_rcp_f32_e32 v56, v56
	s_nop 0
	v_mul_f32_e32 v56, v57, v56
	v_cvt_pk_bf16_f32 v55, v55, v56
	v_mul_f32_e32 v56, 0x3d372713, v50
	v_mul_f32_e32 v56, v50, v56
	v_fma_f32 v56, v50, v56, v50
	v_mul_f32_e32 v56, 0xbfcc422a, v56
	v_mul_f32_e32 v56, 0x3fb8aa3b, v56
	v_exp_f32_e32 v56, v56
	s_nop 0
	v_add_f32_e32 v56, 1.0, v56
	v_rcp_f32_e32 v57, v56
	s_nop 0
	v_mul_f32_e32 v50, v50, v57
	v_mul_f32_e32 v56, 0x3d372713, v51
	v_mul_f32_e32 v56, v51, v56
	v_fma_f32 v56, v51, v56, v51
	v_mul_f32_e32 v56, 0xbfcc422a, v56
	v_mul_f32_e32 v56, 0x3fb8aa3b, v56
	v_exp_f32_e32 v56, v56
	s_nop 0
	v_add_f32_e32 v56, 1.0, v56
	v_rcp_f32_e32 v57, v56
	s_nop 0
	v_mul_f32_e32 v51, v51, v57
	v_cvt_pk_bf16_f32 v56, v50, v51
	v_mul_f32_e32 v50, 0x3d372713, v52
	v_mul_f32_e32 v50, v52, v50
	v_fma_f32 v50, v52, v50, v52
	v_mul_f32_e32 v50, 0xbfcc422a, v50
	v_mul_f32_e32 v50, 0x3fb8aa3b, v50
	v_exp_f32_e32 v50, v50
	s_nop 0
	v_add_f32_e32 v50, 1.0, v50
	v_rcp_f32_e32 v50, v50
	s_nop 0
	v_mul_f32_e32 v50, v52, v50
	v_mul_f32_e32 v51, 0x3d372713, v53
	v_mul_f32_e32 v51, v53, v51
	v_fma_f32 v51, v53, v51, v53
	v_mul_f32_e32 v51, 0xbfcc422a, v51
	v_mul_f32_e32 v51, 0x3fb8aa3b, v51
	v_exp_f32_e32 v51, v51
	s_nop 0
	v_add_f32_e32 v51, 1.0, v51
	v_rcp_f32_e32 v51, v51
	s_nop 0
	v_mul_f32_e32 v51, v53, v51
	v_mul_f32_e32 v52, 0x3d372713, v46
	v_mul_f32_e32 v52, v46, v52
	v_fma_f32 v52, v46, v52, v46
	v_mul_f32_e32 v52, 0xbfcc422a, v52
	v_mul_f32_e32 v52, 0x3fb8aa3b, v52
	v_exp_f32_e32 v52, v52
	v_cvt_pk_bf16_f32 v57, v50, v51
	global_store_dwordx4 v[68:69], v[54:57], off offset:256
	v_lshl_add_u64 v[50:51], v[66:67], 0, s[48:49]
	v_add_f32_e32 v52, 1.0, v52
	v_rcp_f32_e32 v53, v52
	s_nop 0
	v_mul_f32_e32 v46, v46, v53
	v_mul_f32_e32 v52, 0x3d372713, v47
	v_mul_f32_e32 v52, v47, v52
	v_fma_f32 v52, v47, v52, v47
	v_mul_f32_e32 v52, 0xbfcc422a, v52
	v_mul_f32_e32 v52, 0x3fb8aa3b, v52
	v_exp_f32_e32 v52, v52
	s_nop 0
	v_add_f32_e32 v52, 1.0, v52
	v_rcp_f32_e32 v53, v52
	s_nop 0
	v_mul_f32_e32 v47, v47, v53
	v_cvt_pk_bf16_f32 v46, v46, v47
	v_mul_f32_e32 v47, 0x3d372713, v48
	v_mul_f32_e32 v47, v48, v47
	v_fma_f32 v47, v48, v47, v48
	v_mul_f32_e32 v47, 0xbfcc422a, v47
	v_mul_f32_e32 v47, 0x3fb8aa3b, v47
	v_exp_f32_e32 v47, v47
	s_nop 0
	v_add_f32_e32 v47, 1.0, v47
	v_rcp_f32_e32 v47, v47
	s_nop 0
	v_mul_f32_e32 v47, v48, v47
	v_mul_f32_e32 v48, 0x3d372713, v49
	v_mul_f32_e32 v48, v49, v48
	v_fma_f32 v48, v49, v48, v49
	v_mul_f32_e32 v48, 0xbfcc422a, v48
	v_mul_f32_e32 v48, 0x3fb8aa3b, v48
	v_exp_f32_e32 v48, v48
	s_nop 0
	v_add_f32_e32 v48, 1.0, v48
	v_rcp_f32_e32 v48, v48
	s_nop 0
	v_mul_f32_e32 v48, v49, v48
	v_cvt_pk_bf16_f32 v47, v47, v48
	v_mul_f32_e32 v48, 0x3d372713, v42
	v_mul_f32_e32 v48, v42, v48
	v_fma_f32 v48, v42, v48, v42
	v_mul_f32_e32 v48, 0xbfcc422a, v48
	v_mul_f32_e32 v48, 0x3fb8aa3b, v48
	v_exp_f32_e32 v48, v48
	s_nop 0
	v_add_f32_e32 v48, 1.0, v48
	v_rcp_f32_e32 v49, v48
	s_nop 0
	v_mul_f32_e32 v42, v42, v49
	v_mul_f32_e32 v48, 0x3d372713, v43
	v_mul_f32_e32 v48, v43, v48
	v_fma_f32 v48, v43, v48, v43
	v_mul_f32_e32 v48, 0xbfcc422a, v48
; template <int ACT> __device__ __forceinline__ void store_tile_bf16(AccRef acc, bf16_t* dst, int ld, int row0, int col0) {
;     ...
;         for (int m = 0; m < 4; ++m) { bf16_t* rowp = dst + (size_t)(row0 + ai * 128 + m * 16) * ld + col0;
; #pragma unroll
;             for (int bj = 0; bj < 2; ++bj) { const f32x4 v0 = acc[ai][bj][m][0], v1 = acc[ai][bj][m][1];
;                 u32x4 w; w.x = cvt_pk_bf16(actf<ACT>(v0[0]), actf<ACT>(v0[1])); w.y = cvt_pk_bf16(actf<ACT>(v0[2]), actf<ACT>(v0[3]));
;                 w.z = cvt_pk_bf16(actf<ACT>(v1[0]), actf<ACT>(v1[1])); w.w = cvt_pk_bf16(actf<ACT>(v1[2]), actf<ACT>(v1[3]));
;                 *(u32x4*)(rowp + bj * 128) = w; } }
	v_mul_f32_e32 v48, 0x3fb8aa3b, v48
	v_exp_f32_e32 v48, v48
	s_nop 0
	v_add_f32_e32 v48, 1.0, v48
	v_rcp_f32_e32 v49, v48
	s_nop 0
	v_mul_f32_e32 v43, v43, v49
	v_cvt_pk_bf16_f32 v48, v42, v43
	v_mul_f32_e32 v42, 0x3d372713, v44
	v_mul_f32_e32 v42, v44, v42
	v_fma_f32 v42, v44, v42, v44
	v_mul_f32_e32 v42, 0xbfcc422a, v42
	v_mul_f32_e32 v42, 0x3fb8aa3b, v42
	v_exp_f32_e32 v42, v42
	s_nop 0
	v_add_f32_e32 v42, 1.0, v42
	v_rcp_f32_e32 v42, v42
	s_nop 0
	v_mul_f32_e32 v42, v44, v42
	v_mul_f32_e32 v43, 0x3d372713, v45
	v_mul_f32_e32 v43, v45, v43
	v_fma_f32 v43, v45, v43, v45
	v_mul_f32_e32 v43, 0xbfcc422a, v43
	v_mul_f32_e32 v43, 0x3fb8aa3b, v43
	v_exp_f32_e32 v43, v43
	s_nop 0
	v_add_f32_e32 v43, 1.0, v43
	v_rcp_f32_e32 v43, v43
	s_nop 0
	v_mul_f32_e32 v43, v45, v43
	v_cvt_pk_bf16_f32 v49, v42, v43
	v_add_co_u32_e32 v42, vcc, s86, v66
	s_nop 1
	v_addc_co_u32_e32 v43, vcc, 0, v67, vcc
	global_store_dwordx4 v[42:43], v[46:49], off
	v_mul_f32_e32 v42, 0x3d372713, v38
	v_mul_f32_e32 v42, v38, v42
	v_fma_f32 v42, v38, v42, v38
	v_mul_f32_e32 v42, 0xbfcc422a, v42
	v_mul_f32_e32 v42, 0x3fb8aa3b, v42
	v_exp_f32_e32 v42, v42
	s_nop 0
	v_add_f32_e32 v42, 1.0, v42
	v_rcp_f32_e32 v43, v42
	s_nop 0
	v_mul_f32_e32 v38, v38, v43
	v_mul_f32_e32 v42, 0x3d372713, v39
	v_mul_f32_e32 v42, v39, v42
	v_fma_f32 v42, v39, v42, v39
	v_mul_f32_e32 v42, 0xbfcc422a, v42
	v_mul_f32_e32 v42, 0x3fb8aa3b, v42
	v_exp_f32_e32 v42, v42
	s_nop 0
	v_add_f32_e32 v42, 1.0, v42
	v_rcp_f32_e32 v43, v42
	s_nop 0
	v_mul_f32_e32 v39, v39, v43
	v_cvt_pk_bf16_f32 v38, v38, v39
	v_mul_f32_e32 v39, 0x3d372713, v40
	v_mul_f32_e32 v39, v40, v39
	v_fma_f32 v39, v40, v39, v40
	v_mul_f32_e32 v39, 0xbfcc422a, v39
	v_mul_f32_e32 v39, 0x3fb8aa3b, v39
	v_exp_f32_e32 v39, v39
	s_nop 0
	v_add_f32_e32 v39, 1.0, v39
	v_rcp_f32_e32 v39, v39
	s_nop 0
	v_mul_f32_e32 v39, v40, v39
	v_mul_f32_e32 v40, 0x3d372713, v41
	v_mul_f32_e32 v40, v41, v40
	v_fma_f32 v40, v41, v40, v41
	v_mul_f32_e32 v40, 0xbfcc422a, v40
	v_mul_f32_e32 v40, 0x3fb8aa3b, v40
	v_exp_f32_e32 v40, v40
	s_nop 0
	v_add_f32_e32 v40, 1.0, v40
	v_rcp_f32_e32 v40, v40
	s_nop 0
	v_mul_f32_e32 v40, v41, v40
	v_cvt_pk_bf16_f32 v39, v39, v40
	v_mul_f32_e32 v40, 0x3d372713, v34
	v_mul_f32_e32 v40, v34, v40
	v_fma_f32 v40, v34, v40, v34
	v_mul_f32_e32 v40, 0xbfcc422a, v40
	v_mul_f32_e32 v40, 0x3fb8aa3b, v40
	v_exp_f32_e32 v40, v40
	s_nop 0
	v_add_f32_e32 v40, 1.0, v40
	v_rcp_f32_e32 v41, v40
	s_nop 0
	v_mul_f32_e32 v34, v34, v41
	v_mul_f32_e32 v40, 0x3d372713, v35
	v_mul_f32_e32 v40, v35, v40
	v_fma_f32 v40, v35, v40, v35
	v_mul_f32_e32 v40, 0xbfcc422a, v40
	v_mul_f32_e32 v40, 0x3fb8aa3b, v40
	v_exp_f32_e32 v40, v40
	s_nop 0
	v_add_f32_e32 v40, 1.0, v40
	v_rcp_f32_e32 v41, v40
	s_nop 0
	v_mul_f32_e32 v35, v35, v41
	v_cvt_pk_bf16_f32 v40, v34, v35
	v_mul_f32_e32 v34, 0x3d372713, v36
	v_mul_f32_e32 v34, v36, v34
	v_fma_f32 v34, v36, v34, v36
	v_mul_f32_e32 v34, 0xbfcc422a, v34
	v_mul_f32_e32 v34, 0x3fb8aa3b, v34
	v_exp_f32_e32 v34, v34
	s_nop 0
	v_add_f32_e32 v34, 1.0, v34
	v_rcp_f32_e32 v34, v34
	s_nop 0
	v_mul_f32_e32 v34, v36, v34
	v_mul_f32_e32 v35, 0x3d372713, v37
	v_mul_f32_e32 v35, v37, v35
	v_fma_f32 v35, v37, v35, v37
	v_mul_f32_e32 v35, 0xbfcc422a, v35
	v_mul_f32_e32 v35, 0x3fb8aa3b, v35
	v_exp_f32_e32 v35, v35
	s_nop 0
	v_add_f32_e32 v35, 1.0, v35
	v_rcp_f32_e32 v35, v35
	s_nop 0
	v_mul_f32_e32 v35, v37, v35
	v_mul_f32_e32 v36, 0x3d372713, v30
	v_mul_f32_e32 v36, v30, v36
	v_fma_f32 v36, v30, v36, v30
	v_mul_f32_e32 v36, 0xbfcc422a, v36
	v_mul_f32_e32 v36, 0x3fb8aa3b, v36
	v_exp_f32_e32 v36, v36
	v_cvt_pk_bf16_f32 v41, v34, v35
	global_store_dwordx4 v[50:51], v[38:41], off offset:256
	v_lshl_add_u64 v[34:35], v[66:67], 0, s[50:51]
	v_add_f32_e32 v36, 1.0, v36
	v_rcp_f32_e32 v37, v36
	s_nop 0
	v_mul_f32_e32 v30, v30, v37
	v_mul_f32_e32 v36, 0x3d372713, v31
	v_mul_f32_e32 v36, v31, v36
	v_fma_f32 v36, v31, v36, v31
	v_mul_f32_e32 v36, 0xbfcc422a, v36
	v_mul_f32_e32 v36, 0x3fb8aa3b, v36
	v_exp_f32_e32 v36, v36
	s_nop 0
	v_add_f32_e32 v36, 1.0, v36
	v_rcp_f32_e32 v37, v36
	s_nop 0
	v_mul_f32_e32 v31, v31, v37
	v_cvt_pk_bf16_f32 v30, v30, v31
	v_mul_f32_e32 v31, 0x3d372713, v32
	v_mul_f32_e32 v31, v32, v31
	v_fma_f32 v31, v32, v31, v32
	v_mul_f32_e32 v31, 0xbfcc422a, v31
	v_mul_f32_e32 v31, 0x3fb8aa3b, v31
	v_exp_f32_e32 v31, v31
	s_nop 0
	v_add_f32_e32 v31, 1.0, v31
	v_rcp_f32_e32 v31, v31
	s_nop 0
	v_mul_f32_e32 v31, v32, v31
	v_mul_f32_e32 v32, 0x3d372713, v33
	v_mul_f32_e32 v32, v33, v32
	v_fma_f32 v32, v33, v32, v33
	v_mul_f32_e32 v32, 0xbfcc422a, v32
	v_mul_f32_e32 v32, 0x3fb8aa3b, v32
	v_exp_f32_e32 v32, v32
	s_nop 0
	v_add_f32_e32 v32, 1.0, v32
	v_rcp_f32_e32 v32, v32
	s_nop 0
	v_mul_f32_e32 v32, v33, v32
	v_cvt_pk_bf16_f32 v31, v31, v32
	v_mul_f32_e32 v32, 0x3d372713, v26
	v_mul_f32_e32 v32, v26, v32
	v_fma_f32 v32, v26, v32, v26
	v_mul_f32_e32 v32, 0xbfcc422a, v32
	v_mul_f32_e32 v32, 0x3fb8aa3b, v32
	v_exp_f32_e32 v32, v32
	s_nop 0
	v_add_f32_e32 v32, 1.0, v32
	v_rcp_f32_e32 v33, v32
	s_nop 0
	v_mul_f32_e32 v26, v26, v33
	v_mul_f32_e32 v32, 0x3d372713, v27
	v_mul_f32_e32 v32, v27, v32
	v_fma_f32 v32, v27, v32, v27
	v_mul_f32_e32 v32, 0xbfcc422a, v32
	v_mul_f32_e32 v32, 0x3fb8aa3b, v32
	v_exp_f32_e32 v32, v32
	s_nop 0
	v_add_f32_e32 v32, 1.0, v32
	v_rcp_f32_e32 v33, v32
	s_nop 0
	v_mul_f32_e32 v27, v27, v33
	v_cvt_pk_bf16_f32 v32, v26, v27
	v_mul_f32_e32 v26, 0x3d372713, v28
	v_mul_f32_e32 v26, v28, v26
	v_fma_f32 v26, v28, v26, v28
	v_mul_f32_e32 v26, 0xbfcc422a, v26
	v_mul_f32_e32 v26, 0x3fb8aa3b, v26
	v_exp_f32_e32 v26, v26
	s_nop 0
	v_add_f32_e32 v26, 1.0, v26
	v_rcp_f32_e32 v26, v26
	s_nop 0
	v_mul_f32_e32 v26, v28, v26
; template <int ACT> __device__ __forceinline__ void store_tile_bf16(AccRef acc, bf16_t* dst, int ld, int row0, int col0) {
;     ...
;         for (int m = 0; m < 4; ++m) { bf16_t* rowp = dst + (size_t)(row0 + ai * 128 + m * 16) * ld + col0;
; #pragma unroll
;             for (int bj = 0; bj < 2; ++bj) { const f32x4 v0 = acc[ai][bj][m][0], v1 = acc[ai][bj][m][1];
;                 u32x4 w; w.x = cvt_pk_bf16(actf<ACT>(v0[0]), actf<ACT>(v0[1])); w.y = cvt_pk_bf16(actf<ACT>(v0[2]), actf<ACT>(v0[3]));
;                 w.z = cvt_pk_bf16(actf<ACT>(v1[0]), actf<ACT>(v1[1])); w.w = cvt_pk_bf16(actf<ACT>(v1[2]), actf<ACT>(v1[3]));
;                 *(u32x4*)(rowp + bj * 128) = w; } }
	v_mul_f32_e32 v27, 0x3d372713, v29
	v_mul_f32_e32 v27, v29, v27
	v_fma_f32 v27, v29, v27, v29
	v_mul_f32_e32 v27, 0xbfcc422a, v27
	v_mul_f32_e32 v27, 0x3fb8aa3b, v27
	v_exp_f32_e32 v27, v27
	s_nop 0
	v_add_f32_e32 v27, 1.0, v27
	v_rcp_f32_e32 v27, v27
	s_nop 0
	v_mul_f32_e32 v27, v29, v27
	v_cvt_pk_bf16_f32 v33, v26, v27
	v_add_co_u32_e32 v26, vcc, s87, v66
	s_nop 1
	v_addc_co_u32_e32 v27, vcc, 0, v67, vcc
	global_store_dwordx4 v[26:27], v[30:33], off
	v_mul_f32_e32 v26, 0x3d372713, v22
	v_mul_f32_e32 v26, v22, v26
	v_fma_f32 v26, v22, v26, v22
	v_mul_f32_e32 v26, 0xbfcc422a, v26
	v_mul_f32_e32 v26, 0x3fb8aa3b, v26
	v_exp_f32_e32 v26, v26
	s_nop 0
	v_add_f32_e32 v26, 1.0, v26
	v_rcp_f32_e32 v27, v26
	s_nop 0
	v_mul_f32_e32 v22, v22, v27
	v_mul_f32_e32 v26, 0x3d372713, v23
	v_mul_f32_e32 v26, v23, v26
	v_fma_f32 v26, v23, v26, v23
	v_mul_f32_e32 v26, 0xbfcc422a, v26
	v_mul_f32_e32 v26, 0x3fb8aa3b, v26
	v_exp_f32_e32 v26, v26
	s_nop 0
	v_add_f32_e32 v26, 1.0, v26
	v_rcp_f32_e32 v27, v26
	s_nop 0
	v_mul_f32_e32 v23, v23, v27
	v_cvt_pk_bf16_f32 v22, v22, v23
	v_mul_f32_e32 v23, 0x3d372713, v24
	v_mul_f32_e32 v23, v24, v23
	v_fma_f32 v23, v24, v23, v24
	v_mul_f32_e32 v23, 0xbfcc422a, v23
	v_mul_f32_e32 v23, 0x3fb8aa3b, v23
	v_exp_f32_e32 v23, v23
	s_nop 0
	v_add_f32_e32 v23, 1.0, v23
	v_rcp_f32_e32 v23, v23
	s_nop 0
	v_mul_f32_e32 v23, v24, v23
	v_mul_f32_e32 v24, 0x3d372713, v25
	v_mul_f32_e32 v24, v25, v24
	v_fma_f32 v24, v25, v24, v25
	v_mul_f32_e32 v24, 0xbfcc422a, v24
	v_mul_f32_e32 v24, 0x3fb8aa3b, v24
	v_exp_f32_e32 v24, v24
	s_nop 0
	v_add_f32_e32 v24, 1.0, v24
	v_rcp_f32_e32 v24, v24
	s_nop 0
	v_mul_f32_e32 v24, v25, v24
	v_cvt_pk_bf16_f32 v23, v23, v24
	v_mul_f32_e32 v24, 0x3d372713, v18
	v_mul_f32_e32 v24, v18, v24
	v_fma_f32 v24, v18, v24, v18
	v_mul_f32_e32 v24, 0xbfcc422a, v24
	v_mul_f32_e32 v24, 0x3fb8aa3b, v24
	v_exp_f32_e32 v24, v24
	s_nop 0
	v_add_f32_e32 v24, 1.0, v24
	v_rcp_f32_e32 v25, v24
	s_nop 0
	v_mul_f32_e32 v18, v18, v25
	v_mul_f32_e32 v24, 0x3d372713, v19
	v_mul_f32_e32 v24, v19, v24
	v_fma_f32 v24, v19, v24, v19
	v_mul_f32_e32 v24, 0xbfcc422a, v24
	v_mul_f32_e32 v24, 0x3fb8aa3b, v24
	v_exp_f32_e32 v24, v24
	s_nop 0
	v_add_f32_e32 v24, 1.0, v24
	v_rcp_f32_e32 v25, v24
	s_nop 0
	v_mul_f32_e32 v19, v19, v25
	v_cvt_pk_bf16_f32 v24, v18, v19
	v_mul_f32_e32 v18, 0x3d372713, v20
	v_mul_f32_e32 v18, v20, v18
	v_fma_f32 v18, v20, v18, v20
	v_mul_f32_e32 v18, 0xbfcc422a, v18
	v_mul_f32_e32 v18, 0x3fb8aa3b, v18
	v_exp_f32_e32 v18, v18
	s_nop 0
	v_add_f32_e32 v18, 1.0, v18
	v_rcp_f32_e32 v18, v18
	s_nop 0
	v_mul_f32_e32 v18, v20, v18
	v_mul_f32_e32 v19, 0x3d372713, v21
	v_mul_f32_e32 v19, v21, v19
	v_fma_f32 v19, v21, v19, v21
	v_mul_f32_e32 v19, 0xbfcc422a, v19
	v_mul_f32_e32 v19, 0x3fb8aa3b, v19
	v_exp_f32_e32 v19, v19
	s_nop 0
	v_add_f32_e32 v19, 1.0, v19
	v_rcp_f32_e32 v19, v19
	s_nop 0
	v_mul_f32_e32 v19, v21, v19
	v_cvt_pk_bf16_f32 v25, v18, v19
	v_mul_f32_e32 v18, 0x3d372713, v14
	v_mul_f32_e32 v18, v14, v18
	v_fma_f32 v18, v14, v18, v14
	v_mul_f32_e32 v18, 0xbfcc422a, v18
	v_mul_f32_e32 v18, 0x3fb8aa3b, v18
	v_exp_f32_e32 v18, v18
	global_store_dwordx4 v[34:35], v[22:25], off offset:256
	v_add_f32_e32 v18, 1.0, v18
	v_rcp_f32_e32 v19, v18
	s_nop 0
	v_mul_f32_e32 v14, v14, v19
	v_mul_f32_e32 v18, 0x3d372713, v15
	v_mul_f32_e32 v18, v15, v18
	v_fma_f32 v18, v15, v18, v15
	v_mul_f32_e32 v18, 0xbfcc422a, v18
	v_mul_f32_e32 v18, 0x3fb8aa3b, v18
	v_exp_f32_e32 v18, v18
	s_nop 0
	v_add_f32_e32 v18, 1.0, v18
	v_rcp_f32_e32 v19, v18
	s_nop 0
	v_mul_f32_e32 v15, v15, v19
	v_cvt_pk_bf16_f32 v14, v14, v15
	v_mul_f32_e32 v15, 0x3d372713, v16
	v_mul_f32_e32 v15, v16, v15
	v_fma_f32 v15, v16, v15, v16
	v_mul_f32_e32 v15, 0xbfcc422a, v15
	v_mul_f32_e32 v15, 0x3fb8aa3b, v15
	v_exp_f32_e32 v15, v15
	s_nop 0
	v_add_f32_e32 v15, 1.0, v15
	v_rcp_f32_e32 v15, v15
	s_nop 0
	v_mul_f32_e32 v15, v16, v15
	v_mul_f32_e32 v16, 0x3d372713, v17
	v_mul_f32_e32 v16, v17, v16
; template <int ACT> __device__ __forceinline__ void store_tile_bf16(AccRef acc, bf16_t* dst, int ld, int row0, int col0) {
;     ...
;         for (int m = 0; m < 4; ++m) { bf16_t* rowp = dst + (size_t)(row0 + ai * 128 + m * 16) * ld + col0;
; #pragma unroll
;             for (int bj = 0; bj < 2; ++bj) { const f32x4 v0 = acc[ai][bj][m][0], v1 = acc[ai][bj][m][1];
;                 u32x4 w; w.x = cvt_pk_bf16(actf<ACT>(v0[0]), actf<ACT>(v0[1])); w.y = cvt_pk_bf16(actf<ACT>(v0[2]), actf<ACT>(v0[3]));
;                 w.z = cvt_pk_bf16(actf<ACT>(v1[0]), actf<ACT>(v1[1])); w.w = cvt_pk_bf16(actf<ACT>(v1[2]), actf<ACT>(v1[3]));
;                 *(u32x4*)(rowp + bj * 128) = w; } }
	v_fma_f32 v16, v17, v16, v17
	v_mul_f32_e32 v16, 0xbfcc422a, v16
	v_mul_f32_e32 v16, 0x3fb8aa3b, v16
	v_exp_f32_e32 v16, v16
	s_nop 0
	v_add_f32_e32 v16, 1.0, v16
	v_rcp_f32_e32 v16, v16
	s_nop 0
	v_mul_f32_e32 v16, v17, v16
	v_cvt_pk_bf16_f32 v15, v15, v16
	v_mul_f32_e32 v16, 0x3d372713, v10
	v_mul_f32_e32 v16, v10, v16
	v_fma_f32 v16, v10, v16, v10
	v_mul_f32_e32 v16, 0xbfcc422a, v16
	v_mul_f32_e32 v16, 0x3fb8aa3b, v16
	v_exp_f32_e32 v16, v16
	s_nop 0
	v_add_f32_e32 v16, 1.0, v16
	v_rcp_f32_e32 v17, v16
	s_nop 0
	v_mul_f32_e32 v10, v10, v17
	v_mul_f32_e32 v16, 0x3d372713, v11
	v_mul_f32_e32 v16, v11, v16
	v_fma_f32 v16, v11, v16, v11
	v_mul_f32_e32 v16, 0xbfcc422a, v16
	v_mul_f32_e32 v16, 0x3fb8aa3b, v16
	v_exp_f32_e32 v16, v16
	s_nop 0
	v_add_f32_e32 v16, 1.0, v16
	v_rcp_f32_e32 v17, v16
	s_nop 0
	v_mul_f32_e32 v11, v11, v17
	v_cvt_pk_bf16_f32 v16, v10, v11
	v_mul_f32_e32 v10, 0x3d372713, v12
	v_mul_f32_e32 v10, v12, v10
	v_fma_f32 v10, v12, v10, v12
	v_mul_f32_e32 v10, 0xbfcc422a, v10
	v_mul_f32_e32 v10, 0x3fb8aa3b, v10
	v_exp_f32_e32 v10, v10
	s_nop 0
	v_add_f32_e32 v10, 1.0, v10
	v_rcp_f32_e32 v10, v10
	s_nop 0
	v_mul_f32_e32 v10, v12, v10
	v_mul_f32_e32 v11, 0x3d372713, v13
	v_mul_f32_e32 v11, v13, v11
	v_fma_f32 v11, v13, v11, v13
	v_mul_f32_e32 v11, 0xbfcc422a, v11
	v_mul_f32_e32 v11, 0x3fb8aa3b, v11
	v_exp_f32_e32 v11, v11
	s_nop 0
	v_add_f32_e32 v11, 1.0, v11
	s_mov_b32 s0, 0xb0000
	v_rcp_f32_e32 v11, v11
	s_nop 0
	v_mul_f32_e32 v11, v13, v11
	v_cvt_pk_bf16_f32 v17, v10, v11
	v_add_co_u32_e32 v10, vcc, s0, v66
	s_nop 1
	v_addc_co_u32_e32 v11, vcc, 0, v67, vcc
	global_store_dwordx4 v[10:11], v[14:17], off
	v_mul_f32_e32 v10, 0x3d372713, v6
	v_mul_f32_e32 v10, v6, v10
	v_fma_f32 v10, v6, v10, v6
	v_mul_f32_e32 v10, 0xbfcc422a, v10
	v_mul_f32_e32 v10, 0x3fb8aa3b, v10
	v_exp_f32_e32 v10, v10
	s_nop 0
	v_add_f32_e32 v10, 1.0, v10
	v_rcp_f32_e32 v11, v10
	s_nop 0
	v_mul_f32_e32 v6, v6, v11
	v_mul_f32_e32 v10, 0x3d372713, v7
	v_mul_f32_e32 v10, v7, v10
	v_fma_f32 v10, v7, v10, v7
	v_mul_f32_e32 v10, 0xbfcc422a, v10
	v_mul_f32_e32 v10, 0x3fb8aa3b, v10
	v_exp_f32_e32 v10, v10
	s_nop 0
	v_add_f32_e32 v10, 1.0, v10
	v_rcp_f32_e32 v11, v10
	s_nop 0
	v_mul_f32_e32 v7, v7, v11
	v_cvt_pk_bf16_f32 v130, v6, v7
	v_mul_f32_e32 v6, 0x3d372713, v8
	v_mul_f32_e32 v6, v8, v6
	v_fma_f32 v6, v8, v6, v8
	v_mul_f32_e32 v6, 0xbfcc422a, v6
	v_mul_f32_e32 v6, 0x3fb8aa3b, v6
	v_exp_f32_e32 v6, v6
	s_nop 0
	v_add_f32_e32 v6, 1.0, v6
	v_rcp_f32_e32 v6, v6
	s_nop 0
	v_mul_f32_e32 v6, v8, v6
	v_mul_f32_e32 v7, 0x3d372713, v9
	v_mul_f32_e32 v7, v9, v7
	v_fma_f32 v7, v9, v7, v9
	v_mul_f32_e32 v7, 0xbfcc422a, v7
	v_mul_f32_e32 v7, 0x3fb8aa3b, v7
	v_exp_f32_e32 v7, v7
	s_nop 0
	v_add_f32_e32 v7, 1.0, v7
	v_rcp_f32_e32 v7, v7
	s_nop 0
	v_mul_f32_e32 v7, v9, v7
	v_cvt_pk_bf16_f32 v131, v6, v7
	v_mul_f32_e32 v6, 0x3d372713, v2
	v_mul_f32_e32 v6, v2, v6
	v_fma_f32 v6, v2, v6, v2
	v_mul_f32_e32 v6, 0xbfcc422a, v6
	v_mul_f32_e32 v6, 0x3fb8aa3b, v6
	v_exp_f32_e32 v6, v6
	s_nop 0
	v_add_f32_e32 v6, 1.0, v6
	v_rcp_f32_e32 v7, v6
	s_nop 0
	v_mul_f32_e32 v2, v2, v7
	v_mul_f32_e32 v6, 0x3d372713, v3
	v_mul_f32_e32 v6, v3, v6
	v_fma_f32 v6, v3, v6, v3
	v_mul_f32_e32 v6, 0xbfcc422a, v6
	v_mul_f32_e32 v6, 0x3fb8aa3b, v6
	v_exp_f32_e32 v6, v6
	s_nop 0
	v_add_f32_e32 v6, 1.0, v6
	v_rcp_f32_e32 v7, v6
	s_nop 0
	v_mul_f32_e32 v3, v3, v7
	v_cvt_pk_bf16_f32 v132, v2, v3
	v_mul_f32_e32 v2, 0x3d372713, v4
	v_mul_f32_e32 v3, 0x3d372713, v5
	v_mul_f32_e32 v2, v4, v2
	v_mul_f32_e32 v3, v5, v3
	v_fma_f32 v2, v4, v2, v4
	v_fma_f32 v3, v5, v3, v5
	v_mul_f32_e32 v2, 0xbfcc422a, v2
	v_mul_f32_e32 v3, 0xbfcc422a, v3
	v_mul_f32_e32 v2, 0x3fb8aa3b, v2
	v_mul_f32_e32 v3, 0x3fb8aa3b, v3
	v_exp_f32_e32 v2, v2
	v_exp_f32_e32 v3, v3
	s_nop 0
	v_pk_add_f32 v[2:3], v[2:3], 1.0 op_sel_hi:[1,0]
	s_nop 0
	v_rcp_f32_e32 v6, v2
	s_nop 0
	v_mul_f32_e32 v4, v4, v6
	v_rcp_f32_e32 v2, v3
	s_nop 0
	v_mul_f32_e32 v5, v5, v2
	s_branch .LBB0_3283

; #define PG8_STAGE(bufoff, gbase, voff) do { _Pragma("unroll") for (int _i = 0; _i < 2; ++_i) \
;         __builtin_amdgcn_global_load_lds((const unsigned*)((const char*)(gbase) + (voff)[_i]), (LAS unsigned*)(lds + (bufoff) + ldsw + _i * 8192), 16, 0, 0); } while (0)
; #define PG8_LDA(dst, b, h) do { _Pragma("unroll") for (int m = 0; m < 4; ++m) _Pragma("unroll") for (int k = 0; k < 2; ++k) dst[m][k] = *(const LAS bf16x8*)(lds + PG8_SA(b, h) + aoff + m * 2048 + k * 1024); } while (0)
; #define PG8_LDB(dst, b, h) do { _Pragma("unroll") for (int n = 0; n < 2; ++n) _Pragma("unroll") for (int k = 0; k < 2; ++k) dst[n][k] = *(const LAS bf16x8*)(lds + PG8_SB(b, h) + boff + n * 2048 + k * 1024); } while (0)
; #define PG8_MMA(ai, bj, At, Bt) do { __builtin_amdgcn_s_setprio(1); _Pragma("unroll") for (int m = 0; m < 4; ++m) _Pragma("unroll") for (int n = 0; n < 2; ++n) _Pragma("unroll") for (int k = 0; k < 2; ++k) \
;         acc[ai][bj][m][n] = __builtin_amdgcn_mfma_f32_16x16x32_bf16(Bt[n][k], At[m][k], acc[ai][bj][m][n], 0, 0, 0); __builtin_amdgcn_s_setprio(0); } while (0)
; #define PG8_WAIT_V(n) asm volatile("s_waitcnt vmcnt(" #n ")" ::: "memory")
; #define PG8_WAIT_L(n) asm volatile("s_waitcnt lgkmcnt(" #n ")" ::: "memory")
; #define PG8_BAR __builtin_amdgcn_s_barrier()
; #define PG8_SCHED __builtin_amdgcn_sched_barrier(0)
; template <class Epi, class GT>
; __device__ __forceinline__ void gemm_phase(LAS unsigned char* lds, const GT g, const StaticOrder& S, const Epi& E) {
;     ...
;             PG8_LDB(B0, 0, 0); PG8_SCHED; PG8_LDA(At, 0, 0); PG8_STAGE(PG8_SA(1, 1), a1 + hstepA, voffA);
;             PG8_WAIT_L(8); PG8_BAR; PG8_WAIT_L(0); PG8_MMA(0, 0, At, B0); PG8_BAR; PG8_SCHED;
;             PG8_LDB(B1, 0, 1); PG8_STAGE(PG8_SB(0, 0), b2, voffB);
;             PG8_BAR; PG8_WAIT_L(0); PG8_MMA(0, 1, At, B1); PG8_BAR;
;             PG8_LDA(At, 0, 1); PG8_STAGE(PG8_SA(0, 0), a2, voffA);
;             PG8_BAR; PG8_WAIT_L(0); PG8_MMA(1, 0, At, B0); PG8_BAR; PG8_SCHED;
;             PG8_STAGE(PG8_SB(0, 1), b2 + hstepB, voffB);
;             PG8_WAIT_V(6); PG8_BAR; PG8_MMA(1, 1, At, B1); PG8_BAR;
;             PG8_LDB(B0, 1, 0); PG8_SCHED; PG8_LDA(At, 1, 0); PG8_STAGE(PG8_SA(0, 1), a2 + hstepA, voffA);
;             PG8_WAIT_L(8); PG8_BAR; PG8_WAIT_L(0); PG8_MMA(0, 0, At, B0); PG8_BAR; PG8_SCHED;
.LBB0_3435:
	s_add_u32 s14, s64, s10
	s_addc_u32 s15, s65, 0
	s_add_u32 s11, s14, 0x100
	s_addc_u32 s16, s15, 0
	s_and_b64 s[12:13], s[68:69], exec
	s_cselect_b32 s75, s4, s16
	s_cselect_b32 s74, s5, s11
	s_add_u32 s10, s62, s10
	s_addc_u32 s11, s63, 0
	s_add_u32 s12, s10, 0x100
	s_addc_u32 s13, s11, 0
	s_and_b64 s[10:11], s[68:69], exec
	s_cselect_b32 s77, s8, s13
	s_cselect_b32 s76, s9, s12
	s_add_u32 s78, s14, 0x80080
	s_addc_u32 s79, s15, 0
	s_add_i32 s19, s90, s81
	s_add_i32 m0, s83, 0xc000
	s_add_i32 s20, s83, 0xe000
	s_add_i32 s18, s19, 0x2000
	s_add_u32 s72, s76, 0x10000
	s_addc_u32 s73, s77, 0
	s_add_i32 s17, s91, s81
	s_add_i32 s16, s17, 0x2000
	s_add_i32 s15, 0, 0x18000
	ds_read_b128 v[2:5], v219
	ds_read_b128 v[26:29], v219 offset:1024
	ds_read_b128 v[30:33], v219 offset:2048
	ds_read_b128 v[34:37], v219 offset:3072
	s_add_u32 s70, s74, 0x80000
	s_addc_u32 s71, s75, 0
	s_add_i32 s14, s15, s81
	s_add_i32 s13, 0, 0x1c000
	s_add_i32 s12, s14, 0x2000
	s_add_u32 s68, s76, 0x10080
	s_addc_u32 s69, s77, 0
	s_add_i32 s11, s13, s81
	s_add_i32 s10, s11, 0x2000
	v_lshl_add_u64 v[192:193], s[78:79], 0, v[184:185]
	ds_read_b128 v[38:41], v220
	ds_read_b128 v[46:49], v220 offset:1024
	ds_read_b128 v[66:69], v220 offset:2048
	ds_read_b128 v[86:89], v220 offset:3072
	ds_read_b128 v[106:109], v220 offset:4096
	ds_read_b128 v[126:129], v220 offset:5120
	ds_read_b128 v[146:149], v220 offset:6144
	ds_read_b128 v[166:169], v220 offset:7168
	global_load_lds_dwordx4 v[192:193], off
	v_lshl_add_u64 v[192:193], s[78:79], 0, v[180:181]
	s_mov_b32 m0, s20
	s_nop 0
	global_load_lds_dwordx4 v[192:193], off
	s_waitcnt lgkmcnt(8)
	s_barrier
	s_waitcnt lgkmcnt(0)
	s_setprio 1
	s_waitcnt lgkmcnt(0)
	v_mfma_f32_16x16x32_bf16 v[174:177], v[2:5], v[38:41], v[174:177]
	v_mfma_f32_16x16x32_bf16 v[170:173], v[30:33], v[38:41], v[170:173]
	v_mfma_f32_16x16x32_bf16 v[162:165], v[2:5], v[66:69], v[162:165]
	v_mfma_f32_16x16x32_bf16 v[158:161], v[30:33], v[66:69], v[158:161]
	v_mfma_f32_16x16x32_bf16 v[142:145], v[2:5], v[106:109], v[142:145]
	v_mfma_f32_16x16x32_bf16 v[138:141], v[30:33], v[106:109], v[138:141]
	v_mfma_f32_16x16x32_bf16 v[122:125], v[2:5], v[146:149], v[122:125]
	v_mfma_f32_16x16x32_bf16 v[118:121], v[30:33], v[146:149], v[118:121]
	v_mfma_f32_16x16x32_bf16 v[174:177], v[26:29], v[46:49], v[174:177]
	v_mfma_f32_16x16x32_bf16 v[170:173], v[34:37], v[46:49], v[170:173]
	v_mfma_f32_16x16x32_bf16 v[162:165], v[26:29], v[86:89], v[162:165]
	v_mfma_f32_16x16x32_bf16 v[158:161], v[34:37], v[86:89], v[158:161]
	v_mfma_f32_16x16x32_bf16 v[142:145], v[26:29], v[126:129], v[142:145]
	v_mfma_f32_16x16x32_bf16 v[138:141], v[34:37], v[126:129], v[138:141]
	v_mfma_f32_16x16x32_bf16 v[122:125], v[26:29], v[166:169], v[122:125]
	v_mfma_f32_16x16x32_bf16 v[118:121], v[34:37], v[166:169], v[118:121]
	s_setprio 0
	s_barrier
	s_mov_b32 m0, s19
	v_lshl_add_u64 v[224:225], s[76:77], 0, v[182:183]
	ds_read_b128 v[192:195], v221
	ds_read_b128 v[196:199], v221 offset:1024
	ds_read_b128 v[200:203], v221 offset:2048
	ds_read_b128 v[204:207], v221 offset:3072
	global_load_lds_dwordx4 v[224:225], off
	v_lshl_add_u64 v[226:227], s[76:77], 0, v[178:179]
	s_mov_b32 m0, s18
	s_nop 0
	global_load_lds_dwordx4 v[226:227], off
	s_barrier
	s_waitcnt lgkmcnt(0)
	s_setprio 1
	s_waitcnt lgkmcnt(0)
	v_mfma_f32_16x16x32_bf16 v[42:45], v[192:195], v[38:41], v[42:45]
	v_mfma_f32_16x16x32_bf16 v[22:25], v[200:203], v[38:41], v[22:25]
	v_mfma_f32_16x16x32_bf16 v[42:45], v[196:199], v[46:49], v[42:45]
	v_mfma_f32_16x16x32_bf16 v[22:25], v[204:207], v[46:49], v[22:25]
	v_mfma_f32_16x16x32_bf16 v[38:41], v[192:195], v[66:69], v[154:157]
	v_mfma_f32_16x16x32_bf16 v[46:49], v[200:203], v[66:69], v[150:153]
	v_mfma_f32_16x16x32_bf16 v[110:113], v[200:203], v[146:149], v[110:113]
	v_mfma_f32_16x16x32_bf16 v[38:41], v[196:199], v[86:89], v[38:41]
	v_mfma_f32_16x16x32_bf16 v[46:49], v[204:207], v[86:89], v[46:49]
	v_mfma_f32_16x16x32_bf16 v[66:69], v[192:195], v[106:109], v[134:137]
	v_mfma_f32_16x16x32_bf16 v[86:89], v[200:203], v[106:109], v[130:133]
	v_mfma_f32_16x16x32_bf16 v[106:109], v[192:195], v[146:149], v[114:117]
	v_mfma_f32_16x16x32_bf16 v[110:113], v[204:207], v[166:169], v[110:113]
	v_mfma_f32_16x16x32_bf16 v[66:69], v[196:199], v[126:129], v[66:69]
	v_mfma_f32_16x16x32_bf16 v[86:89], v[204:207], v[126:129], v[86:89]
	v_mfma_f32_16x16x32_bf16 v[106:109], v[196:199], v[166:169], v[106:109]
	s_setprio 0
	s_mov_b32 m0, s83
	v_lshl_add_u64 v[228:229], s[74:75], 0, v[184:185]
	s_barrier
	ds_read_b128 v[114:117], v220 offset:16384
	ds_read_b128 v[126:129], v220 offset:17408
	ds_read_b128 v[130:133], v220 offset:18432
	ds_read_b128 v[134:137], v220 offset:19456
	ds_read_b128 v[146:149], v220 offset:20480
	ds_read_b128 v[150:153], v220 offset:21504
	ds_read_b128 v[154:157], v220 offset:22528
	ds_read_b128 v[166:169], v220 offset:23552
	global_load_lds_dwordx4 v[228:229], off
	v_lshl_add_u64 v[230:231], s[74:75], 0, v[180:181]
	s_mov_b32 m0, s84
	s_nop 0
	global_load_lds_dwordx4 v[230:231], off
	s_barrier
	s_waitcnt lgkmcnt(0)
	s_setprio 1
	s_waitcnt lgkmcnt(0)
	v_mfma_f32_16x16x32_bf16 v[102:105], v[2:5], v[114:117], v[102:105]
	v_mfma_f32_16x16x32_bf16 v[98:101], v[30:33], v[114:117], v[98:101]
	v_mfma_f32_16x16x32_bf16 v[82:85], v[2:5], v[130:133], v[82:85]
	v_mfma_f32_16x16x32_bf16 v[78:81], v[30:33], v[130:133], v[78:81]
	v_mfma_f32_16x16x32_bf16 v[62:65], v[2:5], v[146:149], v[62:65]
	v_mfma_f32_16x16x32_bf16 v[58:61], v[30:33], v[146:149], v[58:61]
	v_mfma_f32_16x16x32_bf16 v[14:17], v[30:33], v[154:157], v[14:17]
	v_mfma_f32_16x16x32_bf16 v[102:105], v[26:29], v[126:129], v[102:105]
	v_mfma_f32_16x16x32_bf16 v[98:101], v[34:37], v[126:129], v[98:101]
	v_mfma_f32_16x16x32_bf16 v[82:85], v[26:29], v[134:137], v[82:85]
	v_mfma_f32_16x16x32_bf16 v[78:81], v[34:37], v[134:137], v[78:81]
	v_mfma_f32_16x16x32_bf16 v[62:65], v[26:29], v[150:153], v[62:65]
	v_mfma_f32_16x16x32_bf16 v[58:61], v[34:37], v[150:153], v[58:61]
	v_mfma_f32_16x16x32_bf16 v[2:5], v[2:5], v[154:157], v[18:21]
	v_mfma_f32_16x16x32_bf16 v[14:17], v[34:37], v[166:169], v[14:17]
	v_mfma_f32_16x16x32_bf16 v[2:5], v[26:29], v[166:169], v[2:5]
	s_setprio 0
	s_barrier
; #define PG8_STAGE(bufoff, gbase, voff) do { _Pragma("unroll") for (int _i = 0; _i < 2; ++_i) \
;         __builtin_amdgcn_global_load_lds((const unsigned*)((const char*)(gbase) + (voff)[_i]), (LAS unsigned*)(lds + (bufoff) + ldsw + _i * 8192), 16, 0, 0); } while (0)
; #define PG8_LDA(dst, b, h) do { _Pragma("unroll") for (int m = 0; m < 4; ++m) _Pragma("unroll") for (int k = 0; k < 2; ++k) dst[m][k] = *(const LAS bf16x8*)(lds + PG8_SA(b, h) + aoff + m * 2048 + k * 1024); } while (0)
; #define PG8_LDB(dst, b, h) do { _Pragma("unroll") for (int n = 0; n < 2; ++n) _Pragma("unroll") for (int k = 0; k < 2; ++k) dst[n][k] = *(const LAS bf16x8*)(lds + PG8_SB(b, h) + boff + n * 2048 + k * 1024); } while (0)
; #define PG8_MMA(ai, bj, At, Bt) do { __builtin_amdgcn_s_setprio(1); _Pragma("unroll") for (int m = 0; m < 4; ++m) _Pragma("unroll") for (int n = 0; n < 2; ++n) _Pragma("unroll") for (int k = 0; k < 2; ++k) \
;         acc[ai][bj][m][n] = __builtin_amdgcn_mfma_f32_16x16x32_bf16(Bt[n][k], At[m][k], acc[ai][bj][m][n], 0, 0, 0); __builtin_amdgcn_s_setprio(0); } while (0)
; #define PG8_WAIT_V(n) asm volatile("s_waitcnt vmcnt(" #n ")" ::: "memory")
; #define PG8_WAIT_L(n) asm volatile("s_waitcnt lgkmcnt(" #n ")" ::: "memory")
; #define PG8_BAR __builtin_amdgcn_s_barrier()
; #define PG8_SCHED __builtin_amdgcn_sched_barrier(0)
; template <class Epi, class GT>
; __device__ __forceinline__ void gemm_phase(LAS unsigned char* lds, const GT g, const StaticOrder& S, const Epi& E) {
;     ...
;             PG8_BAR; PG8_WAIT_L(0); PG8_MMA(1, 0, At, B0); PG8_BAR; PG8_SCHED;
;             PG8_STAGE(PG8_SB(0, 1), b2 + hstepB, voffB);
;             PG8_WAIT_V(6); PG8_BAR; PG8_MMA(1, 1, At, B1); PG8_BAR;
;             PG8_LDB(B0, 1, 0); PG8_SCHED; PG8_LDA(At, 1, 0); PG8_STAGE(PG8_SA(0, 1), a2 + hstepA, voffA);
;             PG8_WAIT_L(8); PG8_BAR; PG8_WAIT_L(0); PG8_MMA(0, 0, At, B0); PG8_BAR; PG8_SCHED;
;             PG8_LDB(B1, 1, 1); PG8_STAGE(PG8_SB(1, 0), b3, voffB);
;             PG8_BAR; PG8_WAIT_L(0); PG8_MMA(0, 1, At, B1); PG8_BAR;
;             PG8_LDA(At, 1, 1); PG8_STAGE(PG8_SA(1, 0), a3, voffA);
;             PG8_BAR; PG8_WAIT_L(0); PG8_MMA(1, 0, At, B0); PG8_BAR; PG8_SCHED;
	s_mov_b32 m0, s17
	v_lshl_add_u64 v[18:19], s[72:73], 0, v[182:183]
	global_load_lds_dwordx4 v[18:19], off
	v_lshl_add_u64 v[18:19], s[72:73], 0, v[178:179]
	s_mov_b32 m0, s16
	s_nop 0
	global_load_lds_dwordx4 v[18:19], off
	s_waitcnt vmcnt(6)
	s_barrier
	s_setprio 1
	v_mfma_f32_16x16x32_bf16 v[18:21], v[192:195], v[114:117], v[94:97]
	v_mfma_f32_16x16x32_bf16 v[26:29], v[196:199], v[126:129], v[18:21]
	v_mfma_f32_16x16x32_bf16 v[18:21], v[200:203], v[114:117], v[90:93]
	v_mfma_f32_16x16x32_bf16 v[30:33], v[204:207], v[126:129], v[18:21]
	v_mfma_f32_16x16x32_bf16 v[18:21], v[192:195], v[130:133], v[74:77]
	v_mfma_f32_16x16x32_bf16 v[34:37], v[196:199], v[134:137], v[18:21]
	v_mfma_f32_16x16x32_bf16 v[18:21], v[200:203], v[130:133], v[70:73]
	v_mfma_f32_16x16x32_bf16 v[70:73], v[204:207], v[134:137], v[18:21]
	v_mfma_f32_16x16x32_bf16 v[18:21], v[192:195], v[146:149], v[54:57]
	v_mfma_f32_16x16x32_bf16 v[54:57], v[196:199], v[150:153], v[18:21]
	v_mfma_f32_16x16x32_bf16 v[18:21], v[200:203], v[146:149], v[50:53]
	v_mfma_f32_16x16x32_bf16 v[10:13], v[192:195], v[154:157], v[10:13]
	v_mfma_f32_16x16x32_bf16 v[6:9], v[200:203], v[154:157], v[6:9]
	v_mfma_f32_16x16x32_bf16 v[50:53], v[204:207], v[150:153], v[18:21]
	v_mfma_f32_16x16x32_bf16 v[10:13], v[196:199], v[166:169], v[10:13]
	v_mfma_f32_16x16x32_bf16 v[6:9], v[204:207], v[166:169], v[6:9]
	s_setprio 0
	v_add_u32_e32 v94, s15, v217
	s_barrier
	ds_read_b128 v[18:21], v94
	ds_read_b128 v[74:77], v94 offset:1024
	ds_read_b128 v[90:93], v94 offset:2048
	ds_read_b128 v[94:97], v94 offset:3072
	s_mov_b32 m0, s85
	v_lshl_add_u64 v[150:151], s[70:71], 0, v[184:185]
	ds_read_b128 v[114:117], v220 offset:32768
	ds_read_b128 v[126:129], v220 offset:33792
	ds_read_b128 v[130:133], v220 offset:34816
	ds_read_b128 v[134:137], v220 offset:35840
	ds_read_b128 v[146:149], v220 offset:36864
	ds_read_b128 v[166:169], v220 offset:37888
	ds_read_b128 v[192:195], v220 offset:38912
	ds_read_b128 v[196:199], v220 offset:39936
	global_load_lds_dwordx4 v[150:151], off
	v_lshl_add_u64 v[150:151], s[70:71], 0, v[180:181]
	s_mov_b32 m0, s86
	s_nop 0
	global_load_lds_dwordx4 v[150:151], off
	s_waitcnt lgkmcnt(8)
	s_barrier
	s_waitcnt lgkmcnt(0)
	s_setprio 1
	s_waitcnt lgkmcnt(0)
	v_mfma_f32_16x16x32_bf16 v[150:153], v[18:21], v[114:117], v[174:177]
	v_mfma_f32_16x16x32_bf16 v[174:177], v[74:77], v[126:129], v[150:153]
	v_mfma_f32_16x16x32_bf16 v[150:153], v[90:93], v[114:117], v[170:173]
	v_mfma_f32_16x16x32_bf16 v[170:173], v[94:97], v[126:129], v[150:153]
	v_mfma_f32_16x16x32_bf16 v[150:153], v[18:21], v[130:133], v[162:165]
	v_mfma_f32_16x16x32_bf16 v[162:165], v[74:77], v[134:137], v[150:153]
	v_mfma_f32_16x16x32_bf16 v[150:153], v[90:93], v[130:133], v[158:161]
	v_mfma_f32_16x16x32_bf16 v[142:145], v[18:21], v[146:149], v[142:145]
	v_mfma_f32_16x16x32_bf16 v[138:141], v[90:93], v[146:149], v[138:141]
	v_mfma_f32_16x16x32_bf16 v[122:125], v[18:21], v[192:195], v[122:125]
	v_mfma_f32_16x16x32_bf16 v[118:121], v[90:93], v[192:195], v[118:121]
	v_mfma_f32_16x16x32_bf16 v[158:161], v[94:97], v[134:137], v[150:153]
	v_mfma_f32_16x16x32_bf16 v[142:145], v[74:77], v[166:169], v[142:145]
	v_mfma_f32_16x16x32_bf16 v[138:141], v[94:97], v[166:169], v[138:141]
	v_mfma_f32_16x16x32_bf16 v[122:125], v[74:77], v[196:199], v[122:125]
	v_mfma_f32_16x16x32_bf16 v[118:121], v[94:97], v[196:199], v[118:121]
	s_setprio 0
	s_barrier
	v_add_u32_e32 v150, s13, v217
	s_mov_b32 m0, s14
	ds_read_b128 v[200:203], v150
	ds_read_b128 v[204:207], v150 offset:1024
	ds_read_b128 v[208:211], v150 offset:2048
	ds_read_b128 v[212:215], v150 offset:3072
	v_lshl_add_u64 v[150:151], v[224:225], 0, s[52:53]
	global_load_lds_dwordx4 v[150:151], off
	v_lshl_add_u64 v[150:151], v[226:227], 0, s[52:53]
	s_mov_b32 m0, s12
	s_nop 0
	global_load_lds_dwordx4 v[150:151], off
	s_barrier
	s_waitcnt lgkmcnt(0)
	s_setprio 1
	s_waitcnt lgkmcnt(0)
	v_mfma_f32_16x16x32_bf16 v[38:41], v[200:203], v[130:133], v[38:41]
	v_mfma_f32_16x16x32_bf16 v[154:157], v[204:207], v[134:137], v[38:41]
	v_mfma_f32_16x16x32_bf16 v[38:41], v[208:211], v[130:133], v[46:49]
	v_mfma_f32_16x16x32_bf16 v[150:153], v[212:215], v[134:137], v[38:41]
	v_mfma_f32_16x16x32_bf16 v[38:41], v[200:203], v[146:149], v[66:69]
	v_mfma_f32_16x16x32_bf16 v[134:137], v[204:207], v[166:169], v[38:41]
	v_mfma_f32_16x16x32_bf16 v[38:41], v[208:211], v[146:149], v[86:89]
	v_mfma_f32_16x16x32_bf16 v[130:133], v[212:215], v[166:169], v[38:41]
	v_mfma_f32_16x16x32_bf16 v[38:41], v[200:203], v[192:195], v[106:109]
	v_mfma_f32_16x16x32_bf16 v[42:45], v[200:203], v[114:117], v[42:45]
	v_mfma_f32_16x16x32_bf16 v[22:25], v[208:211], v[114:117], v[22:25]
	v_mfma_f32_16x16x32_bf16 v[114:117], v[204:207], v[196:199], v[38:41]
	v_mfma_f32_16x16x32_bf16 v[38:41], v[208:211], v[192:195], v[110:113]
	v_mfma_f32_16x16x32_bf16 v[42:45], v[204:207], v[126:129], v[42:45]
	v_mfma_f32_16x16x32_bf16 v[22:25], v[212:215], v[126:129], v[22:25]
	v_mfma_f32_16x16x32_bf16 v[110:113], v[212:215], v[196:199], v[38:41]
	s_setprio 0
	s_mov_b32 m0, s88
	v_lshl_add_u64 v[192:193], v[228:229], 0, s[52:53]
	s_barrier
	s_nop 0
	ds_read_b128 v[38:41], v220 offset:49152
	ds_read_b128 v[46:49], v220 offset:50176
	ds_read_b128 v[66:69], v220 offset:51200
	ds_read_b128 v[86:89], v220 offset:52224
	ds_read_b128 v[106:109], v220 offset:53248
	ds_read_b128 v[126:129], v220 offset:54272
	ds_read_b128 v[146:149], v220 offset:55296
	ds_read_b128 v[166:169], v220 offset:56320
	global_load_lds_dwordx4 v[192:193], off
	v_lshl_add_u64 v[192:193], v[230:231], 0, s[52:53]
	s_mov_b32 m0, s89
	s_nop 0
	global_load_lds_dwordx4 v[192:193], off
	s_barrier
; #define PG8_STAGE(bufoff, gbase, voff) do { _Pragma("unroll") for (int _i = 0; _i < 2; ++_i) \
;         __builtin_amdgcn_global_load_lds((const unsigned*)((const char*)(gbase) + (voff)[_i]), (LAS unsigned*)(lds + (bufoff) + ldsw + _i * 8192), 16, 0, 0); } while (0)
; #define PG8_MMA(ai, bj, At, Bt) do { __builtin_amdgcn_s_setprio(1); _Pragma("unroll") for (int m = 0; m < 4; ++m) _Pragma("unroll") for (int n = 0; n < 2; ++n) _Pragma("unroll") for (int k = 0; k < 2; ++k) \
;         acc[ai][bj][m][n] = __builtin_amdgcn_mfma_f32_16x16x32_bf16(Bt[n][k], At[m][k], acc[ai][bj][m][n], 0, 0, 0); __builtin_amdgcn_s_setprio(0); } while (0)
; #define PG8_WAIT_V(n) asm volatile("s_waitcnt vmcnt(" #n ")" ::: "memory")
; #define PG8_WAIT_L(n) asm volatile("s_waitcnt lgkmcnt(" #n ")" ::: "memory")
; #define PG8_BAR __builtin_amdgcn_s_barrier()
; #define PG8_SCHED __builtin_amdgcn_sched_barrier(0)
; template <class Epi, class GT>
; __device__ __forceinline__ void gemm_phase(LAS unsigned char* lds, const GT g, const StaticOrder& S, const Epi& E) {
;     ...
;             PG8_BAR; PG8_WAIT_L(0); PG8_MMA(1, 0, At, B0); PG8_BAR; PG8_SCHED;
;             PG8_STAGE(PG8_SB(1, 1), b3 + hstepB, voffB);
;             PG8_WAIT_V(6); PG8_BAR; PG8_MMA(1, 1, At, B1); PG8_BAR;
	s_waitcnt lgkmcnt(0)
	s_setprio 1
	s_waitcnt lgkmcnt(0)
	v_mfma_f32_16x16x32_bf16 v[2:5], v[18:21], v[146:149], v[2:5]
	v_mfma_f32_16x16x32_bf16 v[102:105], v[18:21], v[38:41], v[102:105]
	v_mfma_f32_16x16x32_bf16 v[98:101], v[90:93], v[38:41], v[98:101]
	v_mfma_f32_16x16x32_bf16 v[82:85], v[18:21], v[66:69], v[82:85]
	v_mfma_f32_16x16x32_bf16 v[78:81], v[90:93], v[66:69], v[78:81]
	v_mfma_f32_16x16x32_bf16 v[62:65], v[18:21], v[106:109], v[62:65]
	v_mfma_f32_16x16x32_bf16 v[58:61], v[90:93], v[106:109], v[58:61]
	v_mfma_f32_16x16x32_bf16 v[18:21], v[74:77], v[166:169], v[2:5]
	v_mfma_f32_16x16x32_bf16 v[2:5], v[90:93], v[146:149], v[14:17]
	v_mfma_f32_16x16x32_bf16 v[102:105], v[74:77], v[46:49], v[102:105]
	v_mfma_f32_16x16x32_bf16 v[98:101], v[94:97], v[46:49], v[98:101]
	v_mfma_f32_16x16x32_bf16 v[82:85], v[74:77], v[86:89], v[82:85]
	v_mfma_f32_16x16x32_bf16 v[78:81], v[94:97], v[86:89], v[78:81]
	v_mfma_f32_16x16x32_bf16 v[62:65], v[74:77], v[126:129], v[62:65]
	v_mfma_f32_16x16x32_bf16 v[58:61], v[94:97], v[126:129], v[58:61]
	v_mfma_f32_16x16x32_bf16 v[14:17], v[94:97], v[166:169], v[2:5]
	s_setprio 0
	s_barrier
	s_mov_b32 m0, s11
	v_lshl_add_u64 v[2:3], s[68:69], 0, v[182:183]
	global_load_lds_dwordx4 v[2:3], off
	v_lshl_add_u64 v[2:3], s[68:69], 0, v[178:179]
	s_mov_b32 m0, s10
	s_nop 0
	global_load_lds_dwordx4 v[2:3], off
	s_waitcnt vmcnt(6)
	s_barrier
	s_setprio 1
	v_mfma_f32_16x16x32_bf16 v[2:5], v[200:203], v[38:41], v[26:29]
	v_mfma_f32_16x16x32_bf16 v[94:97], v[204:207], v[46:49], v[2:5]
	v_mfma_f32_16x16x32_bf16 v[2:5], v[208:211], v[38:41], v[30:33]
	v_mfma_f32_16x16x32_bf16 v[90:93], v[212:215], v[46:49], v[2:5]
	v_mfma_f32_16x16x32_bf16 v[2:5], v[200:203], v[66:69], v[34:37]
	v_mfma_f32_16x16x32_bf16 v[74:77], v[204:207], v[86:89], v[2:5]
	v_mfma_f32_16x16x32_bf16 v[2:5], v[208:211], v[66:69], v[70:73]
	v_mfma_f32_16x16x32_bf16 v[70:73], v[212:215], v[86:89], v[2:5]
	v_mfma_f32_16x16x32_bf16 v[2:5], v[200:203], v[106:109], v[54:57]
	v_mfma_f32_16x16x32_bf16 v[54:57], v[204:207], v[126:129], v[2:5]
	v_mfma_f32_16x16x32_bf16 v[2:5], v[208:211], v[106:109], v[50:53]
	v_mfma_f32_16x16x32_bf16 v[50:53], v[212:215], v[126:129], v[2:5]
	v_mfma_f32_16x16x32_bf16 v[2:5], v[200:203], v[146:149], v[10:13]
	v_mfma_f32_16x16x32_bf16 v[10:13], v[204:207], v[166:169], v[2:5]
	v_mfma_f32_16x16x32_bf16 v[2:5], v[208:211], v[146:149], v[6:9]
	v_mfma_f32_16x16x32_bf16 v[6:9], v[212:215], v[166:169], v[2:5]
	s_setprio 0
	s_movk_i32 s10, 0x100
	s_andn2_b64 vcc, exec, s[66:67]
	s_mov_b64 s[68:69], -1
	s_mov_b64 s[66:67], 0
	s_barrier
	s_cbranch_vccz .LBB0_3435
	s_ashr_i32 s62, s3, 4
	s_lshl_b32 s3, s3, 7
	s_and_b32 s3, s3, 0x780
	v_or_b32_e32 v46, s3, v218
	v_lshl_or_b32 v2, s62, 12, v46
	v_ashrrev_i32_e32 v3, 31, v2
	v_lshl_add_u64 v[2:3], v[2:3], 2, s[48:49]
	s_mov_b64 s[4:5], 0x2000
	s_movk_i32 s3, 0x2000
	global_load_dwordx4 v[26:29], v[2:3], off offset:16
	global_load_dwordx4 v[34:37], v[2:3], off
	v_lshl_add_u64 v[30:31], v[2:3], 0, s[4:5]
	v_add_co_u32_e32 v2, vcc, s3, v2
	v_lshl_or_b32 v4, s62, 11, v46
	s_nop 0
	v_addc_co_u32_e32 v3, vcc, 0, v3, vcc
	global_load_dwordx4 v[38:41], v[2:3], off
	global_load_dwordx4 v[30:33], v[30:31], off offset:16
	v_lshl_add_u32 v2, s40, 8, v216
	v_ashrrev_i32_e32 v5, 31, v4
	v_lshlrev_b32_e32 v186, 1, v46
	v_ashrrev_i32_e32 v3, 31, v2
	v_lshl_add_u64 v[210:211], v[4:5], 2, s[50:51]
	v_lshl_add_u64 v[4:5], s[42:43], 0, v[186:187]
	v_lshlrev_b64 v[200:201], 12, v[2:3]
	v_lshl_add_u64 v[46:47], v[4:5], 0, v[200:201]
	global_load_dwordx4 v[166:169], v[46:47], off
	v_or_b32_e32 v46, 16, v2
	v_ashrrev_i32_e32 v47, 31, v46
	v_lshlrev_b64 v[198:199], 12, v[46:47]
	v_lshl_add_u64 v[46:47], v[4:5], 0, v[198:199]
	global_load_dwordx4 v[146:149], v[46:47], off
	v_or_b32_e32 v46, 32, v2
	v_ashrrev_i32_e32 v47, 31, v46
	v_lshlrev_b64 v[196:197], 12, v[46:47]
	v_lshl_add_u64 v[46:47], v[4:5], 0, v[196:197]
	global_load_dwordx4 v[126:129], v[46:47], off
	v_or_b32_e32 v46, 48, v2
	v_ashrrev_i32_e32 v47, 31, v46
	v_lshlrev_b64 v[194:195], 12, v[46:47]
	s_mov_b64 s[4:5], 0x80000
	v_lshl_add_u64 v[46:47], v[4:5], 0, v[194:195]
	v_lshl_add_u64 v[192:193], v[200:201], 0, s[4:5]
	global_load_dwordx4 v[106:109], v[46:47], off
	v_lshl_add_u64 v[46:47], v[4:5], 0, v[192:193]
	global_load_dwordx4 v[86:89], v[46:47], off
	v_add_u32_e32 v46, 0x90, v2
	v_ashrrev_i32_e32 v47, 31, v46
	v_lshlrev_b64 v[46:47], 12, v[46:47]
	v_lshl_add_u64 v[46:47], v[4:5], 0, v[46:47]
	global_load_dwordx4 v[66:69], v[46:47], off
	v_add_u32_e32 v46, 0xa0, v2
	v_add_u32_e32 v2, 0xb0, v2
	v_ashrrev_i32_e32 v47, 31, v46
	v_ashrrev_i32_e32 v3, 31, v2
	v_lshlrev_b64 v[46:47], 12, v[46:47]
	v_lshlrev_b64 v[2:3], 12, v[2:3]
	v_lshl_add_u64 v[46:47], v[4:5], 0, v[46:47]
	v_lshl_add_u64 v[2:3], v[4:5], 0, v[2:3]
	global_load_dwordx4 v[46:49], v[46:47], off
	s_ashr_i32 s63, s62, 31
	global_load_dwordx4 v[2:5], v[2:3], off
	s_lshl_b64 s[62:63], s[62:63], 11
	s_mov_b32 s3, s54
	s_mov_b64 s[64:65], s[58:59]
	s_waitcnt vmcnt(0)
	v_add_f32_e32 v174, v174, v34
	v_mul_f32_e32 v174, 0xbfb8aa3b, v174
	v_exp_f32_e32 v214, v174
	v_add_f32_e32 v162, v162, v34
	v_mul_f32_e32 v162, 0xbfb8aa3b, v162
	v_add_f32_e32 v142, v142, v34
	v_add_f32_e32 v42, v42, v38
	v_mul_f32_e32 v42, 0xbfb8aa3b, v42
	v_exp_f32_e32 v206, v42
	v_add_f32_e32 v42, v175, v35
	v_add_f32_e32 v22, v22, v30
	v_mul_f32_e32 v42, 0xbfb8aa3b, v42
	v_mul_f32_e32 v22, 0xbfb8aa3b, v22
	v_exp_f32_e32 v215, v42
	v_add_f32_e32 v42, v43, v39
	v_exp_f32_e32 v202, v22
	v_add_f32_e32 v22, v171, v27
	v_mul_f32_e32 v42, 0xbfb8aa3b, v42
	v_mul_f32_e32 v22, 0xbfb8aa3b, v22
	v_exp_f32_e32 v207, v42
	v_add_f32_e32 v42, v176, v36
	v_exp_f32_e32 v209, v22
	v_add_f32_e32 v22, v23, v31
	v_mul_f32_e32 v42, 0xbfb8aa3b, v42
	v_mul_f32_e32 v22, 0xbfb8aa3b, v22
	v_exp_f32_e32 v212, v42
	v_add_f32_e32 v42, v44, v40
	v_exp_f32_e32 v203, v22
	v_add_f32_e32 v22, v172, v28
	v_mul_f32_e32 v42, 0xbfb8aa3b, v42
	v_mul_f32_e32 v22, 0xbfb8aa3b, v22
	v_exp_f32_e32 v204, v42
	v_add_f32_e32 v42, v177, v37
	v_exp_f32_e32 v174, v22
	v_add_f32_e32 v22, v24, v32
	v_mul_f32_e32 v42, 0xbfb8aa3b, v42
	v_mul_f32_e32 v22, 0xbfb8aa3b, v22
	v_exp_f32_e32 v213, v42
	v_add_f32_e32 v42, v45, v41
	v_exp_f32_e32 v176, v22
	v_add_f32_e32 v22, v173, v29
	v_mul_f32_e32 v42, 0xbfb8aa3b, v42
	v_mul_f32_e32 v22, 0xbfb8aa3b, v22
	v_exp_f32_e32 v205, v42
	v_add_f32_e32 v42, v170, v26
	v_exp_f32_e32 v175, v22
	v_add_f32_e32 v22, v25, v33
	v_mul_f32_e32 v42, 0xbfb8aa3b, v42
	v_mul_f32_e32 v22, 0xbfb8aa3b, v22
	v_exp_f32_e32 v208, v42
	v_exp_f32_e32 v177, v22
	global_load_dwordx4 v[22:25], v[210:211], off offset:16
	global_load_dwordx4 v[42:45], v[210:211], off
	v_pk_add_f32 v[170:171], v[214:215], 1.0 op_sel_hi:[1,0]
	v_pk_add_f32 v[174:175], v[174:175], 1.0 op_sel_hi:[1,0]
	v_add_f32_e32 v154, v154, v38
	v_mul_f32_e32 v154, 0xbfb8aa3b, v154
	v_add_f32_e32 v150, v150, v30
	v_rcp_f32_e32 v171, v171
	v_mul_f32_e32 v150, 0xbfb8aa3b, v150
	v_add_f32_e32 v134, v134, v38
	v_mul_f32_e32 v134, 0xbfb8aa3b, v134
	v_rcp_f32_e32 v170, v170
	v_add_f32_e32 v130, v130, v30
	v_mul_f32_e32 v130, 0xbfb8aa3b, v130
	v_mul_f32_e32 v142, 0xbfb8aa3b, v142
	v_add_f32_e32 v114, v114, v38
	v_mul_f32_e32 v114, 0xbfb8aa3b, v114
	v_add_f32_e32 v110, v110, v30
	v_mul_f32_e32 v110, 0xbfb8aa3b, v110
	v_add_f32_e32 v122, v122, v34
	v_mul_f32_e32 v122, 0xbfb8aa3b, v122
	v_add_f32_e32 v94, v94, v38
	v_mul_f32_e32 v94, 0xbfb8aa3b, v94
	v_add_f32_e32 v90, v90, v30
	v_mul_f32_e32 v90, 0xbfb8aa3b, v90
	v_add_f32_e32 v102, v102, v34
	v_mul_f32_e32 v102, 0xbfb8aa3b, v102
	v_add_f32_e32 v74, v74, v38
	v_mul_f32_e32 v74, 0xbfb8aa3b, v74
	v_add_f32_e32 v70, v70, v30
	v_mul_f32_e32 v70, 0xbfb8aa3b, v70
	v_add_f32_e32 v82, v82, v34
	v_mul_f32_e32 v82, 0xbfb8aa3b, v82
	v_add_f32_e32 v54, v54, v38
	v_mul_f32_e32 v54, 0xbfb8aa3b, v54
	v_add_f32_e32 v50, v50, v30
	v_mul_f32_e32 v50, 0xbfb8aa3b, v50
	v_add_f32_e32 v62, v62, v34
	v_mul_f32_e32 v62, 0xbfb8aa3b, v62
	v_add_f32_e32 v10, v10, v38
	v_mul_f32_e32 v10, 0xbfb8aa3b, v10
	v_add_f32_e32 v18, v18, v34
	v_exp_f32_e32 v34, v10
	v_add_f32_e32 v10, v19, v35
	v_mul_f32_e32 v10, 0xbfb8aa3b, v10
	v_add_f32_e32 v6, v6, v30
	v_mul_f32_e32 v6, 0xbfb8aa3b, v6
	v_mul_f32_e32 v18, 0xbfb8aa3b, v18
	s_waitcnt vmcnt(0)
	v_pk_mul_f32 v[170:171], v[42:43], v[170:171]
	s_nop 0
	v_add_f32_e32 v172, v170, v170
	v_mul_f32_e32 v172, 0x3fb8aa3b, v172
	v_exp_f32_e32 v172, v172
	v_cvt_pk_bf16_f32 v170, v170, v171
	v_sub_f32_e32 v172, 1.0, v172
	v_sqrt_f32_e32 v210, v172
	v_add_f32_e32 v172, v171, v171
	v_mul_f32_e32 v172, 0x3fb8aa3b, v172
	v_exp_f32_e32 v172, v172
	s_nop 0
	v_sub_f32_e32 v172, 1.0, v172
	v_sqrt_f32_e32 v211, v172
	v_pk_add_f32 v[172:173], v[212:213], 1.0 op_sel_hi:[1,0]
	s_nop 0
	v_rcp_f32_e32 v173, v173
	v_rcp_f32_e32 v172, v172
	s_nop 0
	v_pk_mul_f32 v[172:173], v[44:45], v[172:173]
	s_nop 0
	v_add_f32_e32 v171, v172, v172
	v_mul_f32_e32 v171, 0x3fb8aa3b, v171
	v_exp_f32_e32 v171, v171
	s_nop 0
	v_sub_f32_e32 v171, 1.0, v171
	v_sqrt_f32_e32 v212, v171
	v_add_f32_e32 v171, v173, v173
	v_mul_f32_e32 v171, 0x3fb8aa3b, v171
	v_exp_f32_e32 v171, v171
	s_nop 0
	v_sub_f32_e32 v171, 1.0, v171
	v_sqrt_f32_e32 v213, v171
	v_cvt_pk_bf16_f32 v171, v172, v173
	v_pk_add_f32 v[172:173], v[208:209], 1.0 op_sel_hi:[1,0]
	s_nop 0
	v_rcp_f32_e32 v173, v173
	v_rcp_f32_e32 v172, v172
	s_nop 0
	v_pk_mul_f32 v[172:173], v[22:23], v[172:173]
	s_nop 0
	v_add_f32_e32 v208, v172, v172
	v_mul_f32_e32 v208, 0x3fb8aa3b, v208
	v_exp_f32_e32 v208, v208
	v_cvt_pk_bf16_f32 v172, v172, v173
	v_sub_f32_e32 v208, 1.0, v208
	v_sqrt_f32_e32 v208, v208
	v_add_f32_e32 v209, v173, v173
	v_mul_f32_e32 v209, 0x3fb8aa3b, v209
	v_exp_f32_e32 v209, v209
	s_nop 0
	v_sub_f32_e32 v209, 1.0, v209
	v_sqrt_f32_e32 v209, v209
	v_rcp_f32_e32 v175, v175
	v_rcp_f32_e32 v174, v174
	s_nop 0
	v_pk_mul_f32 v[174:175], v[24:25], v[174:175]
	s_nop 0
	v_add_f32_e32 v173, v174, v174
	v_mul_f32_e32 v173, 0x3fb8aa3b, v173
	v_exp_f32_e32 v173, v173
	s_nop 0
	v_sub_f32_e32 v173, 1.0, v173
	v_sqrt_f32_e32 v214, v173
	v_add_f32_e32 v173, v175, v175
	v_mul_f32_e32 v173, 0x3fb8aa3b, v173
	v_exp_f32_e32 v173, v173
	s_nop 0
	v_sub_f32_e32 v173, 1.0, v173
	v_sqrt_f32_e32 v215, v173
	v_cvt_pk_bf16_f32 v173, v174, v175
	v_lshl_add_u64 v[174:175], v[200:201], 0, s[62:63]
	v_lshlrev_b64 v[174:175], 1, v[174:175]
	v_lshl_add_u64 v[200:201], s[44:45], 0, v[174:175]
	v_lshl_add_u64 v[200:201], v[200:201], 0, v[186:187]
	global_store_dwordx4 v[200:201], v[170:173], off
	s_nop 1
	v_pk_add_f32 v[172:173], v[206:207], 1.0 op_sel_hi:[1,0]
	v_lshlrev_b32_e32 v170, 16, v166
	v_and_b32_e32 v171, 0xffff0000, v166
	v_rcp_f32_e32 v173, v173
	v_rcp_f32_e32 v172, v172
	s_nop 0
	v_pk_mul_f32 v[170:171], v[172:173], v[170:171]
	v_pk_add_f32 v[172:173], v[204:205], 1.0 op_sel_hi:[1,0]
	v_pk_mul_f32 v[170:171], v[210:211], v[170:171]
	s_nop 0
	v_cvt_pk_bf16_f32 v166, v170, v171
	v_lshlrev_b32_e32 v170, 16, v167
	v_and_b32_e32 v171, 0xffff0000, v167
	v_rcp_f32_e32 v173, v173
	v_rcp_f32_e32 v172, v172
	s_nop 0
	v_pk_mul_f32 v[170:171], v[172:173], v[170:171]
	v_pk_add_f32 v[172:173], v[202:203], 1.0 op_sel_hi:[1,0]
	v_pk_mul_f32 v[170:171], v[212:213], v[170:171]
	s_nop 0
	v_cvt_pk_bf16_f32 v167, v170, v171
	v_lshlrev_b32_e32 v170, 16, v168
	v_and_b32_e32 v171, 0xffff0000, v168
	v_rcp_f32_e32 v173, v173
	v_rcp_f32_e32 v172, v172
	s_nop 0
	v_pk_mul_f32 v[170:171], v[172:173], v[170:171]
	v_pk_add_f32 v[172:173], v[176:177], 1.0 op_sel_hi:[1,0]
	v_pk_mul_f32 v[170:171], v[208:209], v[170:171]
	s_nop 0
	v_cvt_pk_bf16_f32 v168, v170, v171
	v_lshlrev_b32_e32 v170, 16, v169
	v_and_b32_e32 v171, 0xffff0000, v169
	v_rcp_f32_e32 v173, v173
	v_rcp_f32_e32 v172, v172
	s_nop 0
	v_pk_mul_f32 v[170:171], v[172:173], v[170:171]
	s_nop 0
	v_pk_mul_f32 v[170:171], v[170:171], v[214:215]
	s_nop 0
	v_cvt_pk_bf16_f32 v169, v170, v171
	v_lshl_add_u64 v[170:171], s[46:47], 0, v[174:175]
	v_lshl_add_u64 v[170:171], v[170:171], 0, v[186:187]
	global_store_dwordx4 v[170:171], v[166:169], off
	v_exp_f32_e32 v170, v162
	s_nop 0
	v_exp_f32_e32 v166, v154
	v_add_f32_e32 v154, v163, v35
	v_mul_f32_e32 v154, 0xbfb8aa3b, v154
	v_exp_f32_e32 v171, v154
	v_add_f32_e32 v154, v155, v39
	v_mul_f32_e32 v154, 0xbfb8aa3b, v154
	v_exp_f32_e32 v167, v154
	v_add_f32_e32 v154, v164, v36
	v_mul_f32_e32 v154, 0xbfb8aa3b, v154
	v_exp_f32_e32 v164, v154
	v_add_f32_e32 v154, v156, v40
	v_exp_f32_e32 v156, v150
	v_add_f32_e32 v150, v159, v27
	v_mul_f32_e32 v154, 0xbfb8aa3b, v154
	v_mul_f32_e32 v150, 0xbfb8aa3b, v150
	v_exp_f32_e32 v162, v154
	v_add_f32_e32 v154, v165, v37
	v_exp_f32_e32 v169, v150
	v_add_f32_e32 v150, v151, v31
	v_mul_f32_e32 v154, 0xbfb8aa3b, v154
	v_mul_f32_e32 v150, 0xbfb8aa3b, v150
	v_exp_f32_e32 v165, v154
	v_add_f32_e32 v154, v157, v41
	v_exp_f32_e32 v157, v150
	v_add_f32_e32 v150, v160, v28
	v_mul_f32_e32 v154, 0xbfb8aa3b, v154
	v_mul_f32_e32 v150, 0xbfb8aa3b, v150
	v_exp_f32_e32 v163, v154
	v_add_f32_e32 v154, v158, v26
	v_exp_f32_e32 v160, v150
	v_add_f32_e32 v150, v152, v32
	v_mul_f32_e32 v154, 0xbfb8aa3b, v154
	v_mul_f32_e32 v150, 0xbfb8aa3b, v150
	v_exp_f32_e32 v168, v154
	v_exp_f32_e32 v154, v150
	v_add_f32_e32 v150, v161, v29
	v_mul_f32_e32 v150, 0xbfb8aa3b, v150
	v_exp_f32_e32 v161, v150
	v_add_f32_e32 v150, v153, v33
	v_mul_f32_e32 v150, 0xbfb8aa3b, v150
	v_exp_f32_e32 v155, v150
	v_pk_add_f32 v[150:151], v[170:171], 1.0 op_sel_hi:[1,0]
	v_pk_add_f32 v[160:161], v[160:161], 1.0 op_sel_hi:[1,0]
	v_rcp_f32_e32 v151, v151
	v_rcp_f32_e32 v150, v150
	s_nop 0
	v_pk_mul_f32 v[150:151], v[42:43], v[150:151]
	s_nop 0
	v_add_f32_e32 v152, v150, v150
	v_mul_f32_e32 v152, 0x3fb8aa3b, v152
	v_exp_f32_e32 v152, v152
	v_cvt_pk_bf16_f32 v150, v150, v151
	v_sub_f32_e32 v152, 1.0, v152
	v_sqrt_f32_e32 v158, v152
	v_add_f32_e32 v152, v151, v151
	v_mul_f32_e32 v152, 0x3fb8aa3b, v152
	v_exp_f32_e32 v152, v152
	s_nop 0
	v_sub_f32_e32 v152, 1.0, v152
	v_sqrt_f32_e32 v159, v152
	v_pk_add_f32 v[152:153], v[164:165], 1.0 op_sel_hi:[1,0]
	s_nop 0
	v_rcp_f32_e32 v153, v153
	v_rcp_f32_e32 v152, v152
	s_nop 0
	v_pk_mul_f32 v[152:153], v[44:45], v[152:153]
	s_nop 0
	v_add_f32_e32 v151, v152, v152
	v_mul_f32_e32 v151, 0x3fb8aa3b, v151
	v_exp_f32_e32 v151, v151
	s_nop 0
	v_sub_f32_e32 v151, 1.0, v151
	v_sqrt_f32_e32 v164, v151
	v_add_f32_e32 v151, v153, v153
	v_mul_f32_e32 v151, 0x3fb8aa3b, v151
	v_exp_f32_e32 v151, v151
	s_nop 0
	v_sub_f32_e32 v151, 1.0, v151
	v_sqrt_f32_e32 v165, v151
	v_cvt_pk_bf16_f32 v151, v152, v153
	v_pk_add_f32 v[152:153], v[168:169], 1.0 op_sel_hi:[1,0]
	s_nop 0
	v_rcp_f32_e32 v153, v153
	v_rcp_f32_e32 v152, v152
	s_nop 0
	v_pk_mul_f32 v[152:153], v[22:23], v[152:153]
	s_nop 0
	v_add_f32_e32 v168, v152, v152
	v_mul_f32_e32 v168, 0x3fb8aa3b, v168
	v_exp_f32_e32 v168, v168
	v_cvt_pk_bf16_f32 v152, v152, v153
	v_sub_f32_e32 v168, 1.0, v168
	v_sqrt_f32_e32 v168, v168
	v_add_f32_e32 v169, v153, v153
	v_mul_f32_e32 v169, 0x3fb8aa3b, v169
	v_exp_f32_e32 v169, v169
	s_nop 0
	v_sub_f32_e32 v169, 1.0, v169
	v_sqrt_f32_e32 v169, v169
	v_rcp_f32_e32 v161, v161
	v_rcp_f32_e32 v160, v160
	s_nop 0
	v_pk_mul_f32 v[170:171], v[24:25], v[160:161]
	s_nop 0
	v_add_f32_e32 v153, v170, v170
	v_mul_f32_e32 v153, 0x3fb8aa3b, v153
	v_exp_f32_e32 v153, v153
	s_nop 0
	v_sub_f32_e32 v153, 1.0, v153
	v_sqrt_f32_e32 v160, v153
	v_add_f32_e32 v153, v171, v171
	v_mul_f32_e32 v153, 0x3fb8aa3b, v153
	v_exp_f32_e32 v153, v153
	s_nop 0
	v_sub_f32_e32 v153, 1.0, v153
	v_sqrt_f32_e32 v161, v153
	v_cvt_pk_bf16_f32 v153, v170, v171
	v_lshl_add_u64 v[170:171], v[198:199], 0, s[62:63]
	v_lshlrev_b64 v[170:171], 1, v[170:171]
	v_lshl_add_u64 v[172:173], s[44:45], 0, v[170:171]
	v_lshl_add_u64 v[172:173], v[172:173], 0, v[186:187]
	global_store_dwordx4 v[172:173], v[150:153], off
	s_nop 1
	v_pk_add_f32 v[152:153], v[166:167], 1.0 op_sel_hi:[1,0]
	v_lshlrev_b32_e32 v150, 16, v146
	v_and_b32_e32 v151, 0xffff0000, v146
	v_rcp_f32_e32 v153, v153
	v_rcp_f32_e32 v152, v152
	s_nop 0
	v_pk_mul_f32 v[150:151], v[152:153], v[150:151]
	v_pk_add_f32 v[152:153], v[162:163], 1.0 op_sel_hi:[1,0]
	v_pk_mul_f32 v[150:151], v[158:159], v[150:151]
	s_nop 0
	v_cvt_pk_bf16_f32 v146, v150, v151
	v_lshlrev_b32_e32 v150, 16, v147
	v_and_b32_e32 v151, 0xffff0000, v147
	v_rcp_f32_e32 v153, v153
	v_rcp_f32_e32 v152, v152
	s_nop 0
	v_pk_mul_f32 v[150:151], v[152:153], v[150:151]
	v_pk_add_f32 v[152:153], v[156:157], 1.0 op_sel_hi:[1,0]
	v_pk_mul_f32 v[150:151], v[164:165], v[150:151]
	s_nop 0
	v_cvt_pk_bf16_f32 v147, v150, v151
	v_lshlrev_b32_e32 v150, 16, v148
	v_and_b32_e32 v151, 0xffff0000, v148
	v_rcp_f32_e32 v153, v153
	v_rcp_f32_e32 v152, v152
	s_nop 0
	v_pk_mul_f32 v[150:151], v[152:153], v[150:151]
	v_pk_add_f32 v[152:153], v[154:155], 1.0 op_sel_hi:[1,0]
	v_pk_mul_f32 v[150:151], v[168:169], v[150:151]
	s_nop 0
	v_cvt_pk_bf16_f32 v148, v150, v151
	v_lshlrev_b32_e32 v150, 16, v149
	v_and_b32_e32 v151, 0xffff0000, v149
	v_rcp_f32_e32 v153, v153
	v_rcp_f32_e32 v152, v152
	s_nop 0
	v_pk_mul_f32 v[150:151], v[152:153], v[150:151]
	s_nop 0
	v_pk_mul_f32 v[150:151], v[160:161], v[150:151]
	s_nop 0
	v_cvt_pk_bf16_f32 v149, v150, v151
	v_lshl_add_u64 v[150:151], s[46:47], 0, v[170:171]
	v_lshl_add_u64 v[150:151], v[150:151], 0, v[186:187]
	global_store_dwordx4 v[150:151], v[146:149], off
	v_exp_f32_e32 v150, v142
	s_nop 0
	v_exp_f32_e32 v146, v134
	v_add_f32_e32 v134, v143, v35
	v_mul_f32_e32 v134, 0xbfb8aa3b, v134
	v_exp_f32_e32 v151, v134
	v_add_f32_e32 v134, v135, v39
	v_mul_f32_e32 v134, 0xbfb8aa3b, v134
	v_exp_f32_e32 v147, v134
	v_add_f32_e32 v134, v144, v36
	v_mul_f32_e32 v134, 0xbfb8aa3b, v134
	v_exp_f32_e32 v144, v134
	v_add_f32_e32 v134, v136, v40
	v_exp_f32_e32 v136, v130
	v_add_f32_e32 v130, v139, v27
	v_mul_f32_e32 v134, 0xbfb8aa3b, v134
	v_mul_f32_e32 v130, 0xbfb8aa3b, v130
	v_exp_f32_e32 v142, v134
	v_add_f32_e32 v134, v145, v37
	v_exp_f32_e32 v149, v130
	v_add_f32_e32 v130, v131, v31
	v_mul_f32_e32 v134, 0xbfb8aa3b, v134
	v_mul_f32_e32 v130, 0xbfb8aa3b, v130
	v_exp_f32_e32 v145, v134
	v_add_f32_e32 v134, v137, v41
	v_exp_f32_e32 v137, v130
	v_add_f32_e32 v130, v140, v28
	v_mul_f32_e32 v134, 0xbfb8aa3b, v134
	v_mul_f32_e32 v130, 0xbfb8aa3b, v130
	v_exp_f32_e32 v143, v134
	v_add_f32_e32 v134, v138, v26
	v_exp_f32_e32 v140, v130
	v_add_f32_e32 v130, v132, v32
	v_mul_f32_e32 v134, 0xbfb8aa3b, v134
	v_mul_f32_e32 v130, 0xbfb8aa3b, v130
	v_exp_f32_e32 v148, v134
	v_exp_f32_e32 v134, v130
	v_add_f32_e32 v130, v141, v29
	v_mul_f32_e32 v130, 0xbfb8aa3b, v130
	v_exp_f32_e32 v141, v130
	v_add_f32_e32 v130, v133, v33
	v_mul_f32_e32 v130, 0xbfb8aa3b, v130
	v_exp_f32_e32 v135, v130
	v_pk_add_f32 v[130:131], v[150:151], 1.0 op_sel_hi:[1,0]
	v_pk_add_f32 v[140:141], v[140:141], 1.0 op_sel_hi:[1,0]
	v_rcp_f32_e32 v131, v131
	v_rcp_f32_e32 v130, v130
	s_nop 0
	v_pk_mul_f32 v[130:131], v[42:43], v[130:131]
	s_nop 0
	v_add_f32_e32 v132, v130, v130
	v_mul_f32_e32 v132, 0x3fb8aa3b, v132
	v_exp_f32_e32 v132, v132
	v_cvt_pk_bf16_f32 v130, v130, v131
	v_sub_f32_e32 v132, 1.0, v132
	v_sqrt_f32_e32 v138, v132
	v_add_f32_e32 v132, v131, v131
	v_mul_f32_e32 v132, 0x3fb8aa3b, v132
	v_exp_f32_e32 v132, v132
	s_nop 0
	v_sub_f32_e32 v132, 1.0, v132
	v_sqrt_f32_e32 v139, v132
	v_pk_add_f32 v[132:133], v[144:145], 1.0 op_sel_hi:[1,0]
	s_nop 0
	v_rcp_f32_e32 v133, v133
	v_rcp_f32_e32 v132, v132
	s_nop 0
	v_pk_mul_f32 v[132:133], v[44:45], v[132:133]
	s_nop 0
	v_add_f32_e32 v131, v132, v132
	v_mul_f32_e32 v131, 0x3fb8aa3b, v131
	v_exp_f32_e32 v131, v131
	s_nop 0
	v_sub_f32_e32 v131, 1.0, v131
	v_sqrt_f32_e32 v144, v131
	v_add_f32_e32 v131, v133, v133
	v_mul_f32_e32 v131, 0x3fb8aa3b, v131
	v_exp_f32_e32 v131, v131
	s_nop 0
	v_sub_f32_e32 v131, 1.0, v131
	v_sqrt_f32_e32 v145, v131
	v_cvt_pk_bf16_f32 v131, v132, v133
	v_pk_add_f32 v[132:133], v[148:149], 1.0 op_sel_hi:[1,0]
	s_nop 0
	v_rcp_f32_e32 v133, v133
	v_rcp_f32_e32 v132, v132
	s_nop 0
	v_pk_mul_f32 v[132:133], v[22:23], v[132:133]
	s_nop 0
	v_add_f32_e32 v148, v132, v132
	v_mul_f32_e32 v148, 0x3fb8aa3b, v148
	v_exp_f32_e32 v148, v148
	v_cvt_pk_bf16_f32 v132, v132, v133
	v_sub_f32_e32 v148, 1.0, v148
	v_sqrt_f32_e32 v148, v148
	v_add_f32_e32 v149, v133, v133
	v_mul_f32_e32 v149, 0x3fb8aa3b, v149
	v_exp_f32_e32 v149, v149
	s_nop 0
	v_sub_f32_e32 v149, 1.0, v149
	v_sqrt_f32_e32 v149, v149
	v_rcp_f32_e32 v141, v141
	v_rcp_f32_e32 v140, v140
	s_nop 0
	v_pk_mul_f32 v[150:151], v[24:25], v[140:141]
	s_nop 0
	v_add_f32_e32 v133, v150, v150
	v_mul_f32_e32 v133, 0x3fb8aa3b, v133
	v_exp_f32_e32 v133, v133
	s_nop 0
	v_sub_f32_e32 v133, 1.0, v133
	v_sqrt_f32_e32 v140, v133
	v_add_f32_e32 v133, v151, v151
	v_mul_f32_e32 v133, 0x3fb8aa3b, v133
	v_exp_f32_e32 v133, v133
	s_nop 0
	v_sub_f32_e32 v133, 1.0, v133
	v_sqrt_f32_e32 v141, v133
	v_cvt_pk_bf16_f32 v133, v150, v151
	v_lshl_add_u64 v[150:151], v[196:197], 0, s[62:63]
	v_lshlrev_b64 v[150:151], 1, v[150:151]
	v_lshl_add_u64 v[152:153], s[44:45], 0, v[150:151]
	v_lshl_add_u64 v[152:153], v[152:153], 0, v[186:187]
	global_store_dwordx4 v[152:153], v[130:133], off
	s_nop 1
	v_pk_add_f32 v[132:133], v[146:147], 1.0 op_sel_hi:[1,0]
	v_lshlrev_b32_e32 v130, 16, v126
	v_and_b32_e32 v131, 0xffff0000, v126
	v_rcp_f32_e32 v133, v133
	v_rcp_f32_e32 v132, v132
	s_nop 0
	v_pk_mul_f32 v[130:131], v[132:133], v[130:131]
	v_pk_add_f32 v[132:133], v[142:143], 1.0 op_sel_hi:[1,0]
	v_pk_mul_f32 v[130:131], v[138:139], v[130:131]
	s_nop 0
	v_cvt_pk_bf16_f32 v126, v130, v131
	v_lshlrev_b32_e32 v130, 16, v127
	v_and_b32_e32 v131, 0xffff0000, v127
	v_rcp_f32_e32 v133, v133
	v_rcp_f32_e32 v132, v132
	s_nop 0
	v_pk_mul_f32 v[130:131], v[132:133], v[130:131]
	v_pk_add_f32 v[132:133], v[136:137], 1.0 op_sel_hi:[1,0]
	v_pk_mul_f32 v[130:131], v[144:145], v[130:131]
	s_nop 0
	v_cvt_pk_bf16_f32 v127, v130, v131
	v_lshlrev_b32_e32 v130, 16, v128
	v_and_b32_e32 v131, 0xffff0000, v128
	v_rcp_f32_e32 v133, v133
	v_rcp_f32_e32 v132, v132
	s_nop 0
	v_pk_mul_f32 v[130:131], v[132:133], v[130:131]
	v_pk_add_f32 v[132:133], v[134:135], 1.0 op_sel_hi:[1,0]
	v_pk_mul_f32 v[130:131], v[148:149], v[130:131]
	s_nop 0
	v_cvt_pk_bf16_f32 v128, v130, v131
	v_lshlrev_b32_e32 v130, 16, v129
	v_and_b32_e32 v131, 0xffff0000, v129
	v_rcp_f32_e32 v133, v133
	v_rcp_f32_e32 v132, v132
	s_nop 0
	v_pk_mul_f32 v[130:131], v[132:133], v[130:131]
	s_nop 0
	v_pk_mul_f32 v[130:131], v[140:141], v[130:131]
	s_nop 0
	v_cvt_pk_bf16_f32 v129, v130, v131
	v_lshl_add_u64 v[130:131], s[46:47], 0, v[150:151]
	v_lshl_add_u64 v[130:131], v[130:131], 0, v[186:187]
	global_store_dwordx4 v[130:131], v[126:129], off
	v_exp_f32_e32 v130, v122
	s_nop 0
	v_exp_f32_e32 v126, v114
	v_add_f32_e32 v114, v123, v35
	v_mul_f32_e32 v114, 0xbfb8aa3b, v114
	v_exp_f32_e32 v131, v114
	v_add_f32_e32 v114, v115, v39
	v_mul_f32_e32 v114, 0xbfb8aa3b, v114
	v_exp_f32_e32 v127, v114
	v_add_f32_e32 v114, v124, v36
	v_mul_f32_e32 v114, 0xbfb8aa3b, v114
	v_exp_f32_e32 v124, v114
	v_add_f32_e32 v114, v116, v40
	v_exp_f32_e32 v116, v110
	v_add_f32_e32 v110, v119, v27
	v_mul_f32_e32 v114, 0xbfb8aa3b, v114
	v_mul_f32_e32 v110, 0xbfb8aa3b, v110
	v_exp_f32_e32 v122, v114
	v_add_f32_e32 v114, v125, v37
	v_exp_f32_e32 v129, v110
	v_add_f32_e32 v110, v111, v31
	v_mul_f32_e32 v114, 0xbfb8aa3b, v114
	v_mul_f32_e32 v110, 0xbfb8aa3b, v110
	v_exp_f32_e32 v125, v114
	v_add_f32_e32 v114, v117, v41
	v_exp_f32_e32 v117, v110
	v_add_f32_e32 v110, v120, v28
	v_mul_f32_e32 v114, 0xbfb8aa3b, v114
	v_mul_f32_e32 v110, 0xbfb8aa3b, v110
	v_exp_f32_e32 v123, v114
	v_add_f32_e32 v114, v118, v26
	v_exp_f32_e32 v120, v110
	v_add_f32_e32 v110, v112, v32
	v_mul_f32_e32 v114, 0xbfb8aa3b, v114
	v_mul_f32_e32 v110, 0xbfb8aa3b, v110
	v_exp_f32_e32 v128, v114
	v_exp_f32_e32 v114, v110
	v_add_f32_e32 v110, v121, v29
	v_mul_f32_e32 v110, 0xbfb8aa3b, v110
	v_exp_f32_e32 v121, v110
	v_add_f32_e32 v110, v113, v33
	v_mul_f32_e32 v110, 0xbfb8aa3b, v110
	v_exp_f32_e32 v115, v110
	v_pk_add_f32 v[110:111], v[130:131], 1.0 op_sel_hi:[1,0]
	v_pk_add_f32 v[120:121], v[120:121], 1.0 op_sel_hi:[1,0]
	v_rcp_f32_e32 v111, v111
	v_rcp_f32_e32 v110, v110
	s_nop 0
	v_pk_mul_f32 v[110:111], v[42:43], v[110:111]
	s_nop 0
	v_add_f32_e32 v112, v110, v110
	v_mul_f32_e32 v112, 0x3fb8aa3b, v112
	v_exp_f32_e32 v112, v112
	v_cvt_pk_bf16_f32 v110, v110, v111
	v_sub_f32_e32 v112, 1.0, v112
	v_sqrt_f32_e32 v118, v112
	v_add_f32_e32 v112, v111, v111
	v_mul_f32_e32 v112, 0x3fb8aa3b, v112
	v_exp_f32_e32 v112, v112
	s_nop 0
	v_sub_f32_e32 v112, 1.0, v112
	v_sqrt_f32_e32 v119, v112
	v_pk_add_f32 v[112:113], v[124:125], 1.0 op_sel_hi:[1,0]
	s_nop 0
	v_rcp_f32_e32 v113, v113
	v_rcp_f32_e32 v112, v112
	s_nop 0
	v_pk_mul_f32 v[112:113], v[44:45], v[112:113]
	s_nop 0
	v_add_f32_e32 v111, v112, v112
	v_mul_f32_e32 v111, 0x3fb8aa3b, v111
	v_exp_f32_e32 v111, v111
	s_nop 0
	v_sub_f32_e32 v111, 1.0, v111
	v_sqrt_f32_e32 v124, v111
	v_add_f32_e32 v111, v113, v113
	v_mul_f32_e32 v111, 0x3fb8aa3b, v111
	v_exp_f32_e32 v111, v111
	s_nop 0
	v_sub_f32_e32 v111, 1.0, v111
	v_sqrt_f32_e32 v125, v111
	v_cvt_pk_bf16_f32 v111, v112, v113
	v_pk_add_f32 v[112:113], v[128:129], 1.0 op_sel_hi:[1,0]
	s_nop 0
	v_rcp_f32_e32 v113, v113
	v_rcp_f32_e32 v112, v112
	s_nop 0
	v_pk_mul_f32 v[112:113], v[22:23], v[112:113]
	s_nop 0
	v_add_f32_e32 v128, v112, v112
	v_mul_f32_e32 v128, 0x3fb8aa3b, v128
	v_exp_f32_e32 v128, v128
	v_cvt_pk_bf16_f32 v112, v112, v113
	v_sub_f32_e32 v128, 1.0, v128
	v_sqrt_f32_e32 v128, v128
	v_add_f32_e32 v129, v113, v113
	v_mul_f32_e32 v129, 0x3fb8aa3b, v129
	v_exp_f32_e32 v129, v129
	s_nop 0
	v_sub_f32_e32 v129, 1.0, v129
	v_sqrt_f32_e32 v129, v129
	v_rcp_f32_e32 v121, v121
	v_rcp_f32_e32 v120, v120
	s_nop 0
	v_pk_mul_f32 v[130:131], v[24:25], v[120:121]
	s_nop 0
	v_add_f32_e32 v113, v130, v130
	v_mul_f32_e32 v113, 0x3fb8aa3b, v113
	v_exp_f32_e32 v113, v113
	s_nop 0
	v_sub_f32_e32 v113, 1.0, v113
	v_sqrt_f32_e32 v120, v113
	v_add_f32_e32 v113, v131, v131
	v_mul_f32_e32 v113, 0x3fb8aa3b, v113
	v_exp_f32_e32 v113, v113
	s_nop 0
	v_sub_f32_e32 v113, 1.0, v113
	v_sqrt_f32_e32 v121, v113
	v_cvt_pk_bf16_f32 v113, v130, v131
	v_lshl_add_u64 v[130:131], v[194:195], 0, s[62:63]
	v_lshlrev_b64 v[130:131], 1, v[130:131]
	v_lshl_add_u64 v[132:133], s[44:45], 0, v[130:131]
	v_lshl_add_u64 v[132:133], v[132:133], 0, v[186:187]
	global_store_dwordx4 v[132:133], v[110:113], off
	s_nop 1
	v_pk_add_f32 v[112:113], v[126:127], 1.0 op_sel_hi:[1,0]
	v_lshlrev_b32_e32 v110, 16, v106
	v_and_b32_e32 v111, 0xffff0000, v106
	v_rcp_f32_e32 v113, v113
	v_rcp_f32_e32 v112, v112
	s_nop 0
	v_pk_mul_f32 v[110:111], v[112:113], v[110:111]
	v_pk_add_f32 v[112:113], v[122:123], 1.0 op_sel_hi:[1,0]
	v_pk_mul_f32 v[110:111], v[118:119], v[110:111]
	s_nop 0
	v_cvt_pk_bf16_f32 v106, v110, v111
	v_lshlrev_b32_e32 v110, 16, v107
	v_and_b32_e32 v111, 0xffff0000, v107
	v_rcp_f32_e32 v113, v113
	v_rcp_f32_e32 v112, v112
	s_nop 0
	v_pk_mul_f32 v[110:111], v[112:113], v[110:111]
	v_pk_add_f32 v[112:113], v[116:117], 1.0 op_sel_hi:[1,0]
	v_pk_mul_f32 v[110:111], v[124:125], v[110:111]
	s_nop 0
	v_cvt_pk_bf16_f32 v107, v110, v111
	v_lshlrev_b32_e32 v110, 16, v108
	v_and_b32_e32 v111, 0xffff0000, v108
	v_rcp_f32_e32 v113, v113
	v_rcp_f32_e32 v112, v112
	s_nop 0
	v_pk_mul_f32 v[110:111], v[112:113], v[110:111]
	v_pk_add_f32 v[112:113], v[114:115], 1.0 op_sel_hi:[1,0]
	v_pk_mul_f32 v[110:111], v[128:129], v[110:111]
	s_nop 0
	v_cvt_pk_bf16_f32 v108, v110, v111
	v_lshlrev_b32_e32 v110, 16, v109
	v_and_b32_e32 v111, 0xffff0000, v109
	v_rcp_f32_e32 v113, v113
	v_rcp_f32_e32 v112, v112
	s_nop 0
	v_pk_mul_f32 v[110:111], v[112:113], v[110:111]
	s_nop 0
	v_pk_mul_f32 v[110:111], v[120:121], v[110:111]
	s_nop 0
	v_cvt_pk_bf16_f32 v109, v110, v111
	v_lshl_add_u64 v[110:111], s[46:47], 0, v[130:131]
	v_lshl_add_u64 v[110:111], v[110:111], 0, v[186:187]
	global_store_dwordx4 v[110:111], v[106:109], off
	v_exp_f32_e32 v110, v102
	s_nop 0
	v_exp_f32_e32 v106, v94
	v_add_f32_e32 v94, v103, v35
	v_mul_f32_e32 v94, 0xbfb8aa3b, v94
	v_exp_f32_e32 v111, v94
	v_add_f32_e32 v94, v95, v39
	v_mul_f32_e32 v94, 0xbfb8aa3b, v94
	v_exp_f32_e32 v107, v94
	v_add_f32_e32 v94, v104, v36
	v_mul_f32_e32 v94, 0xbfb8aa3b, v94
	v_exp_f32_e32 v104, v94
	v_add_f32_e32 v94, v96, v40
	v_exp_f32_e32 v96, v90
	v_add_f32_e32 v90, v99, v27
	v_mul_f32_e32 v94, 0xbfb8aa3b, v94
	v_mul_f32_e32 v90, 0xbfb8aa3b, v90
	v_exp_f32_e32 v102, v94
	v_add_f32_e32 v94, v105, v37
	v_exp_f32_e32 v109, v90
	v_add_f32_e32 v90, v91, v31
	v_mul_f32_e32 v94, 0xbfb8aa3b, v94
	v_mul_f32_e32 v90, 0xbfb8aa3b, v90
	v_exp_f32_e32 v105, v94
	v_add_f32_e32 v94, v97, v41
	v_exp_f32_e32 v97, v90
	v_add_f32_e32 v90, v100, v28
	v_mul_f32_e32 v94, 0xbfb8aa3b, v94
	v_mul_f32_e32 v90, 0xbfb8aa3b, v90
	v_exp_f32_e32 v103, v94
	v_add_f32_e32 v94, v98, v26
	v_exp_f32_e32 v100, v90
	v_add_f32_e32 v90, v92, v32
	v_mul_f32_e32 v94, 0xbfb8aa3b, v94
	v_mul_f32_e32 v90, 0xbfb8aa3b, v90
	v_exp_f32_e32 v108, v94
	v_exp_f32_e32 v94, v90
	v_add_f32_e32 v90, v101, v29
	v_mul_f32_e32 v90, 0xbfb8aa3b, v90
	v_exp_f32_e32 v101, v90
	v_add_f32_e32 v90, v93, v33
	v_mul_f32_e32 v90, 0xbfb8aa3b, v90
	v_exp_f32_e32 v95, v90
	v_pk_add_f32 v[90:91], v[110:111], 1.0 op_sel_hi:[1,0]
	v_pk_add_f32 v[100:101], v[100:101], 1.0 op_sel_hi:[1,0]
	v_rcp_f32_e32 v91, v91
	v_rcp_f32_e32 v90, v90
	s_nop 0
	v_pk_mul_f32 v[90:91], v[42:43], v[90:91]
	s_nop 0
	v_add_f32_e32 v92, v90, v90
	v_mul_f32_e32 v92, 0x3fb8aa3b, v92
	v_exp_f32_e32 v92, v92
	v_cvt_pk_bf16_f32 v90, v90, v91
	v_sub_f32_e32 v92, 1.0, v92
	v_sqrt_f32_e32 v98, v92
	v_add_f32_e32 v92, v91, v91
	v_mul_f32_e32 v92, 0x3fb8aa3b, v92
	v_exp_f32_e32 v92, v92
	s_nop 0
	v_sub_f32_e32 v92, 1.0, v92
	v_sqrt_f32_e32 v99, v92
	v_pk_add_f32 v[92:93], v[104:105], 1.0 op_sel_hi:[1,0]
	s_nop 0
	v_rcp_f32_e32 v93, v93
	v_rcp_f32_e32 v92, v92
	s_nop 0
	v_pk_mul_f32 v[92:93], v[44:45], v[92:93]
	s_nop 0
	v_add_f32_e32 v91, v92, v92
	v_mul_f32_e32 v91, 0x3fb8aa3b, v91
	v_exp_f32_e32 v91, v91
	s_nop 0
	v_sub_f32_e32 v91, 1.0, v91
	v_sqrt_f32_e32 v104, v91
	v_add_f32_e32 v91, v93, v93
	v_mul_f32_e32 v91, 0x3fb8aa3b, v91
	v_exp_f32_e32 v91, v91
	s_nop 0
	v_sub_f32_e32 v91, 1.0, v91
	v_sqrt_f32_e32 v105, v91
	v_cvt_pk_bf16_f32 v91, v92, v93
	v_pk_add_f32 v[92:93], v[108:109], 1.0 op_sel_hi:[1,0]
	s_nop 0
	v_rcp_f32_e32 v93, v93
	v_rcp_f32_e32 v92, v92
	s_nop 0
	v_pk_mul_f32 v[92:93], v[22:23], v[92:93]
	s_nop 0
	v_add_f32_e32 v108, v92, v92
	v_mul_f32_e32 v108, 0x3fb8aa3b, v108
	v_exp_f32_e32 v108, v108
	v_cvt_pk_bf16_f32 v92, v92, v93
	v_sub_f32_e32 v108, 1.0, v108
	v_sqrt_f32_e32 v108, v108
	v_add_f32_e32 v109, v93, v93
	v_mul_f32_e32 v109, 0x3fb8aa3b, v109
	v_exp_f32_e32 v109, v109
	s_nop 0
	v_sub_f32_e32 v109, 1.0, v109
	v_sqrt_f32_e32 v109, v109
	v_rcp_f32_e32 v101, v101
	v_rcp_f32_e32 v100, v100
	s_nop 0
	v_pk_mul_f32 v[110:111], v[24:25], v[100:101]
	s_nop 0
	v_add_f32_e32 v93, v110, v110
	v_mul_f32_e32 v93, 0x3fb8aa3b, v93
	v_exp_f32_e32 v93, v93
	s_nop 0
	v_sub_f32_e32 v93, 1.0, v93
	v_sqrt_f32_e32 v100, v93
	v_add_f32_e32 v93, v111, v111
	v_mul_f32_e32 v93, 0x3fb8aa3b, v93
	v_exp_f32_e32 v93, v93
	s_nop 0
	v_sub_f32_e32 v93, 1.0, v93
	v_sqrt_f32_e32 v101, v93
	v_cvt_pk_bf16_f32 v93, v110, v111
	v_lshl_add_u64 v[110:111], v[192:193], 0, s[62:63]
	v_lshlrev_b64 v[110:111], 1, v[110:111]
	v_lshl_add_u64 v[112:113], s[44:45], 0, v[110:111]
	v_lshl_add_u64 v[112:113], v[112:113], 0, v[186:187]
	global_store_dwordx4 v[112:113], v[90:93], off
	s_mov_b64 s[62:63], s[60:61]
	s_nop 0
	v_pk_add_f32 v[92:93], v[106:107], 1.0 op_sel_hi:[1,0]
	v_lshlrev_b32_e32 v90, 16, v86
	v_and_b32_e32 v91, 0xffff0000, v86
	v_rcp_f32_e32 v93, v93
	v_rcp_f32_e32 v92, v92
	s_nop 0
	v_pk_mul_f32 v[90:91], v[92:93], v[90:91]
	v_pk_add_f32 v[92:93], v[102:103], 1.0 op_sel_hi:[1,0]
	v_pk_mul_f32 v[90:91], v[98:99], v[90:91]
	s_nop 0
	v_cvt_pk_bf16_f32 v86, v90, v91
	v_lshlrev_b32_e32 v90, 16, v87
	v_and_b32_e32 v91, 0xffff0000, v87
	v_rcp_f32_e32 v93, v93
	v_rcp_f32_e32 v92, v92
	s_nop 0
	v_pk_mul_f32 v[90:91], v[92:93], v[90:91]
	v_pk_add_f32 v[92:93], v[96:97], 1.0 op_sel_hi:[1,0]
	v_pk_mul_f32 v[90:91], v[104:105], v[90:91]
	s_nop 0
	v_cvt_pk_bf16_f32 v87, v90, v91
	v_lshlrev_b32_e32 v90, 16, v88
	v_and_b32_e32 v91, 0xffff0000, v88
	v_rcp_f32_e32 v93, v93
	v_rcp_f32_e32 v92, v92
	s_nop 0
	v_pk_mul_f32 v[90:91], v[92:93], v[90:91]
	v_pk_add_f32 v[92:93], v[94:95], 1.0 op_sel_hi:[1,0]
	v_pk_mul_f32 v[90:91], v[108:109], v[90:91]
	s_nop 0
	v_cvt_pk_bf16_f32 v88, v90, v91
	v_lshlrev_b32_e32 v90, 16, v89
	v_and_b32_e32 v91, 0xffff0000, v89
	v_rcp_f32_e32 v93, v93
	v_rcp_f32_e32 v92, v92
	s_nop 0
	v_pk_mul_f32 v[90:91], v[92:93], v[90:91]
	s_nop 0
	v_pk_mul_f32 v[90:91], v[100:101], v[90:91]
	s_nop 0
	v_cvt_pk_bf16_f32 v89, v90, v91
	v_lshl_add_u64 v[90:91], s[46:47], 0, v[110:111]
	v_lshl_add_u64 v[90:91], v[90:91], 0, v[186:187]
	global_store_dwordx4 v[90:91], v[86:89], off
	v_exp_f32_e32 v90, v82
	s_nop 0
	v_exp_f32_e32 v86, v74
	v_add_f32_e32 v74, v83, v35
	v_mul_f32_e32 v74, 0xbfb8aa3b, v74
	v_exp_f32_e32 v91, v74
	v_add_f32_e32 v74, v75, v39
	v_mul_f32_e32 v74, 0xbfb8aa3b, v74
	v_exp_f32_e32 v87, v74
	v_add_f32_e32 v74, v84, v36
	v_mul_f32_e32 v74, 0xbfb8aa3b, v74
	v_exp_f32_e32 v84, v74
	v_add_f32_e32 v74, v76, v40
	v_exp_f32_e32 v76, v70
	v_add_f32_e32 v70, v79, v27
	v_mul_f32_e32 v74, 0xbfb8aa3b, v74
	v_mul_f32_e32 v70, 0xbfb8aa3b, v70
	v_exp_f32_e32 v82, v74
	v_add_f32_e32 v74, v85, v37
	v_exp_f32_e32 v89, v70
	v_add_f32_e32 v70, v71, v31
	v_mul_f32_e32 v74, 0xbfb8aa3b, v74
	v_mul_f32_e32 v70, 0xbfb8aa3b, v70
	v_exp_f32_e32 v85, v74
	v_add_f32_e32 v74, v77, v41
	v_exp_f32_e32 v77, v70
	v_add_f32_e32 v70, v80, v28
	v_mul_f32_e32 v74, 0xbfb8aa3b, v74
	v_mul_f32_e32 v70, 0xbfb8aa3b, v70
	v_exp_f32_e32 v83, v74
	v_add_f32_e32 v74, v78, v26
	v_exp_f32_e32 v80, v70
	v_add_f32_e32 v70, v72, v32
	v_mul_f32_e32 v74, 0xbfb8aa3b, v74
	v_mul_f32_e32 v70, 0xbfb8aa3b, v70
	v_exp_f32_e32 v88, v74
	v_exp_f32_e32 v74, v70
	v_add_f32_e32 v70, v81, v29
	v_mul_f32_e32 v70, 0xbfb8aa3b, v70
	v_exp_f32_e32 v81, v70
	v_add_f32_e32 v70, v73, v33
	v_mul_f32_e32 v70, 0xbfb8aa3b, v70
	v_exp_f32_e32 v75, v70
	v_pk_add_f32 v[70:71], v[90:91], 1.0 op_sel_hi:[1,0]
	v_pk_add_f32 v[80:81], v[80:81], 1.0 op_sel_hi:[1,0]
	v_rcp_f32_e32 v71, v71
	v_rcp_f32_e32 v70, v70
	s_nop 0
	v_pk_mul_f32 v[70:71], v[42:43], v[70:71]
	s_nop 0
	v_add_f32_e32 v72, v70, v70
	v_mul_f32_e32 v72, 0x3fb8aa3b, v72
	v_exp_f32_e32 v72, v72
	v_cvt_pk_bf16_f32 v70, v70, v71
	v_sub_f32_e32 v72, 1.0, v72
	v_sqrt_f32_e32 v78, v72
	v_add_f32_e32 v72, v71, v71
	v_mul_f32_e32 v72, 0x3fb8aa3b, v72
	v_exp_f32_e32 v72, v72
	s_nop 0
	v_sub_f32_e32 v72, 1.0, v72
	v_sqrt_f32_e32 v79, v72
	v_pk_add_f32 v[72:73], v[84:85], 1.0 op_sel_hi:[1,0]
	s_nop 0
	v_rcp_f32_e32 v73, v73
	v_rcp_f32_e32 v72, v72
	s_nop 0
	v_pk_mul_f32 v[72:73], v[44:45], v[72:73]
	s_nop 0
	v_add_f32_e32 v71, v72, v72
	v_mul_f32_e32 v71, 0x3fb8aa3b, v71
	v_exp_f32_e32 v71, v71
	s_nop 0
	v_sub_f32_e32 v71, 1.0, v71
	v_sqrt_f32_e32 v84, v71
	v_add_f32_e32 v71, v73, v73
	v_mul_f32_e32 v71, 0x3fb8aa3b, v71
	v_exp_f32_e32 v71, v71
	s_nop 0
	v_sub_f32_e32 v71, 1.0, v71
	v_sqrt_f32_e32 v85, v71
	v_cvt_pk_bf16_f32 v71, v72, v73
	v_pk_add_f32 v[72:73], v[88:89], 1.0 op_sel_hi:[1,0]
	s_nop 0
	v_rcp_f32_e32 v73, v73
	v_rcp_f32_e32 v72, v72
	s_nop 0
	v_pk_mul_f32 v[72:73], v[22:23], v[72:73]
	s_nop 0
	v_add_f32_e32 v88, v72, v72
	v_mul_f32_e32 v88, 0x3fb8aa3b, v88
	v_exp_f32_e32 v88, v88
	v_cvt_pk_bf16_f32 v72, v72, v73
	v_sub_f32_e32 v88, 1.0, v88
	v_sqrt_f32_e32 v88, v88
	v_add_f32_e32 v89, v73, v73
	v_mul_f32_e32 v89, 0x3fb8aa3b, v89
	v_exp_f32_e32 v89, v89
	s_nop 0
	v_sub_f32_e32 v89, 1.0, v89
	v_sqrt_f32_e32 v89, v89
	v_rcp_f32_e32 v81, v81
	s_mov_b64 s[4:5], 0x120000
	v_rcp_f32_e32 v80, v80
	s_nop 0
	v_pk_mul_f32 v[90:91], v[24:25], v[80:81]
	s_nop 0
	v_add_f32_e32 v73, v90, v90
	v_mul_f32_e32 v73, 0x3fb8aa3b, v73
	v_exp_f32_e32 v73, v73
	s_nop 0
	v_sub_f32_e32 v73, 1.0, v73
	v_sqrt_f32_e32 v80, v73
	v_add_f32_e32 v73, v91, v91
	v_mul_f32_e32 v73, 0x3fb8aa3b, v73
	v_exp_f32_e32 v73, v73
	s_nop 0
	v_sub_f32_e32 v73, 1.0, v73
	v_sqrt_f32_e32 v81, v73
	v_cvt_pk_bf16_f32 v73, v90, v91
	v_lshl_add_u64 v[90:91], v[174:175], 0, s[4:5]
	v_lshl_add_u64 v[92:93], s[44:45], 0, v[90:91]
	v_lshl_add_u64 v[92:93], v[92:93], 0, v[186:187]
	global_store_dwordx4 v[92:93], v[70:73], off
	s_nop 1
	v_pk_add_f32 v[72:73], v[86:87], 1.0 op_sel_hi:[1,0]
	v_lshlrev_b32_e32 v70, 16, v66
	v_and_b32_e32 v71, 0xffff0000, v66
	v_rcp_f32_e32 v73, v73
	v_rcp_f32_e32 v72, v72
	s_nop 0
	v_pk_mul_f32 v[70:71], v[72:73], v[70:71]
	v_pk_add_f32 v[72:73], v[82:83], 1.0 op_sel_hi:[1,0]
	v_pk_mul_f32 v[70:71], v[78:79], v[70:71]
	s_nop 0
	v_cvt_pk_bf16_f32 v66, v70, v71
	v_lshlrev_b32_e32 v70, 16, v67
	v_and_b32_e32 v71, 0xffff0000, v67
	v_rcp_f32_e32 v73, v73
	v_rcp_f32_e32 v72, v72
	s_nop 0
	v_pk_mul_f32 v[70:71], v[72:73], v[70:71]
	v_pk_add_f32 v[72:73], v[76:77], 1.0 op_sel_hi:[1,0]
	v_pk_mul_f32 v[70:71], v[84:85], v[70:71]
	s_nop 0
	v_cvt_pk_bf16_f32 v67, v70, v71
	v_lshlrev_b32_e32 v70, 16, v68
	v_and_b32_e32 v71, 0xffff0000, v68
	v_rcp_f32_e32 v73, v73
	v_rcp_f32_e32 v72, v72
	s_nop 0
	v_pk_mul_f32 v[70:71], v[72:73], v[70:71]
	v_pk_add_f32 v[72:73], v[74:75], 1.0 op_sel_hi:[1,0]
	v_pk_mul_f32 v[70:71], v[88:89], v[70:71]
	s_nop 0
	v_cvt_pk_bf16_f32 v68, v70, v71
	v_lshlrev_b32_e32 v70, 16, v69
	v_and_b32_e32 v71, 0xffff0000, v69
	v_rcp_f32_e32 v73, v73
	v_rcp_f32_e32 v72, v72
	s_nop 0
	v_pk_mul_f32 v[70:71], v[72:73], v[70:71]
	s_nop 0
	v_pk_mul_f32 v[70:71], v[80:81], v[70:71]
	s_nop 0
	v_cvt_pk_bf16_f32 v69, v70, v71
	v_lshl_add_u64 v[70:71], s[46:47], 0, v[90:91]
	v_lshl_add_u64 v[70:71], v[70:71], 0, v[186:187]
	global_store_dwordx4 v[70:71], v[66:69], off
	v_exp_f32_e32 v70, v62
	s_nop 0
	v_exp_f32_e32 v66, v54
	v_add_f32_e32 v54, v63, v35
	v_mul_f32_e32 v54, 0xbfb8aa3b, v54
	v_exp_f32_e32 v71, v54
	v_add_f32_e32 v54, v55, v39
	v_mul_f32_e32 v54, 0xbfb8aa3b, v54
	v_exp_f32_e32 v67, v54
	v_add_f32_e32 v54, v64, v36
	v_mul_f32_e32 v54, 0xbfb8aa3b, v54
	v_exp_f32_e32 v64, v54
	v_add_f32_e32 v54, v56, v40
	v_exp_f32_e32 v56, v50
	v_add_f32_e32 v50, v59, v27
	v_mul_f32_e32 v54, 0xbfb8aa3b, v54
	v_mul_f32_e32 v50, 0xbfb8aa3b, v50
	v_exp_f32_e32 v62, v54
	v_add_f32_e32 v54, v65, v37
	v_exp_f32_e32 v69, v50
	v_add_f32_e32 v50, v51, v31
	v_mul_f32_e32 v54, 0xbfb8aa3b, v54
	v_mul_f32_e32 v50, 0xbfb8aa3b, v50
	v_exp_f32_e32 v65, v54
	v_add_f32_e32 v54, v57, v41
	v_exp_f32_e32 v57, v50
	v_add_f32_e32 v50, v60, v28
	v_mul_f32_e32 v54, 0xbfb8aa3b, v54
	v_mul_f32_e32 v50, 0xbfb8aa3b, v50
	v_exp_f32_e32 v63, v54
	v_add_f32_e32 v54, v58, v26
	v_exp_f32_e32 v60, v50
	v_add_f32_e32 v50, v52, v32
	v_mul_f32_e32 v54, 0xbfb8aa3b, v54
	v_mul_f32_e32 v50, 0xbfb8aa3b, v50
	v_exp_f32_e32 v68, v54
	v_exp_f32_e32 v54, v50
	v_add_f32_e32 v50, v61, v29
	v_mul_f32_e32 v50, 0xbfb8aa3b, v50
	v_exp_f32_e32 v61, v50
	v_add_f32_e32 v50, v53, v33
	v_mul_f32_e32 v50, 0xbfb8aa3b, v50
	v_exp_f32_e32 v55, v50
	v_pk_add_f32 v[50:51], v[70:71], 1.0 op_sel_hi:[1,0]
	v_pk_add_f32 v[60:61], v[60:61], 1.0 op_sel_hi:[1,0]
	v_rcp_f32_e32 v51, v51
	v_rcp_f32_e32 v50, v50
	s_nop 0
	v_pk_mul_f32 v[50:51], v[42:43], v[50:51]
	s_nop 0
	v_add_f32_e32 v52, v50, v50
	v_mul_f32_e32 v52, 0x3fb8aa3b, v52
	v_exp_f32_e32 v52, v52
	v_cvt_pk_bf16_f32 v50, v50, v51
	v_sub_f32_e32 v52, 1.0, v52
	v_sqrt_f32_e32 v58, v52
	v_add_f32_e32 v52, v51, v51
	v_mul_f32_e32 v52, 0x3fb8aa3b, v52
	v_exp_f32_e32 v52, v52
	s_nop 0
	v_sub_f32_e32 v52, 1.0, v52
	v_sqrt_f32_e32 v59, v52
	v_pk_add_f32 v[52:53], v[64:65], 1.0 op_sel_hi:[1,0]
	s_nop 0
	v_rcp_f32_e32 v53, v53
	v_rcp_f32_e32 v52, v52
	s_nop 0
	v_pk_mul_f32 v[52:53], v[44:45], v[52:53]
	s_nop 0
	v_add_f32_e32 v51, v52, v52
	v_mul_f32_e32 v51, 0x3fb8aa3b, v51
	v_exp_f32_e32 v51, v51
	s_nop 0
	v_sub_f32_e32 v51, 1.0, v51
	v_sqrt_f32_e32 v64, v51
	v_add_f32_e32 v51, v53, v53
	v_mul_f32_e32 v51, 0x3fb8aa3b, v51
	v_exp_f32_e32 v51, v51
	s_nop 0
	v_sub_f32_e32 v51, 1.0, v51
	v_sqrt_f32_e32 v65, v51
	v_cvt_pk_bf16_f32 v51, v52, v53
	v_pk_add_f32 v[52:53], v[68:69], 1.0 op_sel_hi:[1,0]
	s_nop 0
	v_rcp_f32_e32 v53, v53
	v_rcp_f32_e32 v52, v52
	s_nop 0
	v_pk_mul_f32 v[52:53], v[22:23], v[52:53]
	s_nop 0
	v_add_f32_e32 v68, v52, v52
	v_mul_f32_e32 v68, 0x3fb8aa3b, v68
	v_exp_f32_e32 v68, v68
	v_cvt_pk_bf16_f32 v52, v52, v53
	v_sub_f32_e32 v68, 1.0, v68
	v_sqrt_f32_e32 v68, v68
	v_add_f32_e32 v69, v53, v53
	v_mul_f32_e32 v69, 0x3fb8aa3b, v69
	v_exp_f32_e32 v69, v69
	s_nop 0
	v_sub_f32_e32 v69, 1.0, v69
	v_sqrt_f32_e32 v69, v69
	v_rcp_f32_e32 v61, v61
	s_mov_b64 s[4:5], 0x140000
	v_rcp_f32_e32 v60, v60
	s_nop 0
	v_pk_mul_f32 v[70:71], v[24:25], v[60:61]
	s_nop 0
	v_add_f32_e32 v53, v70, v70
	v_mul_f32_e32 v53, 0x3fb8aa3b, v53
	v_exp_f32_e32 v53, v53
	s_nop 0
	v_sub_f32_e32 v53, 1.0, v53
	v_sqrt_f32_e32 v60, v53
	v_add_f32_e32 v53, v71, v71
	v_mul_f32_e32 v53, 0x3fb8aa3b, v53
	v_exp_f32_e32 v53, v53
	s_nop 0
	v_sub_f32_e32 v53, 1.0, v53
	v_sqrt_f32_e32 v61, v53
	v_cvt_pk_bf16_f32 v53, v70, v71
	v_lshl_add_u64 v[70:71], v[174:175], 0, s[4:5]
	v_lshl_add_u64 v[72:73], s[44:45], 0, v[70:71]
	v_lshl_add_u64 v[72:73], v[72:73], 0, v[186:187]
	global_store_dwordx4 v[72:73], v[50:53], off
	s_nop 1
	v_pk_add_f32 v[52:53], v[66:67], 1.0 op_sel_hi:[1,0]
	v_lshlrev_b32_e32 v50, 16, v46
	v_and_b32_e32 v51, 0xffff0000, v46
	v_rcp_f32_e32 v53, v53
	v_rcp_f32_e32 v52, v52
	s_nop 0
	v_pk_mul_f32 v[50:51], v[52:53], v[50:51]
	v_pk_add_f32 v[52:53], v[62:63], 1.0 op_sel_hi:[1,0]
	v_pk_mul_f32 v[50:51], v[58:59], v[50:51]
	s_nop 0
	v_cvt_pk_bf16_f32 v46, v50, v51
	v_lshlrev_b32_e32 v50, 16, v47
	v_and_b32_e32 v51, 0xffff0000, v47
	v_rcp_f32_e32 v53, v53
	v_rcp_f32_e32 v52, v52
	s_nop 0
	v_pk_mul_f32 v[50:51], v[52:53], v[50:51]
	v_pk_add_f32 v[52:53], v[56:57], 1.0 op_sel_hi:[1,0]
	v_pk_mul_f32 v[50:51], v[64:65], v[50:51]
	s_nop 0
	v_cvt_pk_bf16_f32 v47, v50, v51
	v_lshlrev_b32_e32 v50, 16, v48
	v_and_b32_e32 v51, 0xffff0000, v48
	v_rcp_f32_e32 v53, v53
	v_rcp_f32_e32 v52, v52
	s_nop 0
	v_pk_mul_f32 v[50:51], v[52:53], v[50:51]
	v_pk_add_f32 v[52:53], v[54:55], 1.0 op_sel_hi:[1,0]
	v_pk_mul_f32 v[50:51], v[68:69], v[50:51]
	s_nop 0
	v_cvt_pk_bf16_f32 v48, v50, v51
	v_lshlrev_b32_e32 v50, 16, v49
	v_and_b32_e32 v51, 0xffff0000, v49
	v_rcp_f32_e32 v53, v53
	v_rcp_f32_e32 v52, v52
	s_nop 0
	v_pk_mul_f32 v[50:51], v[52:53], v[50:51]
	s_nop 0
	v_pk_mul_f32 v[50:51], v[60:61], v[50:51]
	s_nop 0
	v_cvt_pk_bf16_f32 v49, v50, v51
	v_lshl_add_u64 v[50:51], s[46:47], 0, v[70:71]
	v_lshl_add_u64 v[50:51], v[50:51], 0, v[186:187]
	global_store_dwordx4 v[50:51], v[46:49], off
	s_nop 1
	v_exp_f32_e32 v47, v10
	v_add_f32_e32 v10, v11, v39
	v_mul_f32_e32 v10, 0xbfb8aa3b, v10
	v_exp_f32_e32 v35, v10
	v_add_f32_e32 v10, v20, v36
	v_mul_f32_e32 v10, 0xbfb8aa3b, v10
	v_exp_f32_e32 v20, v10
	v_add_f32_e32 v10, v12, v40
	v_exp_f32_e32 v12, v6
	v_add_f32_e32 v6, v15, v27
	v_mul_f32_e32 v10, 0xbfb8aa3b, v10
	v_mul_f32_e32 v6, 0xbfb8aa3b, v6
	v_exp_f32_e32 v46, v18
	v_exp_f32_e32 v18, v10
	v_add_f32_e32 v10, v21, v37
	v_exp_f32_e32 v27, v6
	v_add_f32_e32 v6, v7, v31
	v_mul_f32_e32 v10, 0xbfb8aa3b, v10
	v_mul_f32_e32 v6, 0xbfb8aa3b, v6
	v_exp_f32_e32 v21, v10
	v_add_f32_e32 v10, v13, v41
	v_exp_f32_e32 v13, v6
	v_add_f32_e32 v6, v16, v28
	v_mul_f32_e32 v10, 0xbfb8aa3b, v10
	v_mul_f32_e32 v6, 0xbfb8aa3b, v6
	v_exp_f32_e32 v19, v10
	v_add_f32_e32 v10, v14, v26
	v_exp_f32_e32 v16, v6
	v_add_f32_e32 v6, v8, v32
	v_mul_f32_e32 v10, 0xbfb8aa3b, v10
; #define PG8_WAIT_V(n) asm volatile("s_waitcnt vmcnt(" #n ")" ::: "memory")
; #define PG8_BAR __builtin_amdgcn_s_barrier()
; template <class Epi, class GT>
; __device__ __forceinline__ void gemm_phase(LAS unsigned char* lds, const GT g, const StaticOrder& S, const Epi& E) {
;     ...
;         if (!has_next) break;
; #pragma unroll
;         for (int a = 0; a < 2; ++a)
; #pragma unroll
;             for (int b = 0; b < 2; ++b)
; #pragma unroll
;                 for (int m = 0; m < 4; ++m)
; #pragma unroll
;                     for (int n = 0; n < 2; ++n) acc[a][b][m][n] = (f32x4){0.f, 0.f, 0.f, 0.f};
;         cur = nxt; cA = nA; cB = nB; ++ui;
;     }
;     PG8_WAIT_V(0);
;     if (wr == 0) PG8_BAR;
;     PG8_BAR;
	v_mul_f32_e32 v6, 0xbfb8aa3b, v6
	v_exp_f32_e32 v26, v10
	v_exp_f32_e32 v10, v6
	v_add_f32_e32 v6, v17, v29
	v_mul_f32_e32 v6, 0xbfb8aa3b, v6
	v_exp_f32_e32 v17, v6
	v_add_f32_e32 v6, v9, v33
	v_mul_f32_e32 v6, 0xbfb8aa3b, v6
	v_exp_f32_e32 v11, v6
	v_pk_add_f32 v[6:7], v[46:47], 1.0 op_sel_hi:[1,0]
	v_pk_add_f32 v[16:17], v[16:17], 1.0 op_sel_hi:[1,0]
	v_rcp_f32_e32 v7, v7
	v_rcp_f32_e32 v6, v6
	s_nop 0
	v_pk_mul_f32 v[6:7], v[42:43], v[6:7]
	s_nop 0
	v_add_f32_e32 v8, v6, v6
	v_mul_f32_e32 v8, 0x3fb8aa3b, v8
	v_exp_f32_e32 v8, v8
	v_cvt_pk_bf16_f32 v6, v6, v7
	v_sub_f32_e32 v8, 1.0, v8
	v_sqrt_f32_e32 v14, v8
	v_add_f32_e32 v8, v7, v7
	v_mul_f32_e32 v8, 0x3fb8aa3b, v8
	v_exp_f32_e32 v8, v8
	s_nop 0
	v_sub_f32_e32 v8, 1.0, v8
	v_sqrt_f32_e32 v15, v8
	v_pk_add_f32 v[8:9], v[20:21], 1.0 op_sel_hi:[1,0]
	s_nop 0
	v_rcp_f32_e32 v9, v9
	v_rcp_f32_e32 v8, v8
	s_nop 0
	v_pk_mul_f32 v[8:9], v[44:45], v[8:9]
	s_nop 0
	v_add_f32_e32 v7, v8, v8
	v_mul_f32_e32 v7, 0x3fb8aa3b, v7
	v_exp_f32_e32 v7, v7
	s_nop 0
	v_sub_f32_e32 v7, 1.0, v7
	v_sqrt_f32_e32 v20, v7
	v_add_f32_e32 v7, v9, v9
	v_mul_f32_e32 v7, 0x3fb8aa3b, v7
	v_exp_f32_e32 v7, v7
	s_nop 0
	v_sub_f32_e32 v7, 1.0, v7
	v_sqrt_f32_e32 v21, v7
	v_cvt_pk_bf16_f32 v7, v8, v9
	v_pk_add_f32 v[8:9], v[26:27], 1.0 op_sel_hi:[1,0]
	s_nop 0
	v_rcp_f32_e32 v9, v9
	v_rcp_f32_e32 v8, v8
	s_nop 0
	v_pk_mul_f32 v[8:9], v[22:23], v[8:9]
	s_nop 0
	v_add_f32_e32 v22, v8, v8
	v_mul_f32_e32 v22, 0x3fb8aa3b, v22
	v_exp_f32_e32 v22, v22
	v_cvt_pk_bf16_f32 v8, v8, v9
	v_sub_f32_e32 v22, 1.0, v22
	v_sqrt_f32_e32 v22, v22
	v_add_f32_e32 v23, v9, v9
	v_mul_f32_e32 v23, 0x3fb8aa3b, v23
	v_exp_f32_e32 v23, v23
	s_nop 0
	v_sub_f32_e32 v23, 1.0, v23
	v_sqrt_f32_e32 v23, v23
	v_rcp_f32_e32 v17, v17
	s_mov_b64 s[4:5], 0x160000
	v_rcp_f32_e32 v16, v16
	s_nop 0
	v_pk_mul_f32 v[24:25], v[24:25], v[16:17]
	s_nop 0
	v_add_f32_e32 v9, v24, v24
	v_mul_f32_e32 v9, 0x3fb8aa3b, v9
	v_exp_f32_e32 v9, v9
	s_nop 0
	v_sub_f32_e32 v9, 1.0, v9
	v_sqrt_f32_e32 v16, v9
	v_add_f32_e32 v9, v25, v25
	v_mul_f32_e32 v9, 0x3fb8aa3b, v9
	v_exp_f32_e32 v9, v9
	s_nop 0
	v_sub_f32_e32 v9, 1.0, v9
	v_cmp_gt_f32_e32 vcc, s96, v9
	v_mul_f32_e32 v17, 0x4f800000, v9
	s_nop 0
	v_cndmask_b32_e32 v9, v9, v17, vcc
	v_sqrt_f32_e32 v17, v9
	s_nop 0
	v_add_u32_e32 v26, -1, v17
	v_fma_f32 v27, -v26, v17, v9
	v_cmp_ge_f32_e64 s[40:41], 0, v27
	v_add_u32_e32 v27, 1, v17
	s_nop 0
	v_cndmask_b32_e64 v26, v17, v26, s[40:41]
	v_fma_f32 v17, -v27, v17, v9
	v_cmp_lt_f32_e64 s[40:41], 0, v17
	s_nop 1
	v_cndmask_b32_e64 v17, v26, v27, s[40:41]
	v_mul_f32_e32 v26, 0x37800000, v17
	v_cndmask_b32_e32 v17, v17, v26, vcc
	v_cmp_class_f32_e32 vcc, v9, v222
	s_mov_b32 s40, s56
	s_nop 0
	v_cndmask_b32_e32 v17, v17, v9, vcc
	v_cvt_pk_bf16_f32 v9, v24, v25
	v_lshl_add_u64 v[24:25], v[174:175], 0, s[4:5]
	v_lshl_add_u64 v[26:27], s[44:45], 0, v[24:25]
	v_lshl_add_u64 v[26:27], v[26:27], 0, v[186:187]
	global_store_dwordx4 v[26:27], v[6:9], off
	s_nop 1
	v_pk_add_f32 v[8:9], v[34:35], 1.0 op_sel_hi:[1,0]
	v_lshlrev_b32_e32 v6, 16, v2
	v_and_b32_e32 v7, 0xffff0000, v2
	v_rcp_f32_e32 v9, v9
	v_rcp_f32_e32 v8, v8
	s_nop 0
	v_pk_mul_f32 v[6:7], v[8:9], v[6:7]
	v_pk_add_f32 v[8:9], v[18:19], 1.0 op_sel_hi:[1,0]
	v_pk_mul_f32 v[6:7], v[14:15], v[6:7]
	s_nop 0
	v_cvt_pk_bf16_f32 v2, v6, v7
	v_lshlrev_b32_e32 v6, 16, v3
	v_and_b32_e32 v7, 0xffff0000, v3
	v_rcp_f32_e32 v9, v9
	v_rcp_f32_e32 v8, v8
	s_nop 0
	v_pk_mul_f32 v[6:7], v[8:9], v[6:7]
	v_pk_add_f32 v[8:9], v[12:13], 1.0 op_sel_hi:[1,0]
	v_pk_mul_f32 v[6:7], v[20:21], v[6:7]
	s_nop 0
	v_cvt_pk_bf16_f32 v3, v6, v7
	v_lshlrev_b32_e32 v6, 16, v4
	v_and_b32_e32 v7, 0xffff0000, v4
	v_rcp_f32_e32 v9, v9
	v_rcp_f32_e32 v8, v8
	s_nop 0
	v_pk_mul_f32 v[6:7], v[8:9], v[6:7]
	v_pk_add_f32 v[8:9], v[10:11], 1.0 op_sel_hi:[1,0]
	v_pk_mul_f32 v[6:7], v[22:23], v[6:7]
	s_nop 0
	v_cvt_pk_bf16_f32 v4, v6, v7
	v_lshlrev_b32_e32 v6, 16, v5
	v_and_b32_e32 v7, 0xffff0000, v5
	v_rcp_f32_e32 v9, v9
	v_rcp_f32_e32 v8, v8
	s_nop 0
	v_pk_mul_f32 v[6:7], v[8:9], v[6:7]
	s_and_b64 vcc, exec, s[38:39]
	v_pk_mul_f32 v[6:7], v[16:17], v[6:7]
	s_nop 0
	v_cvt_pk_bf16_f32 v5, v6, v7
	v_lshl_add_u64 v[6:7], s[46:47], 0, v[24:25]
	v_lshl_add_u64 v[6:7], v[6:7], 0, v[186:187]
	global_store_dwordx4 v[6:7], v[2:5], off
	s_cbranch_vccz .LBB0_3432
	s_waitcnt vmcnt(0)
	s_cmpk_gt_u32 s80, 0xff
	s_cbranch_scc1 .LBB0_3439
	s_barrier
